# L1 down epilogue: residual/gain loads issued before the stats exchange; sc1 dwordx4 stores
# speedup vs baseline: 1.0105x; 1.0105x over previous
.LBB0_36:
	s_cmpk_gt_u32 s18, 0x7ff
	s_cbranch_scc0 .LBB0_46
	s_cmpk_gt_u32 s18, 0xd7f
	s_cbranch_scc0 .LBB0_43
	s_cmpk_gt_u32 s18, 0x12ff
	s_cbranch_scc0 .LBB0_40
	v_add_u32_e32 v78, v203, v226
	v_add_u32_e32 v79, 0x420, v78
	s_waitcnt vmcnt(7)
	ds_write2_b32 v78, v38, v39 offset1:1
	ds_write2_b32 v78, v40, v41 offset0:2 offset1:3
	s_waitcnt vmcnt(6)
	ds_write2_b32 v79, v34, v35 offset1:1
	v_add_u32_e32 v79, 0x428, v78
	ds_write2_b32 v79, v36, v37 offset1:1
	v_add_u32_e32 v79, 0x840, v78
	s_waitcnt vmcnt(5)
	ds_write2_b32 v79, v30, v31 offset1:1
	v_add_u32_e32 v79, 0x848, v78
	ds_write2_b32 v79, v32, v33 offset1:1
	v_add_u32_e32 v79, 0xc60, v78
	s_waitcnt vmcnt(4)
	ds_write2_b32 v79, v14, v15 offset1:1
	v_add_u32_e32 v79, 0xc68, v78
	ds_write2_b32 v79, v16, v17 offset1:1
	v_add_u32_e32 v79, 0x1080, v78
	s_waitcnt vmcnt(3)
	ds_write2_b32 v79, v22, v23 offset1:1
	v_add_u32_e32 v79, 0x1088, v78
	ds_write2_b32 v79, v24, v25 offset1:1
	v_add_u32_e32 v79, 0x14a0, v78
	s_waitcnt vmcnt(2)
	ds_write2_b32 v79, v6, v7 offset1:1
	v_add_u32_e32 v79, 0x14a8, v78
	ds_write2_b32 v79, v8, v9 offset1:1
	v_add_u32_e32 v79, 0x18c0, v78
	s_waitcnt vmcnt(1)
	ds_write2_b32 v79, v10, v11 offset1:1
	v_add_u32_e32 v79, 0x18c8, v78
	ds_write2_b32 v79, v12, v13 offset1:1
	v_add_u32_e32 v79, 0x1ce0, v78
	v_add_u32_e32 v78, 0x1ce8, v78
	s_waitcnt vmcnt(0)
	ds_write2_b32 v79, v2, v3 offset1:1
	ds_write2_b32 v78, v4, v5 offset1:1
	s_waitcnt lgkmcnt(0)
	ds_read2_b32 v[82:83], v76 offset1:8
	ds_read2_b32 v[86:87], v76 offset0:33 offset1:41
	ds_read2_b32 v[88:89], v76 offset0:66 offset1:74
	ds_read2_b32 v[90:91], v76 offset0:99 offset1:107
	ds_read2_b32 v[92:93], v76 offset0:132 offset1:140
	s_waitcnt lgkmcnt(4)
	v_bfe_u32 v78, v82, 16, 1
	v_add3_u32 v78, v82, v78, s13
	s_waitcnt lgkmcnt(3)
	v_bfe_u32 v79, v86, 16, 1
	v_lshrrev_b32_e32 v78, 16, v78
	v_add3_u32 v79, v86, v79, s13
	ds_read2_b32 v[94:95], v76 offset0:165 offset1:173
	v_and_or_b32 v78, v79, s16, v78
	s_waitcnt lgkmcnt(3)
	v_bfe_u32 v79, v88, 16, 1
	v_add3_u32 v79, v88, v79, s13
	s_waitcnt lgkmcnt(2)
	v_bfe_u32 v80, v90, 16, 1
	ds_read2_b32 v[96:97], v76 offset0:198 offset1:206
	v_lshrrev_b32_e32 v79, 16, v79
	v_add3_u32 v80, v90, v80, s13
	ds_read2_b32 v[98:99], v76 offset0:231 offset1:239
	v_and_or_b32 v79, v80, s16, v79
	s_waitcnt lgkmcnt(3)
	v_bfe_u32 v80, v92, 16, 1
	v_add3_u32 v80, v92, v80, s13
	s_waitcnt lgkmcnt(2)
	v_bfe_u32 v81, v94, 16, 1
	v_lshrrev_b32_e32 v80, 16, v80
	v_add3_u32 v81, v94, v81, s13
	v_and_or_b32 v80, v81, s16, v80
	s_waitcnt lgkmcnt(1)
	v_bfe_u32 v81, v96, 16, 1
	v_add3_u32 v81, v96, v81, s13
	s_waitcnt lgkmcnt(0)
	v_bfe_u32 v82, v98, 16, 1
	s_and_b32 s0, s12, 0xfc0
	s_and_b32 s6, s3, 0x3e0
	v_lshrrev_b32_e32 v81, 16, v81
	v_add3_u32 v82, v98, v82, s13
	s_lshl_b32 s0, s0, 1
	v_and_or_b32 v81, v82, s16, v81
	v_or_b32_e32 v82, s6, v199
	v_lshl_add_u64 v[84:85], v[68:69], 0, s[0:1]
	v_mul_u32_u24_e32 v100, 0x1600, v82
	v_mov_b32_e32 v101, v67
	v_lshl_add_u64 v[100:101], v[84:85], 0, v[100:101]
	global_store_dwordx4 v[100:101], v[78:81], off sc1
	v_bfe_u32 v82, v99, 16, 1
	v_add3_u32 v82, v99, v82, s13
	v_bfe_u32 v78, v83, 16, 1
	v_add3_u32 v78, v83, v78, s13
	v_bfe_u32 v79, v87, 16, 1
	v_lshrrev_b32_e32 v78, 16, v78
	v_add3_u32 v79, v87, v79, s13
	v_and_or_b32 v78, v79, s16, v78
	v_bfe_u32 v79, v89, 16, 1
	v_add3_u32 v79, v89, v79, s13
	v_bfe_u32 v80, v91, 16, 1
	v_lshrrev_b32_e32 v79, 16, v79
	v_add3_u32 v80, v91, v80, s13
	v_and_or_b32 v79, v80, s16, v79
	v_bfe_u32 v80, v93, 16, 1
	v_add3_u32 v80, v93, v80, s13
	v_bfe_u32 v81, v95, 16, 1
	v_lshrrev_b32_e32 v80, 16, v80
	v_add3_u32 v81, v95, v81, s13
	v_and_or_b32 v80, v81, s16, v80
	v_bfe_u32 v81, v97, 16, 1
	v_add3_u32 v81, v97, v81, s13
	v_lshrrev_b32_e32 v81, 16, v81
	v_and_or_b32 v81, v82, s16, v81
	v_or_b32_e32 v82, s6, v227
	v_mul_u32_u24_e32 v82, 0x1600, v82
	v_mov_b32_e32 v83, v67
	ds_read2_b32 v[86:87], v76 offset0:16 offset1:24
	v_lshl_add_u64 v[82:83], v[84:85], 0, v[82:83]
	global_store_dwordx4 v[82:83], v[78:81], off sc1
	ds_read2_b32 v[82:83], v76 offset0:49 offset1:57
	ds_read2_b32 v[88:89], v76 offset0:82 offset1:90
	ds_read2_b32 v[90:91], v76 offset0:115 offset1:123
	s_waitcnt lgkmcnt(3)
	v_bfe_u32 v78, v86, 16, 1
	v_add3_u32 v78, v86, v78, s13
	s_waitcnt lgkmcnt(2)
	v_bfe_u32 v79, v82, 16, 1
	ds_read2_b32 v[92:93], v76 offset0:148 offset1:156
	v_lshrrev_b32_e32 v78, 16, v78
	v_add3_u32 v79, v82, v79, s13
	ds_read2_b32 v[94:95], v76 offset0:181 offset1:189
	v_and_or_b32 v78, v79, s16, v78
	s_waitcnt lgkmcnt(3)
	v_bfe_u32 v79, v88, 16, 1
	v_add3_u32 v79, v88, v79, s13
	s_waitcnt lgkmcnt(2)
	v_bfe_u32 v80, v90, 16, 1
	ds_read2_b32 v[96:97], v76 offset0:214 offset1:222
	v_lshrrev_b32_e32 v79, 16, v79
	v_add3_u32 v80, v90, v80, s13
	ds_read2_b32 v[98:99], v76 offset0:247 offset1:255
	v_and_or_b32 v79, v80, s16, v79
	s_waitcnt lgkmcnt(3)
	v_bfe_u32 v80, v92, 16, 1
	v_add3_u32 v80, v92, v80, s13
	s_waitcnt lgkmcnt(2)
	v_bfe_u32 v81, v94, 16, 1
	v_lshrrev_b32_e32 v80, 16, v80
	v_add3_u32 v81, v94, v81, s13
	v_and_or_b32 v80, v81, s16, v80
	s_waitcnt lgkmcnt(1)
	v_bfe_u32 v81, v96, 16, 1
	v_add3_u32 v81, v96, v81, s13
	s_waitcnt lgkmcnt(0)
	v_bfe_u32 v82, v98, 16, 1
	v_lshrrev_b32_e32 v81, 16, v81
	v_add3_u32 v82, v98, v82, s13
	v_and_or_b32 v81, v82, s16, v81
	v_or_b32_e32 v82, s6, v228
	v_mul_u32_u24_e32 v100, 0x1600, v82
	v_mov_b32_e32 v101, v67
	v_lshl_add_u64 v[100:101], v[84:85], 0, v[100:101]
	global_store_dwordx4 v[100:101], v[78:81], off sc1
	v_bfe_u32 v82, v99, 16, 1
	v_add3_u32 v82, v99, v82, s13
	v_bfe_u32 v78, v87, 16, 1
	v_add3_u32 v78, v87, v78, s13
	v_bfe_u32 v79, v83, 16, 1
	v_lshrrev_b32_e32 v78, 16, v78
	v_add3_u32 v79, v83, v79, s13
	v_and_or_b32 v78, v79, s16, v78
	v_bfe_u32 v79, v89, 16, 1
	v_add3_u32 v79, v89, v79, s13
	v_bfe_u32 v80, v91, 16, 1
	v_lshrrev_b32_e32 v79, 16, v79
	v_add3_u32 v80, v91, v80, s13
	v_and_or_b32 v79, v80, s16, v79
	v_bfe_u32 v80, v93, 16, 1
	v_add3_u32 v80, v93, v80, s13
	v_bfe_u32 v81, v95, 16, 1
	v_lshrrev_b32_e32 v80, 16, v80
	v_add3_u32 v81, v95, v81, s13
	v_and_or_b32 v80, v81, s16, v80
	v_bfe_u32 v81, v97, 16, 1
	v_add3_u32 v81, v97, v81, s13
	v_lshrrev_b32_e32 v81, 16, v81
	v_and_or_b32 v81, v82, s16, v81
	v_or_b32_e32 v82, s6, v229
	v_mul_u32_u24_e32 v82, 0x1600, v82
	v_mov_b32_e32 v83, v67
	v_lshl_add_u64 v[82:83], v[84:85], 0, v[82:83]
	global_store_dwordx4 v[82:83], v[78:81], off sc1
	s_waitcnt lgkmcnt(0)
	s_mov_b64 s[6:7], 0
.LBB0_40:
	s_andn2_b64 vcc, exec, s[6:7]
	s_cbranch_vccnz .LBB0_42
	v_add_u32_e32 v78, v203, v226
	v_add_u32_e32 v79, 0x420, v78
	s_waitcnt vmcnt(7)
	ds_write2_b32 v78, v38, v39 offset1:1
	ds_write2_b32 v78, v40, v41 offset0:2 offset1:3
	s_waitcnt vmcnt(6)
	ds_write2_b32 v79, v34, v35 offset1:1
	v_add_u32_e32 v79, 0x428, v78
	ds_write2_b32 v79, v36, v37 offset1:1
	v_add_u32_e32 v79, 0x840, v78
	s_waitcnt vmcnt(5)
	ds_write2_b32 v79, v30, v31 offset1:1
	v_add_u32_e32 v79, 0x848, v78
	ds_write2_b32 v79, v32, v33 offset1:1
	v_add_u32_e32 v79, 0xc60, v78
	s_waitcnt vmcnt(4)
	ds_write2_b32 v79, v14, v15 offset1:1
	v_add_u32_e32 v79, 0xc68, v78
	ds_write2_b32 v79, v16, v17 offset1:1
	v_add_u32_e32 v79, 0x1080, v78
	s_waitcnt vmcnt(3)
	ds_write2_b32 v79, v22, v23 offset1:1
	v_add_u32_e32 v79, 0x1088, v78
	ds_write2_b32 v79, v24, v25 offset1:1
	v_add_u32_e32 v79, 0x14a0, v78
	s_waitcnt vmcnt(2)
	ds_write2_b32 v79, v6, v7 offset1:1
	v_add_u32_e32 v79, 0x14a8, v78
	ds_write2_b32 v79, v8, v9 offset1:1
	v_add_u32_e32 v79, 0x18c0, v78
	s_waitcnt vmcnt(1)
	ds_write2_b32 v79, v10, v11 offset1:1
	v_add_u32_e32 v79, 0x18c8, v78
	ds_write2_b32 v79, v12, v13 offset1:1
	v_add_u32_e32 v79, 0x1ce0, v78
	v_add_u32_e32 v78, 0x1ce8, v78
	s_waitcnt vmcnt(0)
	ds_write2_b32 v79, v2, v3 offset1:1
	ds_write2_b32 v78, v4, v5 offset1:1
	s_waitcnt lgkmcnt(0)
	ds_read2_b32 v[82:83], v76 offset1:8
	ds_read2_b32 v[86:87], v76 offset0:33 offset1:41
	ds_read2_b32 v[88:89], v76 offset0:66 offset1:74
	ds_read2_b32 v[90:91], v76 offset0:99 offset1:107
	ds_read2_b32 v[92:93], v76 offset0:132 offset1:140
	s_waitcnt lgkmcnt(4)
	v_bfe_u32 v78, v82, 16, 1
	v_add3_u32 v78, v82, v78, s13
	s_waitcnt lgkmcnt(3)
	v_bfe_u32 v79, v86, 16, 1
	s_add_i32 s0, s18, 0xf280
	v_lshrrev_b32_e32 v78, 16, v78
	v_add3_u32 v79, v86, v79, s13
	ds_read2_b32 v[94:95], v76 offset0:165 offset1:173
	s_and_b32 s6, s0, 0xffff
	v_and_or_b32 v78, v79, s16, v78
	s_waitcnt lgkmcnt(3)
	v_bfe_u32 v79, v88, 16, 1
	s_mul_i32 s6, s6, 0xba2f
	v_add3_u32 v79, v88, v79, s13
	s_waitcnt lgkmcnt(2)
	v_bfe_u32 v80, v90, 16, 1
	ds_read2_b32 v[96:97], v76 offset0:198 offset1:206
	s_lshr_b32 s7, s6, 22
	v_lshrrev_b32_e32 v79, 16, v79
	v_add3_u32 v80, v90, v80, s13
	ds_read2_b32 v[98:99], v76 offset0:231 offset1:239
	s_mulk_i32 s7, 0x58
	v_and_or_b32 v79, v80, s16, v79
	s_waitcnt lgkmcnt(3)
	v_bfe_u32 v80, v92, 16, 1
	s_sub_i32 s0, s0, s7
	v_add3_u32 v80, v92, v80, s13
	s_waitcnt lgkmcnt(2)
	v_bfe_u32 v81, v94, 16, 1
	s_lshl_b32 s7, s0, 5
	s_lshl_b32 s0, s0, 6
	v_lshrrev_b32_e32 v80, 16, v80
	v_add3_u32 v81, v94, v81, s13
	s_and_b32 s0, s0, 0x1f00
	s_and_b32 s7, s7, 0x60
	v_and_or_b32 v80, v81, s16, v80
	s_waitcnt lgkmcnt(1)
	v_bfe_u32 v81, v96, 16, 1
	s_or_b32 s0, s7, s0
	v_add3_u32 v81, v96, v81, s13
	s_waitcnt lgkmcnt(0)
	v_bfe_u32 v82, v98, 16, 1
	s_or_b32 s7, s0, 0x80
	s_lshr_b32 s0, s6, 15
	v_lshrrev_b32_e32 v81, 16, v81
	v_add3_u32 v82, v98, v82, s13
	s_and_b32 s0, s0, 0x1ff80
	v_and_or_b32 v81, v82, s16, v81
	v_or_b32_e32 v82, s7, v199
	v_lshl_add_u64 v[84:85], v[70:71], 0, s[0:1]
	v_lshlrev_b32_e32 v100, 11, v82
	v_mov_b32_e32 v101, v67
	v_lshl_add_u64 v[100:101], v[84:85], 0, v[100:101]
	global_store_dwordx4 v[100:101], v[78:81], off sc1
	v_bfe_u32 v82, v99, 16, 1
	v_add3_u32 v82, v99, v82, s13
	v_bfe_u32 v78, v83, 16, 1
	v_add3_u32 v78, v83, v78, s13
	v_bfe_u32 v79, v87, 16, 1
	v_lshrrev_b32_e32 v78, 16, v78
	v_add3_u32 v79, v87, v79, s13
	v_and_or_b32 v78, v79, s16, v78
	v_bfe_u32 v79, v89, 16, 1
	v_add3_u32 v79, v89, v79, s13
	v_bfe_u32 v80, v91, 16, 1
	v_lshrrev_b32_e32 v79, 16, v79
	v_add3_u32 v80, v91, v80, s13
	v_and_or_b32 v79, v80, s16, v79
	v_bfe_u32 v80, v93, 16, 1
	v_add3_u32 v80, v93, v80, s13
	v_bfe_u32 v81, v95, 16, 1
	v_lshrrev_b32_e32 v80, 16, v80
	v_add3_u32 v81, v95, v81, s13
	v_and_or_b32 v80, v81, s16, v80
	v_bfe_u32 v81, v97, 16, 1
	v_add3_u32 v81, v97, v81, s13
	v_lshrrev_b32_e32 v81, 16, v81
	v_and_or_b32 v81, v82, s16, v81
	v_or_b32_e32 v82, s7, v227
	v_lshlrev_b32_e32 v82, 11, v82
	v_mov_b32_e32 v83, v67
	ds_read2_b32 v[86:87], v76 offset0:16 offset1:24
	v_lshl_add_u64 v[82:83], v[84:85], 0, v[82:83]
	global_store_dwordx4 v[82:83], v[78:81], off sc1
	ds_read2_b32 v[82:83], v76 offset0:49 offset1:57
	ds_read2_b32 v[88:89], v76 offset0:82 offset1:90
	ds_read2_b32 v[90:91], v76 offset0:115 offset1:123
	s_waitcnt lgkmcnt(3)
	v_bfe_u32 v78, v86, 16, 1
	v_add3_u32 v78, v86, v78, s13
	s_waitcnt lgkmcnt(2)
	v_bfe_u32 v79, v82, 16, 1
	ds_read2_b32 v[92:93], v76 offset0:148 offset1:156
	v_lshrrev_b32_e32 v78, 16, v78
	v_add3_u32 v79, v82, v79, s13
	ds_read2_b32 v[94:95], v76 offset0:181 offset1:189
	v_and_or_b32 v78, v79, s16, v78
	s_waitcnt lgkmcnt(3)
	v_bfe_u32 v79, v88, 16, 1
	v_add3_u32 v79, v88, v79, s13
	s_waitcnt lgkmcnt(2)
	v_bfe_u32 v80, v90, 16, 1
	ds_read2_b32 v[96:97], v76 offset0:214 offset1:222
	v_lshrrev_b32_e32 v79, 16, v79
	v_add3_u32 v80, v90, v80, s13
	ds_read2_b32 v[98:99], v76 offset0:247 offset1:255
	v_and_or_b32 v79, v80, s16, v79
	s_waitcnt lgkmcnt(3)
	v_bfe_u32 v80, v92, 16, 1
	v_add3_u32 v80, v92, v80, s13
	s_waitcnt lgkmcnt(2)
	v_bfe_u32 v81, v94, 16, 1
	v_lshrrev_b32_e32 v80, 16, v80
	v_add3_u32 v81, v94, v81, s13
	v_and_or_b32 v80, v81, s16, v80
	s_waitcnt lgkmcnt(1)
	v_bfe_u32 v81, v96, 16, 1
	v_add3_u32 v81, v96, v81, s13
	s_waitcnt lgkmcnt(0)
	v_bfe_u32 v82, v98, 16, 1
	v_lshrrev_b32_e32 v81, 16, v81
	v_add3_u32 v82, v98, v82, s13
	v_and_or_b32 v81, v82, s16, v81
	v_or_b32_e32 v82, s7, v228
	v_lshlrev_b32_e32 v100, 11, v82
	v_mov_b32_e32 v101, v67
	v_lshl_add_u64 v[100:101], v[84:85], 0, v[100:101]
	global_store_dwordx4 v[100:101], v[78:81], off sc1
	v_bfe_u32 v82, v99, 16, 1
	v_add3_u32 v82, v99, v82, s13
	v_bfe_u32 v78, v87, 16, 1
	v_add3_u32 v78, v87, v78, s13
	v_bfe_u32 v79, v83, 16, 1
	v_lshrrev_b32_e32 v78, 16, v78
	v_add3_u32 v79, v83, v79, s13
	v_and_or_b32 v78, v79, s16, v78
	v_bfe_u32 v79, v89, 16, 1
	v_add3_u32 v79, v89, v79, s13
	v_bfe_u32 v80, v91, 16, 1
	v_lshrrev_b32_e32 v79, 16, v79
	v_add3_u32 v80, v91, v80, s13
	v_and_or_b32 v79, v80, s16, v79
	v_bfe_u32 v80, v93, 16, 1
	v_add3_u32 v80, v93, v80, s13
	v_bfe_u32 v81, v95, 16, 1
	v_lshrrev_b32_e32 v80, 16, v80
	v_add3_u32 v81, v95, v81, s13
	v_and_or_b32 v80, v81, s16, v80
	v_bfe_u32 v81, v97, 16, 1
	v_add3_u32 v81, v97, v81, s13
	v_lshrrev_b32_e32 v81, 16, v81
	v_and_or_b32 v81, v82, s16, v81
	v_or_b32_e32 v82, s7, v229
	v_lshlrev_b32_e32 v82, 11, v82
	v_mov_b32_e32 v83, v67
	v_lshl_add_u64 v[82:83], v[84:85], 0, v[82:83]
	global_store_dwordx4 v[82:83], v[78:81], off sc1
	s_waitcnt lgkmcnt(0)

.LBB0_43:
	s_andn2_b64 vcc, exec, s[6:7]
	s_cbranch_vccnz .LBB0_45
	v_add_u32_e32 v78, v203, v226
	v_add_u32_e32 v79, 0x420, v78
	s_waitcnt vmcnt(7)
	ds_write2_b32 v78, v38, v39 offset1:1
	ds_write2_b32 v78, v40, v41 offset0:2 offset1:3
	s_waitcnt vmcnt(6)
	ds_write2_b32 v79, v34, v35 offset1:1
	v_add_u32_e32 v79, 0x428, v78
	ds_write2_b32 v79, v36, v37 offset1:1
	v_add_u32_e32 v79, 0x840, v78
	s_waitcnt vmcnt(5)
	ds_write2_b32 v79, v30, v31 offset1:1
	v_add_u32_e32 v79, 0x848, v78
	ds_write2_b32 v79, v32, v33 offset1:1
	v_add_u32_e32 v79, 0xc60, v78
	s_waitcnt vmcnt(4)
	ds_write2_b32 v79, v14, v15 offset1:1
	v_add_u32_e32 v79, 0xc68, v78
	ds_write2_b32 v79, v16, v17 offset1:1
	v_add_u32_e32 v79, 0x1080, v78
	s_waitcnt vmcnt(3)
	ds_write2_b32 v79, v22, v23 offset1:1
	v_add_u32_e32 v79, 0x1088, v78
	ds_write2_b32 v79, v24, v25 offset1:1
	v_add_u32_e32 v79, 0x14a0, v78
	s_waitcnt vmcnt(2)
	ds_write2_b32 v79, v6, v7 offset1:1
	v_add_u32_e32 v79, 0x14a8, v78
	ds_write2_b32 v79, v8, v9 offset1:1
	v_add_u32_e32 v79, 0x18c0, v78
	s_waitcnt vmcnt(1)
	ds_write2_b32 v79, v10, v11 offset1:1
	v_add_u32_e32 v79, 0x18c8, v78
	ds_write2_b32 v79, v12, v13 offset1:1
	v_add_u32_e32 v79, 0x1ce0, v78
	v_add_u32_e32 v78, 0x1ce8, v78
	s_waitcnt vmcnt(0)
	ds_write2_b32 v79, v2, v3 offset1:1
	ds_write2_b32 v78, v4, v5 offset1:1
	s_waitcnt lgkmcnt(0)
	ds_read2_b32 v[82:83], v76 offset1:8
	ds_read2_b32 v[86:87], v76 offset0:33 offset1:41
	ds_read2_b32 v[88:89], v76 offset0:66 offset1:74
	ds_read2_b32 v[90:91], v76 offset0:99 offset1:107
	ds_read2_b32 v[92:93], v76 offset0:132 offset1:140
	s_waitcnt lgkmcnt(4)
	v_bfe_u32 v78, v82, 16, 1
	v_add3_u32 v78, v82, v78, s13
	s_waitcnt lgkmcnt(3)
	v_bfe_u32 v79, v86, 16, 1
	v_lshrrev_b32_e32 v78, 16, v78
	v_add3_u32 v79, v86, v79, s13
	ds_read2_b32 v[94:95], v76 offset0:165 offset1:173
	s_add_i32 s0, s18, 0xf800
	v_and_or_b32 v78, v79, s16, v78
	s_waitcnt lgkmcnt(3)
	v_bfe_u32 v79, v88, 16, 1
	s_and_b32 s6, s0, 0xffff
	v_add3_u32 v79, v88, v79, s13
	s_waitcnt lgkmcnt(2)
	v_bfe_u32 v80, v90, 16, 1
	ds_read2_b32 v[96:97], v76 offset0:198 offset1:206
	s_mul_i32 s6, s6, 0xba2f
	v_lshrrev_b32_e32 v79, 16, v79
	v_add3_u32 v80, v90, v80, s13
	ds_read2_b32 v[98:99], v76 offset0:231 offset1:239
	s_lshr_b32 s7, s6, 22
	v_and_or_b32 v79, v80, s16, v79
	s_waitcnt lgkmcnt(3)
	v_bfe_u32 v80, v92, 16, 1
	s_mulk_i32 s7, 0x58
	v_add3_u32 v80, v92, v80, s13
	s_waitcnt lgkmcnt(2)
	v_bfe_u32 v81, v94, 16, 1
	s_sub_i32 s0, s0, s7
	v_lshrrev_b32_e32 v80, 16, v80
	v_add3_u32 v81, v94, v81, s13
	s_lshl_b32 s7, s0, 5
	s_lshl_b32 s0, s0, 6
	v_and_or_b32 v80, v81, s16, v80
	s_waitcnt lgkmcnt(1)
	v_bfe_u32 v81, v96, 16, 1
	s_and_b32 s0, s0, 0x1f00
	s_and_b32 s7, s7, 0x60
	v_add3_u32 v81, v96, v81, s13
	s_waitcnt lgkmcnt(0)
	v_bfe_u32 v82, v98, 16, 1
	s_or_b32 s7, s0, s7
	s_lshr_b32 s0, s6, 15
	v_lshrrev_b32_e32 v81, 16, v81
	v_add3_u32 v82, v98, v82, s13
	s_and_b32 s0, s0, 0x1ff80
	v_and_or_b32 v81, v82, s16, v81
	v_or_b32_e32 v82, s7, v199
	v_lshl_add_u64 v[84:85], v[70:71], 0, s[0:1]
	v_lshlrev_b32_e32 v100, 11, v82
	v_mov_b32_e32 v101, v67
	v_lshl_add_u64 v[100:101], v[84:85], 0, v[100:101]
	global_store_dwordx4 v[100:101], v[78:81], off sc1
	v_bfe_u32 v82, v99, 16, 1
	v_add3_u32 v82, v99, v82, s13
	v_bfe_u32 v78, v83, 16, 1
	v_add3_u32 v78, v83, v78, s13
	v_bfe_u32 v79, v87, 16, 1
	v_lshrrev_b32_e32 v78, 16, v78
	v_add3_u32 v79, v87, v79, s13
	v_and_or_b32 v78, v79, s16, v78
	v_bfe_u32 v79, v89, 16, 1
	v_add3_u32 v79, v89, v79, s13
	v_bfe_u32 v80, v91, 16, 1
	v_lshrrev_b32_e32 v79, 16, v79
	v_add3_u32 v80, v91, v80, s13
	v_and_or_b32 v79, v80, s16, v79
	v_bfe_u32 v80, v93, 16, 1
	v_add3_u32 v80, v93, v80, s13
	v_bfe_u32 v81, v95, 16, 1
	v_lshrrev_b32_e32 v80, 16, v80
	v_add3_u32 v81, v95, v81, s13
	v_and_or_b32 v80, v81, s16, v80
	v_bfe_u32 v81, v97, 16, 1
	v_add3_u32 v81, v97, v81, s13
	v_lshrrev_b32_e32 v81, 16, v81
	v_and_or_b32 v81, v82, s16, v81
	v_or_b32_e32 v82, s7, v227
	v_lshlrev_b32_e32 v82, 11, v82
	v_mov_b32_e32 v83, v67
	ds_read2_b32 v[86:87], v76 offset0:16 offset1:24
	v_lshl_add_u64 v[82:83], v[84:85], 0, v[82:83]
	global_store_dwordx4 v[82:83], v[78:81], off sc1
	ds_read2_b32 v[82:83], v76 offset0:49 offset1:57
	ds_read2_b32 v[88:89], v76 offset0:82 offset1:90
	ds_read2_b32 v[90:91], v76 offset0:115 offset1:123
	s_waitcnt lgkmcnt(3)
	v_bfe_u32 v78, v86, 16, 1
	v_add3_u32 v78, v86, v78, s13
	s_waitcnt lgkmcnt(2)
	v_bfe_u32 v79, v82, 16, 1
	ds_read2_b32 v[92:93], v76 offset0:148 offset1:156
	v_lshrrev_b32_e32 v78, 16, v78
	v_add3_u32 v79, v82, v79, s13
	ds_read2_b32 v[94:95], v76 offset0:181 offset1:189
	v_and_or_b32 v78, v79, s16, v78
	s_waitcnt lgkmcnt(3)
	v_bfe_u32 v79, v88, 16, 1
	v_add3_u32 v79, v88, v79, s13
	s_waitcnt lgkmcnt(2)
	v_bfe_u32 v80, v90, 16, 1
	ds_read2_b32 v[96:97], v76 offset0:214 offset1:222
	v_lshrrev_b32_e32 v79, 16, v79
	v_add3_u32 v80, v90, v80, s13
	ds_read2_b32 v[98:99], v76 offset0:247 offset1:255
	v_and_or_b32 v79, v80, s16, v79
	s_waitcnt lgkmcnt(3)
	v_bfe_u32 v80, v92, 16, 1
	v_add3_u32 v80, v92, v80, s13
	s_waitcnt lgkmcnt(2)
	v_bfe_u32 v81, v94, 16, 1
	v_lshrrev_b32_e32 v80, 16, v80
	v_add3_u32 v81, v94, v81, s13
	v_and_or_b32 v80, v81, s16, v80
	s_waitcnt lgkmcnt(1)
	v_bfe_u32 v81, v96, 16, 1
	v_add3_u32 v81, v96, v81, s13
	s_waitcnt lgkmcnt(0)
	v_bfe_u32 v82, v98, 16, 1
	v_lshrrev_b32_e32 v81, 16, v81
	v_add3_u32 v82, v98, v82, s13
	v_and_or_b32 v81, v82, s16, v81
	v_or_b32_e32 v82, s7, v228
	v_lshlrev_b32_e32 v100, 11, v82
	v_mov_b32_e32 v101, v67
	v_lshl_add_u64 v[100:101], v[84:85], 0, v[100:101]
	global_store_dwordx4 v[100:101], v[78:81], off sc1
	v_bfe_u32 v82, v99, 16, 1
	v_add3_u32 v82, v99, v82, s13
	v_bfe_u32 v78, v87, 16, 1
	v_add3_u32 v78, v87, v78, s13
	v_bfe_u32 v79, v83, 16, 1
	v_lshrrev_b32_e32 v78, 16, v78
	v_add3_u32 v79, v83, v79, s13
	v_and_or_b32 v78, v79, s16, v78
	v_bfe_u32 v79, v89, 16, 1
	v_add3_u32 v79, v89, v79, s13
	v_bfe_u32 v80, v91, 16, 1
	v_lshrrev_b32_e32 v79, 16, v79
	v_add3_u32 v80, v91, v80, s13
	v_and_or_b32 v79, v80, s16, v79
	v_bfe_u32 v80, v93, 16, 1
	v_add3_u32 v80, v93, v80, s13
	v_bfe_u32 v81, v95, 16, 1
	v_lshrrev_b32_e32 v80, 16, v80
	v_add3_u32 v81, v95, v81, s13
	v_and_or_b32 v80, v81, s16, v80
	v_bfe_u32 v81, v97, 16, 1
	v_add3_u32 v81, v97, v81, s13
	v_lshrrev_b32_e32 v81, 16, v81
	v_and_or_b32 v81, v82, s16, v81
	v_or_b32_e32 v82, s7, v229
	v_lshlrev_b32_e32 v82, 11, v82
	v_mov_b32_e32 v83, v67
	v_lshl_add_u64 v[82:83], v[84:85], 0, v[82:83]
	global_store_dwordx4 v[82:83], v[78:81], off sc1
	s_waitcnt lgkmcnt(0)

.LBB0_46:
	s_andn2_b64 vcc, exec, s[6:7]
	s_cbranch_vccnz .LBB0_48
	v_add_u32_e32 v78, v203, v226
	v_add_u32_e32 v79, 0x420, v78
	s_waitcnt vmcnt(7)
	ds_write2_b32 v78, v38, v39 offset1:1
	ds_write2_b32 v78, v40, v41 offset0:2 offset1:3
	s_waitcnt vmcnt(6)
	ds_write2_b32 v79, v34, v35 offset1:1
	v_add_u32_e32 v79, 0x428, v78
	ds_write2_b32 v79, v36, v37 offset1:1
	v_add_u32_e32 v79, 0x840, v78
	s_waitcnt vmcnt(5)
	ds_write2_b32 v79, v30, v31 offset1:1
	v_add_u32_e32 v79, 0x848, v78
	ds_write2_b32 v79, v32, v33 offset1:1
	v_add_u32_e32 v79, 0xc60, v78
	s_waitcnt vmcnt(4)
	ds_write2_b32 v79, v14, v15 offset1:1
	v_add_u32_e32 v79, 0xc68, v78
	ds_write2_b32 v79, v16, v17 offset1:1
	v_add_u32_e32 v79, 0x1080, v78
	s_waitcnt vmcnt(3)
	ds_write2_b32 v79, v22, v23 offset1:1
	v_add_u32_e32 v79, 0x1088, v78
	ds_write2_b32 v79, v24, v25 offset1:1
	v_add_u32_e32 v79, 0x14a0, v78
	s_waitcnt vmcnt(2)
	ds_write2_b32 v79, v6, v7 offset1:1
	v_add_u32_e32 v79, 0x14a8, v78
	ds_write2_b32 v79, v8, v9 offset1:1
	v_add_u32_e32 v79, 0x18c0, v78
	s_waitcnt vmcnt(1)
	ds_write2_b32 v79, v10, v11 offset1:1
	v_add_u32_e32 v79, 0x18c8, v78
	ds_write2_b32 v79, v12, v13 offset1:1
	v_add_u32_e32 v79, 0x1ce0, v78
	v_add_u32_e32 v78, 0x1ce8, v78
	s_waitcnt vmcnt(0)
	ds_write2_b32 v79, v2, v3 offset1:1
	ds_write2_b32 v78, v4, v5 offset1:1
	s_waitcnt lgkmcnt(0)
	ds_read2_b32 v[82:83], v76 offset1:8
	ds_read2_b32 v[86:87], v76 offset0:33 offset1:41
	ds_read2_b32 v[88:89], v76 offset0:66 offset1:74
	ds_read2_b32 v[90:91], v76 offset0:99 offset1:107
	ds_read2_b32 v[92:93], v76 offset0:132 offset1:140
	s_waitcnt lgkmcnt(4)
	v_bfe_u32 v78, v82, 16, 1
	v_add3_u32 v78, v82, v78, s13
	s_waitcnt lgkmcnt(3)
	v_bfe_u32 v79, v86, 16, 1
	v_lshrrev_b32_e32 v78, 16, v78
	v_add3_u32 v79, v86, v79, s13
	ds_read2_b32 v[94:95], v76 offset0:165 offset1:173
	v_and_or_b32 v78, v79, s16, v78
	s_waitcnt lgkmcnt(3)
	v_bfe_u32 v79, v88, 16, 1
	v_add3_u32 v79, v88, v79, s13
	s_waitcnt lgkmcnt(2)
	v_bfe_u32 v80, v90, 16, 1
	ds_read2_b32 v[96:97], v76 offset0:198 offset1:206
	v_lshrrev_b32_e32 v79, 16, v79
	v_add3_u32 v80, v90, v80, s13
	ds_read2_b32 v[98:99], v76 offset0:231 offset1:239
	v_and_or_b32 v79, v80, s16, v79
	s_waitcnt lgkmcnt(3)
	v_bfe_u32 v80, v92, 16, 1
	v_add3_u32 v80, v92, v80, s13
	s_waitcnt lgkmcnt(2)
	v_bfe_u32 v81, v94, 16, 1
	v_lshrrev_b32_e32 v80, 16, v80
	v_add3_u32 v81, v94, v81, s13
	v_and_or_b32 v80, v81, s16, v80
	s_waitcnt lgkmcnt(1)
	v_bfe_u32 v81, v96, 16, 1
	s_add_i32 s0, s12, 0x1a00
	s_add_i32 s6, s3, 0x1a000
	v_add3_u32 v81, v96, v81, s13
	s_waitcnt lgkmcnt(0)
	v_bfe_u32 v82, v98, 16, 1
	s_and_b32 s0, s0, 0xfc0
	s_and_b32 s6, s6, 0x3e0
	v_lshrrev_b32_e32 v81, 16, v81
	v_add3_u32 v82, v98, v82, s13
	s_lshl_b32 s0, s0, 1
	v_and_or_b32 v81, v82, s16, v81
	v_or_b32_e32 v82, s6, v199
	v_lshl_add_u64 v[84:85], v[72:73], 0, s[0:1]
	v_lshlrev_b32_e32 v100, 11, v82
	v_mov_b32_e32 v101, v67
	v_lshl_add_u64 v[100:101], v[84:85], 0, v[100:101]
	global_store_dwordx4 v[100:101], v[78:81], off sc1
	v_bfe_u32 v82, v99, 16, 1
	v_add3_u32 v82, v99, v82, s13
	v_bfe_u32 v78, v83, 16, 1
	v_add3_u32 v78, v83, v78, s13
	v_bfe_u32 v79, v87, 16, 1
	v_lshrrev_b32_e32 v78, 16, v78
	v_add3_u32 v79, v87, v79, s13
	v_and_or_b32 v78, v79, s16, v78
	v_bfe_u32 v79, v89, 16, 1
	v_add3_u32 v79, v89, v79, s13
	v_bfe_u32 v80, v91, 16, 1
	v_lshrrev_b32_e32 v79, 16, v79
	v_add3_u32 v80, v91, v80, s13
	v_and_or_b32 v79, v80, s16, v79
	v_bfe_u32 v80, v93, 16, 1
	v_add3_u32 v80, v93, v80, s13
	v_bfe_u32 v81, v95, 16, 1
	v_lshrrev_b32_e32 v80, 16, v80
	v_add3_u32 v81, v95, v81, s13
	v_and_or_b32 v80, v81, s16, v80
	v_bfe_u32 v81, v97, 16, 1
	v_add3_u32 v81, v97, v81, s13
	v_lshrrev_b32_e32 v81, 16, v81
	v_and_or_b32 v81, v82, s16, v81
	v_or_b32_e32 v82, s6, v227
	v_lshlrev_b32_e32 v82, 11, v82
	v_mov_b32_e32 v83, v67
	ds_read2_b32 v[86:87], v76 offset0:16 offset1:24
	v_lshl_add_u64 v[82:83], v[84:85], 0, v[82:83]
	global_store_dwordx4 v[82:83], v[78:81], off sc1
	ds_read2_b32 v[82:83], v76 offset0:49 offset1:57
	ds_read2_b32 v[88:89], v76 offset0:82 offset1:90
	ds_read2_b32 v[90:91], v76 offset0:115 offset1:123
	s_waitcnt lgkmcnt(3)
	v_bfe_u32 v78, v86, 16, 1
	v_add3_u32 v78, v86, v78, s13
	s_waitcnt lgkmcnt(2)
	v_bfe_u32 v79, v82, 16, 1
	ds_read2_b32 v[92:93], v76 offset0:148 offset1:156
	v_lshrrev_b32_e32 v78, 16, v78
	v_add3_u32 v79, v82, v79, s13
	ds_read2_b32 v[94:95], v76 offset0:181 offset1:189
	v_and_or_b32 v78, v79, s16, v78
	s_waitcnt lgkmcnt(3)
	v_bfe_u32 v79, v88, 16, 1
	v_add3_u32 v79, v88, v79, s13
	s_waitcnt lgkmcnt(2)
	v_bfe_u32 v80, v90, 16, 1
	ds_read2_b32 v[96:97], v76 offset0:214 offset1:222
	v_lshrrev_b32_e32 v79, 16, v79
	v_add3_u32 v80, v90, v80, s13
	ds_read2_b32 v[98:99], v76 offset0:247 offset1:255
	v_and_or_b32 v79, v80, s16, v79
	s_waitcnt lgkmcnt(3)
	v_bfe_u32 v80, v92, 16, 1
	v_add3_u32 v80, v92, v80, s13
	s_waitcnt lgkmcnt(2)
	v_bfe_u32 v81, v94, 16, 1
	v_lshrrev_b32_e32 v80, 16, v80
	v_add3_u32 v81, v94, v81, s13
	v_and_or_b32 v80, v81, s16, v80
	s_waitcnt lgkmcnt(1)
	v_bfe_u32 v81, v96, 16, 1
	v_add3_u32 v81, v96, v81, s13
	s_waitcnt lgkmcnt(0)
	v_bfe_u32 v82, v98, 16, 1
	v_lshrrev_b32_e32 v81, 16, v81
	v_add3_u32 v82, v98, v82, s13
	v_and_or_b32 v81, v82, s16, v81
	v_or_b32_e32 v82, s6, v228
	v_lshlrev_b32_e32 v100, 11, v82
	v_mov_b32_e32 v101, v67
	v_lshl_add_u64 v[100:101], v[84:85], 0, v[100:101]
	global_store_dwordx4 v[100:101], v[78:81], off sc1
	v_bfe_u32 v82, v99, 16, 1
	v_add3_u32 v82, v99, v82, s13
	v_bfe_u32 v78, v87, 16, 1
	v_add3_u32 v78, v87, v78, s13
	v_bfe_u32 v79, v83, 16, 1
	v_lshrrev_b32_e32 v78, 16, v78
	v_add3_u32 v79, v83, v79, s13
	v_and_or_b32 v78, v79, s16, v78
	v_bfe_u32 v79, v89, 16, 1
	v_add3_u32 v79, v89, v79, s13
	v_bfe_u32 v80, v91, 16, 1
	v_lshrrev_b32_e32 v79, 16, v79
	v_add3_u32 v80, v91, v80, s13
	v_and_or_b32 v79, v80, s16, v79
	v_bfe_u32 v80, v93, 16, 1
	v_add3_u32 v80, v93, v80, s13
	v_bfe_u32 v81, v95, 16, 1
	v_lshrrev_b32_e32 v80, 16, v80
	v_add3_u32 v81, v95, v81, s13
	v_and_or_b32 v80, v81, s16, v80
	v_bfe_u32 v81, v97, 16, 1
	v_add3_u32 v81, v97, v81, s13
	v_lshrrev_b32_e32 v81, 16, v81
	v_and_or_b32 v81, v82, s16, v81
	v_or_b32_e32 v82, s6, v229
	v_lshlrev_b32_e32 v82, 11, v82
	v_mov_b32_e32 v83, v67
	v_lshl_add_u64 v[82:83], v[84:85], 0, v[82:83]
	global_store_dwordx4 v[82:83], v[78:81], off sc1
	s_waitcnt lgkmcnt(0)

.LBB0_54:
	s_mul_hi_i32 s0, s18, 0x2aaaaaab
	s_lshr_b32 s6, s0, 31
	s_ashr_i32 s0, s0, 4
	s_add_i32 s0, s0, s6
	s_mul_i32 s6, s0, 0xffffffa0
	s_add_i32 s7, s18, s6
	s_lshl_b32 s6, s0, 6
	s_cmp_lt_i32 s7, 16
	s_cselect_b64 s[8:9], -1, 0
	s_and_b32 s7, s7, 0x3fffff0
	s_cmp_eq_u32 s7, 48
	s_cselect_b64 s[10:11], -1, 0
	s_or_b64 vcc, s[8:9], s[10:11]
	v_cndmask_b32_e32 v78, 1.0, v77, vcc
	s_waitcnt vmcnt(7)
	v_pk_mul_f32 v[38:39], v[78:79], v[38:39] op_sel_hi:[0,1]
	v_add_u32_e32 v79, v203, v226
	ds_write2_b32 v79, v38, v39 offset1:1
	v_pk_mul_f32 v[38:39], v[78:79], v[40:41] op_sel_hi:[0,1]
	ds_write2_b32 v79, v38, v39 offset0:2 offset1:3
	s_waitcnt vmcnt(6)
	v_pk_mul_f32 v[34:35], v[78:79], v[34:35] op_sel_hi:[0,1]
	v_add_u32_e32 v38, 0x420, v79
	ds_write2_b32 v38, v34, v35 offset1:1
	v_pk_mul_f32 v[34:35], v[78:79], v[36:37] op_sel_hi:[0,1]
	v_add_u32_e32 v36, 0x428, v79
	ds_write2_b32 v36, v34, v35 offset1:1
	s_waitcnt vmcnt(5)
	v_pk_mul_f32 v[30:31], v[78:79], v[30:31] op_sel_hi:[0,1]
	v_add_u32_e32 v34, 0x840, v79
	ds_write2_b32 v34, v30, v31 offset1:1
	v_pk_mul_f32 v[30:31], v[78:79], v[32:33] op_sel_hi:[0,1]
	v_add_u32_e32 v32, 0x848, v79
	ds_write2_b32 v32, v30, v31 offset1:1
	s_waitcnt vmcnt(4)
	v_pk_mul_f32 v[14:15], v[78:79], v[14:15] op_sel_hi:[0,1]
	v_add_u32_e32 v30, 0xc60, v79
	ds_write2_b32 v30, v14, v15 offset1:1
	v_pk_mul_f32 v[14:15], v[78:79], v[16:17] op_sel_hi:[0,1]
	v_add_u32_e32 v16, 0xc68, v79
	ds_write2_b32 v16, v14, v15 offset1:1
	s_waitcnt vmcnt(3)
	v_pk_mul_f32 v[14:15], v[22:23], v[78:79] op_sel_hi:[1,0]
	v_add_u32_e32 v16, 0x1080, v79
	ds_write2_b32 v16, v14, v15 offset1:1
	v_pk_mul_f32 v[14:15], v[24:25], v[78:79] op_sel_hi:[1,0]
	v_add_u32_e32 v16, 0x1088, v79
	ds_write2_b32 v16, v14, v15 offset1:1
	s_waitcnt vmcnt(2)
	v_pk_mul_f32 v[6:7], v[6:7], v[78:79] op_sel_hi:[1,0]
	v_add_u32_e32 v14, 0x14a0, v79
	ds_write2_b32 v14, v6, v7 offset1:1
	v_pk_mul_f32 v[6:7], v[8:9], v[78:79] op_sel_hi:[1,0]
	v_add_u32_e32 v8, 0x14a8, v79
	ds_write2_b32 v8, v6, v7 offset1:1
	s_waitcnt vmcnt(1)
	v_pk_mul_f32 v[6:7], v[10:11], v[78:79] op_sel_hi:[1,0]
	v_add_u32_e32 v8, 0x18c0, v79
	ds_write2_b32 v8, v6, v7 offset1:1
	v_pk_mul_f32 v[6:7], v[12:13], v[78:79] op_sel_hi:[1,0]
	v_add_u32_e32 v8, 0x18c8, v79
	ds_write2_b32 v8, v6, v7 offset1:1
	s_waitcnt vmcnt(0)
	v_pk_mul_f32 v[2:3], v[2:3], v[78:79] op_sel_hi:[1,0]
	v_add_u32_e32 v6, 0x1ce0, v79
	ds_write2_b32 v6, v2, v3 offset1:1
	v_pk_mul_f32 v[2:3], v[4:5], v[78:79] op_sel_hi:[1,0]
	v_add_u32_e32 v4, 0x1ce8, v79
	ds_write2_b32 v4, v2, v3 offset1:1
	s_waitcnt lgkmcnt(0)
	ds_read2_b32 v[6:7], v76 offset1:8
	ds_read2_b32 v[10:11], v76 offset0:33 offset1:41
	ds_read2_b32 v[12:13], v76 offset0:66 offset1:74
	ds_read2_b32 v[14:15], v76 offset0:99 offset1:107
	ds_read2_b32 v[16:17], v76 offset0:132 offset1:140
	s_waitcnt lgkmcnt(4)
	v_bfe_u32 v2, v6, 16, 1
	v_add3_u32 v2, v6, v2, s13
	s_waitcnt lgkmcnt(3)
	v_bfe_u32 v3, v10, 16, 1
	v_lshrrev_b32_e32 v2, 16, v2
	v_add3_u32 v3, v10, v3, s13
	ds_read2_b32 v[22:23], v76 offset0:165 offset1:173
	v_and_or_b32 v2, v3, s16, v2
	s_waitcnt lgkmcnt(3)
	v_bfe_u32 v3, v12, 16, 1
	v_add3_u32 v3, v12, v3, s13
	s_waitcnt lgkmcnt(2)
	v_bfe_u32 v4, v14, 16, 1
	ds_read2_b32 v[24:25], v76 offset0:198 offset1:206
	v_lshrrev_b32_e32 v3, 16, v3
	v_add3_u32 v4, v14, v4, s13
	ds_read2_b32 v[30:31], v76 offset0:231 offset1:239
	v_and_or_b32 v3, v4, s16, v3
	s_waitcnt lgkmcnt(3)
	v_bfe_u32 v4, v16, 16, 1
	s_mulk_i32 s0, 0xf400
	v_add3_u32 v4, v16, v4, s13
	s_waitcnt lgkmcnt(2)
	v_bfe_u32 v5, v22, 16, 1
	s_add_i32 s0, s0, s3
	v_lshrrev_b32_e32 v4, 16, v4
	v_add3_u32 v5, v22, v5, s13
	v_add_u32_e32 v34, s0, v199
	v_and_or_b32 v4, v5, s16, v4
	s_waitcnt lgkmcnt(1)
	v_bfe_u32 v5, v24, 16, 1
	v_add_u32_e32 v32, 0x26000, v34
	s_ashr_i32 s7, s6, 31
	v_add3_u32 v5, v24, v5, s13
	s_waitcnt lgkmcnt(0)
	v_bfe_u32 v6, v30, 16, 1
	v_ashrrev_i32_e32 v33, 31, v32
	v_lshl_add_u64 v[8:9], s[6:7], 1, v[74:75]
	v_lshrrev_b32_e32 v5, 16, v5
	v_add3_u32 v6, v30, v6, s13
	v_lshlrev_b64 v[32:33], 11, v[32:33]
	v_and_or_b32 v5, v6, s16, v5
	v_lshl_add_u64 v[32:33], v[8:9], 0, v[32:33]
	global_store_dwordx4 v[32:33], v[2:5], off sc1
	v_bfe_u32 v6, v31, 16, 1
	v_add3_u32 v6, v31, v6, s13
	v_bfe_u32 v2, v7, 16, 1
	v_add3_u32 v2, v7, v2, s13
	v_bfe_u32 v3, v11, 16, 1
	v_lshrrev_b32_e32 v2, 16, v2
	v_add3_u32 v3, v11, v3, s13
	v_and_or_b32 v2, v3, s16, v2
	v_bfe_u32 v3, v13, 16, 1
	v_add3_u32 v3, v13, v3, s13
	v_bfe_u32 v4, v15, 16, 1
	v_lshrrev_b32_e32 v3, 16, v3
	v_add3_u32 v4, v15, v4, s13
	v_and_or_b32 v3, v4, s16, v3
	v_bfe_u32 v4, v17, 16, 1
	v_add3_u32 v4, v17, v4, s13
	v_bfe_u32 v5, v23, 16, 1
	v_lshrrev_b32_e32 v4, 16, v4
	v_add3_u32 v5, v23, v5, s13
	v_and_or_b32 v4, v5, s16, v4
	v_bfe_u32 v5, v25, 16, 1
	v_add3_u32 v5, v25, v5, s13
	v_lshrrev_b32_e32 v5, 16, v5
	v_and_or_b32 v5, v6, s16, v5
	v_add_u32_e32 v6, 0x26008, v34
	v_ashrrev_i32_e32 v7, 31, v6
	v_lshlrev_b64 v[6:7], 11, v[6:7]
	ds_read2_b32 v[10:11], v76 offset0:16 offset1:24
	v_lshl_add_u64 v[6:7], v[8:9], 0, v[6:7]
	global_store_dwordx4 v[6:7], v[2:5], off sc1
	ds_read2_b32 v[6:7], v76 offset0:49 offset1:57
	ds_read2_b32 v[12:13], v76 offset0:82 offset1:90
	ds_read2_b32 v[14:15], v76 offset0:115 offset1:123
	s_waitcnt lgkmcnt(3)
	v_bfe_u32 v2, v10, 16, 1
	v_add3_u32 v2, v10, v2, s13
	s_waitcnt lgkmcnt(2)
	v_bfe_u32 v3, v6, 16, 1
	ds_read2_b32 v[16:17], v76 offset0:148 offset1:156
	v_lshrrev_b32_e32 v2, 16, v2
	v_add3_u32 v3, v6, v3, s13
	ds_read2_b32 v[22:23], v76 offset0:181 offset1:189
	v_and_or_b32 v2, v3, s16, v2
	s_waitcnt lgkmcnt(3)
	v_bfe_u32 v3, v12, 16, 1
	v_add3_u32 v3, v12, v3, s13
	s_waitcnt lgkmcnt(2)
	v_bfe_u32 v4, v14, 16, 1
	ds_read2_b32 v[24:25], v76 offset0:214 offset1:222
	v_lshrrev_b32_e32 v3, 16, v3
	v_add3_u32 v4, v14, v4, s13
	ds_read2_b32 v[30:31], v76 offset0:247 offset1:255
	v_and_or_b32 v3, v4, s16, v3
	s_waitcnt lgkmcnt(3)
	v_bfe_u32 v4, v16, 16, 1
	v_add3_u32 v4, v16, v4, s13
	s_waitcnt lgkmcnt(2)
	v_bfe_u32 v5, v22, 16, 1
	v_lshrrev_b32_e32 v4, 16, v4
	v_add3_u32 v5, v22, v5, s13
	v_and_or_b32 v4, v5, s16, v4
	s_waitcnt lgkmcnt(1)
	v_bfe_u32 v5, v24, 16, 1
	v_add_u32_e32 v32, 0x26010, v34
	v_add3_u32 v5, v24, v5, s13
	s_waitcnt lgkmcnt(0)
	v_bfe_u32 v6, v30, 16, 1
	v_ashrrev_i32_e32 v33, 31, v32
	v_lshrrev_b32_e32 v5, 16, v5
	v_add3_u32 v6, v30, v6, s13
	v_lshlrev_b64 v[32:33], 11, v[32:33]
	v_and_or_b32 v5, v6, s16, v5
	v_lshl_add_u64 v[32:33], v[8:9], 0, v[32:33]
	global_store_dwordx4 v[32:33], v[2:5], off sc1
	v_bfe_u32 v6, v31, 16, 1
	v_add3_u32 v6, v31, v6, s13
	v_bfe_u32 v2, v11, 16, 1
	v_add3_u32 v2, v11, v2, s13
	v_bfe_u32 v3, v7, 16, 1
	v_lshrrev_b32_e32 v2, 16, v2
	v_add3_u32 v3, v7, v3, s13
	v_and_or_b32 v2, v3, s16, v2
	v_bfe_u32 v3, v13, 16, 1
	v_add3_u32 v3, v13, v3, s13
	v_bfe_u32 v4, v15, 16, 1
	v_lshrrev_b32_e32 v3, 16, v3
	v_add3_u32 v4, v15, v4, s13
	v_and_or_b32 v3, v4, s16, v3
	v_bfe_u32 v4, v17, 16, 1
	v_add3_u32 v4, v17, v4, s13
	v_bfe_u32 v5, v23, 16, 1
	v_lshrrev_b32_e32 v4, 16, v4
	v_add3_u32 v5, v23, v5, s13
	v_and_or_b32 v4, v5, s16, v4
	v_bfe_u32 v5, v25, 16, 1
	v_add3_u32 v5, v25, v5, s13
	v_lshrrev_b32_e32 v5, 16, v5
	v_and_or_b32 v5, v6, s16, v5
	v_add_u32_e32 v6, 0x26018, v34
	v_ashrrev_i32_e32 v7, 31, v6
	v_lshlrev_b64 v[6:7], 11, v[6:7]
	v_lshl_add_u64 v[6:7], v[8:9], 0, v[6:7]
	global_store_dwordx4 v[6:7], v[2:5], off sc1
	s_waitcnt lgkmcnt(0)
	s_branch .LBB0_27

.LBB0_204:
	s_ashr_i32 s17, s44, 31
	s_lshr_b32 s17, s17, 30
	s_add_i32 s17, s44, s17
	s_ashr_i32 s24, s17, 2
	s_ashr_i32 s25, s24, 31
	s_lshl_b32 s13, s44, 8
	s_lshl_b64 s[28:29], s[24:25], 25
	s_add_u32 s28, s36, s28
	s_addc_u32 s29, s37, s29
	s_lshl_b32 s17, s24, 10
	s_sub_i32 s13, s13, s17
	v_lshl_add_u32 v156, s22, 8, v149
	v_or_b32_e32 v146, s13, v151
	v_ashrrev_i32_e32 v147, 31, v146
	v_ashrrev_i32_e32 v157, 31, v156
	v_lshl_add_u64 v[158:159], v[146:147], 1, s[28:29]
	v_lshlrev_b64 v[146:147], 11, v[156:157]
	v_lshl_add_u64 v[146:147], v[158:159], 0, v[146:147]
	v_pk_add_f32 v[128:129], v[128:129], 0 op_sel_hi:[1,0]
	v_pk_add_f32 v[126:127], v[126:127], 0 op_sel_hi:[1,0]
	v_pk_add_f32 v[160:161], v[124:125], 0 op_sel_hi:[1,0]
	v_pk_add_f32 v[124:125], v[122:123], 0 op_sel_hi:[1,0]
	v_cvt_pk_bf16_f32 v122, v126, v127
	v_cvt_pk_bf16_f32 v123, v128, v129
	v_pk_add_f32 v[118:119], v[118:119], 0 op_sel_hi:[1,0]
	v_cvt_pk_bf16_f32 v124, v124, v125
	v_cvt_pk_bf16_f32 v125, v160, v161
	global_store_dwordx4 v[146:147], v[122:125], off sc1
	v_pk_add_f32 v[120:121], v[120:121], 0 op_sel_hi:[1,0]
	v_pk_add_f32 v[114:115], v[114:115], 0 op_sel_hi:[1,0]
	v_pk_add_f32 v[122:123], v[112:113], 0 op_sel_hi:[1,0]
	v_pk_add_f32 v[112:113], v[110:111], 0 op_sel_hi:[1,0]
	v_cvt_pk_bf16_f32 v110, v118, v119
	v_cvt_pk_bf16_f32 v111, v120, v121
	v_pk_add_f32 v[102:103], v[102:103], 0 op_sel_hi:[1,0]
	v_cvt_pk_bf16_f32 v112, v112, v113
	v_cvt_pk_bf16_f32 v113, v122, v123
	global_store_dwordx4 v[146:147], v[110:113], off offset:256 sc1
	v_pk_add_f32 v[104:105], v[104:105], 0 op_sel_hi:[1,0]
	v_pk_add_f32 v[98:99], v[98:99], 0 op_sel_hi:[1,0]
	v_or_b32_e32 v110, 16, v156
	v_ashrrev_i32_e32 v111, 31, v110
	v_lshlrev_b64 v[110:111], 11, v[110:111]
	v_lshl_add_u64 v[110:111], v[158:159], 0, v[110:111]
	v_pk_add_f32 v[112:113], v[116:117], 0 op_sel_hi:[1,0]
	v_pk_add_f32 v[116:117], v[108:109], 0 op_sel_hi:[1,0]
	v_pk_add_f32 v[108:109], v[106:107], 0 op_sel_hi:[1,0]
	v_cvt_pk_bf16_f32 v106, v114, v115
	v_cvt_pk_bf16_f32 v107, v112, v113
	v_pk_add_f32 v[86:87], v[86:87], 0 op_sel_hi:[1,0]
	v_cvt_pk_bf16_f32 v108, v108, v109
	v_cvt_pk_bf16_f32 v109, v116, v117
	global_store_dwordx4 v[110:111], v[106:109], off sc1
	v_pk_add_f32 v[88:89], v[88:89], 0 op_sel_hi:[1,0]
	v_pk_add_f32 v[82:83], v[82:83], 0 op_sel_hi:[1,0]
	v_pk_add_f32 v[106:107], v[96:97], 0 op_sel_hi:[1,0]
	v_pk_add_f32 v[96:97], v[94:95], 0 op_sel_hi:[1,0]
	v_cvt_pk_bf16_f32 v94, v102, v103
	v_cvt_pk_bf16_f32 v95, v104, v105
	v_pk_add_f32 v[72:73], v[72:73], 0 op_sel_hi:[1,0]
	v_cvt_pk_bf16_f32 v96, v96, v97
	v_cvt_pk_bf16_f32 v97, v106, v107
	global_store_dwordx4 v[110:111], v[94:97], off offset:256 sc1
	v_pk_add_f32 v[70:71], v[70:71], 0 op_sel_hi:[1,0]
	v_pk_add_f32 v[62:63], v[62:63], 0 op_sel_hi:[1,0]
	v_or_b32_e32 v94, 32, v156
	v_ashrrev_i32_e32 v95, 31, v94
	v_lshlrev_b64 v[94:95], 11, v[94:95]
	v_lshl_add_u64 v[94:95], v[158:159], 0, v[94:95]
	v_pk_add_f32 v[96:97], v[100:101], 0 op_sel_hi:[1,0]
	v_pk_add_f32 v[100:101], v[92:93], 0 op_sel_hi:[1,0]
	v_pk_add_f32 v[92:93], v[90:91], 0 op_sel_hi:[1,0]
	v_cvt_pk_bf16_f32 v90, v98, v99
	v_cvt_pk_bf16_f32 v91, v96, v97
	s_mov_b32 s13, 0x40000
	v_cvt_pk_bf16_f32 v92, v92, v93
	v_cvt_pk_bf16_f32 v93, v100, v101
	global_store_dwordx4 v[94:95], v[90:93], off sc1
	v_pk_add_f32 v[64:65], v[64:65], 0 op_sel_hi:[1,0]
	s_mov_b64 s[24:25], 0x40000
	v_pk_add_f32 v[90:91], v[80:81], 0 op_sel_hi:[1,0]
	v_pk_add_f32 v[80:81], v[78:79], 0 op_sel_hi:[1,0]
	v_cvt_pk_bf16_f32 v78, v86, v87
	v_cvt_pk_bf16_f32 v79, v88, v89
	v_pk_add_f32 v[56:57], v[56:57], 0 op_sel_hi:[1,0]
	v_cvt_pk_bf16_f32 v80, v80, v81
	v_cvt_pk_bf16_f32 v81, v90, v91
	global_store_dwordx4 v[94:95], v[78:81], off offset:256 sc1
	v_pk_add_f32 v[54:55], v[54:55], 0 op_sel_hi:[1,0]
	v_pk_add_f32 v[50:51], v[50:51], 0 op_sel_hi:[1,0]
	v_or_b32_e32 v78, 48, v156
	v_ashrrev_i32_e32 v79, 31, v78
	v_lshlrev_b64 v[78:79], 11, v[78:79]
	v_lshl_add_u64 v[78:79], v[158:159], 0, v[78:79]
	v_pk_add_f32 v[80:81], v[84:85], 0 op_sel_hi:[1,0]
	v_pk_add_f32 v[84:85], v[76:77], 0 op_sel_hi:[1,0]
	v_pk_add_f32 v[76:77], v[74:75], 0 op_sel_hi:[1,0]
	v_cvt_pk_bf16_f32 v74, v82, v83
	v_cvt_pk_bf16_f32 v75, v80, v81
	v_pk_add_f32 v[40:41], v[40:41], 0 op_sel_hi:[1,0]
	v_cvt_pk_bf16_f32 v76, v76, v77
	v_cvt_pk_bf16_f32 v77, v84, v85
	global_store_dwordx4 v[78:79], v[74:77], off sc1
	v_pk_add_f32 v[38:39], v[38:39], 0 op_sel_hi:[1,0]
	v_pk_add_f32 v[34:35], v[34:35], 0 op_sel_hi:[1,0]
	v_pk_add_f32 v[74:75], v[68:69], 0 op_sel_hi:[1,0]
	v_pk_add_f32 v[68:69], v[66:67], 0 op_sel_hi:[1,0]
	v_cvt_pk_bf16_f32 v66, v70, v71
	v_cvt_pk_bf16_f32 v67, v72, v73
	v_pk_add_f32 v[24:25], v[24:25], 0 op_sel_hi:[1,0]
	v_cvt_pk_bf16_f32 v68, v68, v69
	v_cvt_pk_bf16_f32 v69, v74, v75
	global_store_dwordx4 v[78:79], v[66:69], off offset:256 sc1
	v_pk_add_f32 v[22:23], v[22:23], 0 op_sel_hi:[1,0]
	v_pk_add_f32 v[18:19], v[18:19], 0 op_sel_hi:[1,0]
	v_pk_add_f32 v[68:69], v[60:61], 0 op_sel_hi:[1,0]
	v_pk_add_f32 v[60:61], v[58:59], 0 op_sel_hi:[1,0]
	v_cvt_pk_bf16_f32 v58, v62, v63
	v_add_co_u32_e32 v62, vcc, s13, v146
	v_cvt_pk_bf16_f32 v59, v64, v65
	v_cvt_pk_bf16_f32 v60, v60, v61
	v_cvt_pk_bf16_f32 v61, v68, v69
	v_lshl_add_u64 v[66:67], v[146:147], 0, s[24:25]
	s_nop 0
	v_addc_co_u32_e32 v63, vcc, 0, v147, vcc
	global_store_dwordx4 v[62:63], v[58:61], off sc1
	s_mov_b32 s13, 0x48000
	s_mov_b64 s[24:25], 0x48000
	v_pk_add_f32 v[58:59], v[48:49], 0 op_sel_hi:[1,0]
	v_pk_add_f32 v[48:49], v[46:47], 0 op_sel_hi:[1,0]
	v_cvt_pk_bf16_f32 v46, v54, v55
	v_cvt_pk_bf16_f32 v47, v56, v57
	v_pk_add_f32 v[8:9], v[8:9], 0 op_sel_hi:[1,0]
	v_cvt_pk_bf16_f32 v48, v48, v49
	v_cvt_pk_bf16_f32 v49, v58, v59
	global_store_dwordx4 v[66:67], v[46:49], off offset:256 sc1
	v_pk_add_f32 v[6:7], v[6:7], 0 op_sel_hi:[1,0]
	s_nop 0
	v_pk_add_f32 v[48:49], v[52:53], 0 op_sel_hi:[1,0]
	v_pk_add_f32 v[52:53], v[44:45], 0 op_sel_hi:[1,0]
	v_pk_add_f32 v[44:45], v[42:43], 0 op_sel_hi:[1,0]
	v_cvt_pk_bf16_f32 v42, v50, v51
	v_cvt_pk_bf16_f32 v43, v48, v49
	v_add_co_u32_e32 v48, vcc, s13, v146
	v_cvt_pk_bf16_f32 v44, v44, v45
	v_cvt_pk_bf16_f32 v45, v52, v53
	v_lshl_add_u64 v[46:47], v[146:147], 0, s[24:25]
	s_nop 0
	v_addc_co_u32_e32 v49, vcc, 0, v147, vcc
	global_store_dwordx4 v[48:49], v[42:45], off sc1
	s_mov_b32 s13, 0x50000
	s_mov_b64 s[24:25], 0x50000
	v_pk_add_f32 v[42:43], v[32:33], 0 op_sel_hi:[1,0]
	v_pk_add_f32 v[32:33], v[30:31], 0 op_sel_hi:[1,0]
	v_cvt_pk_bf16_f32 v30, v38, v39
	v_cvt_pk_bf16_f32 v31, v40, v41
	s_nop 0
	v_cvt_pk_bf16_f32 v32, v32, v33
	v_cvt_pk_bf16_f32 v33, v42, v43
	global_store_dwordx4 v[46:47], v[30:33], off offset:256 sc1
	s_nop 1
	v_pk_add_f32 v[32:33], v[36:37], 0 op_sel_hi:[1,0]
	v_pk_add_f32 v[36:37], v[28:29], 0 op_sel_hi:[1,0]
	v_pk_add_f32 v[28:29], v[26:27], 0 op_sel_hi:[1,0]
	v_cvt_pk_bf16_f32 v26, v34, v35
	v_cvt_pk_bf16_f32 v27, v32, v33
	v_add_co_u32_e32 v32, vcc, s13, v146
	v_cvt_pk_bf16_f32 v28, v28, v29
	v_cvt_pk_bf16_f32 v29, v36, v37
	v_lshl_add_u64 v[30:31], v[146:147], 0, s[24:25]
	s_nop 0
	v_addc_co_u32_e32 v33, vcc, 0, v147, vcc
	global_store_dwordx4 v[32:33], v[26:29], off sc1
	s_mov_b32 s13, 0x58000
	s_mov_b64 s[24:25], 0x58000
	v_pk_add_f32 v[26:27], v[16:17], 0 op_sel_hi:[1,0]
	v_pk_add_f32 v[16:17], v[14:15], 0 op_sel_hi:[1,0]
	v_cvt_pk_bf16_f32 v14, v22, v23
	v_cvt_pk_bf16_f32 v15, v24, v25
	s_nop 0
	v_cvt_pk_bf16_f32 v16, v16, v17
	v_cvt_pk_bf16_f32 v17, v26, v27
	global_store_dwordx4 v[30:31], v[14:17], off offset:256 sc1
	s_nop 1
	v_pk_add_f32 v[16:17], v[20:21], 0 op_sel_hi:[1,0]
	v_pk_add_f32 v[20:21], v[12:13], 0 op_sel_hi:[1,0]
	v_pk_add_f32 v[12:13], v[10:11], 0 op_sel_hi:[1,0]
	v_cvt_pk_bf16_f32 v10, v18, v19
	v_cvt_pk_bf16_f32 v11, v16, v17
	v_add_co_u32_e32 v16, vcc, s13, v146
	v_lshl_add_u64 v[14:15], v[146:147], 0, s[24:25]
	s_nop 0
	v_addc_co_u32_e32 v17, vcc, 0, v147, vcc
	v_cvt_pk_bf16_f32 v12, v12, v13
	v_cvt_pk_bf16_f32 v13, v20, v21
	global_store_dwordx4 v[16:17], v[10:13], off sc1
	s_andn2_b64 vcc, exec, s[0:1]
	s_mov_b64 s[0:1], -1
	v_pk_add_f32 v[10:11], v[4:5], 0 op_sel_hi:[1,0]
	v_pk_add_f32 v[4:5], v[2:3], 0 op_sel_hi:[1,0]
	v_cvt_pk_bf16_f32 v2, v6, v7
	v_cvt_pk_bf16_f32 v3, v8, v9
	s_nop 0
	v_cvt_pk_bf16_f32 v4, v4, v5
	v_cvt_pk_bf16_f32 v5, v10, v11
	global_store_dwordx4 v[14:15], v[2:5], off offset:256 sc1
	s_cbranch_vccnz .LBB0_197
	s_andn2_b64 vcc, exec, s[6:7]
	s_cbranch_vccnz .LBB0_196
	s_barrier
	s_branch .LBB0_196

.LBB0_375:
	s_or_b64 exec, exec, s[54:55]
	s_waitcnt lgkmcnt(0)
	ds_read_b128 v[34:37], v89 offset:128
	ds_read_b128 v[38:41], v89 offset:160
	s_lshl_b64 s[0:1], s[52:53], 24
	s_add_u32 s0, s19, s0
	s_addc_u32 s1, s20, s1
	s_waitcnt lgkmcnt(1)
	v_rcp_f32_e32 v42, v34
	s_lshl_b32 s46, s46, 12
	s_add_i32 s46, s46, 0
	v_rcp_f32_e32 v43, v35
	s_add_i32 s46, s46, 0x18800
	v_lshlrev_b32_e32 v50, 1, v86
	v_lshlrev_b32_e32 v51, 9, v88
	v_mul_f32_e32 v2, v2, v42
	v_add3_u32 v50, s46, v50, v51
	v_cvt_pk_bf16_f32 v2, v2, s0
	ds_write_b16 v50, v2
	v_mul_f32_e32 v2, v18, v42
	v_cvt_pk_bf16_f32 v2, v2, s0
	v_rcp_f32_e32 v44, v36
	ds_write_b16 v50, v2 offset:64
	v_mul_f32_e32 v2, v3, v43
	v_cvt_pk_bf16_f32 v2, v2, s0
	ds_write_b16 v50, v2 offset:128
	v_mul_f32_e32 v2, v19, v43
	v_cvt_pk_bf16_f32 v2, v2, s0
	v_rcp_f32_e32 v45, v37
	ds_write_b16 v50, v2 offset:192
	v_mul_f32_e32 v2, v4, v44
	v_cvt_pk_bf16_f32 v2, v2, s0
	ds_write_b16 v50, v2 offset:256
	v_mul_f32_e32 v2, v20, v44
	v_cvt_pk_bf16_f32 v2, v2, s0
	s_waitcnt lgkmcnt(5)
	v_rcp_f32_e32 v46, v38
	ds_write_b16 v50, v2 offset:320
	v_mul_f32_e32 v2, v5, v45
	v_cvt_pk_bf16_f32 v2, v2, s0
	ds_write_b16 v50, v2 offset:384
	v_mul_f32_e32 v2, v21, v45
	v_cvt_pk_bf16_f32 v2, v2, s0
	v_rcp_f32_e32 v47, v39
	ds_write_b16 v50, v2 offset:448
	v_mul_f32_e32 v2, v6, v46
	v_cvt_pk_bf16_f32 v2, v2, s0
	ds_write_b16 v50, v2 offset:1024
	v_mul_f32_e32 v2, v22, v46
	v_cvt_pk_bf16_f32 v2, v2, s0
	v_rcp_f32_e32 v48, v40
	ds_write_b16 v50, v2 offset:1088
	v_mul_f32_e32 v2, v7, v47
	v_cvt_pk_bf16_f32 v2, v2, s0
	ds_write_b16 v50, v2 offset:1152
	v_mul_f32_e32 v2, v23, v47
	ds_read_b128 v[34:37], v89 offset:192
	v_cvt_pk_bf16_f32 v2, v2, s0
	v_rcp_f32_e32 v49, v41
	ds_write_b16 v50, v2 offset:1216
	v_mul_f32_e32 v2, v8, v48
	v_cvt_pk_bf16_f32 v2, v2, s0
	ds_write_b16 v50, v2 offset:1280
	v_mul_f32_e32 v2, v24, v48
	v_cvt_pk_bf16_f32 v2, v2, s0
	ds_read_b128 v[38:41], v89 offset:224
	s_waitcnt lgkmcnt(3)
	v_rcp_f32_e32 v34, v34
	ds_write_b16 v50, v2 offset:1344
	v_mul_f32_e32 v2, v9, v49
	v_cvt_pk_bf16_f32 v2, v2, s0
	ds_write_b16 v50, v2 offset:1408
	v_mul_f32_e32 v2, v25, v49
	v_cvt_pk_bf16_f32 v2, v2, s0
	v_rcp_f32_e32 v35, v35
	ds_write_b16 v50, v2 offset:1472
	v_mul_f32_e32 v2, v10, v34
	v_cvt_pk_bf16_f32 v2, v2, s0
	ds_write_b16 v50, v2 offset:2048
	v_mul_f32_e32 v2, v26, v34
	v_cvt_pk_bf16_f32 v2, v2, s0
	v_rcp_f32_e32 v36, v36
	ds_write_b16 v50, v2 offset:2112
	v_mul_f32_e32 v2, v11, v35
	v_cvt_pk_bf16_f32 v2, v2, s0
	ds_write_b16 v50, v2 offset:2176
	v_mul_f32_e32 v2, v27, v35
	v_cvt_pk_bf16_f32 v2, v2, s0
	v_rcp_f32_e32 v37, v37
	ds_write_b16 v50, v2 offset:2240
	v_mul_f32_e32 v2, v12, v36
	v_cvt_pk_bf16_f32 v2, v2, s0
	ds_write_b16 v50, v2 offset:2304
	v_mul_f32_e32 v2, v28, v36
	v_cvt_pk_bf16_f32 v2, v2, s0
	s_waitcnt lgkmcnt(8)
	v_rcp_f32_e32 v38, v38
	ds_write_b16 v50, v2 offset:2368
	v_mul_f32_e32 v2, v13, v37
	v_cvt_pk_bf16_f32 v2, v2, s0
	ds_write_b16 v50, v2 offset:2432
	v_mul_f32_e32 v2, v29, v37
	v_cvt_pk_bf16_f32 v2, v2, s0
	v_rcp_f32_e32 v39, v39
	ds_write_b16 v50, v2 offset:2496
	v_mul_f32_e32 v2, v14, v38
	v_cvt_pk_bf16_f32 v2, v2, s0
	ds_write_b16 v50, v2 offset:3072
	v_mul_f32_e32 v2, v30, v38
	v_cvt_pk_bf16_f32 v2, v2, s0
	v_rcp_f32_e32 v40, v40
	ds_write_b16 v50, v2 offset:3136
	v_mul_f32_e32 v2, v15, v39
	v_cvt_pk_bf16_f32 v2, v2, s0
	ds_write_b16 v50, v2 offset:3200
	v_mul_f32_e32 v2, v31, v39
	v_cvt_pk_bf16_f32 v2, v2, s0
	v_rcp_f32_e32 v41, v41
	ds_write_b16 v50, v2 offset:3264
	v_mul_f32_e32 v2, v16, v40
	v_cvt_pk_bf16_f32 v2, v2, s0
	ds_write_b16 v50, v2 offset:3328
	v_mul_f32_e32 v2, v32, v40
	v_cvt_pk_bf16_f32 v2, v2, s0
	ds_write_b16 v50, v2 offset:3392
	v_mul_f32_e32 v2, v17, v41
	v_cvt_pk_bf16_f32 v2, v2, s0
	ds_write_b16 v50, v2 offset:3456
	v_mul_f32_e32 v2, v33, v41
	v_cvt_pk_bf16_f32 v2, v2, s0
	ds_write_b16 v50, v2 offset:3520
	v_lshlrev_b32_e32 v2, 1, v87
	v_and_b32_e32 v206, 0x70, v2
	v_lshrrev_b32_e32 v14, 3, v85
	v_add_u32_e32 v15, s46, v206
	s_add_i32 s48, s48, s45
	s_waitcnt lgkmcnt(0)
	v_lshl_add_u32 v2, v14, 7, v15
	v_or_b32_e32 v6, s48, v14
	ds_read_b128 v[2:5], v2
	v_ashrrev_i32_e32 v7, 31, v6
	s_add_u32 s0, s0, s30
	v_lshlrev_b64 v[6:7], s44, v[6:7]
	s_addc_u32 s1, s1, s31
	v_lshl_add_u64 v[6:7], v[6:7], 0, s[28:29]
	v_lshl_add_u64 v[10:11], s[0:1], 0, v[206:207]
	v_lshlrev_b64 v[6:7], 10, v[6:7]
	v_or_b32_e32 v16, 8, v14
	v_lshl_add_u64 v[12:13], v[10:11], 0, v[6:7]
	v_lshl_add_u32 v6, v16, 7, v15
	ds_read_b128 v[6:9], v6
	s_waitcnt lgkmcnt(1)
	global_store_dwordx4 v[12:13], v[2:5], off sc1
	s_nop 1
	v_or_b32_e32 v2, s48, v16
	v_ashrrev_i32_e32 v3, 31, v2
	v_lshlrev_b64 v[2:3], s44, v[2:3]
	v_lshl_add_u64 v[2:3], v[2:3], 0, s[28:29]
	v_lshlrev_b64 v[2:3], 10, v[2:3]
	v_lshl_add_u64 v[2:3], v[10:11], 0, v[2:3]
	s_waitcnt lgkmcnt(0)
	global_store_dwordx4 v[2:3], v[6:9], off sc1
	s_nop 1
	v_or_b32_e32 v6, 16, v14
	v_lshl_add_u32 v2, v6, 7, v15
	v_or_b32_e32 v6, s48, v6
	ds_read_b128 v[2:5], v2
	v_ashrrev_i32_e32 v7, 31, v6
	v_lshlrev_b64 v[6:7], s44, v[6:7]
	v_lshl_add_u64 v[6:7], v[6:7], 0, s[28:29]
	v_lshlrev_b64 v[6:7], 10, v[6:7]
	v_or_b32_e32 v14, 24, v14
	v_lshl_add_u64 v[12:13], v[10:11], 0, v[6:7]
	v_lshl_add_u32 v6, v14, 7, v15
	ds_read_b128 v[6:9], v6
	s_waitcnt lgkmcnt(1)
	global_store_dwordx4 v[12:13], v[2:5], off sc1
	s_nop 1
	v_or_b32_e32 v2, s48, v14
	v_ashrrev_i32_e32 v3, 31, v2
	v_lshlrev_b64 v[2:3], s44, v[2:3]
	v_lshl_add_u64 v[2:3], v[2:3], 0, s[28:29]
	v_lshlrev_b64 v[2:3], 10, v[2:3]
	v_lshl_add_u64 v[2:3], v[10:11], 0, v[2:3]
	s_waitcnt lgkmcnt(0)
	global_store_dwordx4 v[2:3], v[6:9], off sc1
	s_barrier

.LBB0_384:
	v_add_f32_e32 v35, v52, v53
	v_add_f32_e32 v35, v54, v35
	v_add_f32_e32 v35, v55, v35
	v_add_f32_e32 v35, v56, v35
	v_add_f32_e32 v35, v57, v35
	v_add_f32_e32 v35, v58, v35
	v_add_f32_e32 v35, v59, v35
	v_add_f32_e32 v35, v60, v35
	v_add_f32_e32 v35, v61, v35
	v_add_f32_e32 v35, v62, v35
	v_add_f32_e32 v35, v63, v35
	v_add_f32_e32 v35, v64, v35
	v_add_f32_e32 v35, v65, v35
	v_add_f32_e32 v35, v66, v35
	v_add_f32_e32 v35, v67, v35
	v_add_f32_e32 v35, v36, v35
	v_add_f32_e32 v35, v37, v35
	v_add_f32_e32 v35, v38, v35
	v_add_f32_e32 v35, v39, v35
	v_add_f32_e32 v35, v40, v35
	v_add_f32_e32 v35, v41, v35
	v_add_f32_e32 v35, v42, v35
	v_add_f32_e32 v35, v43, v35
	v_add_f32_e32 v35, v44, v35
	v_add_f32_e32 v35, v45, v35
	v_add_f32_e32 v35, v46, v35
	v_add_f32_e32 v35, v47, v35
	v_add_f32_e32 v35, v48, v35
	v_add_f32_e32 v35, v49, v35
	s_cmp_lg_u32 0, -1
	v_add_f32_e32 v35, v50, v35
	s_cselect_b32 s0, 0, 0
	v_add_f32_e32 v35, v51, v35
	s_addk_i32 s0, 0x6000
	v_pk_mul_f32 v[32:33], v[210:211], v[32:33] op_sel_hi:[0,1]
	v_pk_mul_f32 v[30:31], v[210:211], v[30:31] op_sel_hi:[0,1]
	v_pk_mul_f32 v[28:29], v[210:211], v[28:29] op_sel_hi:[0,1]
	v_pk_mul_f32 v[26:27], v[210:211], v[26:27] op_sel_hi:[0,1]
	v_pk_mul_f32 v[24:25], v[210:211], v[24:25] op_sel_hi:[0,1]
	v_pk_mul_f32 v[22:23], v[210:211], v[22:23] op_sel_hi:[0,1]
	v_pk_mul_f32 v[20:21], v[210:211], v[20:21] op_sel_hi:[0,1]
	v_pk_mul_f32 v[18:19], v[210:211], v[18:19] op_sel_hi:[0,1]
	v_pk_mul_f32 v[16:17], v[210:211], v[16:17] op_sel_hi:[0,1]
	v_pk_mul_f32 v[14:15], v[210:211], v[14:15] op_sel_hi:[0,1]
	v_pk_mul_f32 v[12:13], v[210:211], v[12:13] op_sel_hi:[0,1]
	v_pk_mul_f32 v[10:11], v[210:211], v[10:11] op_sel_hi:[0,1]
	v_pk_mul_f32 v[8:9], v[210:211], v[8:9] op_sel_hi:[0,1]
	v_pk_mul_f32 v[6:7], v[210:211], v[6:7] op_sel_hi:[0,1]
	v_pk_mul_f32 v[4:5], v[210:211], v[4:5] op_sel_hi:[0,1]
	v_pk_mul_f32 v[2:3], v[210:211], v[2:3] op_sel_hi:[0,1]
	v_fmac_f32_e32 v35, v210, v34
	v_add3_u32 v68, v244, s0, v240
	v_cvt_pk_bf16_f32 v52, v52, v53
	v_cvt_pk_bf16_f32 v53, v54, v55
	v_cvt_pk_bf16_f32 v54, v56, v57
	v_cvt_pk_bf16_f32 v55, v58, v59
	v_cvt_pk_bf16_f32 v56, v60, v61
	v_cvt_pk_bf16_f32 v57, v62, v63
	v_cvt_pk_bf16_f32 v58, v64, v65
	v_cvt_pk_bf16_f32 v59, v66, v67
	v_cvt_pk_bf16_f32 v36, v36, v37
	v_cvt_pk_bf16_f32 v37, v38, v39
	v_cvt_pk_bf16_f32 v38, v40, v41
	v_cvt_pk_bf16_f32 v39, v42, v43
	v_cvt_pk_bf16_f32 v40, v44, v45
	v_cvt_pk_bf16_f32 v41, v46, v47
	v_cvt_pk_bf16_f32 v42, v48, v49
	v_cvt_pk_bf16_f32 v43, v50, v51
	v_add3_u32 v34, v68, v241, s46
	ds_read_b64_tr_b16 v[44:45],v34 offset:0
	ds_read_b64_tr_b16 v[46:47],v34 offset:512
	ds_read_b64_tr_b16 v[48:49],v34 offset:1024
	ds_read_b64_tr_b16 v[50:51],v34 offset:1536
	ds_read_b64_tr_b16 v[60:61],v34 offset:2048
	ds_read_b64_tr_b16 v[62:63],v34 offset:2560
	ds_read_b64_tr_b16 v[64:65],v34 offset:3072
	ds_read_b64_tr_b16 v[66:67],v34 offset:3584
	s_waitcnt lgkmcnt(0)
	s_nop 0
	v_mfma_f32_32x32x16_bf16 v[2:17], v[52:55], v[44:47], v[2:17]
	ds_read_b64_tr_b16 v[44:45],v34 offset:4096
	ds_read_b64_tr_b16 v[46:47],v34 offset:4608
	v_mfma_f32_32x32x16_bf16 v[2:17], v[56:59], v[48:51], v[2:17]
	ds_read_b64_tr_b16 v[48:49],v34 offset:5120
	ds_read_b64_tr_b16 v[50:51],v34 offset:5632
	v_mfma_f32_32x32x16_bf16 v[2:17], v[36:39], v[60:63], v[2:17]
	ds_read_b64_tr_b16 v[60:61],v34 offset:6144
	ds_read_b64_tr_b16 v[62:63],v34 offset:6656
	v_mfma_f32_32x32x16_bf16 v[2:17], v[40:43], v[64:67], v[2:17]
	ds_read_b64_tr_b16 v[64:65],v34 offset:7168
	ds_read_b64_tr_b16 v[66:67],v34 offset:7680
	s_waitcnt lgkmcnt(0)
	v_mfma_f32_32x32x16_bf16 v[18:33], v[52:55], v[44:47], v[18:33]
	v_mov_b32_e32 v34, v35
	s_nop 1
	v_permlane32_swap_b32_e32 v35, v34
	v_cmp_gt_u32_e32 vcc, 32, v209
	v_mfma_f32_32x32x16_bf16 v[18:33], v[56:59], v[48:51], v[18:33]
	v_mfma_f32_32x32x16_bf16 v[18:33], v[36:39], v[60:63], v[18:33]
	v_mfma_f32_32x32x16_bf16 v[18:33], v[40:43], v[64:67], v[18:33]
	s_and_saveexec_b64 s[0:1], vcc
	v_add_f32_e32 v34, v35, v34
	ds_write_b32 v243, v34 offset:49280
	s_or_b64 exec, exec, s[0:1]
	s_waitcnt lgkmcnt(0)
	ds_read_b128 v[34:37], v242 offset:49280
	ds_read_b128 v[38:41], v242 offset:49312
	s_lshl_b32 s0, s43, 12
	s_add_i32 s6, s0, 0
	v_lshlrev_b32_e32 v50, 1, v238
	s_waitcnt lgkmcnt(1)
	v_rcp_f32_e32 v42, v34
	v_rcp_f32_e32 v43, v35
	v_lshlrev_b32_e32 v51, 9, v239
	v_add3_u32 v50, s6, v50, v51
	v_mul_f32_e32 v2, v2, v42
	v_cvt_pk_bf16_f32 v2, v2, s0
	v_rcp_f32_e32 v44, v36
	v_rcp_f32_e32 v45, v37
	s_waitcnt lgkmcnt(0)
	v_rcp_f32_e32 v46, v38
	ds_read_b128 v[34:37], v242 offset:49344
	v_rcp_f32_e32 v47, v39
	v_rcp_f32_e32 v48, v40
	v_rcp_f32_e32 v49, v41
	ds_read_b128 v[38:41], v242 offset:49376
	ds_write_b16 v50, v2 offset:51200
	v_mul_f32_e32 v2, v18, v42
	v_cvt_pk_bf16_f32 v2, v2, s0
	ds_write_b16 v50, v2 offset:51264
	v_mul_f32_e32 v2, v3, v43
	v_cvt_pk_bf16_f32 v2, v2, s0
	ds_write_b16 v50, v2 offset:51328
	v_mul_f32_e32 v2, v19, v43
	v_cvt_pk_bf16_f32 v2, v2, s0
	ds_write_b16 v50, v2 offset:51392
	v_mul_f32_e32 v2, v4, v44
	v_cvt_pk_bf16_f32 v2, v2, s0
	ds_write_b16 v50, v2 offset:51456
	v_mul_f32_e32 v2, v20, v44
	v_cvt_pk_bf16_f32 v2, v2, s0
	ds_write_b16 v50, v2 offset:51520
	v_mul_f32_e32 v2, v5, v45
	v_cvt_pk_bf16_f32 v2, v2, s0
	ds_write_b16 v50, v2 offset:51584
	v_mul_f32_e32 v2, v21, v45
	v_cvt_pk_bf16_f32 v2, v2, s0
	ds_write_b16 v50, v2 offset:51648
	v_mul_f32_e32 v2, v6, v46
	v_cvt_pk_bf16_f32 v2, v2, s0
	ds_write_b16 v50, v2 offset:52224
	v_mul_f32_e32 v2, v22, v46
	v_cvt_pk_bf16_f32 v2, v2, s0
	ds_write_b16 v50, v2 offset:52288
	v_mul_f32_e32 v2, v7, v47
	v_cvt_pk_bf16_f32 v2, v2, s0
	ds_write_b16 v50, v2 offset:52352
	v_mul_f32_e32 v2, v23, v47
	v_cvt_pk_bf16_f32 v2, v2, s0
	ds_write_b16 v50, v2 offset:52416
	v_mul_f32_e32 v2, v8, v48
	v_cvt_pk_bf16_f32 v2, v2, s0
	ds_write_b16 v50, v2 offset:52480
	v_mul_f32_e32 v2, v24, v48
	v_cvt_pk_bf16_f32 v2, v2, s0
	s_waitcnt lgkmcnt(14)
	v_rcp_f32_e32 v34, v34
	ds_write_b16 v50, v2 offset:52544
	v_mul_f32_e32 v2, v9, v49
	v_cvt_pk_bf16_f32 v2, v2, s0
	ds_write_b16 v50, v2 offset:52608
	v_mul_f32_e32 v2, v25, v49
	v_cvt_pk_bf16_f32 v2, v2, s0
	v_rcp_f32_e32 v35, v35
	ds_write_b16 v50, v2 offset:52672
	v_mul_f32_e32 v2, v10, v34
	v_cvt_pk_bf16_f32 v2, v2, s0
	ds_write_b16 v50, v2 offset:53248
	v_mul_f32_e32 v2, v26, v34
	v_cvt_pk_bf16_f32 v2, v2, s0
	v_rcp_f32_e32 v36, v36
	ds_write_b16 v50, v2 offset:53312
	v_mul_f32_e32 v2, v11, v35
	v_cvt_pk_bf16_f32 v2, v2, s0
	ds_write_b16 v50, v2 offset:53376
	v_mul_f32_e32 v2, v27, v35
	v_cvt_pk_bf16_f32 v2, v2, s0
	v_rcp_f32_e32 v37, v37
	ds_write_b16 v50, v2 offset:53440
	v_mul_f32_e32 v2, v12, v36
	v_cvt_pk_bf16_f32 v2, v2, s0
	ds_write_b16 v50, v2 offset:53504
	v_mul_f32_e32 v2, v28, v36
	v_cvt_pk_bf16_f32 v2, v2, s0
	s_waitcnt lgkmcnt(14)
	v_rcp_f32_e32 v38, v38
	ds_write_b16 v50, v2 offset:53568
	v_mul_f32_e32 v2, v13, v37
	v_cvt_pk_bf16_f32 v2, v2, s0
	ds_write_b16 v50, v2 offset:53632
	v_mul_f32_e32 v2, v29, v37
	v_cvt_pk_bf16_f32 v2, v2, s0
	v_rcp_f32_e32 v39, v39
	ds_write_b16 v50, v2 offset:53696
	v_mul_f32_e32 v2, v14, v38
	v_cvt_pk_bf16_f32 v2, v2, s0
	ds_write_b16 v50, v2 offset:54272
	v_mul_f32_e32 v2, v30, v38
	v_cvt_pk_bf16_f32 v2, v2, s0
	v_rcp_f32_e32 v40, v40
	ds_write_b16 v50, v2 offset:54336
	v_mul_f32_e32 v2, v15, v39
	v_cvt_pk_bf16_f32 v2, v2, s0
	ds_write_b16 v50, v2 offset:54400
	v_mul_f32_e32 v2, v31, v39
	v_cvt_pk_bf16_f32 v2, v2, s0
	v_rcp_f32_e32 v41, v41
	ds_write_b16 v50, v2 offset:54464
	v_mul_f32_e32 v2, v16, v40
	v_cvt_pk_bf16_f32 v2, v2, s0
	ds_write_b16 v50, v2 offset:54528
	v_mul_f32_e32 v2, v32, v40
	v_cvt_pk_bf16_f32 v2, v2, s0
	ds_write_b16 v50, v2 offset:54592
	v_mul_f32_e32 v2, v17, v41
	v_cvt_pk_bf16_f32 v2, v2, s0
	ds_write_b16 v50, v2 offset:54656
	v_mul_f32_e32 v2, v33, v41
	v_cvt_pk_bf16_f32 v2, v2, s0
	ds_write_b16 v50, v2 offset:54720
	v_lshlrev_b32_e32 v2, 1, v237
	v_and_b32_e32 v206, 0x70, v2
	s_ashr_i32 s29, s28, 31
	s_lshl_b64 s[0:1], s[30:31], 1
	v_lshrrev_b32_e32 v14, 3, v209
	v_add_u32_e32 v15, s6, v206
	s_add_u32 s7, s56, s0
	s_waitcnt lgkmcnt(0)
	v_lshl_add_u32 v2, v14, 7, v15
	v_or_b32_e32 v16, 8, v14
	s_addc_u32 s10, s57, s1
	s_lshl_b64 s[0:1], s[28:29], 1
	ds_read_b128 v[2:5], v2 offset:51200
	v_lshl_add_u32 v6, v16, 7, v15
	s_add_u32 s0, s7, s0
	ds_read_b128 v[6:9], v6 offset:51200
	s_addc_u32 s1, s10, s1
	v_lshl_add_u64 v[10:11], s[0:1], 0, v[206:207]
	v_lshlrev_b32_e32 v206, 11, v14
	v_lshl_add_u64 v[12:13], v[10:11], 0, v[206:207]
	v_lshlrev_b32_e32 v206, 11, v16
	s_waitcnt lgkmcnt(1)
	global_store_dwordx4 v[12:13], v[2:5], off sc1
	v_mov_b32_e32 v84, v236
	s_nop 0
	v_lshl_add_u64 v[2:3], v[10:11], 0, v[206:207]
	s_waitcnt lgkmcnt(0)
	global_store_dwordx4 v[2:3], v[6:9], off sc1
	s_nop 1
	v_or_b32_e32 v6, 16, v14
	v_lshl_add_u32 v2, v6, 7, v15
	v_or_b32_e32 v14, 24, v14
	ds_read_b128 v[2:5], v2 offset:51200
	v_lshlrev_b32_e32 v206, 11, v6
	v_lshl_add_u32 v6, v14, 7, v15
	ds_read_b128 v[6:9], v6 offset:51200
	v_lshl_add_u64 v[12:13], v[10:11], 0, v[206:207]
	v_lshlrev_b32_e32 v206, 11, v14
	s_waitcnt lgkmcnt(1)
	global_store_dwordx4 v[12:13], v[2:5], off sc1
	s_nop 1
	v_lshl_add_u64 v[2:3], v[10:11], 0, v[206:207]
	s_waitcnt lgkmcnt(0)
	global_store_dwordx4 v[2:3], v[6:9], off sc1
	s_waitcnt lgkmcnt(0)
	s_barrier
	s_and_saveexec_b64 s[0:1], s[14:15]
	s_cbranch_execz .LBB0_330

.LBB0_495:
	s_nop 0
	v_lshl_add_u64 v[8:9], s[34:35], 0, v[130:131]
	v_add_co_u32_e32 v8, vcc, s11, v8
	s_addk_i32 s10, 0x2000
	s_nop 0
	v_addc_co_u32_e32 v9, vcc, 0, v9, vcc
	global_load_dwordx4 v[84:87], v[8:9], off
	global_load_dwordx4 v[80:83], v[8:9], off offset:256
	v_lshl_add_u64 v[8:9], s[34:35], 0, v[128:129]
	v_add_co_u32_e32 v10, vcc, s12, v8
	v_lshl_add_u64 v[128:129], v[128:129], 0, s[6:7]
	s_nop 0
	v_addc_co_u32_e32 v11, vcc, 0, v9, vcc
	global_load_dword v151, v[10:11], off
	v_add_co_u32_e32 v10, vcc, s13, v8
	v_lshl_add_u64 v[130:131], v[130:131], 0, s[8:9]
	s_nop 0
	v_addc_co_u32_e32 v11, vcc, 0, v9, vcc
	v_add_co_u32_e32 v8, vcc, s16, v8
	global_load_dword v152, v[10:11], off
	s_nop 0
	v_addc_co_u32_e32 v9, vcc, 0, v9, vcc
	global_load_dword v153, v[8:9], off
	v_lshl_add_u64 v[8:9], s[34:35], 0, v[126:127]
	v_add_co_u32_e32 v10, vcc, s17, v8
	v_lshl_add_u64 v[126:127], v[126:127], 0, s[4:5]
	s_nop 0
	v_addc_co_u32_e32 v11, vcc, 0, v9, vcc
	global_load_dwordx4 v[72:75], v[10:11], off
	v_add_co_u32_e32 v10, vcc, s18, v8
	s_cmpk_lt_i32 s10, 0x2000
	s_nop 0
	v_addc_co_u32_e32 v11, vcc, 0, v9, vcc
	v_add_co_u32_e32 v8, vcc, s19, v8
	global_load_dwordx4 v[76:79], v[10:11], off
	s_nop 0
	v_addc_co_u32_e32 v9, vcc, 0, v9, vcc
	global_load_dwordx4 v[68:71], v[8:9], off
	v_lshl_add_u64 v[8:9], s[34:35], 0, v[116:117]
	v_add_co_u32_e32 v8, vcc, s11, v8
	v_lshl_add_u64 v[116:117], v[116:117], 0, s[8:9]
	s_nop 0
	v_addc_co_u32_e32 v9, vcc, 0, v9, vcc
	global_load_dwordx4 v[64:67], v[8:9], off
	global_load_dwordx4 v[60:63], v[8:9], off offset:256
	v_lshl_add_u64 v[8:9], s[34:35], 0, v[114:115]
	v_add_co_u32_e32 v10, vcc, s12, v8
	v_lshl_add_u64 v[114:115], v[114:115], 0, s[6:7]
	s_nop 0
	v_addc_co_u32_e32 v11, vcc, 0, v9, vcc
	global_load_dword v148, v[10:11], off
	v_add_co_u32_e32 v10, vcc, s13, v8
	s_waitcnt vmcnt(10)
	v_lshlrev_b32_e32 v155, 16, v85
	v_addc_co_u32_e32 v11, vcc, 0, v9, vcc
	v_add_co_u32_e32 v8, vcc, s16, v8
	global_load_dword v149, v[10:11], off
	s_nop 0
	v_addc_co_u32_e32 v9, vcc, 0, v9, vcc
	global_load_dword v150, v[8:9], off
	v_lshl_add_u64 v[8:9], s[34:35], 0, v[112:113]
	v_add_co_u32_e32 v10, vcc, s17, v8
	v_lshlrev_b32_e32 v154, 16, v84
	s_nop 0
	v_addc_co_u32_e32 v11, vcc, 0, v9, vcc
	global_load_dwordx4 v[52:55], v[10:11], off
	v_add_co_u32_e32 v10, vcc, s18, v8
	s_waitcnt vmcnt(12)
	v_lshlrev_b32_e32 v157, 16, v81
	v_addc_co_u32_e32 v11, vcc, 0, v9, vcc
	v_add_co_u32_e32 v8, vcc, s19, v8
	v_lshlrev_b32_e32 v156, 16, v80
	s_nop 0
	v_addc_co_u32_e32 v9, vcc, 0, v9, vcc
	v_and_b32_e32 v85, 0xffff0000, v85
	v_and_b32_e32 v84, 0xffff0000, v84
	v_and_b32_e32 v81, 0xffff0000, v81
	v_and_b32_e32 v80, 0xffff0000, v80
	global_load_dwordx4 v[56:59], v[10:11], off
	global_load_dwordx4 v[48:51], v[8:9], off
	v_lshl_add_u64 v[8:9], s[34:35], 0, v[106:107]
	v_pk_fma_f32 v[154:155], v[122:123], v[156:157], v[154:155] neg_lo:[1,0,0] neg_hi:[1,0,0]
	v_pk_fma_f32 v[80:81], v[122:123], v[80:81], v[84:85] neg_lo:[1,0,0] neg_hi:[1,0,0]
	v_add_co_u32_e32 v8, vcc, s11, v8
	v_pk_mul_f32 v[84:85], v[154:155], v[154:155]
	v_pk_mul_f32 v[156:157], v[80:81], v[80:81]
	v_lshlrev_b32_e32 v159, 16, v87
	v_lshlrev_b32_e32 v158, 16, v86
	v_lshlrev_b32_e32 v161, 16, v83
	v_lshlrev_b32_e32 v160, 16, v82
	v_and_b32_e32 v87, 0xffff0000, v87
	v_and_b32_e32 v86, 0xffff0000, v86
	v_and_b32_e32 v83, 0xffff0000, v83
	v_and_b32_e32 v82, 0xffff0000, v82
	v_addc_co_u32_e32 v9, vcc, 0, v9, vcc
	v_pk_fma_f32 v[158:159], v[122:123], v[160:161], v[158:159] neg_lo:[1,0,0] neg_hi:[1,0,0]
	v_pk_fma_f32 v[82:83], v[122:123], v[82:83], v[86:87] neg_lo:[1,0,0] neg_hi:[1,0,0]
	v_add_f32_e32 v84, v84, v156
	global_load_dwordx4 v[44:47], v[8:9], off
	global_load_dwordx4 v[40:43], v[8:9], off offset:256
	v_lshl_add_u64 v[8:9], s[34:35], 0, v[104:105]
	v_mov_b32_e32 v86, v82
	v_mov_b32_e32 v87, v158
	v_add_f32_e32 v84, v85, v84
	v_add_co_u32_e32 v10, vcc, s12, v8
	v_pk_mul_f32 v[86:87], v[86:87], v[86:87]
	v_add_f32_e32 v84, v157, v84
	v_addc_co_u32_e32 v11, vcc, 0, v9, vcc
	v_mov_b32_e32 v160, v83
	v_mov_b32_e32 v161, v159
	v_add_f32_e32 v84, v87, v84
	global_load_dword v145, v[10:11], off
	v_add_co_u32_e32 v10, vcc, s13, v8
	v_pk_mul_f32 v[160:161], v[160:161], v[160:161]
	v_add_f32_e32 v84, v86, v84
	v_addc_co_u32_e32 v11, vcc, 0, v9, vcc
	v_add_f32_e32 v84, v161, v84
	v_add_co_u32_e32 v8, vcc, s16, v8
	v_add_f32_e32 v84, v160, v84
	s_nop 0
	v_addc_co_u32_e32 v9, vcc, 0, v9, vcc
	ds_bpermute_b32 v85, v136, v84
	global_load_dword v146, v[10:11], off
	global_load_dword v147, v[8:9], off
	v_lshl_add_u64 v[8:9], s[34:35], 0, v[102:103]
	v_add_co_u32_e32 v10, vcc, s17, v8
	s_waitcnt lgkmcnt(0)
	v_add_f32_e32 v84, v84, v85
	v_addc_co_u32_e32 v11, vcc, 0, v9, vcc
	global_load_dwordx4 v[32:35], v[10:11], off
	v_add_co_u32_e32 v10, vcc, s18, v8
	ds_bpermute_b32 v85, v137, v84
	s_nop 0
	v_addc_co_u32_e32 v11, vcc, 0, v9, vcc
	v_add_co_u32_e32 v8, vcc, s19, v8
	global_load_dwordx4 v[36:39], v[10:11], off
	s_nop 0
	v_addc_co_u32_e32 v9, vcc, 0, v9, vcc
	global_load_dwordx4 v[28:31], v[8:9], off
	v_lshl_add_u64 v[8:9], s[34:35], 0, v[94:95]
	v_add_co_u32_e32 v8, vcc, s11, v8
	s_waitcnt lgkmcnt(0)
	v_add_f32_e32 v84, v84, v85
	v_addc_co_u32_e32 v9, vcc, 0, v9, vcc
	global_load_dwordx4 v[24:27], v[8:9], off
	global_load_dwordx4 v[20:23], v[8:9], off offset:256
	v_lshl_add_u64 v[8:9], s[34:35], 0, v[92:93]
	v_add_co_u32_e32 v10, vcc, s12, v8
	ds_bpermute_b32 v85, v138, v84
	s_nop 0
	v_addc_co_u32_e32 v11, vcc, 0, v9, vcc
	global_load_dword v142, v[10:11], off
	v_add_co_u32_e32 v10, vcc, s13, v8
	s_waitcnt lgkmcnt(0)
	v_add_f32_e32 v84, v84, v85
	v_addc_co_u32_e32 v11, vcc, 0, v9, vcc
	v_add_co_u32_e32 v8, vcc, s16, v8
	global_load_dword v143, v[10:11], off
	s_nop 0
	v_addc_co_u32_e32 v9, vcc, 0, v9, vcc
	global_load_dword v144, v[8:9], off
	v_lshl_add_u64 v[8:9], s[34:35], 0, v[90:91]
	ds_bpermute_b32 v85, v139, v84
	v_add_co_u32_e32 v10, vcc, s17, v8
	v_lshl_add_u64 v[90:91], v[90:91], 0, s[4:5]
	s_nop 0
	v_addc_co_u32_e32 v11, vcc, 0, v9, vcc
	global_load_dwordx4 v[12:15], v[10:11], off
	v_add_co_u32_e32 v10, vcc, s18, v8
	s_waitcnt lgkmcnt(0)
	v_add_f32_e32 v84, v84, v85
	v_addc_co_u32_e32 v11, vcc, 0, v9, vcc
	v_add_co_u32_e32 v8, vcc, s19, v8
	v_fmamk_f32 v84, v84, 0x3c000000, v140
	s_nop 0
	v_addc_co_u32_e32 v9, vcc, 0, v9, vcc
	v_cmp_gt_f32_e32 vcc, s21, v84
	v_mul_f32_e32 v85, 0x4f800000, v84
	global_load_dwordx4 v[16:19], v[10:11], off
	v_cndmask_b32_e32 v84, v84, v85, vcc
	v_sqrt_f32_e32 v85, v84
	global_load_dwordx4 v[8:11], v[8:9], off
	v_lshl_add_u64 v[92:93], v[92:93], 0, s[6:7]
	v_lshl_add_u64 v[94:95], v[94:95], 0, s[8:9]
	v_add_u32_e32 v86, -1, v85
	v_fma_f32 v87, -v86, v85, v84
	v_cmp_ge_f32_e64 s[0:1], 0, v87
	v_add_u32_e32 v87, 1, v85
	v_lshl_add_u64 v[102:103], v[102:103], 0, s[4:5]
	v_cndmask_b32_e64 v86, v85, v86, s[0:1]
	v_fma_f32 v85, -v87, v85, v84
	v_cmp_lt_f32_e64 s[0:1], 0, v85
	v_lshl_add_u64 v[104:105], v[104:105], 0, s[6:7]
	v_lshl_add_u64 v[106:107], v[106:107], 0, s[8:9]
	v_cndmask_b32_e64 v85, v86, v87, s[0:1]
	v_mul_f32_e32 v86, 0x37800000, v85
	v_cndmask_b32_e32 v85, v85, v86, vcc
	v_cmp_class_f32_e32 vcc, v84, v141
	v_lshl_add_u64 v[112:113], v[112:113], 0, s[4:5]
	s_nop 0
	v_cndmask_b32_e32 v84, v85, v84, vcc
	v_div_scale_f32 v85, s[0:1], v84, v84, s22
	v_rcp_f32_e32 v86, v85
	s_nop 0
	v_fma_f32 v87, -v85, v86, 1.0
	v_fmac_f32_e32 v86, v87, v86
	v_div_scale_f32 v87, vcc, s22, v84, s22
	v_mul_f32_e32 v156, v87, v86
	v_fma_f32 v157, -v85, v156, v87
	v_fmac_f32_e32 v156, v157, v86
	v_fma_f32 v85, -v85, v156, v87
	v_div_fmas_f32 v85, v85, v86, v156
	v_div_fixup_f32 v84, v85, v84, s22
	v_pk_mul_f32 v[82:83], v[82:83], v[84:85] op_sel_hi:[1,0]
	v_pk_mul_f32 v[86:87], v[154:155], v[84:85] op_sel_hi:[1,0]
	v_pk_mul_f32 v[82:83], v[4:5], v[82:83]
	v_pk_mul_f32 v[86:87], v[2:3], v[86:87]
	v_pk_mul_f32 v[80:81], v[80:81], v[84:85] op_sel_hi:[1,0]
	v_pk_mul_f32 v[154:155], v[158:159], v[84:85] op_sel_hi:[1,0]
	v_bfe_u32 v84, v83, 16, 1
	v_bfe_u32 v85, v82, 16, 1
	v_pk_mul_f32 v[80:81], v[124:125], v[80:81]
	v_add3_u32 v82, v82, v85, s23
	v_add3_u32 v83, v83, v84, s23
	v_bfe_u32 v84, v86, 16, 1
	v_bfe_u32 v85, v87, 16, 1
	v_pk_mul_f32 v[154:155], v[6:7], v[154:155]
	v_bfe_u32 v156, v81, 16, 1
	v_bfe_u32 v157, v80, 16, 1
	v_add3_u32 v85, v87, v85, s23
	v_add3_u32 v84, v86, v84, s23
	v_add3_u32 v80, v80, v157, s23
	v_add3_u32 v81, v81, v156, s23
	v_bfe_u32 v156, v154, 16, 1
	v_bfe_u32 v157, v155, 16, 1
	v_lshrrev_b32_e32 v84, 16, v84
	v_lshrrev_b32_e32 v85, 16, v85
	v_add3_u32 v155, v155, v157, s23
	v_add3_u32 v154, v154, v156, s23
	v_and_or_b32 v81, v81, s20, v85
	v_and_or_b32 v80, v80, s20, v84
	v_lshl_add_u64 v[84:85], v[100:101], 0, v[134:135]
	v_lshrrev_b32_e32 v86, 16, v154
	v_lshrrev_b32_e32 v87, 16, v155
	v_add_co_u32_e32 v84, vcc, s24, v84
	v_and_or_b32 v83, v83, s20, v87
	v_and_or_b32 v82, v82, s20, v86
	v_addc_co_u32_e32 v85, vcc, -1, v85, vcc
	global_store_dwordx4 v[84:85], v[80:83], off offset:-256 sc1
	v_lshl_add_u64 v[134:135], v[134:135], 0, s[8:9]
	s_waitcnt vmcnt(28)
	v_max3_f32 v80, v151, v152, v153
	v_sub_f32_e32 v81, v151, v80
	v_exp_f32_e32 v83, v81
	v_sub_f32_e32 v81, v152, v80
	v_exp_f32_e32 v82, v81
	v_sub_f32_e32 v80, v153, v80
	v_exp_f32_e32 v80, v80
	v_add_f32_e32 v81, v83, v82
	v_add_f32_e32 v81, v80, v81
	v_div_scale_f32 v84, s[0:1], v81, v81, 1.0
	v_rcp_f32_e32 v85, v84
	s_nop 0
	v_fma_f32 v86, -v84, v85, 1.0
	v_fmac_f32_e32 v85, v86, v85
	v_div_scale_f32 v86, vcc, 1.0, v81, 1.0
	v_mul_f32_e32 v87, v86, v85
	v_fma_f32 v151, -v84, v87, v86
	v_fmac_f32_e32 v87, v151, v85
	v_fma_f32 v84, -v84, v87, v86
	v_div_fmas_f32 v84, v84, v85, v87
	v_div_fixup_f32 v84, v84, v81, 1.0
	v_pk_mul_f32 v[82:83], v[82:83], v[84:85] op_sel_hi:[1,0]
	s_waitcnt vmcnt(26)
	v_lshlrev_b32_e32 v87, 16, v77
	v_lshlrev_b32_e32 v86, 16, v72
	v_mul_f32_e32 v80, v80, v84
	v_lshlrev_b32_e32 v85, 16, v73
	v_lshlrev_b32_e32 v84, 16, v76
	v_pk_mul_f32 v[86:87], v[82:83], v[86:87] op_sel:[1,0] op_sel_hi:[0,1]
	v_pk_fma_f32 v[84:85], v[82:83], v[84:85], v[86:87]
	s_waitcnt vmcnt(25)
	v_lshlrev_b32_e32 v87, 16, v69
	v_lshlrev_b32_e32 v86, 16, v68
	v_pk_fma_f32 v[84:85], v[80:81], v[86:87], v[84:85] op_sel_hi:[0,1,1]
	v_and_b32_e32 v87, 0xffff0000, v73
	v_and_b32_e32 v73, 0xffff0000, v77
	v_and_b32_e32 v72, 0xffff0000, v72
	v_and_b32_e32 v86, 0xffff0000, v76
	v_pk_mul_f32 v[72:73], v[82:83], v[72:73] op_sel:[1,0] op_sel_hi:[0,1]
	v_pk_fma_f32 v[72:73], v[82:83], v[86:87], v[72:73]
	v_and_b32_e32 v69, 0xffff0000, v69
	v_and_b32_e32 v68, 0xffff0000, v68
	v_lshlrev_b32_e32 v77, 16, v79
	v_lshlrev_b32_e32 v76, 16, v74
	v_pk_fma_f32 v[68:69], v[80:81], v[68:69], v[72:73] op_sel_hi:[0,1,1]
	v_lshlrev_b32_e32 v73, 16, v75
	v_lshlrev_b32_e32 v72, 16, v78
	v_pk_mul_f32 v[76:77], v[82:83], v[76:77] op_sel:[1,0] op_sel_hi:[0,1]
	v_pk_fma_f32 v[72:73], v[82:83], v[72:73], v[76:77]
	v_lshlrev_b32_e32 v77, 16, v71
	v_lshlrev_b32_e32 v76, 16, v70
	v_pk_fma_f32 v[72:73], v[80:81], v[76:77], v[72:73] op_sel_hi:[0,1,1]
	v_and_b32_e32 v77, 0xffff0000, v75
	v_and_b32_e32 v75, 0xffff0000, v79
	v_and_b32_e32 v74, 0xffff0000, v74
	v_and_b32_e32 v76, 0xffff0000, v78
	v_pk_mul_f32 v[74:75], v[82:83], v[74:75] op_sel:[1,0] op_sel_hi:[0,1]
	v_pk_fma_f32 v[74:75], v[82:83], v[76:77], v[74:75]
	v_and_b32_e32 v71, 0xffff0000, v71
	v_and_b32_e32 v70, 0xffff0000, v70
	v_bfe_u32 v76, v69, 16, 1
	v_bfe_u32 v77, v68, 16, 1
	v_pk_fma_f32 v[70:71], v[80:81], v[70:71], v[74:75] op_sel_hi:[0,1,1]
	v_add3_u32 v68, v68, v77, s23
	v_add3_u32 v69, v69, v76, s23
	v_bfe_u32 v76, v72, 16, 1
	v_bfe_u32 v77, v73, 16, 1
	v_bfe_u32 v74, v71, 16, 1
	v_bfe_u32 v75, v70, 16, 1
	v_add3_u32 v73, v73, v77, s23
	v_add3_u32 v72, v72, v76, s23
	v_add3_u32 v70, v70, v75, s23
	v_add3_u32 v71, v71, v74, s23
	v_bfe_u32 v74, v84, 16, 1
	v_bfe_u32 v75, v85, 16, 1
	v_lshrrev_b32_e32 v72, 16, v72
	v_lshrrev_b32_e32 v73, 16, v73
	v_add3_u32 v75, v85, v75, s23
	v_add3_u32 v74, v84, v74, s23
	v_and_or_b32 v71, v71, s20, v73
	v_and_or_b32 v70, v70, s20, v72
	v_lshl_add_u64 v[72:73], v[88:89], 0, v[132:133]
	v_lshrrev_b32_e32 v74, 16, v74
	v_lshrrev_b32_e32 v75, 16, v75
	v_add_co_u32_e32 v72, vcc, s25, v72
	v_and_or_b32 v69, v69, s20, v75
	v_and_or_b32 v68, v68, s20, v74
	v_addc_co_u32_e32 v73, vcc, -1, v73, vcc
	global_store_dwordx4 v[72:73], v[68:71], off offset:-3072 sc1
	s_waitcnt vmcnt(25)
	v_lshlrev_b32_e32 v73, 16, v67
	v_lshlrev_b32_e32 v72, 16, v66
	v_lshlrev_b32_e32 v69, 16, v65
	v_lshlrev_b32_e32 v68, 16, v64
	s_waitcnt vmcnt(24)
	v_lshlrev_b32_e32 v71, 16, v61
	v_lshlrev_b32_e32 v70, 16, v60
	v_and_b32_e32 v65, 0xffff0000, v65
	v_and_b32_e32 v64, 0xffff0000, v64
	v_and_b32_e32 v61, 0xffff0000, v61
	v_and_b32_e32 v60, 0xffff0000, v60
	v_pk_fma_f32 v[68:69], v[122:123], v[70:71], v[68:69] neg_lo:[1,0,0] neg_hi:[1,0,0]
	v_pk_fma_f32 v[60:61], v[122:123], v[60:61], v[64:65] neg_lo:[1,0,0] neg_hi:[1,0,0]
	v_pk_mul_f32 v[64:65], v[68:69], v[68:69]
	v_pk_mul_f32 v[70:71], v[60:61], v[60:61]
	v_lshlrev_b32_e32 v75, 16, v63
	v_lshlrev_b32_e32 v74, 16, v62
	v_and_b32_e32 v67, 0xffff0000, v67
	v_and_b32_e32 v66, 0xffff0000, v66
	v_and_b32_e32 v63, 0xffff0000, v63
	v_and_b32_e32 v62, 0xffff0000, v62
	v_pk_fma_f32 v[72:73], v[122:123], v[74:75], v[72:73] neg_lo:[1,0,0] neg_hi:[1,0,0]
	v_pk_fma_f32 v[62:63], v[122:123], v[62:63], v[66:67] neg_lo:[1,0,0] neg_hi:[1,0,0]
	v_add_f32_e32 v64, v64, v70
	v_mov_b32_e32 v66, v62
	v_mov_b32_e32 v67, v72
	v_add_f32_e32 v64, v65, v64
	v_pk_mul_f32 v[66:67], v[66:67], v[66:67]
	v_add_f32_e32 v64, v71, v64
	v_mov_b32_e32 v74, v63
	v_mov_b32_e32 v75, v73
	v_add_f32_e32 v64, v67, v64
	v_pk_mul_f32 v[74:75], v[74:75], v[74:75]
	v_add_f32_e32 v64, v66, v64
	v_add_f32_e32 v64, v75, v64
	v_add_f32_e32 v64, v74, v64
	ds_bpermute_b32 v65, v136, v64
	v_lshl_add_u64 v[132:133], v[132:133], 0, s[8:9]
	s_waitcnt lgkmcnt(0)
	v_add_f32_e32 v64, v64, v65
	ds_bpermute_b32 v65, v137, v64
	s_waitcnt lgkmcnt(0)
	v_add_f32_e32 v64, v64, v65
	ds_bpermute_b32 v65, v138, v64
	s_waitcnt lgkmcnt(0)
	v_add_f32_e32 v64, v64, v65
	ds_bpermute_b32 v65, v139, v64
	s_waitcnt lgkmcnt(0)
	v_add_f32_e32 v64, v64, v65
	v_fmamk_f32 v64, v64, 0x3c000000, v140
	v_cmp_gt_f32_e32 vcc, s21, v64
	v_mul_f32_e32 v65, 0x4f800000, v64
	s_nop 0
	v_cndmask_b32_e32 v64, v64, v65, vcc
	v_sqrt_f32_e32 v65, v64
	s_nop 0
	v_add_u32_e32 v66, -1, v65
	v_fma_f32 v67, -v66, v65, v64
	v_cmp_ge_f32_e64 s[0:1], 0, v67
	v_add_u32_e32 v67, 1, v65
	s_nop 0
	v_cndmask_b32_e64 v66, v65, v66, s[0:1]
	v_fma_f32 v65, -v67, v65, v64
	v_cmp_lt_f32_e64 s[0:1], 0, v65
	s_nop 1
	v_cndmask_b32_e64 v65, v66, v67, s[0:1]
	v_mul_f32_e32 v66, 0x37800000, v65
	v_cndmask_b32_e32 v65, v65, v66, vcc
	v_cmp_class_f32_e32 vcc, v64, v141
	s_nop 1
	v_cndmask_b32_e32 v64, v65, v64, vcc
	v_div_scale_f32 v65, s[0:1], v64, v64, s22
	v_rcp_f32_e32 v66, v65
	s_nop 0
	v_fma_f32 v67, -v65, v66, 1.0
	v_fmac_f32_e32 v66, v67, v66
	v_div_scale_f32 v67, vcc, s22, v64, s22
	v_mul_f32_e32 v70, v67, v66
	v_fma_f32 v71, -v65, v70, v67
	v_fmac_f32_e32 v70, v71, v66
	v_fma_f32 v65, -v65, v70, v67
	v_div_fmas_f32 v65, v65, v66, v70
	v_div_fixup_f32 v64, v65, v64, s22
	v_pk_mul_f32 v[62:63], v[62:63], v[64:65] op_sel_hi:[1,0]
	v_pk_mul_f32 v[66:67], v[68:69], v[64:65] op_sel_hi:[1,0]
	v_pk_mul_f32 v[62:63], v[4:5], v[62:63]
	v_pk_mul_f32 v[66:67], v[2:3], v[66:67]
	v_pk_mul_f32 v[60:61], v[60:61], v[64:65] op_sel_hi:[1,0]
	v_pk_mul_f32 v[68:69], v[72:73], v[64:65] op_sel_hi:[1,0]
	v_bfe_u32 v64, v63, 16, 1
	v_bfe_u32 v65, v62, 16, 1
	v_pk_mul_f32 v[60:61], v[124:125], v[60:61]
	v_add3_u32 v62, v62, v65, s23
	v_add3_u32 v63, v63, v64, s23
	v_bfe_u32 v64, v66, 16, 1
	v_bfe_u32 v65, v67, 16, 1
	v_pk_mul_f32 v[68:69], v[6:7], v[68:69]
	v_bfe_u32 v70, v61, 16, 1
	v_bfe_u32 v71, v60, 16, 1
	v_add3_u32 v65, v67, v65, s23
	v_add3_u32 v64, v66, v64, s23
	v_add3_u32 v60, v60, v71, s23
	v_add3_u32 v61, v61, v70, s23
	v_bfe_u32 v70, v68, 16, 1
	v_bfe_u32 v71, v69, 16, 1
	v_lshrrev_b32_e32 v64, 16, v64
	v_lshrrev_b32_e32 v65, 16, v65
	v_add3_u32 v69, v69, v71, s23
	v_add3_u32 v68, v68, v70, s23
	v_and_or_b32 v61, v61, s20, v65
	v_and_or_b32 v60, v60, s20, v64
	v_lshl_add_u64 v[64:65], v[100:101], 0, v[120:121]
	v_lshrrev_b32_e32 v66, 16, v68
	v_lshrrev_b32_e32 v67, 16, v69
	v_add_co_u32_e32 v64, vcc, s24, v64
	v_and_or_b32 v63, v63, s20, v67
	v_and_or_b32 v62, v62, s20, v66
	v_addc_co_u32_e32 v65, vcc, -1, v65, vcc
	global_store_dwordx4 v[64:65], v[60:63], off offset:-256 sc1
	v_lshl_add_u64 v[120:121], v[120:121], 0, s[8:9]
	s_waitcnt vmcnt(22)
	v_max3_f32 v60, v148, v149, v150
	v_sub_f32_e32 v61, v148, v60
	v_exp_f32_e32 v63, v61
	v_sub_f32_e32 v61, v149, v60
	v_exp_f32_e32 v62, v61
	v_sub_f32_e32 v60, v150, v60
	v_exp_f32_e32 v60, v60
	v_add_f32_e32 v61, v63, v62
	v_add_f32_e32 v61, v60, v61
	v_div_scale_f32 v64, s[0:1], v61, v61, 1.0
	v_rcp_f32_e32 v65, v64
	s_nop 0
	v_fma_f32 v66, -v64, v65, 1.0
	v_fmac_f32_e32 v65, v66, v65
	v_div_scale_f32 v66, vcc, 1.0, v61, 1.0
	v_mul_f32_e32 v67, v66, v65
	v_fma_f32 v68, -v64, v67, v66
	v_fmac_f32_e32 v67, v68, v65
	v_fma_f32 v64, -v64, v67, v66
	v_div_fmas_f32 v64, v64, v65, v67
	v_div_fixup_f32 v64, v64, v61, 1.0
	v_pk_mul_f32 v[62:63], v[62:63], v[64:65] op_sel_hi:[1,0]
	s_waitcnt vmcnt(20)
	v_lshlrev_b32_e32 v67, 16, v57
	v_lshlrev_b32_e32 v66, 16, v52
	v_mul_f32_e32 v60, v60, v64
	v_lshlrev_b32_e32 v65, 16, v53
	v_lshlrev_b32_e32 v64, 16, v56
	v_pk_mul_f32 v[66:67], v[62:63], v[66:67] op_sel:[1,0] op_sel_hi:[0,1]
	v_pk_fma_f32 v[64:65], v[62:63], v[64:65], v[66:67]
	s_waitcnt vmcnt(19)
	v_lshlrev_b32_e32 v67, 16, v49
	v_lshlrev_b32_e32 v66, 16, v48
	v_pk_fma_f32 v[64:65], v[60:61], v[66:67], v[64:65] op_sel_hi:[0,1,1]
	v_and_b32_e32 v67, 0xffff0000, v53
	v_and_b32_e32 v53, 0xffff0000, v57
	v_and_b32_e32 v52, 0xffff0000, v52
	v_and_b32_e32 v66, 0xffff0000, v56
	v_pk_mul_f32 v[52:53], v[62:63], v[52:53] op_sel:[1,0] op_sel_hi:[0,1]
	v_pk_fma_f32 v[52:53], v[62:63], v[66:67], v[52:53]
	v_and_b32_e32 v49, 0xffff0000, v49
	v_and_b32_e32 v48, 0xffff0000, v48
	v_lshlrev_b32_e32 v57, 16, v59
	v_lshlrev_b32_e32 v56, 16, v54
	v_pk_fma_f32 v[48:49], v[60:61], v[48:49], v[52:53] op_sel_hi:[0,1,1]
	v_lshlrev_b32_e32 v53, 16, v55
	v_lshlrev_b32_e32 v52, 16, v58
	v_pk_mul_f32 v[56:57], v[62:63], v[56:57] op_sel:[1,0] op_sel_hi:[0,1]
	v_pk_fma_f32 v[52:53], v[62:63], v[52:53], v[56:57]
	v_lshlrev_b32_e32 v57, 16, v51
	v_lshlrev_b32_e32 v56, 16, v50
	v_pk_fma_f32 v[52:53], v[60:61], v[56:57], v[52:53] op_sel_hi:[0,1,1]
	v_and_b32_e32 v57, 0xffff0000, v55
	v_and_b32_e32 v55, 0xffff0000, v59
	v_and_b32_e32 v54, 0xffff0000, v54
	v_and_b32_e32 v56, 0xffff0000, v58
	v_pk_mul_f32 v[54:55], v[62:63], v[54:55] op_sel:[1,0] op_sel_hi:[0,1]
	v_pk_fma_f32 v[54:55], v[62:63], v[56:57], v[54:55]
	v_and_b32_e32 v51, 0xffff0000, v51
	v_and_b32_e32 v50, 0xffff0000, v50
	v_bfe_u32 v56, v49, 16, 1
	v_bfe_u32 v57, v48, 16, 1
	v_pk_fma_f32 v[50:51], v[60:61], v[50:51], v[54:55] op_sel_hi:[0,1,1]
	v_add3_u32 v48, v48, v57, s23
	v_add3_u32 v49, v49, v56, s23
	v_bfe_u32 v56, v52, 16, 1
	v_bfe_u32 v57, v53, 16, 1
	v_bfe_u32 v54, v51, 16, 1
	v_bfe_u32 v55, v50, 16, 1
	v_add3_u32 v53, v53, v57, s23
	v_add3_u32 v52, v52, v56, s23
	v_add3_u32 v50, v50, v55, s23
	v_add3_u32 v51, v51, v54, s23
	v_bfe_u32 v54, v64, 16, 1
	v_bfe_u32 v55, v65, 16, 1
	v_lshrrev_b32_e32 v52, 16, v52
	v_lshrrev_b32_e32 v53, 16, v53
	v_add3_u32 v55, v65, v55, s23
	v_add3_u32 v54, v64, v54, s23
	v_and_or_b32 v51, v51, s20, v53
	v_and_or_b32 v50, v50, s20, v52
	v_lshl_add_u64 v[52:53], v[88:89], 0, v[118:119]
	v_lshrrev_b32_e32 v54, 16, v54
	v_lshrrev_b32_e32 v55, 16, v55
	v_add_co_u32_e32 v52, vcc, s25, v52
	v_and_or_b32 v49, v49, s20, v55
	v_and_or_b32 v48, v48, s20, v54
	v_addc_co_u32_e32 v53, vcc, -1, v53, vcc
	global_store_dwordx4 v[52:53], v[48:51], off offset:-3072 sc1
	s_waitcnt vmcnt(19)
	v_lshlrev_b32_e32 v53, 16, v47
	v_lshlrev_b32_e32 v52, 16, v46
	v_lshlrev_b32_e32 v49, 16, v45
	v_lshlrev_b32_e32 v48, 16, v44
	s_waitcnt vmcnt(18)
	v_lshlrev_b32_e32 v51, 16, v41
	v_lshlrev_b32_e32 v50, 16, v40
	v_and_b32_e32 v45, 0xffff0000, v45
	v_and_b32_e32 v44, 0xffff0000, v44
	v_and_b32_e32 v41, 0xffff0000, v41
	v_and_b32_e32 v40, 0xffff0000, v40
	v_pk_fma_f32 v[48:49], v[122:123], v[50:51], v[48:49] neg_lo:[1,0,0] neg_hi:[1,0,0]
	v_pk_fma_f32 v[40:41], v[122:123], v[40:41], v[44:45] neg_lo:[1,0,0] neg_hi:[1,0,0]
	v_pk_mul_f32 v[44:45], v[48:49], v[48:49]
	v_pk_mul_f32 v[50:51], v[40:41], v[40:41]
	v_lshlrev_b32_e32 v55, 16, v43
	v_lshlrev_b32_e32 v54, 16, v42
	v_and_b32_e32 v47, 0xffff0000, v47
	v_and_b32_e32 v46, 0xffff0000, v46
	v_and_b32_e32 v43, 0xffff0000, v43
	v_and_b32_e32 v42, 0xffff0000, v42
	v_pk_fma_f32 v[52:53], v[122:123], v[54:55], v[52:53] neg_lo:[1,0,0] neg_hi:[1,0,0]
	v_pk_fma_f32 v[42:43], v[122:123], v[42:43], v[46:47] neg_lo:[1,0,0] neg_hi:[1,0,0]
	v_add_f32_e32 v44, v44, v50
	v_mov_b32_e32 v46, v42
	v_mov_b32_e32 v47, v52
	v_add_f32_e32 v44, v45, v44
	v_pk_mul_f32 v[46:47], v[46:47], v[46:47]
	v_add_f32_e32 v44, v51, v44
	v_mov_b32_e32 v54, v43
	v_mov_b32_e32 v55, v53
	v_add_f32_e32 v44, v47, v44
	v_pk_mul_f32 v[54:55], v[54:55], v[54:55]
	v_add_f32_e32 v44, v46, v44
	v_add_f32_e32 v44, v55, v44
	v_add_f32_e32 v44, v54, v44
	ds_bpermute_b32 v45, v136, v44
	v_lshl_add_u64 v[118:119], v[118:119], 0, s[8:9]
	s_waitcnt lgkmcnt(0)
	v_add_f32_e32 v44, v44, v45
	ds_bpermute_b32 v45, v137, v44
	s_waitcnt lgkmcnt(0)
	v_add_f32_e32 v44, v44, v45
	ds_bpermute_b32 v45, v138, v44
	s_waitcnt lgkmcnt(0)
	v_add_f32_e32 v44, v44, v45
	ds_bpermute_b32 v45, v139, v44
	s_waitcnt lgkmcnt(0)
	v_add_f32_e32 v44, v44, v45
	v_fmamk_f32 v44, v44, 0x3c000000, v140
	v_cmp_gt_f32_e32 vcc, s21, v44
	v_mul_f32_e32 v45, 0x4f800000, v44
	s_nop 0
	v_cndmask_b32_e32 v44, v44, v45, vcc
	v_sqrt_f32_e32 v45, v44
	s_nop 0
	v_add_u32_e32 v46, -1, v45
	v_fma_f32 v47, -v46, v45, v44
	v_cmp_ge_f32_e64 s[0:1], 0, v47
	v_add_u32_e32 v47, 1, v45
	s_nop 0
	v_cndmask_b32_e64 v46, v45, v46, s[0:1]
	v_fma_f32 v45, -v47, v45, v44
	v_cmp_lt_f32_e64 s[0:1], 0, v45
	s_nop 1
	v_cndmask_b32_e64 v45, v46, v47, s[0:1]
	v_mul_f32_e32 v46, 0x37800000, v45
	v_cndmask_b32_e32 v45, v45, v46, vcc
	v_cmp_class_f32_e32 vcc, v44, v141
	s_nop 1
	v_cndmask_b32_e32 v44, v45, v44, vcc
	v_div_scale_f32 v45, s[0:1], v44, v44, s22
	v_rcp_f32_e32 v46, v45
	s_nop 0
	v_fma_f32 v47, -v45, v46, 1.0
	v_fmac_f32_e32 v46, v47, v46
	v_div_scale_f32 v47, vcc, s22, v44, s22
	v_mul_f32_e32 v50, v47, v46
	v_fma_f32 v51, -v45, v50, v47
	v_fmac_f32_e32 v50, v51, v46
	v_fma_f32 v45, -v45, v50, v47
	v_div_fmas_f32 v45, v45, v46, v50
	v_div_fixup_f32 v44, v45, v44, s22
	v_pk_mul_f32 v[42:43], v[42:43], v[44:45] op_sel_hi:[1,0]
	v_pk_mul_f32 v[46:47], v[48:49], v[44:45] op_sel_hi:[1,0]
	v_pk_mul_f32 v[42:43], v[4:5], v[42:43]
	v_pk_mul_f32 v[46:47], v[2:3], v[46:47]
	v_pk_mul_f32 v[40:41], v[40:41], v[44:45] op_sel_hi:[1,0]
	v_pk_mul_f32 v[48:49], v[52:53], v[44:45] op_sel_hi:[1,0]
	v_bfe_u32 v44, v43, 16, 1
	v_bfe_u32 v45, v42, 16, 1
	v_pk_mul_f32 v[40:41], v[124:125], v[40:41]
	v_add3_u32 v42, v42, v45, s23
	v_add3_u32 v43, v43, v44, s23
	v_bfe_u32 v44, v46, 16, 1
	v_bfe_u32 v45, v47, 16, 1
	v_pk_mul_f32 v[48:49], v[6:7], v[48:49]
	v_bfe_u32 v50, v41, 16, 1
	v_bfe_u32 v51, v40, 16, 1
	v_add3_u32 v45, v47, v45, s23
	v_add3_u32 v44, v46, v44, s23
	v_add3_u32 v40, v40, v51, s23
	v_add3_u32 v41, v41, v50, s23
	v_bfe_u32 v50, v48, 16, 1
	v_bfe_u32 v51, v49, 16, 1
	v_lshrrev_b32_e32 v44, 16, v44
	v_lshrrev_b32_e32 v45, 16, v45
	v_add3_u32 v49, v49, v51, s23
	v_add3_u32 v48, v48, v50, s23
	v_and_or_b32 v41, v41, s20, v45
	v_and_or_b32 v40, v40, s20, v44
	v_lshl_add_u64 v[44:45], v[100:101], 0, v[110:111]
	v_lshrrev_b32_e32 v46, 16, v48
	v_lshrrev_b32_e32 v47, 16, v49
	v_add_co_u32_e32 v44, vcc, s24, v44
	v_and_or_b32 v43, v43, s20, v47
	v_and_or_b32 v42, v42, s20, v46
	v_addc_co_u32_e32 v45, vcc, -1, v45, vcc
	global_store_dwordx4 v[44:45], v[40:43], off offset:-256 sc1
	v_lshl_add_u64 v[110:111], v[110:111], 0, s[8:9]
	s_waitcnt vmcnt(16)
	v_max3_f32 v40, v145, v146, v147
	v_sub_f32_e32 v41, v145, v40
	v_exp_f32_e32 v43, v41
	v_sub_f32_e32 v41, v146, v40
	v_exp_f32_e32 v42, v41
	v_sub_f32_e32 v40, v147, v40
	v_exp_f32_e32 v40, v40
	v_add_f32_e32 v41, v43, v42
	v_add_f32_e32 v41, v40, v41
	v_div_scale_f32 v44, s[0:1], v41, v41, 1.0
	v_rcp_f32_e32 v45, v44
	s_nop 0
	v_fma_f32 v46, -v44, v45, 1.0
	v_fmac_f32_e32 v45, v46, v45
	v_div_scale_f32 v46, vcc, 1.0, v41, 1.0
	v_mul_f32_e32 v47, v46, v45
	v_fma_f32 v48, -v44, v47, v46
	v_fmac_f32_e32 v47, v48, v45
	v_fma_f32 v44, -v44, v47, v46
	v_div_fmas_f32 v44, v44, v45, v47
	v_div_fixup_f32 v44, v44, v41, 1.0
	v_pk_mul_f32 v[42:43], v[42:43], v[44:45] op_sel_hi:[1,0]
	s_waitcnt vmcnt(14)
	v_lshlrev_b32_e32 v47, 16, v37
	v_lshlrev_b32_e32 v46, 16, v32
	v_mul_f32_e32 v40, v40, v44
	v_lshlrev_b32_e32 v45, 16, v33
	v_lshlrev_b32_e32 v44, 16, v36
	v_pk_mul_f32 v[46:47], v[42:43], v[46:47] op_sel:[1,0] op_sel_hi:[0,1]
	v_pk_fma_f32 v[44:45], v[42:43], v[44:45], v[46:47]
	s_waitcnt vmcnt(13)
	v_lshlrev_b32_e32 v47, 16, v29
	v_lshlrev_b32_e32 v46, 16, v28
	v_pk_fma_f32 v[44:45], v[40:41], v[46:47], v[44:45] op_sel_hi:[0,1,1]
	v_and_b32_e32 v47, 0xffff0000, v33
	v_and_b32_e32 v33, 0xffff0000, v37
	v_and_b32_e32 v32, 0xffff0000, v32
	v_and_b32_e32 v46, 0xffff0000, v36
	v_pk_mul_f32 v[32:33], v[42:43], v[32:33] op_sel:[1,0] op_sel_hi:[0,1]
	v_pk_fma_f32 v[32:33], v[42:43], v[46:47], v[32:33]
	v_and_b32_e32 v29, 0xffff0000, v29
	v_and_b32_e32 v28, 0xffff0000, v28
	v_lshlrev_b32_e32 v37, 16, v39
	v_lshlrev_b32_e32 v36, 16, v34
	v_pk_fma_f32 v[28:29], v[40:41], v[28:29], v[32:33] op_sel_hi:[0,1,1]
	v_lshlrev_b32_e32 v33, 16, v35
	v_lshlrev_b32_e32 v32, 16, v38
	v_pk_mul_f32 v[36:37], v[42:43], v[36:37] op_sel:[1,0] op_sel_hi:[0,1]
	v_pk_fma_f32 v[32:33], v[42:43], v[32:33], v[36:37]
	v_lshlrev_b32_e32 v37, 16, v31
	v_lshlrev_b32_e32 v36, 16, v30
	v_pk_fma_f32 v[32:33], v[40:41], v[36:37], v[32:33] op_sel_hi:[0,1,1]
	v_and_b32_e32 v37, 0xffff0000, v35
	v_and_b32_e32 v35, 0xffff0000, v39
	v_and_b32_e32 v34, 0xffff0000, v34
	v_and_b32_e32 v36, 0xffff0000, v38
	v_pk_mul_f32 v[34:35], v[42:43], v[34:35] op_sel:[1,0] op_sel_hi:[0,1]
	v_pk_fma_f32 v[34:35], v[42:43], v[36:37], v[34:35]
	v_and_b32_e32 v31, 0xffff0000, v31
	v_and_b32_e32 v30, 0xffff0000, v30
	v_bfe_u32 v36, v29, 16, 1
	v_bfe_u32 v37, v28, 16, 1
	v_pk_fma_f32 v[30:31], v[40:41], v[30:31], v[34:35] op_sel_hi:[0,1,1]
	v_add3_u32 v28, v28, v37, s23
	v_add3_u32 v29, v29, v36, s23
	v_bfe_u32 v36, v32, 16, 1
	v_bfe_u32 v37, v33, 16, 1
	v_bfe_u32 v34, v31, 16, 1
	v_bfe_u32 v35, v30, 16, 1
	v_add3_u32 v33, v33, v37, s23
	v_add3_u32 v32, v32, v36, s23
	v_add3_u32 v30, v30, v35, s23
	v_add3_u32 v31, v31, v34, s23
	v_bfe_u32 v34, v44, 16, 1
	v_bfe_u32 v35, v45, 16, 1
	v_lshrrev_b32_e32 v32, 16, v32
	v_lshrrev_b32_e32 v33, 16, v33
	v_add3_u32 v35, v45, v35, s23
	v_add3_u32 v34, v44, v34, s23
	v_and_or_b32 v31, v31, s20, v33
	v_and_or_b32 v30, v30, s20, v32
	v_lshl_add_u64 v[32:33], v[88:89], 0, v[108:109]
	v_lshrrev_b32_e32 v34, 16, v34
	v_lshrrev_b32_e32 v35, 16, v35
	v_add_co_u32_e32 v32, vcc, s25, v32
	v_and_or_b32 v29, v29, s20, v35
	v_and_or_b32 v28, v28, s20, v34
	v_addc_co_u32_e32 v33, vcc, -1, v33, vcc
	global_store_dwordx4 v[32:33], v[28:31], off offset:-3072 sc1
	s_waitcnt vmcnt(13)
	v_lshlrev_b32_e32 v33, 16, v27
	v_lshlrev_b32_e32 v32, 16, v26
	v_lshlrev_b32_e32 v29, 16, v25
	v_lshlrev_b32_e32 v28, 16, v24
	s_waitcnt vmcnt(12)
	v_lshlrev_b32_e32 v31, 16, v21
	v_lshlrev_b32_e32 v30, 16, v20
	v_and_b32_e32 v25, 0xffff0000, v25
	v_and_b32_e32 v24, 0xffff0000, v24
	v_and_b32_e32 v21, 0xffff0000, v21
	v_and_b32_e32 v20, 0xffff0000, v20
	v_pk_fma_f32 v[28:29], v[122:123], v[30:31], v[28:29] neg_lo:[1,0,0] neg_hi:[1,0,0]
	v_pk_fma_f32 v[20:21], v[122:123], v[20:21], v[24:25] neg_lo:[1,0,0] neg_hi:[1,0,0]
	v_pk_mul_f32 v[24:25], v[28:29], v[28:29]
	v_pk_mul_f32 v[30:31], v[20:21], v[20:21]
	v_lshlrev_b32_e32 v35, 16, v23
	v_lshlrev_b32_e32 v34, 16, v22
	v_and_b32_e32 v27, 0xffff0000, v27
	v_and_b32_e32 v26, 0xffff0000, v26
	v_and_b32_e32 v23, 0xffff0000, v23
	v_and_b32_e32 v22, 0xffff0000, v22
	v_pk_fma_f32 v[32:33], v[122:123], v[34:35], v[32:33] neg_lo:[1,0,0] neg_hi:[1,0,0]
	v_pk_fma_f32 v[22:23], v[122:123], v[22:23], v[26:27] neg_lo:[1,0,0] neg_hi:[1,0,0]
	v_add_f32_e32 v24, v24, v30
	v_mov_b32_e32 v26, v22
	v_mov_b32_e32 v27, v32
	v_add_f32_e32 v24, v25, v24
	v_pk_mul_f32 v[26:27], v[26:27], v[26:27]
	v_add_f32_e32 v24, v31, v24
	v_mov_b32_e32 v34, v23
	v_mov_b32_e32 v35, v33
	v_add_f32_e32 v24, v27, v24
	v_pk_mul_f32 v[34:35], v[34:35], v[34:35]
	v_add_f32_e32 v24, v26, v24
	v_add_f32_e32 v24, v35, v24
	v_add_f32_e32 v24, v34, v24
	ds_bpermute_b32 v25, v136, v24
	v_lshl_add_u64 v[108:109], v[108:109], 0, s[8:9]
	s_waitcnt lgkmcnt(0)
	v_add_f32_e32 v24, v24, v25
	ds_bpermute_b32 v25, v137, v24
	s_waitcnt lgkmcnt(0)
	v_add_f32_e32 v24, v24, v25
	ds_bpermute_b32 v25, v138, v24
	s_waitcnt lgkmcnt(0)
	v_add_f32_e32 v24, v24, v25
	ds_bpermute_b32 v25, v139, v24
	s_waitcnt lgkmcnt(0)
	v_add_f32_e32 v24, v24, v25
	v_fmamk_f32 v24, v24, 0x3c000000, v140
	v_cmp_gt_f32_e32 vcc, s21, v24
	v_mul_f32_e32 v25, 0x4f800000, v24
	s_nop 0
	v_cndmask_b32_e32 v24, v24, v25, vcc
	v_sqrt_f32_e32 v25, v24
	s_nop 0
	v_add_u32_e32 v26, -1, v25
	v_fma_f32 v27, -v26, v25, v24
	v_cmp_ge_f32_e64 s[0:1], 0, v27
	v_add_u32_e32 v27, 1, v25
	s_nop 0
	v_cndmask_b32_e64 v26, v25, v26, s[0:1]
	v_fma_f32 v25, -v27, v25, v24
	v_cmp_lt_f32_e64 s[0:1], 0, v25
	s_nop 1
	v_cndmask_b32_e64 v25, v26, v27, s[0:1]
	v_mul_f32_e32 v26, 0x37800000, v25
	v_cndmask_b32_e32 v25, v25, v26, vcc
	v_cmp_class_f32_e32 vcc, v24, v141
	s_nop 1
	v_cndmask_b32_e32 v24, v25, v24, vcc
	v_div_scale_f32 v25, s[0:1], v24, v24, s22
	v_rcp_f32_e32 v26, v25
	s_nop 0
	v_fma_f32 v27, -v25, v26, 1.0
	v_fmac_f32_e32 v26, v27, v26
	v_div_scale_f32 v27, vcc, s22, v24, s22
	v_mul_f32_e32 v30, v27, v26
	v_fma_f32 v31, -v25, v30, v27
	v_fmac_f32_e32 v30, v31, v26
	v_fma_f32 v25, -v25, v30, v27
	v_div_fmas_f32 v25, v25, v26, v30
	v_div_fixup_f32 v24, v25, v24, s22
	v_pk_mul_f32 v[22:23], v[22:23], v[24:25] op_sel_hi:[1,0]
	v_pk_mul_f32 v[26:27], v[28:29], v[24:25] op_sel_hi:[1,0]
	v_pk_mul_f32 v[22:23], v[4:5], v[22:23]
	v_pk_mul_f32 v[26:27], v[2:3], v[26:27]
	v_pk_mul_f32 v[20:21], v[20:21], v[24:25] op_sel_hi:[1,0]
	v_pk_mul_f32 v[28:29], v[32:33], v[24:25] op_sel_hi:[1,0]
	v_bfe_u32 v24, v23, 16, 1
	v_bfe_u32 v25, v22, 16, 1
	v_pk_mul_f32 v[20:21], v[124:125], v[20:21]
	v_add3_u32 v22, v22, v25, s23
	v_add3_u32 v23, v23, v24, s23
	v_bfe_u32 v24, v26, 16, 1
	v_bfe_u32 v25, v27, 16, 1
	v_pk_mul_f32 v[28:29], v[6:7], v[28:29]
	v_bfe_u32 v30, v21, 16, 1
	v_bfe_u32 v31, v20, 16, 1
	v_add3_u32 v25, v27, v25, s23
	v_add3_u32 v24, v26, v24, s23
	v_add3_u32 v20, v20, v31, s23
	v_add3_u32 v21, v21, v30, s23
	v_bfe_u32 v30, v28, 16, 1
	v_bfe_u32 v31, v29, 16, 1
	v_lshrrev_b32_e32 v24, 16, v24
	v_lshrrev_b32_e32 v25, 16, v25
	v_add3_u32 v29, v29, v31, s23
	v_add3_u32 v28, v28, v30, s23
	v_and_or_b32 v21, v21, s20, v25
	v_and_or_b32 v20, v20, s20, v24
	v_lshl_add_u64 v[24:25], v[100:101], 0, v[98:99]
	v_lshrrev_b32_e32 v26, 16, v28
	v_lshrrev_b32_e32 v27, 16, v29
	v_add_co_u32_e32 v24, vcc, s24, v24
	v_and_or_b32 v23, v23, s20, v27
	v_and_or_b32 v22, v22, s20, v26
	v_addc_co_u32_e32 v25, vcc, -1, v25, vcc
	global_store_dwordx4 v[24:25], v[20:23], off offset:-256 sc1
	v_lshl_add_u64 v[98:99], v[98:99], 0, s[8:9]
	s_waitcnt vmcnt(10)
	v_max3_f32 v20, v142, v143, v144
	v_sub_f32_e32 v21, v142, v20
	v_exp_f32_e32 v23, v21
	v_sub_f32_e32 v21, v143, v20
	v_exp_f32_e32 v22, v21
	v_sub_f32_e32 v20, v144, v20
	v_exp_f32_e32 v20, v20
	v_add_f32_e32 v21, v23, v22
	v_add_f32_e32 v21, v20, v21
	v_div_scale_f32 v24, s[0:1], v21, v21, 1.0
	v_rcp_f32_e32 v25, v24
	s_nop 0
	v_fma_f32 v26, -v24, v25, 1.0
	v_fmac_f32_e32 v25, v26, v25
	v_div_scale_f32 v26, vcc, 1.0, v21, 1.0
	v_mul_f32_e32 v27, v26, v25
	v_fma_f32 v28, -v24, v27, v26
	v_fmac_f32_e32 v27, v28, v25
	v_fma_f32 v24, -v24, v27, v26
	v_div_fmas_f32 v24, v24, v25, v27
	v_div_fixup_f32 v24, v24, v21, 1.0
	v_pk_mul_f32 v[22:23], v[22:23], v[24:25] op_sel_hi:[1,0]
	s_waitcnt vmcnt(8)
	v_lshlrev_b32_e32 v27, 16, v17
	v_lshlrev_b32_e32 v26, 16, v12
	v_mul_f32_e32 v20, v20, v24
	v_lshlrev_b32_e32 v25, 16, v13
	v_lshlrev_b32_e32 v24, 16, v16
	v_pk_mul_f32 v[26:27], v[22:23], v[26:27] op_sel:[1,0] op_sel_hi:[0,1]
	v_pk_fma_f32 v[24:25], v[22:23], v[24:25], v[26:27]
	s_waitcnt vmcnt(7)
	v_lshlrev_b32_e32 v27, 16, v9
	v_lshlrev_b32_e32 v26, 16, v8
	v_pk_fma_f32 v[24:25], v[20:21], v[26:27], v[24:25] op_sel_hi:[0,1,1]
	v_and_b32_e32 v27, 0xffff0000, v13
	v_and_b32_e32 v13, 0xffff0000, v17
	v_and_b32_e32 v12, 0xffff0000, v12
	v_and_b32_e32 v26, 0xffff0000, v16
	v_pk_mul_f32 v[12:13], v[22:23], v[12:13] op_sel:[1,0] op_sel_hi:[0,1]
	v_pk_fma_f32 v[12:13], v[22:23], v[26:27], v[12:13]
	v_and_b32_e32 v9, 0xffff0000, v9
	v_and_b32_e32 v8, 0xffff0000, v8
	v_lshlrev_b32_e32 v17, 16, v19
	v_lshlrev_b32_e32 v16, 16, v14
	v_pk_fma_f32 v[8:9], v[20:21], v[8:9], v[12:13] op_sel_hi:[0,1,1]
	v_lshlrev_b32_e32 v13, 16, v15
	v_lshlrev_b32_e32 v12, 16, v18
	v_pk_mul_f32 v[16:17], v[22:23], v[16:17] op_sel:[1,0] op_sel_hi:[0,1]
	v_pk_fma_f32 v[12:13], v[22:23], v[12:13], v[16:17]
	v_lshlrev_b32_e32 v17, 16, v11
	v_lshlrev_b32_e32 v16, 16, v10
	v_pk_fma_f32 v[12:13], v[20:21], v[16:17], v[12:13] op_sel_hi:[0,1,1]
	v_and_b32_e32 v17, 0xffff0000, v15
	v_and_b32_e32 v15, 0xffff0000, v19
	v_and_b32_e32 v14, 0xffff0000, v14
	v_and_b32_e32 v16, 0xffff0000, v18
	v_pk_mul_f32 v[14:15], v[22:23], v[14:15] op_sel:[1,0] op_sel_hi:[0,1]
	v_pk_fma_f32 v[14:15], v[22:23], v[16:17], v[14:15]
	v_and_b32_e32 v11, 0xffff0000, v11
	v_and_b32_e32 v10, 0xffff0000, v10
	v_bfe_u32 v16, v9, 16, 1
	v_bfe_u32 v17, v8, 16, 1
	v_pk_fma_f32 v[10:11], v[20:21], v[10:11], v[14:15] op_sel_hi:[0,1,1]
	v_add3_u32 v8, v8, v17, s23
	v_add3_u32 v9, v9, v16, s23
	v_bfe_u32 v16, v12, 16, 1
	v_bfe_u32 v17, v13, 16, 1
	v_bfe_u32 v14, v11, 16, 1
	v_bfe_u32 v15, v10, 16, 1
	v_add3_u32 v13, v13, v17, s23
	v_add3_u32 v12, v12, v16, s23
	v_add3_u32 v10, v10, v15, s23
	v_add3_u32 v11, v11, v14, s23
	v_bfe_u32 v14, v24, 16, 1
	v_bfe_u32 v15, v25, 16, 1
	v_lshrrev_b32_e32 v12, 16, v12
	v_lshrrev_b32_e32 v13, 16, v13
	v_add3_u32 v15, v25, v15, s23
	v_add3_u32 v14, v24, v14, s23
	v_and_or_b32 v11, v11, s20, v13
	v_and_or_b32 v10, v10, s20, v12
	v_lshl_add_u64 v[12:13], v[88:89], 0, v[96:97]
	v_lshrrev_b32_e32 v14, 16, v14
	v_lshrrev_b32_e32 v15, 16, v15
	v_add_co_u32_e32 v12, vcc, s25, v12
	v_and_or_b32 v9, v9, s20, v15
	v_and_or_b32 v8, v8, s20, v14
	v_addc_co_u32_e32 v13, vcc, -1, v13, vcc
	v_lshl_add_u64 v[96:97], v[96:97], 0, s[8:9]
	global_store_dwordx4 v[12:13], v[8:11], off offset:-3072 sc1
	s_cbranch_scc1 .LBB0_495

.LBB0_715:
	v_mul_f32_e32 v146, 0xbfb8aa3b, v126
	v_exp_f32_e32 v155, v146
	v_mul_f32_e32 v146, 0xbfb8aa3b, v127
	v_exp_f32_e32 v158, v146
	v_lshl_or_b32 v156, s46, 7, v150
	v_add_f32_e32 v155, 1.0, v155
	v_rcp_f32_e32 v155, v155
	v_add_f32_e32 v158, 1.0, v158
	v_rcp_f32_e32 v160, v158
	v_lshl_add_u32 v154, s24, 8, v148
	v_mul_f32_e32 v126, v126, v155
	v_mul_f32_e32 v118, v126, v118
	v_mul_f32_e32 v126, v127, v160
	v_mul_f32_e32 v127, 0xbfb8aa3b, v128
	v_exp_f32_e32 v127, v127
	v_mul_f32_e32 v155, 0xbfb8aa3b, v129
	v_exp_f32_e32 v155, v155
	v_mul_f32_e32 v119, v126, v119
	v_add_f32_e32 v126, 1.0, v127
	v_rcp_f32_e32 v126, v126
	v_add_f32_e32 v127, 1.0, v155
	v_mul_f32_e32 v155, 0xbfb8aa3b, v122
	v_rcp_f32_e32 v127, v127
	v_exp_f32_e32 v155, v155
	v_mul_f32_e32 v126, v128, v126
	v_mul_f32_e32 v126, v126, v120
	v_mul_f32_e32 v120, v129, v127
	v_add_f32_e32 v127, 1.0, v155
	v_rcp_f32_e32 v127, v127
	v_mul_f32_e32 v128, 0xbfb8aa3b, v123
	v_mul_f32_e32 v129, v120, v121
	v_exp_f32_e32 v128, v128
	v_mul_f32_e32 v120, v122, v127
	v_mul_f32_e32 v122, v120, v114
	v_mul_f32_e32 v120, 0xbfb8aa3b, v124
	v_exp_f32_e32 v120, v120
	v_mul_f32_e32 v121, 0xbfb8aa3b, v125
	v_exp_f32_e32 v121, v121
	v_add_f32_e32 v114, 1.0, v128
	v_rcp_f32_e32 v114, v114
	v_add_f32_e32 v120, 1.0, v120
	v_rcp_f32_e32 v120, v120
	v_add_f32_e32 v121, 1.0, v121
	v_rcp_f32_e32 v121, v121
	v_mul_f32_e32 v114, v123, v114
	v_mul_f32_e32 v123, v114, v115
	v_mul_f32_e32 v114, v124, v120
	v_ashrrev_i32_e32 v157, 31, v156
	v_mov_b64_e32 v[146:147], s[36:37]
	v_mul_f32_e32 v124, v114, v116
	v_mul_f32_e32 v114, v125, v121
	v_mad_i64_i32 v[158:159], s[28:29], v154, s45, v[146:147]
	v_mul_f32_e32 v125, v114, v117
	v_lshlrev_b64 v[114:115], 1, v[156:157]
	v_lshl_add_u64 v[120:121], v[158:159], 0, v[114:115]
	v_cvt_pk_bf16_f32 v116, v118, v119
	v_cvt_pk_bf16_f32 v117, v126, v129
	v_cvt_pk_bf16_f32 v118, v122, v123
	v_cvt_pk_bf16_f32 v119, v124, v125
	global_store_dwordx4 v[120:121], v[116:119], off sc1
	s_andn2_b64 vcc, exec, s[0:1]
	s_mov_b64 s[0:1], -1
	v_mul_f32_e32 v116, 0xbfb8aa3b, v110
	v_exp_f32_e32 v116, v116
	v_mul_f32_e32 v117, 0xbfb8aa3b, v111
	v_exp_f32_e32 v117, v117
	v_or_b32_e32 v118, 16, v154
	v_add_f32_e32 v116, 1.0, v116
	v_rcp_f32_e32 v119, v116
	v_add_f32_e32 v116, 1.0, v117
	v_rcp_f32_e32 v120, v116
	v_mad_i64_i32 v[116:117], s[28:29], v118, s45, v[146:147]
	v_mul_f32_e32 v110, v110, v119
	v_mul_f32_e32 v110, v110, v102
	v_mul_f32_e32 v102, v111, v120
	v_mul_f32_e32 v111, 0xbfb8aa3b, v112
	v_exp_f32_e32 v111, v111
	v_mul_f32_e32 v118, 0xbfb8aa3b, v113
	v_exp_f32_e32 v118, v118
	v_mul_f32_e32 v119, v102, v103
	v_add_f32_e32 v102, 1.0, v111
	v_rcp_f32_e32 v102, v102
	v_add_f32_e32 v103, 1.0, v118
	v_mul_f32_e32 v111, 0xbfb8aa3b, v106
	v_rcp_f32_e32 v103, v103
	v_exp_f32_e32 v111, v111
	v_mul_f32_e32 v102, v112, v102
	v_mul_f32_e32 v104, v102, v104
	v_mul_f32_e32 v102, v113, v103
	v_add_f32_e32 v103, 1.0, v111
	v_rcp_f32_e32 v103, v103
	v_mul_f32_e32 v111, 0xbfb8aa3b, v107
	v_mul_f32_e32 v105, v102, v105
	v_exp_f32_e32 v111, v111
	v_mul_f32_e32 v102, v106, v103
	v_mul_f32_e32 v106, v102, v98
	v_mul_f32_e32 v102, 0xbfb8aa3b, v108
	v_exp_f32_e32 v102, v102
	v_mul_f32_e32 v103, 0xbfb8aa3b, v109
	v_exp_f32_e32 v103, v103
	v_add_f32_e32 v98, 1.0, v111
	v_rcp_f32_e32 v98, v98
	v_add_f32_e32 v102, 1.0, v102
	v_rcp_f32_e32 v102, v102
	v_add_f32_e32 v103, 1.0, v103
	v_rcp_f32_e32 v103, v103
	v_mul_f32_e32 v98, v107, v98
	v_mul_f32_e32 v107, v98, v99
	v_mul_f32_e32 v98, v108, v102
	v_mul_f32_e32 v108, v98, v100
	v_mul_f32_e32 v98, v109, v103
	v_mul_f32_e32 v101, v98, v101
	v_lshl_add_u64 v[102:103], v[116:117], 0, v[114:115]
	v_cvt_pk_bf16_f32 v98, v110, v119
	v_cvt_pk_bf16_f32 v99, v104, v105
	v_cvt_pk_bf16_f32 v100, v106, v107
	v_cvt_pk_bf16_f32 v101, v108, v101
	global_store_dwordx4 v[102:103], v[98:101], off sc1
	s_nop 1
	v_mul_f32_e32 v98, 0xbfb8aa3b, v94
	v_exp_f32_e32 v98, v98
	v_mul_f32_e32 v99, 0xbfb8aa3b, v95
	v_exp_f32_e32 v99, v99
	v_or_b32_e32 v100, 32, v154
	v_add_f32_e32 v98, 1.0, v98
	v_rcp_f32_e32 v101, v98
	v_add_f32_e32 v98, 1.0, v99
	v_rcp_f32_e32 v102, v98
	v_mad_i64_i32 v[98:99], s[28:29], v100, s45, v[146:147]
	v_mul_f32_e32 v94, v94, v101
	v_mul_f32_e32 v94, v94, v86
	v_mul_f32_e32 v86, v95, v102
	v_mul_f32_e32 v95, 0xbfb8aa3b, v96
	v_exp_f32_e32 v95, v95
	v_mul_f32_e32 v100, 0xbfb8aa3b, v97
	v_exp_f32_e32 v100, v100
	v_mul_f32_e32 v101, v86, v87
	v_add_f32_e32 v86, 1.0, v95
	v_rcp_f32_e32 v86, v86
	v_add_f32_e32 v87, 1.0, v100
	v_mul_f32_e32 v95, 0xbfb8aa3b, v90
	v_rcp_f32_e32 v87, v87
	v_exp_f32_e32 v95, v95
	v_mul_f32_e32 v86, v96, v86
	v_mul_f32_e32 v88, v86, v88
	v_mul_f32_e32 v86, v97, v87
	v_add_f32_e32 v87, 1.0, v95
	v_rcp_f32_e32 v87, v87
	v_mul_f32_e32 v95, 0xbfb8aa3b, v91
	v_mul_f32_e32 v89, v86, v89
	v_exp_f32_e32 v95, v95
	v_mul_f32_e32 v86, v90, v87
	v_mul_f32_e32 v90, v86, v82
	v_mul_f32_e32 v86, 0xbfb8aa3b, v92
	v_exp_f32_e32 v86, v86
	v_mul_f32_e32 v87, 0xbfb8aa3b, v93
	v_exp_f32_e32 v87, v87
	v_add_f32_e32 v82, 1.0, v95
	v_rcp_f32_e32 v82, v82
	v_add_f32_e32 v86, 1.0, v86
	v_rcp_f32_e32 v86, v86
	v_add_f32_e32 v87, 1.0, v87
	v_rcp_f32_e32 v87, v87
	v_mul_f32_e32 v82, v91, v82
	v_mul_f32_e32 v91, v82, v83
	v_mul_f32_e32 v82, v92, v86
	v_mul_f32_e32 v92, v82, v84
	v_mul_f32_e32 v82, v93, v87
	v_mul_f32_e32 v85, v82, v85
	v_lshl_add_u64 v[86:87], v[98:99], 0, v[114:115]
	v_cvt_pk_bf16_f32 v82, v94, v101
	v_cvt_pk_bf16_f32 v83, v88, v89
	v_cvt_pk_bf16_f32 v84, v90, v91
	v_cvt_pk_bf16_f32 v85, v92, v85
	global_store_dwordx4 v[86:87], v[82:85], off sc1
	s_nop 1
	v_mul_f32_e32 v82, 0xbfb8aa3b, v78
	v_exp_f32_e32 v82, v82
	v_mul_f32_e32 v83, 0xbfb8aa3b, v79
	v_exp_f32_e32 v83, v83
	v_or_b32_e32 v84, 48, v154
	v_add_f32_e32 v82, 1.0, v82
	v_rcp_f32_e32 v85, v82
	v_add_f32_e32 v82, 1.0, v83
	v_rcp_f32_e32 v86, v82
	v_mad_i64_i32 v[82:83], s[28:29], v84, s45, v[146:147]
	v_mul_f32_e32 v78, v78, v85
	v_mul_f32_e32 v78, v78, v70
	v_mul_f32_e32 v70, v79, v86
	v_mul_f32_e32 v79, 0xbfb8aa3b, v80
	v_exp_f32_e32 v79, v79
	v_mul_f32_e32 v84, 0xbfb8aa3b, v81
	v_exp_f32_e32 v84, v84
	v_mul_f32_e32 v85, v70, v71
	v_add_f32_e32 v70, 1.0, v79
	v_rcp_f32_e32 v70, v70
	v_add_f32_e32 v71, 1.0, v84
	v_mul_f32_e32 v79, 0xbfb8aa3b, v74
	v_rcp_f32_e32 v71, v71
	v_exp_f32_e32 v79, v79
	v_mul_f32_e32 v70, v80, v70
	v_mul_f32_e32 v72, v70, v72
	v_mul_f32_e32 v70, v81, v71
	v_add_f32_e32 v71, 1.0, v79
	v_rcp_f32_e32 v71, v71
	v_mul_f32_e32 v79, 0xbfb8aa3b, v75
	v_mul_f32_e32 v73, v70, v73
	v_exp_f32_e32 v79, v79
	v_mul_f32_e32 v70, v74, v71
	v_mul_f32_e32 v74, v70, v66
	v_mul_f32_e32 v70, 0xbfb8aa3b, v76
	v_exp_f32_e32 v70, v70
	v_mul_f32_e32 v71, 0xbfb8aa3b, v77
	v_exp_f32_e32 v71, v71
	v_add_f32_e32 v66, 1.0, v79
	v_rcp_f32_e32 v66, v66
	v_add_f32_e32 v70, 1.0, v70
	v_rcp_f32_e32 v70, v70
	v_add_f32_e32 v71, 1.0, v71
	v_rcp_f32_e32 v71, v71
	v_mul_f32_e32 v66, v75, v66
	v_mul_f32_e32 v75, v66, v67
	v_mul_f32_e32 v66, v76, v70
	v_mul_f32_e32 v76, v66, v68
	v_mul_f32_e32 v66, v77, v71
	v_mul_f32_e32 v69, v66, v69
	v_lshl_add_u64 v[70:71], v[82:83], 0, v[114:115]
	v_cvt_pk_bf16_f32 v66, v78, v85
	v_cvt_pk_bf16_f32 v67, v72, v73
	v_cvt_pk_bf16_f32 v68, v74, v75
	v_cvt_pk_bf16_f32 v69, v76, v69
	global_store_dwordx4 v[70:71], v[66:69], off sc1
	s_nop 1
	v_mul_f32_e32 v66, 0xbfb8aa3b, v62
	v_exp_f32_e32 v66, v66
	v_mul_f32_e32 v67, 0xbfb8aa3b, v63
	v_exp_f32_e32 v67, v67
	v_add_u32_e32 v68, 0x80, v154
	v_add_f32_e32 v66, 1.0, v66
	v_rcp_f32_e32 v69, v66
	v_add_f32_e32 v66, 1.0, v67
	v_rcp_f32_e32 v70, v66
	v_mad_i64_i32 v[66:67], s[28:29], v68, s45, v[146:147]
	v_mul_f32_e32 v62, v62, v69
	v_mul_f32_e32 v62, v62, v54
	v_mul_f32_e32 v54, v63, v70
	v_mul_f32_e32 v63, 0xbfb8aa3b, v64
	v_exp_f32_e32 v63, v63
	v_mul_f32_e32 v68, 0xbfb8aa3b, v65
	v_exp_f32_e32 v68, v68
	v_mul_f32_e32 v69, v54, v55
	v_add_f32_e32 v54, 1.0, v63
	v_rcp_f32_e32 v54, v54
	v_add_f32_e32 v55, 1.0, v68
	v_mul_f32_e32 v63, 0xbfb8aa3b, v58
	v_rcp_f32_e32 v55, v55
	v_exp_f32_e32 v63, v63
	v_mul_f32_e32 v54, v64, v54
	v_mul_f32_e32 v56, v54, v56
	v_mul_f32_e32 v54, v65, v55
	v_add_f32_e32 v55, 1.0, v63
	v_rcp_f32_e32 v55, v55
	v_mul_f32_e32 v63, 0xbfb8aa3b, v59
	v_mul_f32_e32 v57, v54, v57
	v_exp_f32_e32 v63, v63
	v_mul_f32_e32 v54, v58, v55
	v_mul_f32_e32 v58, v54, v50
	v_mul_f32_e32 v54, 0xbfb8aa3b, v60
	v_exp_f32_e32 v54, v54
	v_mul_f32_e32 v55, 0xbfb8aa3b, v61
	v_exp_f32_e32 v55, v55
	v_add_f32_e32 v50, 1.0, v63
	v_rcp_f32_e32 v50, v50
	v_add_f32_e32 v54, 1.0, v54
	v_rcp_f32_e32 v54, v54
	v_add_f32_e32 v55, 1.0, v55
	v_rcp_f32_e32 v55, v55
	v_mul_f32_e32 v50, v59, v50
	v_mul_f32_e32 v59, v50, v51
	v_mul_f32_e32 v50, v60, v54
	v_mul_f32_e32 v60, v50, v52
	v_mul_f32_e32 v50, v61, v55
	v_mul_f32_e32 v53, v50, v53
	v_lshl_add_u64 v[54:55], v[66:67], 0, v[114:115]
	v_cvt_pk_bf16_f32 v50, v62, v69
	v_cvt_pk_bf16_f32 v51, v56, v57
	v_cvt_pk_bf16_f32 v52, v58, v59
	v_cvt_pk_bf16_f32 v53, v60, v53
	global_store_dwordx4 v[54:55], v[50:53], off sc1
	s_nop 1
	v_mul_f32_e32 v50, 0xbfb8aa3b, v46
	v_exp_f32_e32 v50, v50
	v_mul_f32_e32 v51, 0xbfb8aa3b, v47
	v_exp_f32_e32 v51, v51
	v_add_u32_e32 v52, 0x90, v154
	v_add_f32_e32 v50, 1.0, v50
	v_rcp_f32_e32 v53, v50
	v_add_f32_e32 v50, 1.0, v51
	v_rcp_f32_e32 v54, v50
	v_mad_i64_i32 v[50:51], s[28:29], v52, s45, v[146:147]
	v_mul_f32_e32 v46, v46, v53
	v_mul_f32_e32 v46, v46, v38
	v_mul_f32_e32 v38, v47, v54
	v_mul_f32_e32 v47, 0xbfb8aa3b, v48
	v_exp_f32_e32 v47, v47
	v_mul_f32_e32 v52, 0xbfb8aa3b, v49
	v_exp_f32_e32 v52, v52
	v_mul_f32_e32 v53, v38, v39
	v_add_f32_e32 v38, 1.0, v47
	v_rcp_f32_e32 v38, v38
	v_add_f32_e32 v39, 1.0, v52
	v_mul_f32_e32 v47, 0xbfb8aa3b, v42
	v_rcp_f32_e32 v39, v39
	v_exp_f32_e32 v47, v47
	v_mul_f32_e32 v38, v48, v38
	v_mul_f32_e32 v40, v38, v40
	v_mul_f32_e32 v38, v49, v39
	v_add_f32_e32 v39, 1.0, v47
	v_rcp_f32_e32 v39, v39
	v_mul_f32_e32 v47, 0xbfb8aa3b, v43
	v_mul_f32_e32 v41, v38, v41
	v_exp_f32_e32 v47, v47
	v_mul_f32_e32 v38, v42, v39
	v_mul_f32_e32 v42, v38, v34
	v_mul_f32_e32 v38, 0xbfb8aa3b, v44
	v_exp_f32_e32 v38, v38
	v_mul_f32_e32 v39, 0xbfb8aa3b, v45
	v_exp_f32_e32 v39, v39
	v_add_f32_e32 v34, 1.0, v47
	v_rcp_f32_e32 v34, v34
	v_add_f32_e32 v38, 1.0, v38
	v_rcp_f32_e32 v38, v38
	v_add_f32_e32 v39, 1.0, v39
	v_rcp_f32_e32 v39, v39
	v_mul_f32_e32 v34, v43, v34
	v_mul_f32_e32 v43, v34, v35
	v_mul_f32_e32 v34, v44, v38
	v_mul_f32_e32 v44, v34, v36
	v_mul_f32_e32 v34, v45, v39
	v_mul_f32_e32 v37, v34, v37
	v_lshl_add_u64 v[38:39], v[50:51], 0, v[114:115]
	v_cvt_pk_bf16_f32 v34, v46, v53
	v_cvt_pk_bf16_f32 v35, v40, v41
	v_cvt_pk_bf16_f32 v36, v42, v43
	v_cvt_pk_bf16_f32 v37, v44, v37
	global_store_dwordx4 v[38:39], v[34:37], off sc1
	s_nop 1
	v_mul_f32_e32 v34, 0xbfb8aa3b, v30
	v_exp_f32_e32 v34, v34
	v_mul_f32_e32 v35, 0xbfb8aa3b, v31
	v_exp_f32_e32 v35, v35
	v_add_u32_e32 v36, 0xa0, v154
	v_add_f32_e32 v34, 1.0, v34
	v_rcp_f32_e32 v37, v34
	v_add_f32_e32 v34, 1.0, v35
	v_rcp_f32_e32 v38, v34
	v_mad_i64_i32 v[34:35], s[28:29], v36, s45, v[146:147]
	v_mul_f32_e32 v30, v30, v37
	v_mul_f32_e32 v30, v30, v22
	v_mul_f32_e32 v22, v31, v38
	v_mul_f32_e32 v31, 0xbfb8aa3b, v32
	v_exp_f32_e32 v31, v31
	v_mul_f32_e32 v36, 0xbfb8aa3b, v33
	v_exp_f32_e32 v36, v36
	v_mul_f32_e32 v37, v22, v23
	v_add_f32_e32 v22, 1.0, v31
	v_rcp_f32_e32 v22, v22
	v_add_f32_e32 v23, 1.0, v36
	v_mul_f32_e32 v31, 0xbfb8aa3b, v26
	v_rcp_f32_e32 v23, v23
	v_exp_f32_e32 v31, v31
	v_mul_f32_e32 v22, v32, v22
	v_mul_f32_e32 v24, v22, v24
	v_mul_f32_e32 v22, v33, v23
	v_add_f32_e32 v23, 1.0, v31
	v_rcp_f32_e32 v23, v23
	v_mul_f32_e32 v31, 0xbfb8aa3b, v27
	v_mul_f32_e32 v25, v22, v25
	v_exp_f32_e32 v31, v31
	v_mul_f32_e32 v22, v26, v23
	v_mul_f32_e32 v26, v22, v18
	v_mul_f32_e32 v22, 0xbfb8aa3b, v28
	v_exp_f32_e32 v22, v22
	v_mul_f32_e32 v23, 0xbfb8aa3b, v29
	v_exp_f32_e32 v23, v23
	v_add_f32_e32 v18, 1.0, v31
	v_rcp_f32_e32 v18, v18
	v_add_f32_e32 v22, 1.0, v22
	v_rcp_f32_e32 v22, v22
	v_add_f32_e32 v23, 1.0, v23
	v_rcp_f32_e32 v23, v23
	v_mul_f32_e32 v18, v27, v18
	v_mul_f32_e32 v27, v18, v19
	v_mul_f32_e32 v18, v28, v22
	v_mul_f32_e32 v28, v18, v20
	v_mul_f32_e32 v18, v29, v23
	v_mul_f32_e32 v21, v18, v21
	v_lshl_add_u64 v[22:23], v[34:35], 0, v[114:115]
	v_cvt_pk_bf16_f32 v18, v30, v37
	v_cvt_pk_bf16_f32 v19, v24, v25
	v_cvt_pk_bf16_f32 v20, v26, v27
	v_cvt_pk_bf16_f32 v21, v28, v21
	global_store_dwordx4 v[22:23], v[18:21], off sc1
	s_nop 1
	v_mul_f32_e32 v18, 0xbfb8aa3b, v14
	v_exp_f32_e32 v18, v18
	v_mul_f32_e32 v19, 0xbfb8aa3b, v15
	v_exp_f32_e32 v19, v19
	v_add_u32_e32 v20, 0xb0, v154
	v_add_f32_e32 v18, 1.0, v18
	v_rcp_f32_e32 v21, v18
	v_add_f32_e32 v18, 1.0, v19
	v_rcp_f32_e32 v22, v18
	v_mad_i64_i32 v[18:19], s[28:29], v20, s45, v[146:147]
	v_mul_f32_e32 v14, v14, v21
	v_mul_f32_e32 v14, v14, v6
	v_mul_f32_e32 v6, v15, v22
	v_mul_f32_e32 v15, 0xbfb8aa3b, v16
	v_exp_f32_e32 v15, v15
	v_mul_f32_e32 v20, 0xbfb8aa3b, v17
	v_exp_f32_e32 v20, v20
	v_mul_f32_e32 v21, v6, v7
	v_add_f32_e32 v6, 1.0, v15
	v_rcp_f32_e32 v6, v6
	v_add_f32_e32 v7, 1.0, v20
	v_mul_f32_e32 v15, 0xbfb8aa3b, v10
	v_rcp_f32_e32 v7, v7
	v_exp_f32_e32 v15, v15
	v_mul_f32_e32 v6, v16, v6
	v_mul_f32_e32 v8, v6, v8
	v_mul_f32_e32 v6, v17, v7
	v_add_f32_e32 v7, 1.0, v15
	v_rcp_f32_e32 v7, v7
	v_mul_f32_e32 v15, 0xbfb8aa3b, v11
	v_mul_f32_e32 v9, v6, v9
	v_exp_f32_e32 v15, v15
	v_mul_f32_e32 v6, v10, v7
	v_mul_f32_e32 v10, v6, v2
	v_mul_f32_e32 v6, 0xbfb8aa3b, v12
	v_exp_f32_e32 v6, v6
	v_mul_f32_e32 v7, 0xbfb8aa3b, v13
	v_exp_f32_e32 v7, v7
	v_add_f32_e32 v2, 1.0, v15
	v_rcp_f32_e32 v2, v2
	v_add_f32_e32 v6, 1.0, v6
	v_rcp_f32_e32 v6, v6
	v_add_f32_e32 v7, 1.0, v7
	v_rcp_f32_e32 v7, v7
	v_mul_f32_e32 v2, v11, v2
	v_mul_f32_e32 v11, v2, v3
	v_mul_f32_e32 v2, v12, v6
	v_mul_f32_e32 v12, v2, v4
	v_mul_f32_e32 v2, v13, v7
	v_mul_f32_e32 v5, v2, v5
	v_lshl_add_u64 v[6:7], v[18:19], 0, v[114:115]
	v_cvt_pk_bf16_f32 v2, v14, v21
	v_cvt_pk_bf16_f32 v3, v8, v9
	v_cvt_pk_bf16_f32 v4, v10, v11
	v_cvt_pk_bf16_f32 v5, v12, v5
	global_store_dwordx4 v[6:7], v[2:5], off sc1
	s_cbranch_vccnz .LBB0_708
	s_andn2_b64 vcc, exec, s[6:7]
	s_cbranch_vccnz .LBB0_707
	s_barrier
	s_branch .LBB0_707

.LBB0_752:
	s_cmpk_gt_u32 s29, 0x7ff
	s_cbranch_scc0 .LBB0_762
	s_cmpk_gt_u32 s29, 0xd7f
	s_cbranch_scc0 .LBB0_759
	s_cmpk_gt_u32 s29, 0x12ff
	s_cbranch_scc0 .LBB0_756
	v_add_u32_e32 v66, v203, v226
	v_add_u32_e32 v78, 0x420, v66
	s_waitcnt vmcnt(7)
	ds_write2_b32 v66, v62, v63 offset1:1
	ds_write2_b32 v66, v64, v65 offset0:2 offset1:3
	s_waitcnt vmcnt(6)
	ds_write2_b32 v78, v58, v59 offset1:1
	v_add_u32_e32 v78, 0x428, v66
	ds_write2_b32 v78, v60, v61 offset1:1
	v_add_u32_e32 v78, 0x840, v66
	s_waitcnt vmcnt(5)
	ds_write2_b32 v78, v54, v55 offset1:1
	v_add_u32_e32 v78, 0x848, v66
	ds_write2_b32 v78, v56, v57 offset1:1
	v_add_u32_e32 v78, 0xc60, v66
	s_waitcnt vmcnt(4)
	ds_write2_b32 v78, v46, v47 offset1:1
	v_add_u32_e32 v78, 0xc68, v66
	ds_write2_b32 v78, v48, v49 offset1:1
	v_add_u32_e32 v78, 0x1080, v66
	s_waitcnt vmcnt(3)
	ds_write2_b32 v78, v50, v51 offset1:1
	v_add_u32_e32 v78, 0x1088, v66
	ds_write2_b32 v78, v52, v53 offset1:1
	v_add_u32_e32 v78, 0x14a0, v66
	s_waitcnt vmcnt(2)
	ds_write2_b32 v78, v38, v39 offset1:1
	v_add_u32_e32 v78, 0x14a8, v66
	ds_write2_b32 v78, v40, v41 offset1:1
	v_add_u32_e32 v78, 0x18c0, v66
	s_waitcnt vmcnt(1)
	ds_write2_b32 v78, v42, v43 offset1:1
	v_add_u32_e32 v78, 0x18c8, v66
	ds_write2_b32 v78, v44, v45 offset1:1
	v_add_u32_e32 v78, 0x1ce0, v66
	v_add_u32_e32 v66, 0x1ce8, v66
	s_waitcnt vmcnt(0)
	ds_write2_b32 v78, v34, v35 offset1:1
	ds_write2_b32 v66, v36, v37 offset1:1
	s_waitcnt lgkmcnt(0)
	ds_read2_b32 v[82:83], v76 offset1:8
	ds_read2_b32 v[86:87], v76 offset0:33 offset1:41
	ds_read2_b32 v[88:89], v76 offset0:66 offset1:74
	ds_read2_b32 v[90:91], v76 offset0:99 offset1:107
	ds_read2_b32 v[92:93], v76 offset0:132 offset1:140
	s_waitcnt lgkmcnt(4)
	v_bfe_u32 v66, v82, 16, 1
	v_add3_u32 v66, v82, v66, s26
	s_waitcnt lgkmcnt(3)
	v_bfe_u32 v78, v86, 16, 1
	v_lshrrev_b32_e32 v66, 16, v66
	v_add3_u32 v78, v86, v78, s26
	ds_read2_b32 v[94:95], v76 offset0:165 offset1:173
	v_and_or_b32 v78, v78, s27, v66
	s_waitcnt lgkmcnt(3)
	v_bfe_u32 v66, v88, 16, 1
	v_add3_u32 v66, v88, v66, s26
	s_waitcnt lgkmcnt(2)
	v_bfe_u32 v79, v90, 16, 1
	ds_read2_b32 v[96:97], v76 offset0:198 offset1:206
	v_lshrrev_b32_e32 v66, 16, v66
	v_add3_u32 v79, v90, v79, s26
	ds_read2_b32 v[98:99], v76 offset0:231 offset1:239
	v_and_or_b32 v79, v79, s27, v66
	s_waitcnt lgkmcnt(3)
	v_bfe_u32 v66, v92, 16, 1
	v_add3_u32 v66, v92, v66, s26
	s_waitcnt lgkmcnt(2)
	v_bfe_u32 v80, v94, 16, 1
	v_lshrrev_b32_e32 v66, 16, v66
	v_add3_u32 v80, v94, v80, s26
	v_and_or_b32 v80, v80, s27, v66
	s_waitcnt lgkmcnt(1)
	v_bfe_u32 v66, v96, 16, 1
	v_add3_u32 v66, v96, v66, s26
	s_waitcnt lgkmcnt(0)
	v_bfe_u32 v81, v98, 16, 1
	s_and_b32 s8, s31, 0xfc0
	s_and_b32 s18, s30, 0x3e0
	v_lshrrev_b32_e32 v66, 16, v66
	v_add3_u32 v81, v98, v81, s26
	s_lshl_b32 s8, s8, 1
	v_and_or_b32 v81, v81, s27, v66
	v_or_b32_e32 v66, s18, v199
	v_lshl_add_u64 v[84:85], v[68:69], 0, s[8:9]
	v_mul_u32_u24_e32 v66, 0x1600, v66
	v_lshl_add_u64 v[100:101], v[84:85], 0, v[66:67]
	v_bfe_u32 v66, v83, 16, 1
	global_store_dwordx4 v[100:101], v[78:81], off sc1
	v_add3_u32 v66, v83, v66, s26
	v_lshrrev_b32_e32 v66, 16, v66
	v_bfe_u32 v78, v87, 16, 1
	v_add3_u32 v78, v87, v78, s26
	v_and_or_b32 v78, v78, s27, v66
	v_bfe_u32 v66, v89, 16, 1
	v_add3_u32 v66, v89, v66, s26
	v_bfe_u32 v79, v91, 16, 1
	v_lshrrev_b32_e32 v66, 16, v66
	v_add3_u32 v79, v91, v79, s26
	v_and_or_b32 v79, v79, s27, v66
	v_bfe_u32 v66, v93, 16, 1
	v_add3_u32 v66, v93, v66, s26
	v_bfe_u32 v80, v95, 16, 1
	v_lshrrev_b32_e32 v66, 16, v66
	v_add3_u32 v80, v95, v80, s26
	v_and_or_b32 v80, v80, s27, v66
	v_bfe_u32 v66, v97, 16, 1
	v_add3_u32 v66, v97, v66, s26
	v_bfe_u32 v81, v99, 16, 1
	v_lshrrev_b32_e32 v66, 16, v66
	v_add3_u32 v81, v99, v81, s26
	v_and_or_b32 v81, v81, s27, v66
	v_or_b32_e32 v66, s18, v227
	v_mul_u32_u24_e32 v66, 0x1600, v66
	ds_read2_b32 v[82:83], v76 offset0:16 offset1:24
	v_lshl_add_u64 v[86:87], v[84:85], 0, v[66:67]
	global_store_dwordx4 v[86:87], v[78:81], off sc1
	ds_read2_b32 v[86:87], v76 offset0:49 offset1:57
	ds_read2_b32 v[88:89], v76 offset0:82 offset1:90
	ds_read2_b32 v[90:91], v76 offset0:115 offset1:123
	s_waitcnt lgkmcnt(3)
	v_bfe_u32 v66, v82, 16, 1
	v_add3_u32 v66, v82, v66, s26
	s_waitcnt lgkmcnt(2)
	v_bfe_u32 v78, v86, 16, 1
	ds_read2_b32 v[92:93], v76 offset0:148 offset1:156
	v_lshrrev_b32_e32 v66, 16, v66
	v_add3_u32 v78, v86, v78, s26
	ds_read2_b32 v[94:95], v76 offset0:181 offset1:189
	v_and_or_b32 v78, v78, s27, v66
	s_waitcnt lgkmcnt(3)
	v_bfe_u32 v66, v88, 16, 1
	v_add3_u32 v66, v88, v66, s26
	s_waitcnt lgkmcnt(2)
	v_bfe_u32 v79, v90, 16, 1
	ds_read2_b32 v[96:97], v76 offset0:214 offset1:222
	v_lshrrev_b32_e32 v66, 16, v66
	v_add3_u32 v79, v90, v79, s26
	ds_read2_b32 v[98:99], v76 offset0:247 offset1:255
	v_and_or_b32 v79, v79, s27, v66
	s_waitcnt lgkmcnt(3)
	v_bfe_u32 v66, v92, 16, 1
	v_add3_u32 v66, v92, v66, s26
	s_waitcnt lgkmcnt(2)
	v_bfe_u32 v80, v94, 16, 1
	v_lshrrev_b32_e32 v66, 16, v66
	v_add3_u32 v80, v94, v80, s26
	v_and_or_b32 v80, v80, s27, v66
	s_waitcnt lgkmcnt(1)
	v_bfe_u32 v66, v96, 16, 1
	v_add3_u32 v66, v96, v66, s26
	s_waitcnt lgkmcnt(0)
	v_bfe_u32 v81, v98, 16, 1
	v_lshrrev_b32_e32 v66, 16, v66
	v_add3_u32 v81, v98, v81, s26
	v_and_or_b32 v81, v81, s27, v66
	v_or_b32_e32 v66, s18, v228
	v_mul_u32_u24_e32 v66, 0x1600, v66
	v_lshl_add_u64 v[100:101], v[84:85], 0, v[66:67]
	v_bfe_u32 v66, v83, 16, 1
	global_store_dwordx4 v[100:101], v[78:81], off sc1
	v_add3_u32 v66, v83, v66, s26
	v_lshrrev_b32_e32 v66, 16, v66
	v_bfe_u32 v78, v87, 16, 1
	v_add3_u32 v78, v87, v78, s26
	v_and_or_b32 v78, v78, s27, v66
	v_bfe_u32 v66, v89, 16, 1
	v_add3_u32 v66, v89, v66, s26
	v_bfe_u32 v79, v91, 16, 1
	v_lshrrev_b32_e32 v66, 16, v66
	v_add3_u32 v79, v91, v79, s26
	v_and_or_b32 v79, v79, s27, v66
	v_bfe_u32 v66, v93, 16, 1
	v_add3_u32 v66, v93, v66, s26
	v_bfe_u32 v80, v95, 16, 1
	v_lshrrev_b32_e32 v66, 16, v66
	v_add3_u32 v80, v95, v80, s26
	v_and_or_b32 v80, v80, s27, v66
	v_bfe_u32 v66, v97, 16, 1
	v_add3_u32 v66, v97, v66, s26
	v_bfe_u32 v81, v99, 16, 1
	v_lshrrev_b32_e32 v66, 16, v66
	v_add3_u32 v81, v99, v81, s26
	v_and_or_b32 v81, v81, s27, v66
	v_or_b32_e32 v66, s18, v229
	v_mul_u32_u24_e32 v66, 0x1600, v66
	v_lshl_add_u64 v[82:83], v[84:85], 0, v[66:67]
	global_store_dwordx4 v[82:83], v[78:81], off sc1
	s_waitcnt lgkmcnt(0)
	s_mov_b64 s[18:19], 0
.LBB0_756:
	s_andn2_b64 vcc, exec, s[18:19]
	s_cbranch_vccnz .LBB0_758
	v_add_u32_e32 v66, v203, v226
	v_add_u32_e32 v78, 0x420, v66
	s_waitcnt vmcnt(7)
	ds_write2_b32 v66, v62, v63 offset1:1
	ds_write2_b32 v66, v64, v65 offset0:2 offset1:3
	s_waitcnt vmcnt(6)
	ds_write2_b32 v78, v58, v59 offset1:1
	v_add_u32_e32 v78, 0x428, v66
	ds_write2_b32 v78, v60, v61 offset1:1
	v_add_u32_e32 v78, 0x840, v66
	s_waitcnt vmcnt(5)
	ds_write2_b32 v78, v54, v55 offset1:1
	v_add_u32_e32 v78, 0x848, v66
	ds_write2_b32 v78, v56, v57 offset1:1
	v_add_u32_e32 v78, 0xc60, v66
	s_waitcnt vmcnt(4)
	ds_write2_b32 v78, v46, v47 offset1:1
	v_add_u32_e32 v78, 0xc68, v66
	ds_write2_b32 v78, v48, v49 offset1:1
	v_add_u32_e32 v78, 0x1080, v66
	s_waitcnt vmcnt(3)
	ds_write2_b32 v78, v50, v51 offset1:1
	v_add_u32_e32 v78, 0x1088, v66
	ds_write2_b32 v78, v52, v53 offset1:1
	v_add_u32_e32 v78, 0x14a0, v66
	s_waitcnt vmcnt(2)
	ds_write2_b32 v78, v38, v39 offset1:1
	v_add_u32_e32 v78, 0x14a8, v66
	ds_write2_b32 v78, v40, v41 offset1:1
	v_add_u32_e32 v78, 0x18c0, v66
	s_waitcnt vmcnt(1)
	ds_write2_b32 v78, v42, v43 offset1:1
	v_add_u32_e32 v78, 0x18c8, v66
	ds_write2_b32 v78, v44, v45 offset1:1
	v_add_u32_e32 v78, 0x1ce0, v66
	v_add_u32_e32 v66, 0x1ce8, v66
	s_waitcnt vmcnt(0)
	ds_write2_b32 v78, v34, v35 offset1:1
	ds_write2_b32 v66, v36, v37 offset1:1
	s_waitcnt lgkmcnt(0)
	ds_read2_b32 v[82:83], v76 offset1:8
	ds_read2_b32 v[86:87], v76 offset0:33 offset1:41
	ds_read2_b32 v[88:89], v76 offset0:66 offset1:74
	ds_read2_b32 v[90:91], v76 offset0:99 offset1:107
	ds_read2_b32 v[92:93], v76 offset0:132 offset1:140
	s_waitcnt lgkmcnt(4)
	v_bfe_u32 v66, v82, 16, 1
	v_add3_u32 v66, v82, v66, s26
	s_waitcnt lgkmcnt(3)
	v_bfe_u32 v78, v86, 16, 1
	s_add_i32 s8, s29, 0xf280
	v_lshrrev_b32_e32 v66, 16, v66
	v_add3_u32 v78, v86, v78, s26
	ds_read2_b32 v[94:95], v76 offset0:165 offset1:173
	s_and_b32 s18, s8, 0xffff
	v_and_or_b32 v78, v78, s27, v66
	s_waitcnt lgkmcnt(3)
	v_bfe_u32 v66, v88, 16, 1
	s_mul_i32 s18, s18, 0xba2f
	v_add3_u32 v66, v88, v66, s26
	s_waitcnt lgkmcnt(2)
	v_bfe_u32 v79, v90, 16, 1
	ds_read2_b32 v[96:97], v76 offset0:198 offset1:206
	s_lshr_b32 s19, s18, 22
	v_lshrrev_b32_e32 v66, 16, v66
	v_add3_u32 v79, v90, v79, s26
	ds_read2_b32 v[98:99], v76 offset0:231 offset1:239
	s_mulk_i32 s19, 0x58
	v_and_or_b32 v79, v79, s27, v66
	s_waitcnt lgkmcnt(3)
	v_bfe_u32 v66, v92, 16, 1
	s_sub_i32 s8, s8, s19
	v_add3_u32 v66, v92, v66, s26
	s_waitcnt lgkmcnt(2)
	v_bfe_u32 v80, v94, 16, 1
	s_lshl_b32 s19, s8, 5
	s_lshl_b32 s8, s8, 6
	v_lshrrev_b32_e32 v66, 16, v66
	v_add3_u32 v80, v94, v80, s26
	s_and_b32 s8, s8, 0x1f00
	s_and_b32 s19, s19, 0x60
	v_and_or_b32 v80, v80, s27, v66
	s_waitcnt lgkmcnt(1)
	v_bfe_u32 v66, v96, 16, 1
	s_or_b32 s8, s19, s8
	v_add3_u32 v66, v96, v66, s26
	s_waitcnt lgkmcnt(0)
	v_bfe_u32 v81, v98, 16, 1
	s_or_b32 s19, s8, 0x80
	s_lshr_b32 s8, s18, 15
	v_lshrrev_b32_e32 v66, 16, v66
	v_add3_u32 v81, v98, v81, s26
	s_and_b32 s8, s8, 0x1ff80
	v_and_or_b32 v81, v81, s27, v66
	v_or_b32_e32 v66, s19, v199
	v_lshl_add_u64 v[84:85], v[70:71], 0, s[8:9]
	v_lshlrev_b32_e32 v66, 11, v66
	v_lshl_add_u64 v[100:101], v[84:85], 0, v[66:67]
	v_bfe_u32 v66, v83, 16, 1
	global_store_dwordx4 v[100:101], v[78:81], off sc1
	v_add3_u32 v66, v83, v66, s26
	v_lshrrev_b32_e32 v66, 16, v66
	v_bfe_u32 v78, v87, 16, 1
	v_add3_u32 v78, v87, v78, s26
	v_and_or_b32 v78, v78, s27, v66
	v_bfe_u32 v66, v89, 16, 1
	v_add3_u32 v66, v89, v66, s26
	v_bfe_u32 v79, v91, 16, 1
	v_lshrrev_b32_e32 v66, 16, v66
	v_add3_u32 v79, v91, v79, s26
	v_and_or_b32 v79, v79, s27, v66
	v_bfe_u32 v66, v93, 16, 1
	v_add3_u32 v66, v93, v66, s26
	v_bfe_u32 v80, v95, 16, 1
	v_lshrrev_b32_e32 v66, 16, v66
	v_add3_u32 v80, v95, v80, s26
	v_and_or_b32 v80, v80, s27, v66
	v_bfe_u32 v66, v97, 16, 1
	v_add3_u32 v66, v97, v66, s26
	v_bfe_u32 v81, v99, 16, 1
	v_lshrrev_b32_e32 v66, 16, v66
	v_add3_u32 v81, v99, v81, s26
	v_and_or_b32 v81, v81, s27, v66
	v_or_b32_e32 v66, s19, v227
	v_lshlrev_b32_e32 v66, 11, v66
	ds_read2_b32 v[82:83], v76 offset0:16 offset1:24
	v_lshl_add_u64 v[86:87], v[84:85], 0, v[66:67]
	global_store_dwordx4 v[86:87], v[78:81], off sc1
	ds_read2_b32 v[86:87], v76 offset0:49 offset1:57
	ds_read2_b32 v[88:89], v76 offset0:82 offset1:90
	ds_read2_b32 v[90:91], v76 offset0:115 offset1:123
	s_waitcnt lgkmcnt(3)
	v_bfe_u32 v66, v82, 16, 1
	v_add3_u32 v66, v82, v66, s26
	s_waitcnt lgkmcnt(2)
	v_bfe_u32 v78, v86, 16, 1
	ds_read2_b32 v[92:93], v76 offset0:148 offset1:156
	v_lshrrev_b32_e32 v66, 16, v66
	v_add3_u32 v78, v86, v78, s26
	ds_read2_b32 v[94:95], v76 offset0:181 offset1:189
	v_and_or_b32 v78, v78, s27, v66
	s_waitcnt lgkmcnt(3)
	v_bfe_u32 v66, v88, 16, 1
	v_add3_u32 v66, v88, v66, s26
	s_waitcnt lgkmcnt(2)
	v_bfe_u32 v79, v90, 16, 1
	ds_read2_b32 v[96:97], v76 offset0:214 offset1:222
	v_lshrrev_b32_e32 v66, 16, v66
	v_add3_u32 v79, v90, v79, s26
	ds_read2_b32 v[98:99], v76 offset0:247 offset1:255
	v_and_or_b32 v79, v79, s27, v66
	s_waitcnt lgkmcnt(3)
	v_bfe_u32 v66, v92, 16, 1
	v_add3_u32 v66, v92, v66, s26
	s_waitcnt lgkmcnt(2)
	v_bfe_u32 v80, v94, 16, 1
	v_lshrrev_b32_e32 v66, 16, v66
	v_add3_u32 v80, v94, v80, s26
	v_and_or_b32 v80, v80, s27, v66
	s_waitcnt lgkmcnt(1)
	v_bfe_u32 v66, v96, 16, 1
	v_add3_u32 v66, v96, v66, s26
	s_waitcnt lgkmcnt(0)
	v_bfe_u32 v81, v98, 16, 1
	v_lshrrev_b32_e32 v66, 16, v66
	v_add3_u32 v81, v98, v81, s26
	v_and_or_b32 v81, v81, s27, v66
	v_or_b32_e32 v66, s19, v228
	v_lshlrev_b32_e32 v66, 11, v66
	v_lshl_add_u64 v[100:101], v[84:85], 0, v[66:67]
	v_bfe_u32 v66, v83, 16, 1
	global_store_dwordx4 v[100:101], v[78:81], off sc1
	v_add3_u32 v66, v83, v66, s26
	v_lshrrev_b32_e32 v66, 16, v66
	v_bfe_u32 v78, v87, 16, 1
	v_add3_u32 v78, v87, v78, s26
	v_and_or_b32 v78, v78, s27, v66
	v_bfe_u32 v66, v89, 16, 1
	v_add3_u32 v66, v89, v66, s26
	v_bfe_u32 v79, v91, 16, 1
	v_lshrrev_b32_e32 v66, 16, v66
	v_add3_u32 v79, v91, v79, s26
	v_and_or_b32 v79, v79, s27, v66
	v_bfe_u32 v66, v93, 16, 1
	v_add3_u32 v66, v93, v66, s26
	v_bfe_u32 v80, v95, 16, 1
	v_lshrrev_b32_e32 v66, 16, v66
	v_add3_u32 v80, v95, v80, s26
	v_and_or_b32 v80, v80, s27, v66
	v_bfe_u32 v66, v97, 16, 1
	v_add3_u32 v66, v97, v66, s26
	v_bfe_u32 v81, v99, 16, 1
	v_lshrrev_b32_e32 v66, 16, v66
	v_add3_u32 v81, v99, v81, s26
	v_and_or_b32 v81, v81, s27, v66
	v_or_b32_e32 v66, s19, v229
	v_lshlrev_b32_e32 v66, 11, v66
	v_lshl_add_u64 v[82:83], v[84:85], 0, v[66:67]
	global_store_dwordx4 v[82:83], v[78:81], off sc1
	s_waitcnt lgkmcnt(0)

.LBB0_759:
	s_andn2_b64 vcc, exec, s[18:19]
	s_cbranch_vccnz .LBB0_761
	v_add_u32_e32 v66, v203, v226
	v_add_u32_e32 v78, 0x420, v66
	s_waitcnt vmcnt(7)
	ds_write2_b32 v66, v62, v63 offset1:1
	ds_write2_b32 v66, v64, v65 offset0:2 offset1:3
	s_waitcnt vmcnt(6)
	ds_write2_b32 v78, v58, v59 offset1:1
	v_add_u32_e32 v78, 0x428, v66
	ds_write2_b32 v78, v60, v61 offset1:1
	v_add_u32_e32 v78, 0x840, v66
	s_waitcnt vmcnt(5)
	ds_write2_b32 v78, v54, v55 offset1:1
	v_add_u32_e32 v78, 0x848, v66
	ds_write2_b32 v78, v56, v57 offset1:1
	v_add_u32_e32 v78, 0xc60, v66
	s_waitcnt vmcnt(4)
	ds_write2_b32 v78, v46, v47 offset1:1
	v_add_u32_e32 v78, 0xc68, v66
	ds_write2_b32 v78, v48, v49 offset1:1
	v_add_u32_e32 v78, 0x1080, v66
	s_waitcnt vmcnt(3)
	ds_write2_b32 v78, v50, v51 offset1:1
	v_add_u32_e32 v78, 0x1088, v66
	ds_write2_b32 v78, v52, v53 offset1:1
	v_add_u32_e32 v78, 0x14a0, v66
	s_waitcnt vmcnt(2)
	ds_write2_b32 v78, v38, v39 offset1:1
	v_add_u32_e32 v78, 0x14a8, v66
	ds_write2_b32 v78, v40, v41 offset1:1
	v_add_u32_e32 v78, 0x18c0, v66
	s_waitcnt vmcnt(1)
	ds_write2_b32 v78, v42, v43 offset1:1
	v_add_u32_e32 v78, 0x18c8, v66
	ds_write2_b32 v78, v44, v45 offset1:1
	v_add_u32_e32 v78, 0x1ce0, v66
	v_add_u32_e32 v66, 0x1ce8, v66
	s_waitcnt vmcnt(0)
	ds_write2_b32 v78, v34, v35 offset1:1
	ds_write2_b32 v66, v36, v37 offset1:1
	s_waitcnt lgkmcnt(0)
	ds_read2_b32 v[82:83], v76 offset1:8
	ds_read2_b32 v[86:87], v76 offset0:33 offset1:41
	ds_read2_b32 v[88:89], v76 offset0:66 offset1:74
	ds_read2_b32 v[90:91], v76 offset0:99 offset1:107
	ds_read2_b32 v[92:93], v76 offset0:132 offset1:140
	s_waitcnt lgkmcnt(4)
	v_bfe_u32 v66, v82, 16, 1
	v_add3_u32 v66, v82, v66, s26
	s_waitcnt lgkmcnt(3)
	v_bfe_u32 v78, v86, 16, 1
	v_lshrrev_b32_e32 v66, 16, v66
	v_add3_u32 v78, v86, v78, s26
	ds_read2_b32 v[94:95], v76 offset0:165 offset1:173
	s_add_i32 s8, s29, 0xf800
	v_and_or_b32 v78, v78, s27, v66
	s_waitcnt lgkmcnt(3)
	v_bfe_u32 v66, v88, 16, 1
	s_and_b32 s18, s8, 0xffff
	v_add3_u32 v66, v88, v66, s26
	s_waitcnt lgkmcnt(2)
	v_bfe_u32 v79, v90, 16, 1
	ds_read2_b32 v[96:97], v76 offset0:198 offset1:206
	s_mul_i32 s18, s18, 0xba2f
	v_lshrrev_b32_e32 v66, 16, v66
	v_add3_u32 v79, v90, v79, s26
	ds_read2_b32 v[98:99], v76 offset0:231 offset1:239
	s_lshr_b32 s19, s18, 22
	v_and_or_b32 v79, v79, s27, v66
	s_waitcnt lgkmcnt(3)
	v_bfe_u32 v66, v92, 16, 1
	s_mulk_i32 s19, 0x58
	v_add3_u32 v66, v92, v66, s26
	s_waitcnt lgkmcnt(2)
	v_bfe_u32 v80, v94, 16, 1
	s_sub_i32 s8, s8, s19
	v_lshrrev_b32_e32 v66, 16, v66
	v_add3_u32 v80, v94, v80, s26
	s_lshl_b32 s19, s8, 5
	s_lshl_b32 s8, s8, 6
	v_and_or_b32 v80, v80, s27, v66
	s_waitcnt lgkmcnt(1)
	v_bfe_u32 v66, v96, 16, 1
	s_and_b32 s8, s8, 0x1f00
	s_and_b32 s19, s19, 0x60
	v_add3_u32 v66, v96, v66, s26
	s_waitcnt lgkmcnt(0)
	v_bfe_u32 v81, v98, 16, 1
	s_or_b32 s19, s8, s19
	s_lshr_b32 s8, s18, 15
	v_lshrrev_b32_e32 v66, 16, v66
	v_add3_u32 v81, v98, v81, s26
	s_and_b32 s8, s8, 0x1ff80
	v_and_or_b32 v81, v81, s27, v66
	v_or_b32_e32 v66, s19, v199
	v_lshl_add_u64 v[84:85], v[70:71], 0, s[8:9]
	v_lshlrev_b32_e32 v66, 11, v66
	v_lshl_add_u64 v[100:101], v[84:85], 0, v[66:67]
	v_bfe_u32 v66, v83, 16, 1
	global_store_dwordx4 v[100:101], v[78:81], off sc1
	v_add3_u32 v66, v83, v66, s26
	v_lshrrev_b32_e32 v66, 16, v66
	v_bfe_u32 v78, v87, 16, 1
	v_add3_u32 v78, v87, v78, s26
	v_and_or_b32 v78, v78, s27, v66
	v_bfe_u32 v66, v89, 16, 1
	v_add3_u32 v66, v89, v66, s26
	v_bfe_u32 v79, v91, 16, 1
	v_lshrrev_b32_e32 v66, 16, v66
	v_add3_u32 v79, v91, v79, s26
	v_and_or_b32 v79, v79, s27, v66
	v_bfe_u32 v66, v93, 16, 1
	v_add3_u32 v66, v93, v66, s26
	v_bfe_u32 v80, v95, 16, 1
	v_lshrrev_b32_e32 v66, 16, v66
	v_add3_u32 v80, v95, v80, s26
	v_and_or_b32 v80, v80, s27, v66
	v_bfe_u32 v66, v97, 16, 1
	v_add3_u32 v66, v97, v66, s26
	v_bfe_u32 v81, v99, 16, 1
	v_lshrrev_b32_e32 v66, 16, v66
	v_add3_u32 v81, v99, v81, s26
	v_and_or_b32 v81, v81, s27, v66
	v_or_b32_e32 v66, s19, v227
	v_lshlrev_b32_e32 v66, 11, v66
	ds_read2_b32 v[82:83], v76 offset0:16 offset1:24
	v_lshl_add_u64 v[86:87], v[84:85], 0, v[66:67]
	global_store_dwordx4 v[86:87], v[78:81], off sc1
	ds_read2_b32 v[86:87], v76 offset0:49 offset1:57
	ds_read2_b32 v[88:89], v76 offset0:82 offset1:90
	ds_read2_b32 v[90:91], v76 offset0:115 offset1:123
	s_waitcnt lgkmcnt(3)
	v_bfe_u32 v66, v82, 16, 1
	v_add3_u32 v66, v82, v66, s26
	s_waitcnt lgkmcnt(2)
	v_bfe_u32 v78, v86, 16, 1
	ds_read2_b32 v[92:93], v76 offset0:148 offset1:156
	v_lshrrev_b32_e32 v66, 16, v66
	v_add3_u32 v78, v86, v78, s26
	ds_read2_b32 v[94:95], v76 offset0:181 offset1:189
	v_and_or_b32 v78, v78, s27, v66
	s_waitcnt lgkmcnt(3)
	v_bfe_u32 v66, v88, 16, 1
	v_add3_u32 v66, v88, v66, s26
	s_waitcnt lgkmcnt(2)
	v_bfe_u32 v79, v90, 16, 1
	ds_read2_b32 v[96:97], v76 offset0:214 offset1:222
	v_lshrrev_b32_e32 v66, 16, v66
	v_add3_u32 v79, v90, v79, s26
	ds_read2_b32 v[98:99], v76 offset0:247 offset1:255
	v_and_or_b32 v79, v79, s27, v66
	s_waitcnt lgkmcnt(3)
	v_bfe_u32 v66, v92, 16, 1
	v_add3_u32 v66, v92, v66, s26
	s_waitcnt lgkmcnt(2)
	v_bfe_u32 v80, v94, 16, 1
	v_lshrrev_b32_e32 v66, 16, v66
	v_add3_u32 v80, v94, v80, s26
	v_and_or_b32 v80, v80, s27, v66
	s_waitcnt lgkmcnt(1)
	v_bfe_u32 v66, v96, 16, 1
	v_add3_u32 v66, v96, v66, s26
	s_waitcnt lgkmcnt(0)
	v_bfe_u32 v81, v98, 16, 1
	v_lshrrev_b32_e32 v66, 16, v66
	v_add3_u32 v81, v98, v81, s26
	v_and_or_b32 v81, v81, s27, v66
	v_or_b32_e32 v66, s19, v228
	v_lshlrev_b32_e32 v66, 11, v66
	v_lshl_add_u64 v[100:101], v[84:85], 0, v[66:67]
	v_bfe_u32 v66, v83, 16, 1
	global_store_dwordx4 v[100:101], v[78:81], off sc1
	v_add3_u32 v66, v83, v66, s26
	v_lshrrev_b32_e32 v66, 16, v66
	v_bfe_u32 v78, v87, 16, 1
	v_add3_u32 v78, v87, v78, s26
	v_and_or_b32 v78, v78, s27, v66
	v_bfe_u32 v66, v89, 16, 1
	v_add3_u32 v66, v89, v66, s26
	v_bfe_u32 v79, v91, 16, 1
	v_lshrrev_b32_e32 v66, 16, v66
	v_add3_u32 v79, v91, v79, s26
	v_and_or_b32 v79, v79, s27, v66
	v_bfe_u32 v66, v93, 16, 1
	v_add3_u32 v66, v93, v66, s26
	v_bfe_u32 v80, v95, 16, 1
	v_lshrrev_b32_e32 v66, 16, v66
	v_add3_u32 v80, v95, v80, s26
	v_and_or_b32 v80, v80, s27, v66
	v_bfe_u32 v66, v97, 16, 1
	v_add3_u32 v66, v97, v66, s26
	v_bfe_u32 v81, v99, 16, 1
	v_lshrrev_b32_e32 v66, 16, v66
	v_add3_u32 v81, v99, v81, s26
	v_and_or_b32 v81, v81, s27, v66
	v_or_b32_e32 v66, s19, v229
	v_lshlrev_b32_e32 v66, 11, v66
	v_lshl_add_u64 v[82:83], v[84:85], 0, v[66:67]
	global_store_dwordx4 v[82:83], v[78:81], off sc1
	s_waitcnt lgkmcnt(0)

.LBB0_762:
	s_andn2_b64 vcc, exec, s[18:19]
	s_cbranch_vccnz .LBB0_764
	v_add_u32_e32 v66, v203, v226
	v_add_u32_e32 v78, 0x420, v66
	s_waitcnt vmcnt(7)
	ds_write2_b32 v66, v62, v63 offset1:1
	ds_write2_b32 v66, v64, v65 offset0:2 offset1:3
	s_waitcnt vmcnt(6)
	ds_write2_b32 v78, v58, v59 offset1:1
	v_add_u32_e32 v78, 0x428, v66
	ds_write2_b32 v78, v60, v61 offset1:1
	v_add_u32_e32 v78, 0x840, v66
	s_waitcnt vmcnt(5)
	ds_write2_b32 v78, v54, v55 offset1:1
	v_add_u32_e32 v78, 0x848, v66
	ds_write2_b32 v78, v56, v57 offset1:1
	v_add_u32_e32 v78, 0xc60, v66
	s_waitcnt vmcnt(4)
	ds_write2_b32 v78, v46, v47 offset1:1
	v_add_u32_e32 v78, 0xc68, v66
	ds_write2_b32 v78, v48, v49 offset1:1
	v_add_u32_e32 v78, 0x1080, v66
	s_waitcnt vmcnt(3)
	ds_write2_b32 v78, v50, v51 offset1:1
	v_add_u32_e32 v78, 0x1088, v66
	ds_write2_b32 v78, v52, v53 offset1:1
	v_add_u32_e32 v78, 0x14a0, v66
	s_waitcnt vmcnt(2)
	ds_write2_b32 v78, v38, v39 offset1:1
	v_add_u32_e32 v78, 0x14a8, v66
	ds_write2_b32 v78, v40, v41 offset1:1
	v_add_u32_e32 v78, 0x18c0, v66
	s_waitcnt vmcnt(1)
	ds_write2_b32 v78, v42, v43 offset1:1
	v_add_u32_e32 v78, 0x18c8, v66
	ds_write2_b32 v78, v44, v45 offset1:1
	v_add_u32_e32 v78, 0x1ce0, v66
	v_add_u32_e32 v66, 0x1ce8, v66
	s_waitcnt vmcnt(0)
	ds_write2_b32 v78, v34, v35 offset1:1
	ds_write2_b32 v66, v36, v37 offset1:1
	s_waitcnt lgkmcnt(0)
	ds_read2_b32 v[82:83], v76 offset1:8
	ds_read2_b32 v[86:87], v76 offset0:33 offset1:41
	ds_read2_b32 v[88:89], v76 offset0:66 offset1:74
	ds_read2_b32 v[90:91], v76 offset0:99 offset1:107
	ds_read2_b32 v[92:93], v76 offset0:132 offset1:140
	s_waitcnt lgkmcnt(4)
	v_bfe_u32 v66, v82, 16, 1
	v_add3_u32 v66, v82, v66, s26
	s_waitcnt lgkmcnt(3)
	v_bfe_u32 v78, v86, 16, 1
	v_lshrrev_b32_e32 v66, 16, v66
	v_add3_u32 v78, v86, v78, s26
	ds_read2_b32 v[94:95], v76 offset0:165 offset1:173
	v_and_or_b32 v78, v78, s27, v66
	s_waitcnt lgkmcnt(3)
	v_bfe_u32 v66, v88, 16, 1
	v_add3_u32 v66, v88, v66, s26
	s_waitcnt lgkmcnt(2)
	v_bfe_u32 v79, v90, 16, 1
	ds_read2_b32 v[96:97], v76 offset0:198 offset1:206
	v_lshrrev_b32_e32 v66, 16, v66
	v_add3_u32 v79, v90, v79, s26
	ds_read2_b32 v[98:99], v76 offset0:231 offset1:239
	v_and_or_b32 v79, v79, s27, v66
	s_waitcnt lgkmcnt(3)
	v_bfe_u32 v66, v92, 16, 1
	v_add3_u32 v66, v92, v66, s26
	s_waitcnt lgkmcnt(2)
	v_bfe_u32 v80, v94, 16, 1
	v_lshrrev_b32_e32 v66, 16, v66
	v_add3_u32 v80, v94, v80, s26
	v_and_or_b32 v80, v80, s27, v66
	s_waitcnt lgkmcnt(1)
	v_bfe_u32 v66, v96, 16, 1
	s_add_i32 s8, s31, 0x1a00
	s_add_i32 s18, s30, 0x1a000
	v_add3_u32 v66, v96, v66, s26
	s_waitcnt lgkmcnt(0)
	v_bfe_u32 v81, v98, 16, 1
	s_and_b32 s8, s8, 0xfc0
	s_and_b32 s18, s18, 0x3e0
	v_lshrrev_b32_e32 v66, 16, v66
	v_add3_u32 v81, v98, v81, s26
	s_lshl_b32 s8, s8, 1
	v_and_or_b32 v81, v81, s27, v66
	v_or_b32_e32 v66, s18, v199
	v_lshl_add_u64 v[84:85], v[72:73], 0, s[8:9]
	v_lshlrev_b32_e32 v66, 11, v66
	v_lshl_add_u64 v[100:101], v[84:85], 0, v[66:67]
	v_bfe_u32 v66, v83, 16, 1
	global_store_dwordx4 v[100:101], v[78:81], off sc1
	v_add3_u32 v66, v83, v66, s26
	v_lshrrev_b32_e32 v66, 16, v66
	v_bfe_u32 v78, v87, 16, 1
	v_add3_u32 v78, v87, v78, s26
	v_and_or_b32 v78, v78, s27, v66
	v_bfe_u32 v66, v89, 16, 1
	v_add3_u32 v66, v89, v66, s26
	v_bfe_u32 v79, v91, 16, 1
	v_lshrrev_b32_e32 v66, 16, v66
	v_add3_u32 v79, v91, v79, s26
	v_and_or_b32 v79, v79, s27, v66
	v_bfe_u32 v66, v93, 16, 1
	v_add3_u32 v66, v93, v66, s26
	v_bfe_u32 v80, v95, 16, 1
	v_lshrrev_b32_e32 v66, 16, v66
	v_add3_u32 v80, v95, v80, s26
	v_and_or_b32 v80, v80, s27, v66
	v_bfe_u32 v66, v97, 16, 1
	v_add3_u32 v66, v97, v66, s26
	v_bfe_u32 v81, v99, 16, 1
	v_lshrrev_b32_e32 v66, 16, v66
	v_add3_u32 v81, v99, v81, s26
	v_and_or_b32 v81, v81, s27, v66
	v_or_b32_e32 v66, s18, v227
	v_lshlrev_b32_e32 v66, 11, v66
	ds_read2_b32 v[82:83], v76 offset0:16 offset1:24
	v_lshl_add_u64 v[86:87], v[84:85], 0, v[66:67]
	global_store_dwordx4 v[86:87], v[78:81], off sc1
	ds_read2_b32 v[86:87], v76 offset0:49 offset1:57
	ds_read2_b32 v[88:89], v76 offset0:82 offset1:90
	ds_read2_b32 v[90:91], v76 offset0:115 offset1:123
	s_waitcnt lgkmcnt(3)
	v_bfe_u32 v66, v82, 16, 1
	v_add3_u32 v66, v82, v66, s26
	s_waitcnt lgkmcnt(2)
	v_bfe_u32 v78, v86, 16, 1
	ds_read2_b32 v[92:93], v76 offset0:148 offset1:156
	v_lshrrev_b32_e32 v66, 16, v66
	v_add3_u32 v78, v86, v78, s26
	ds_read2_b32 v[94:95], v76 offset0:181 offset1:189
	v_and_or_b32 v78, v78, s27, v66
	s_waitcnt lgkmcnt(3)
	v_bfe_u32 v66, v88, 16, 1
	v_add3_u32 v66, v88, v66, s26
	s_waitcnt lgkmcnt(2)
	v_bfe_u32 v79, v90, 16, 1
	ds_read2_b32 v[96:97], v76 offset0:214 offset1:222
	v_lshrrev_b32_e32 v66, 16, v66
	v_add3_u32 v79, v90, v79, s26
	ds_read2_b32 v[98:99], v76 offset0:247 offset1:255
	v_and_or_b32 v79, v79, s27, v66
	s_waitcnt lgkmcnt(3)
	v_bfe_u32 v66, v92, 16, 1
	v_add3_u32 v66, v92, v66, s26
	s_waitcnt lgkmcnt(2)
	v_bfe_u32 v80, v94, 16, 1
	v_lshrrev_b32_e32 v66, 16, v66
	v_add3_u32 v80, v94, v80, s26
	v_and_or_b32 v80, v80, s27, v66
	s_waitcnt lgkmcnt(1)
	v_bfe_u32 v66, v96, 16, 1
	v_add3_u32 v66, v96, v66, s26
	s_waitcnt lgkmcnt(0)
	v_bfe_u32 v81, v98, 16, 1
	v_lshrrev_b32_e32 v66, 16, v66
	v_add3_u32 v81, v98, v81, s26
	v_and_or_b32 v81, v81, s27, v66
	v_or_b32_e32 v66, s18, v228
	v_lshlrev_b32_e32 v66, 11, v66
	v_lshl_add_u64 v[100:101], v[84:85], 0, v[66:67]
	v_bfe_u32 v66, v83, 16, 1
	global_store_dwordx4 v[100:101], v[78:81], off sc1
	v_add3_u32 v66, v83, v66, s26
	v_lshrrev_b32_e32 v66, 16, v66
	v_bfe_u32 v78, v87, 16, 1
	v_add3_u32 v78, v87, v78, s26
	v_and_or_b32 v78, v78, s27, v66
	v_bfe_u32 v66, v89, 16, 1
	v_add3_u32 v66, v89, v66, s26
	v_bfe_u32 v79, v91, 16, 1
	v_lshrrev_b32_e32 v66, 16, v66
	v_add3_u32 v79, v91, v79, s26
	v_and_or_b32 v79, v79, s27, v66
	v_bfe_u32 v66, v93, 16, 1
	v_add3_u32 v66, v93, v66, s26
	v_bfe_u32 v80, v95, 16, 1
	v_lshrrev_b32_e32 v66, 16, v66
	v_add3_u32 v80, v95, v80, s26
	v_and_or_b32 v80, v80, s27, v66
	v_bfe_u32 v66, v97, 16, 1
	v_add3_u32 v66, v97, v66, s26
	v_bfe_u32 v81, v99, 16, 1
	v_lshrrev_b32_e32 v66, 16, v66
	v_add3_u32 v81, v99, v81, s26
	v_and_or_b32 v81, v81, s27, v66
	v_or_b32_e32 v66, s18, v229
	v_lshlrev_b32_e32 v66, 11, v66
	v_lshl_add_u64 v[82:83], v[84:85], 0, v[66:67]
	global_store_dwordx4 v[82:83], v[78:81], off sc1
	s_waitcnt lgkmcnt(0)

.LBB0_771:
	s_mul_hi_i32 s8, s29, 0x2aaaaaab
	s_lshr_b32 s18, s8, 31
	s_ashr_i32 s8, s8, 4
	s_add_i32 s8, s8, s18
	s_mul_i32 s18, s8, 0xffffffa0
	s_add_i32 s19, s29, s18
	s_lshl_b32 s18, s8, 6
	s_cmp_lt_i32 s19, 16
	s_cselect_b64 vcc, -1, 0
	v_cndmask_b32_e32 v66, 1.0, v77, vcc
	s_waitcnt vmcnt(7)
	v_pk_mul_f32 v[62:63], v[66:67], v[62:63] op_sel_hi:[0,1]
	v_add_u32_e32 v78, v203, v226
	ds_write2_b32 v78, v62, v63 offset1:1
	v_pk_mul_f32 v[62:63], v[66:67], v[64:65] op_sel_hi:[0,1]
	ds_write2_b32 v78, v62, v63 offset0:2 offset1:3
	s_waitcnt vmcnt(6)
	v_pk_mul_f32 v[58:59], v[66:67], v[58:59] op_sel_hi:[0,1]
	v_add_u32_e32 v62, 0x420, v78
	ds_write2_b32 v62, v58, v59 offset1:1
	v_pk_mul_f32 v[58:59], v[66:67], v[60:61] op_sel_hi:[0,1]
	v_add_u32_e32 v60, 0x428, v78
	ds_write2_b32 v60, v58, v59 offset1:1
	s_waitcnt vmcnt(5)
	v_pk_mul_f32 v[54:55], v[66:67], v[54:55] op_sel_hi:[0,1]
	v_add_u32_e32 v58, 0x840, v78
	ds_write2_b32 v58, v54, v55 offset1:1
	v_pk_mul_f32 v[54:55], v[66:67], v[56:57] op_sel_hi:[0,1]
	v_add_u32_e32 v56, 0x848, v78
	ds_write2_b32 v56, v54, v55 offset1:1
	s_waitcnt vmcnt(4)
	v_pk_mul_f32 v[46:47], v[66:67], v[46:47] op_sel_hi:[0,1]
	v_add_u32_e32 v54, 0xc60, v78
	ds_write2_b32 v54, v46, v47 offset1:1
	v_pk_mul_f32 v[46:47], v[66:67], v[48:49] op_sel_hi:[0,1]
	v_add_u32_e32 v48, 0xc68, v78
	ds_write2_b32 v48, v46, v47 offset1:1
	s_waitcnt vmcnt(3)
	v_pk_mul_f32 v[46:47], v[66:67], v[50:51] op_sel_hi:[0,1]
	v_add_u32_e32 v48, 0x1080, v78
	ds_write2_b32 v48, v46, v47 offset1:1
	v_pk_mul_f32 v[46:47], v[66:67], v[52:53] op_sel_hi:[0,1]
	v_add_u32_e32 v48, 0x1088, v78
	ds_write2_b32 v48, v46, v47 offset1:1
	s_waitcnt vmcnt(2)
	v_pk_mul_f32 v[38:39], v[66:67], v[38:39] op_sel_hi:[0,1]
	v_add_u32_e32 v46, 0x14a0, v78
	ds_write2_b32 v46, v38, v39 offset1:1
	v_pk_mul_f32 v[38:39], v[66:67], v[40:41] op_sel_hi:[0,1]
	v_add_u32_e32 v40, 0x14a8, v78
	ds_write2_b32 v40, v38, v39 offset1:1
	s_waitcnt vmcnt(1)
	v_pk_mul_f32 v[38:39], v[42:43], v[66:67] op_sel_hi:[1,0]
	v_add_u32_e32 v40, 0x18c0, v78
	ds_write2_b32 v40, v38, v39 offset1:1
	v_pk_mul_f32 v[38:39], v[44:45], v[66:67] op_sel_hi:[1,0]
	v_add_u32_e32 v40, 0x18c8, v78
	ds_write2_b32 v40, v38, v39 offset1:1
	s_waitcnt vmcnt(0)
	v_pk_mul_f32 v[34:35], v[34:35], v[66:67] op_sel_hi:[1,0]
	v_add_u32_e32 v38, 0x1ce0, v78
	ds_write2_b32 v38, v34, v35 offset1:1
	v_pk_mul_f32 v[34:35], v[36:37], v[66:67] op_sel_hi:[1,0]
	v_add_u32_e32 v36, 0x1ce8, v78
	ds_write2_b32 v36, v34, v35 offset1:1
	s_waitcnt lgkmcnt(0)
	ds_read2_b32 v[38:39], v76 offset1:8
	ds_read2_b32 v[42:43], v76 offset0:33 offset1:41
	ds_read2_b32 v[44:45], v76 offset0:66 offset1:74
	ds_read2_b32 v[46:47], v76 offset0:99 offset1:107
	ds_read2_b32 v[48:49], v76 offset0:132 offset1:140
	s_waitcnt lgkmcnt(4)
	v_bfe_u32 v34, v38, 16, 1
	v_add3_u32 v34, v38, v34, s26
	s_waitcnt lgkmcnt(3)
	v_bfe_u32 v35, v42, 16, 1
	v_lshrrev_b32_e32 v34, 16, v34
	v_add3_u32 v35, v42, v35, s26
	ds_read2_b32 v[50:51], v76 offset0:165 offset1:173
	v_and_or_b32 v34, v35, s27, v34
	s_waitcnt lgkmcnt(3)
	v_bfe_u32 v35, v44, 16, 1
	v_add3_u32 v35, v44, v35, s26
	s_waitcnt lgkmcnt(2)
	v_bfe_u32 v36, v46, 16, 1
	ds_read2_b32 v[52:53], v76 offset0:198 offset1:206
	v_lshrrev_b32_e32 v35, 16, v35
	v_add3_u32 v36, v46, v36, s26
	ds_read2_b32 v[54:55], v76 offset0:231 offset1:239
	v_and_or_b32 v35, v36, s27, v35
	s_waitcnt lgkmcnt(3)
	v_bfe_u32 v36, v48, 16, 1
	s_mulk_i32 s8, 0xf400
	v_add3_u32 v36, v48, v36, s26
	s_waitcnt lgkmcnt(2)
	v_bfe_u32 v37, v50, 16, 1
	s_add_i32 s8, s8, s30
	v_lshrrev_b32_e32 v36, 16, v36
	v_add3_u32 v37, v50, v37, s26
	v_add_u32_e32 v58, s8, v199
	v_and_or_b32 v36, v37, s27, v36
	s_waitcnt lgkmcnt(1)
	v_bfe_u32 v37, v52, 16, 1
	v_add_u32_e32 v56, 0x26000, v58
	s_ashr_i32 s19, s18, 31
	v_add3_u32 v37, v52, v37, s26
	s_waitcnt lgkmcnt(0)
	v_bfe_u32 v38, v54, 16, 1
	v_ashrrev_i32_e32 v57, 31, v56
	v_lshl_add_u64 v[40:41], s[18:19], 1, v[74:75]
	v_lshrrev_b32_e32 v37, 16, v37
	v_add3_u32 v38, v54, v38, s26
	v_lshlrev_b64 v[56:57], 11, v[56:57]
	v_and_or_b32 v37, v38, s27, v37
	v_lshl_add_u64 v[56:57], v[40:41], 0, v[56:57]
	global_store_dwordx4 v[56:57], v[34:37], off sc1
	v_bfe_u32 v38, v55, 16, 1
	v_add3_u32 v38, v55, v38, s26
	v_bfe_u32 v34, v39, 16, 1
	v_add3_u32 v34, v39, v34, s26
	v_bfe_u32 v35, v43, 16, 1
	v_lshrrev_b32_e32 v34, 16, v34
	v_add3_u32 v35, v43, v35, s26
	v_and_or_b32 v34, v35, s27, v34
	v_bfe_u32 v35, v45, 16, 1
	v_add3_u32 v35, v45, v35, s26
	v_bfe_u32 v36, v47, 16, 1
	v_lshrrev_b32_e32 v35, 16, v35
	v_add3_u32 v36, v47, v36, s26
	v_and_or_b32 v35, v36, s27, v35
	v_bfe_u32 v36, v49, 16, 1
	v_add3_u32 v36, v49, v36, s26
	v_bfe_u32 v37, v51, 16, 1
	v_lshrrev_b32_e32 v36, 16, v36
	v_add3_u32 v37, v51, v37, s26
	v_and_or_b32 v36, v37, s27, v36
	v_bfe_u32 v37, v53, 16, 1
	v_add3_u32 v37, v53, v37, s26
	v_lshrrev_b32_e32 v37, 16, v37
	v_and_or_b32 v37, v38, s27, v37
	v_add_u32_e32 v38, 0x26008, v58
	v_ashrrev_i32_e32 v39, 31, v38
	v_lshlrev_b64 v[38:39], 11, v[38:39]
	ds_read2_b32 v[42:43], v76 offset0:16 offset1:24
	v_lshl_add_u64 v[38:39], v[40:41], 0, v[38:39]
	global_store_dwordx4 v[38:39], v[34:37], off sc1
	ds_read2_b32 v[38:39], v76 offset0:49 offset1:57
	ds_read2_b32 v[44:45], v76 offset0:82 offset1:90
	ds_read2_b32 v[46:47], v76 offset0:115 offset1:123
	s_waitcnt lgkmcnt(3)
	v_bfe_u32 v34, v42, 16, 1
	v_add3_u32 v34, v42, v34, s26
	s_waitcnt lgkmcnt(2)
	v_bfe_u32 v35, v38, 16, 1
	ds_read2_b32 v[48:49], v76 offset0:148 offset1:156
	v_lshrrev_b32_e32 v34, 16, v34
	v_add3_u32 v35, v38, v35, s26
	ds_read2_b32 v[50:51], v76 offset0:181 offset1:189
	v_and_or_b32 v34, v35, s27, v34
	s_waitcnt lgkmcnt(3)
	v_bfe_u32 v35, v44, 16, 1
	v_add3_u32 v35, v44, v35, s26
	s_waitcnt lgkmcnt(2)
	v_bfe_u32 v36, v46, 16, 1
	ds_read2_b32 v[52:53], v76 offset0:214 offset1:222
	v_lshrrev_b32_e32 v35, 16, v35
	v_add3_u32 v36, v46, v36, s26
	ds_read2_b32 v[54:55], v76 offset0:247 offset1:255
	v_and_or_b32 v35, v36, s27, v35
	s_waitcnt lgkmcnt(3)
	v_bfe_u32 v36, v48, 16, 1
	v_add3_u32 v36, v48, v36, s26
	s_waitcnt lgkmcnt(2)
	v_bfe_u32 v37, v50, 16, 1
	v_lshrrev_b32_e32 v36, 16, v36
	v_add3_u32 v37, v50, v37, s26
	v_and_or_b32 v36, v37, s27, v36
	s_waitcnt lgkmcnt(1)
	v_bfe_u32 v37, v52, 16, 1
	v_add_u32_e32 v56, 0x26010, v58
	v_add3_u32 v37, v52, v37, s26
	s_waitcnt lgkmcnt(0)
	v_bfe_u32 v38, v54, 16, 1
	v_ashrrev_i32_e32 v57, 31, v56
	v_lshrrev_b32_e32 v37, 16, v37
	v_add3_u32 v38, v54, v38, s26
	v_lshlrev_b64 v[56:57], 11, v[56:57]
	v_and_or_b32 v37, v38, s27, v37
	v_lshl_add_u64 v[56:57], v[40:41], 0, v[56:57]
	global_store_dwordx4 v[56:57], v[34:37], off sc1
	v_bfe_u32 v38, v55, 16, 1
	v_add3_u32 v38, v55, v38, s26
	v_bfe_u32 v34, v43, 16, 1
	v_add3_u32 v34, v43, v34, s26
	v_bfe_u32 v35, v39, 16, 1
	v_lshrrev_b32_e32 v34, 16, v34
	v_add3_u32 v35, v39, v35, s26
	v_and_or_b32 v34, v35, s27, v34
	v_bfe_u32 v35, v45, 16, 1
	v_add3_u32 v35, v45, v35, s26
	v_bfe_u32 v36, v47, 16, 1
	v_lshrrev_b32_e32 v35, 16, v35
	v_add3_u32 v36, v47, v36, s26
	v_and_or_b32 v35, v36, s27, v35
	v_bfe_u32 v36, v49, 16, 1
	v_add3_u32 v36, v49, v36, s26
	v_bfe_u32 v37, v51, 16, 1
	v_lshrrev_b32_e32 v36, 16, v36
	v_add3_u32 v37, v51, v37, s26
	v_and_or_b32 v36, v37, s27, v36
	v_bfe_u32 v37, v53, 16, 1
	v_add3_u32 v37, v53, v37, s26
	v_lshrrev_b32_e32 v37, 16, v37
	v_and_or_b32 v37, v38, s27, v37
	v_add_u32_e32 v38, 0x26018, v58
	v_ashrrev_i32_e32 v39, 31, v38
	v_lshlrev_b64 v[38:39], 11, v[38:39]
	v_lshl_add_u64 v[38:39], v[40:41], 0, v[38:39]
	global_store_dwordx4 v[38:39], v[34:37], off sc1
	s_waitcnt lgkmcnt(0)
	s_add_i32 s30, s30, 0x8000
	s_andn2_b64 vcc, exec, s[16:17]
	s_addk_i32 s31, 0x800
	s_cbranch_vccz .LBB0_721

.LBB0_1001:
	s_ashr_i32 s19, s45, 31
	s_lshr_b32 s19, s19, 30
	s_add_i32 s19, s45, s19
	s_ashr_i32 s28, s19, 2
	s_ashr_i32 s29, s28, 31
	s_lshl_b32 s17, s45, 8
	s_lshl_b64 s[30:31], s[28:29], 25
	s_add_u32 s30, s36, s30
	s_addc_u32 s31, s37, s31
	s_lshl_b32 s19, s28, 10
	s_sub_i32 s17, s17, s19
	v_lshl_add_u32 v154, s24, 8, v148
	v_or_b32_e32 v146, s17, v150
	v_ashrrev_i32_e32 v147, 31, v146
	v_ashrrev_i32_e32 v155, 31, v154
	v_lshl_add_u64 v[156:157], v[146:147], 1, s[30:31]
	v_lshlrev_b64 v[146:147], 11, v[154:155]
	v_lshl_add_u64 v[146:147], v[156:157], 0, v[146:147]
	v_pk_add_f32 v[128:129], v[128:129], 0 op_sel_hi:[1,0]
	v_pk_add_f32 v[126:127], v[126:127], 0 op_sel_hi:[1,0]
	v_pk_add_f32 v[158:159], v[124:125], 0 op_sel_hi:[1,0]
	v_pk_add_f32 v[124:125], v[122:123], 0 op_sel_hi:[1,0]
	v_cvt_pk_bf16_f32 v122, v126, v127
	v_cvt_pk_bf16_f32 v123, v128, v129
	v_pk_add_f32 v[118:119], v[118:119], 0 op_sel_hi:[1,0]
	v_cvt_pk_bf16_f32 v124, v124, v125
	v_cvt_pk_bf16_f32 v125, v158, v159
	global_store_dwordx4 v[146:147], v[122:125], off sc1
	v_pk_add_f32 v[120:121], v[120:121], 0 op_sel_hi:[1,0]
	v_pk_add_f32 v[114:115], v[114:115], 0 op_sel_hi:[1,0]
	v_pk_add_f32 v[122:123], v[112:113], 0 op_sel_hi:[1,0]
	v_pk_add_f32 v[112:113], v[110:111], 0 op_sel_hi:[1,0]
	v_cvt_pk_bf16_f32 v110, v118, v119
	v_cvt_pk_bf16_f32 v111, v120, v121
	v_pk_add_f32 v[102:103], v[102:103], 0 op_sel_hi:[1,0]
	v_cvt_pk_bf16_f32 v112, v112, v113
	v_cvt_pk_bf16_f32 v113, v122, v123
	global_store_dwordx4 v[146:147], v[110:113], off offset:256 sc1
	v_pk_add_f32 v[104:105], v[104:105], 0 op_sel_hi:[1,0]
	v_pk_add_f32 v[98:99], v[98:99], 0 op_sel_hi:[1,0]
	v_or_b32_e32 v110, 16, v154
	v_ashrrev_i32_e32 v111, 31, v110
	v_lshlrev_b64 v[110:111], 11, v[110:111]
	v_lshl_add_u64 v[110:111], v[156:157], 0, v[110:111]
	v_pk_add_f32 v[112:113], v[116:117], 0 op_sel_hi:[1,0]
	v_pk_add_f32 v[116:117], v[108:109], 0 op_sel_hi:[1,0]
	v_pk_add_f32 v[108:109], v[106:107], 0 op_sel_hi:[1,0]
	v_cvt_pk_bf16_f32 v106, v114, v115
	v_cvt_pk_bf16_f32 v107, v112, v113
	v_pk_add_f32 v[86:87], v[86:87], 0 op_sel_hi:[1,0]
	v_cvt_pk_bf16_f32 v108, v108, v109
	v_cvt_pk_bf16_f32 v109, v116, v117
	global_store_dwordx4 v[110:111], v[106:109], off sc1
	v_pk_add_f32 v[88:89], v[88:89], 0 op_sel_hi:[1,0]
	v_pk_add_f32 v[82:83], v[82:83], 0 op_sel_hi:[1,0]
	v_pk_add_f32 v[106:107], v[96:97], 0 op_sel_hi:[1,0]
	v_pk_add_f32 v[96:97], v[94:95], 0 op_sel_hi:[1,0]
	v_cvt_pk_bf16_f32 v94, v102, v103
	v_cvt_pk_bf16_f32 v95, v104, v105
	v_pk_add_f32 v[72:73], v[72:73], 0 op_sel_hi:[1,0]
	v_cvt_pk_bf16_f32 v96, v96, v97
	v_cvt_pk_bf16_f32 v97, v106, v107
	global_store_dwordx4 v[110:111], v[94:97], off offset:256 sc1
	v_pk_add_f32 v[70:71], v[70:71], 0 op_sel_hi:[1,0]
	v_pk_add_f32 v[62:63], v[62:63], 0 op_sel_hi:[1,0]
	v_or_b32_e32 v94, 32, v154
	v_ashrrev_i32_e32 v95, 31, v94
	v_lshlrev_b64 v[94:95], 11, v[94:95]
	v_lshl_add_u64 v[94:95], v[156:157], 0, v[94:95]
	v_pk_add_f32 v[96:97], v[100:101], 0 op_sel_hi:[1,0]
	v_pk_add_f32 v[100:101], v[92:93], 0 op_sel_hi:[1,0]
	v_pk_add_f32 v[92:93], v[90:91], 0 op_sel_hi:[1,0]
	v_cvt_pk_bf16_f32 v90, v98, v99
	v_cvt_pk_bf16_f32 v91, v96, v97
	s_mov_b32 s17, 0x40000
	v_cvt_pk_bf16_f32 v92, v92, v93
	v_cvt_pk_bf16_f32 v93, v100, v101
	global_store_dwordx4 v[94:95], v[90:93], off sc1
	v_pk_add_f32 v[64:65], v[64:65], 0 op_sel_hi:[1,0]
	s_mov_b64 s[28:29], 0x40000
	v_pk_add_f32 v[90:91], v[80:81], 0 op_sel_hi:[1,0]
	v_pk_add_f32 v[80:81], v[78:79], 0 op_sel_hi:[1,0]
	v_cvt_pk_bf16_f32 v78, v86, v87
	v_cvt_pk_bf16_f32 v79, v88, v89
	v_pk_add_f32 v[56:57], v[56:57], 0 op_sel_hi:[1,0]
	v_cvt_pk_bf16_f32 v80, v80, v81
	v_cvt_pk_bf16_f32 v81, v90, v91
	global_store_dwordx4 v[94:95], v[78:81], off offset:256 sc1
	v_pk_add_f32 v[54:55], v[54:55], 0 op_sel_hi:[1,0]
	v_pk_add_f32 v[50:51], v[50:51], 0 op_sel_hi:[1,0]
	v_or_b32_e32 v78, 48, v154
	v_ashrrev_i32_e32 v79, 31, v78
	v_lshlrev_b64 v[78:79], 11, v[78:79]
	v_lshl_add_u64 v[78:79], v[156:157], 0, v[78:79]
	v_pk_add_f32 v[80:81], v[84:85], 0 op_sel_hi:[1,0]
	v_pk_add_f32 v[84:85], v[76:77], 0 op_sel_hi:[1,0]
	v_pk_add_f32 v[76:77], v[74:75], 0 op_sel_hi:[1,0]
	v_cvt_pk_bf16_f32 v74, v82, v83
	v_cvt_pk_bf16_f32 v75, v80, v81
	v_pk_add_f32 v[40:41], v[40:41], 0 op_sel_hi:[1,0]
	v_cvt_pk_bf16_f32 v76, v76, v77
	v_cvt_pk_bf16_f32 v77, v84, v85
	global_store_dwordx4 v[78:79], v[74:77], off sc1
	v_pk_add_f32 v[38:39], v[38:39], 0 op_sel_hi:[1,0]
	v_pk_add_f32 v[34:35], v[34:35], 0 op_sel_hi:[1,0]
	v_pk_add_f32 v[74:75], v[68:69], 0 op_sel_hi:[1,0]
	v_pk_add_f32 v[68:69], v[66:67], 0 op_sel_hi:[1,0]
	v_cvt_pk_bf16_f32 v66, v70, v71
	v_cvt_pk_bf16_f32 v67, v72, v73
	v_pk_add_f32 v[24:25], v[24:25], 0 op_sel_hi:[1,0]
	v_cvt_pk_bf16_f32 v68, v68, v69
	v_cvt_pk_bf16_f32 v69, v74, v75
	global_store_dwordx4 v[78:79], v[66:69], off offset:256 sc1
	v_pk_add_f32 v[22:23], v[22:23], 0 op_sel_hi:[1,0]
	v_pk_add_f32 v[18:19], v[18:19], 0 op_sel_hi:[1,0]
	v_pk_add_f32 v[68:69], v[60:61], 0 op_sel_hi:[1,0]
	v_pk_add_f32 v[60:61], v[58:59], 0 op_sel_hi:[1,0]
	v_cvt_pk_bf16_f32 v58, v62, v63
	v_add_co_u32_e32 v62, vcc, s17, v146
	v_cvt_pk_bf16_f32 v59, v64, v65
	v_cvt_pk_bf16_f32 v60, v60, v61
	v_cvt_pk_bf16_f32 v61, v68, v69
	v_lshl_add_u64 v[66:67], v[146:147], 0, s[28:29]
	s_nop 0
	v_addc_co_u32_e32 v63, vcc, 0, v147, vcc
	global_store_dwordx4 v[62:63], v[58:61], off sc1
	s_mov_b32 s17, 0x48000
	s_mov_b64 s[28:29], 0x48000
	v_pk_add_f32 v[58:59], v[48:49], 0 op_sel_hi:[1,0]
	v_pk_add_f32 v[48:49], v[46:47], 0 op_sel_hi:[1,0]
	v_cvt_pk_bf16_f32 v46, v54, v55
	v_cvt_pk_bf16_f32 v47, v56, v57
	v_pk_add_f32 v[8:9], v[8:9], 0 op_sel_hi:[1,0]
	v_cvt_pk_bf16_f32 v48, v48, v49
	v_cvt_pk_bf16_f32 v49, v58, v59
	global_store_dwordx4 v[66:67], v[46:49], off offset:256 sc1
	v_pk_add_f32 v[6:7], v[6:7], 0 op_sel_hi:[1,0]
	s_nop 0
	v_pk_add_f32 v[48:49], v[52:53], 0 op_sel_hi:[1,0]
	v_pk_add_f32 v[52:53], v[44:45], 0 op_sel_hi:[1,0]
	v_pk_add_f32 v[44:45], v[42:43], 0 op_sel_hi:[1,0]
	v_cvt_pk_bf16_f32 v42, v50, v51
	v_cvt_pk_bf16_f32 v43, v48, v49
	v_add_co_u32_e32 v48, vcc, s17, v146
	v_cvt_pk_bf16_f32 v44, v44, v45
	v_cvt_pk_bf16_f32 v45, v52, v53
	v_lshl_add_u64 v[46:47], v[146:147], 0, s[28:29]
	s_nop 0
	v_addc_co_u32_e32 v49, vcc, 0, v147, vcc
	global_store_dwordx4 v[48:49], v[42:45], off sc1
	s_mov_b32 s17, 0x50000
	s_mov_b64 s[28:29], 0x50000
	v_pk_add_f32 v[42:43], v[32:33], 0 op_sel_hi:[1,0]
	v_pk_add_f32 v[32:33], v[30:31], 0 op_sel_hi:[1,0]
	v_cvt_pk_bf16_f32 v30, v38, v39
	v_cvt_pk_bf16_f32 v31, v40, v41
	s_nop 0
	v_cvt_pk_bf16_f32 v32, v32, v33
	v_cvt_pk_bf16_f32 v33, v42, v43
	global_store_dwordx4 v[46:47], v[30:33], off offset:256 sc1
	s_nop 1
	v_pk_add_f32 v[32:33], v[36:37], 0 op_sel_hi:[1,0]
	v_pk_add_f32 v[36:37], v[28:29], 0 op_sel_hi:[1,0]
	v_pk_add_f32 v[28:29], v[26:27], 0 op_sel_hi:[1,0]
	v_cvt_pk_bf16_f32 v26, v34, v35
	v_cvt_pk_bf16_f32 v27, v32, v33
	v_add_co_u32_e32 v32, vcc, s17, v146
	v_cvt_pk_bf16_f32 v28, v28, v29
	v_cvt_pk_bf16_f32 v29, v36, v37
	v_lshl_add_u64 v[30:31], v[146:147], 0, s[28:29]
	s_nop 0
	v_addc_co_u32_e32 v33, vcc, 0, v147, vcc
	global_store_dwordx4 v[32:33], v[26:29], off sc1
	s_mov_b32 s17, 0x58000
	s_mov_b64 s[28:29], 0x58000
	v_pk_add_f32 v[26:27], v[16:17], 0 op_sel_hi:[1,0]
	v_pk_add_f32 v[16:17], v[14:15], 0 op_sel_hi:[1,0]
	v_cvt_pk_bf16_f32 v14, v22, v23
	v_cvt_pk_bf16_f32 v15, v24, v25
	s_nop 0
	v_cvt_pk_bf16_f32 v16, v16, v17
	v_cvt_pk_bf16_f32 v17, v26, v27
	global_store_dwordx4 v[30:31], v[14:17], off offset:256 sc1
	s_nop 1
	v_pk_add_f32 v[16:17], v[20:21], 0 op_sel_hi:[1,0]
	v_pk_add_f32 v[20:21], v[12:13], 0 op_sel_hi:[1,0]
	v_pk_add_f32 v[12:13], v[10:11], 0 op_sel_hi:[1,0]
	v_cvt_pk_bf16_f32 v10, v18, v19
	v_cvt_pk_bf16_f32 v11, v16, v17
	v_add_co_u32_e32 v16, vcc, s17, v146
	v_lshl_add_u64 v[14:15], v[146:147], 0, s[28:29]
	s_nop 0
	v_addc_co_u32_e32 v17, vcc, 0, v147, vcc
	v_cvt_pk_bf16_f32 v12, v12, v13
	v_cvt_pk_bf16_f32 v13, v20, v21
	global_store_dwordx4 v[16:17], v[10:13], off sc1
	s_andn2_b64 vcc, exec, s[0:1]
	s_mov_b64 s[0:1], -1
	v_pk_add_f32 v[10:11], v[4:5], 0 op_sel_hi:[1,0]
	v_pk_add_f32 v[4:5], v[2:3], 0 op_sel_hi:[1,0]
	v_cvt_pk_bf16_f32 v2, v6, v7
	v_cvt_pk_bf16_f32 v3, v8, v9
	s_nop 0
	v_cvt_pk_bf16_f32 v4, v4, v5
	v_cvt_pk_bf16_f32 v5, v10, v11
	global_store_dwordx4 v[14:15], v[2:5], off offset:256 sc1
	s_cbranch_vccnz .LBB0_994
	s_andn2_b64 vcc, exec, s[8:9]
	s_cbranch_vccnz .LBB0_993
	s_barrier
	s_branch .LBB0_993

.LBB0_1019:
	s_cmpk_gt_u32 s25, 0x7ff
	s_cbranch_scc0 .LBB0_1025
	v_add_u32_e32 v77, v203, v226
	v_add_u32_e32 v78, 0x420, v77
	s_waitcnt vmcnt(7)
	ds_write2_b32 v77, v54, v55 offset1:1
	ds_write2_b32 v77, v56, v57 offset0:2 offset1:3
	s_waitcnt vmcnt(6)
	ds_write2_b32 v78, v50, v51 offset1:1
	v_add_u32_e32 v78, 0x428, v77
	ds_write2_b32 v78, v52, v53 offset1:1
	v_add_u32_e32 v78, 0x840, v77
	s_waitcnt vmcnt(5)
	ds_write2_b32 v78, v42, v43 offset1:1
	v_add_u32_e32 v78, 0x848, v77
	ds_write2_b32 v78, v44, v45 offset1:1
	v_add_u32_e32 v78, 0xc60, v77
	s_waitcnt vmcnt(4)
	ds_write2_b32 v78, v30, v31 offset1:1
	v_add_u32_e32 v78, 0xc68, v77
	ds_write2_b32 v78, v32, v33 offset1:1
	v_add_u32_e32 v78, 0x1080, v77
	s_waitcnt vmcnt(3)
	ds_write2_b32 v78, v34, v35 offset1:1
	v_add_u32_e32 v78, 0x1088, v77
	ds_write2_b32 v78, v36, v37 offset1:1
	v_add_u32_e32 v78, 0x14a0, v77
	s_waitcnt vmcnt(2)
	ds_write2_b32 v78, v22, v23 offset1:1
	v_add_u32_e32 v78, 0x14a8, v77
	ds_write2_b32 v78, v24, v25 offset1:1
	v_add_u32_e32 v78, 0x18c0, v77
	s_waitcnt vmcnt(1)
	ds_write2_b32 v78, v26, v27 offset1:1
	v_add_u32_e32 v78, 0x18c8, v77
	s_cmpk_gt_u32 s25, 0xd7f
	ds_write2_b32 v78, v28, v29 offset1:1
	v_add_u32_e32 v78, 0x1ce0, v77
	v_add_u32_e32 v77, 0x1ce8, v77
	s_waitcnt vmcnt(0)
	ds_write2_b32 v78, v10, v11 offset1:1
	ds_write2_b32 v77, v12, v13 offset1:1
	s_cbranch_scc0 .LBB0_1022
	s_waitcnt lgkmcnt(0)
	ds_read2_b32 v[82:83], v75 offset1:8
	ds_read2_b32 v[86:87], v75 offset0:33 offset1:41
	ds_read2_b32 v[88:89], v75 offset0:66 offset1:74
	ds_read2_b32 v[90:91], v75 offset0:99 offset1:107
	ds_read2_b32 v[92:93], v75 offset0:132 offset1:140
	s_waitcnt lgkmcnt(4)
	v_bfe_u32 v77, v82, 16, 1
	v_add3_u32 v77, v82, v77, s22
	s_waitcnt lgkmcnt(3)
	v_bfe_u32 v78, v86, 16, 1
	s_add_i32 s6, s25, 0xf280
	v_lshrrev_b32_e32 v77, 16, v77
	v_add3_u32 v78, v86, v78, s22
	ds_read2_b32 v[94:95], v75 offset0:165 offset1:173
	s_and_b32 s10, s6, 0xffff
	v_and_or_b32 v78, v78, s23, v77
	s_waitcnt lgkmcnt(3)
	v_bfe_u32 v77, v88, 16, 1
	s_mul_i32 s10, s10, 0xba2f
	v_add3_u32 v77, v88, v77, s22
	s_waitcnt lgkmcnt(2)
	v_bfe_u32 v79, v90, 16, 1
	ds_read2_b32 v[96:97], v75 offset0:198 offset1:206
	s_lshr_b32 s11, s10, 22
	v_lshrrev_b32_e32 v77, 16, v77
	v_add3_u32 v79, v90, v79, s22
	ds_read2_b32 v[98:99], v75 offset0:231 offset1:239
	s_mulk_i32 s11, 0x58
	v_and_or_b32 v79, v79, s23, v77
	s_waitcnt lgkmcnt(3)
	v_bfe_u32 v77, v92, 16, 1
	s_sub_i32 s6, s6, s11
	v_add3_u32 v77, v92, v77, s22
	s_waitcnt lgkmcnt(2)
	v_bfe_u32 v80, v94, 16, 1
	s_lshl_b32 s11, s6, 5
	s_lshl_b32 s6, s6, 6
	v_lshrrev_b32_e32 v77, 16, v77
	v_add3_u32 v80, v94, v80, s22
	s_and_b32 s6, s6, 0x1f00
	s_and_b32 s11, s11, 0x60
	v_and_or_b32 v80, v80, s23, v77
	s_waitcnt lgkmcnt(1)
	v_bfe_u32 v77, v96, 16, 1
	s_or_b32 s6, s11, s6
	v_add3_u32 v77, v96, v77, s22
	s_waitcnt lgkmcnt(0)
	v_bfe_u32 v81, v98, 16, 1
	s_or_b32 s11, s6, 0x80
	s_lshr_b32 s6, s10, 15
	v_lshrrev_b32_e32 v77, 16, v77
	v_add3_u32 v81, v98, v81, s22
	s_and_b32 s6, s6, 0x1ff80
	v_and_or_b32 v81, v81, s23, v77
	v_or_b32_e32 v77, s11, v199
	v_lshl_add_u64 v[84:85], v[68:69], 0, s[6:7]
	v_lshlrev_b32_e32 v100, 11, v77
	v_mov_b32_e32 v101, v67
	v_lshl_add_u64 v[100:101], v[84:85], 0, v[100:101]
	v_bfe_u32 v77, v83, 16, 1
	global_store_dwordx4 v[100:101], v[78:81], off sc1
	v_add3_u32 v77, v83, v77, s22
	v_lshrrev_b32_e32 v77, 16, v77
	v_bfe_u32 v78, v87, 16, 1
	v_add3_u32 v78, v87, v78, s22
	v_and_or_b32 v78, v78, s23, v77
	v_bfe_u32 v77, v89, 16, 1
	v_add3_u32 v77, v89, v77, s22
	v_bfe_u32 v79, v91, 16, 1
	v_lshrrev_b32_e32 v77, 16, v77
	v_add3_u32 v79, v91, v79, s22
	v_and_or_b32 v79, v79, s23, v77
	v_bfe_u32 v77, v93, 16, 1
	v_add3_u32 v77, v93, v77, s22
	v_bfe_u32 v80, v95, 16, 1
	v_lshrrev_b32_e32 v77, 16, v77
	v_add3_u32 v80, v95, v80, s22
	v_and_or_b32 v80, v80, s23, v77
	v_bfe_u32 v77, v97, 16, 1
	v_add3_u32 v77, v97, v77, s22
	v_bfe_u32 v81, v99, 16, 1
	v_lshrrev_b32_e32 v77, 16, v77
	v_add3_u32 v81, v99, v81, s22
	v_and_or_b32 v81, v81, s23, v77
	v_or_b32_e32 v77, s11, v227
	v_lshlrev_b32_e32 v82, 11, v77
	v_mov_b32_e32 v83, v67
	ds_read2_b32 v[86:87], v75 offset0:16 offset1:24
	v_lshl_add_u64 v[82:83], v[84:85], 0, v[82:83]
	global_store_dwordx4 v[82:83], v[78:81], off sc1
	ds_read2_b32 v[82:83], v75 offset0:49 offset1:57
	ds_read2_b32 v[88:89], v75 offset0:82 offset1:90
	ds_read2_b32 v[90:91], v75 offset0:115 offset1:123
	s_waitcnt lgkmcnt(3)
	v_bfe_u32 v77, v86, 16, 1
	v_add3_u32 v77, v86, v77, s22
	s_waitcnt lgkmcnt(2)
	v_bfe_u32 v78, v82, 16, 1
	ds_read2_b32 v[92:93], v75 offset0:148 offset1:156
	v_lshrrev_b32_e32 v77, 16, v77
	v_add3_u32 v78, v82, v78, s22
	ds_read2_b32 v[94:95], v75 offset0:181 offset1:189
	v_and_or_b32 v78, v78, s23, v77
	s_waitcnt lgkmcnt(3)
	v_bfe_u32 v77, v88, 16, 1
	v_add3_u32 v77, v88, v77, s22
	s_waitcnt lgkmcnt(2)
	v_bfe_u32 v79, v90, 16, 1
	ds_read2_b32 v[96:97], v75 offset0:214 offset1:222
	v_lshrrev_b32_e32 v77, 16, v77
	v_add3_u32 v79, v90, v79, s22
	ds_read2_b32 v[98:99], v75 offset0:247 offset1:255
	v_and_or_b32 v79, v79, s23, v77
	s_waitcnt lgkmcnt(3)
	v_bfe_u32 v77, v92, 16, 1
	v_add3_u32 v77, v92, v77, s22
	s_waitcnt lgkmcnt(2)
	v_bfe_u32 v80, v94, 16, 1
	v_lshrrev_b32_e32 v77, 16, v77
	v_add3_u32 v80, v94, v80, s22
	v_and_or_b32 v80, v80, s23, v77
	s_waitcnt lgkmcnt(1)
	v_bfe_u32 v77, v96, 16, 1
	v_add3_u32 v77, v96, v77, s22
	s_waitcnt lgkmcnt(0)
	v_bfe_u32 v81, v98, 16, 1
	v_lshrrev_b32_e32 v77, 16, v77
	v_add3_u32 v81, v98, v81, s22
	v_and_or_b32 v81, v81, s23, v77
	v_or_b32_e32 v77, s11, v228
	v_lshlrev_b32_e32 v100, 11, v77
	v_mov_b32_e32 v101, v67
	v_lshl_add_u64 v[100:101], v[84:85], 0, v[100:101]
	v_bfe_u32 v77, v87, 16, 1
	global_store_dwordx4 v[100:101], v[78:81], off sc1
	v_add3_u32 v77, v87, v77, s22
	v_lshrrev_b32_e32 v77, 16, v77
	v_bfe_u32 v78, v83, 16, 1
	v_add3_u32 v78, v83, v78, s22
	v_and_or_b32 v78, v78, s23, v77
	v_bfe_u32 v77, v89, 16, 1
	v_add3_u32 v77, v89, v77, s22
	v_bfe_u32 v79, v91, 16, 1
	v_lshrrev_b32_e32 v77, 16, v77
	v_add3_u32 v79, v91, v79, s22
	v_and_or_b32 v79, v79, s23, v77
	v_bfe_u32 v77, v93, 16, 1
	v_add3_u32 v77, v93, v77, s22
	v_bfe_u32 v80, v95, 16, 1
	v_lshrrev_b32_e32 v77, 16, v77
	v_add3_u32 v80, v95, v80, s22
	v_and_or_b32 v80, v80, s23, v77
	v_bfe_u32 v77, v97, 16, 1
	v_add3_u32 v77, v97, v77, s22
	v_bfe_u32 v81, v99, 16, 1
	v_lshrrev_b32_e32 v77, 16, v77
	v_add3_u32 v81, v99, v81, s22
	v_and_or_b32 v81, v81, s23, v77
	v_or_b32_e32 v77, s11, v229
	v_lshlrev_b32_e32 v82, 11, v77
	v_mov_b32_e32 v83, v67
	v_lshl_add_u64 v[82:83], v[84:85], 0, v[82:83]
	global_store_dwordx4 v[82:83], v[78:81], off sc1
	s_waitcnt lgkmcnt(0)
	s_mov_b64 s[10:11], 0
.LBB0_1022:
	s_andn2_b64 vcc, exec, s[10:11]
	s_cbranch_vccnz .LBB0_1024
	s_waitcnt lgkmcnt(0)
	ds_read2_b32 v[82:83], v75 offset1:8
	ds_read2_b32 v[86:87], v75 offset0:33 offset1:41
	ds_read2_b32 v[88:89], v75 offset0:66 offset1:74
	ds_read2_b32 v[90:91], v75 offset0:99 offset1:107
	ds_read2_b32 v[92:93], v75 offset0:132 offset1:140
	s_waitcnt lgkmcnt(4)
	v_bfe_u32 v77, v82, 16, 1
	v_add3_u32 v77, v82, v77, s22
	s_waitcnt lgkmcnt(3)
	v_bfe_u32 v78, v86, 16, 1
	v_lshrrev_b32_e32 v77, 16, v77
	v_add3_u32 v78, v86, v78, s22
	ds_read2_b32 v[94:95], v75 offset0:165 offset1:173
	s_add_i32 s6, s25, 0xf800
	v_and_or_b32 v78, v78, s23, v77
	s_waitcnt lgkmcnt(3)
	v_bfe_u32 v77, v88, 16, 1
	s_and_b32 s10, s6, 0xffff
	v_add3_u32 v77, v88, v77, s22
	s_waitcnt lgkmcnt(2)
	v_bfe_u32 v79, v90, 16, 1
	ds_read2_b32 v[96:97], v75 offset0:198 offset1:206
	s_mul_i32 s10, s10, 0xba2f
	v_lshrrev_b32_e32 v77, 16, v77
	v_add3_u32 v79, v90, v79, s22
	ds_read2_b32 v[98:99], v75 offset0:231 offset1:239
	s_lshr_b32 s11, s10, 22
	v_and_or_b32 v79, v79, s23, v77
	s_waitcnt lgkmcnt(3)
	v_bfe_u32 v77, v92, 16, 1
	s_mulk_i32 s11, 0x58
	v_add3_u32 v77, v92, v77, s22
	s_waitcnt lgkmcnt(2)
	v_bfe_u32 v80, v94, 16, 1
	s_sub_i32 s6, s6, s11
	v_lshrrev_b32_e32 v77, 16, v77
	v_add3_u32 v80, v94, v80, s22
	s_lshl_b32 s11, s6, 5
	s_lshl_b32 s6, s6, 6
	v_and_or_b32 v80, v80, s23, v77
	s_waitcnt lgkmcnt(1)
	v_bfe_u32 v77, v96, 16, 1
	s_and_b32 s6, s6, 0x1f00
	s_and_b32 s11, s11, 0x60
	v_add3_u32 v77, v96, v77, s22
	s_waitcnt lgkmcnt(0)
	v_bfe_u32 v81, v98, 16, 1
	s_or_b32 s11, s6, s11
	s_lshr_b32 s6, s10, 15
	v_lshrrev_b32_e32 v77, 16, v77
	v_add3_u32 v81, v98, v81, s22
	s_and_b32 s6, s6, 0x1ff80
	v_and_or_b32 v81, v81, s23, v77
	v_or_b32_e32 v77, s11, v199
	v_lshl_add_u64 v[84:85], v[68:69], 0, s[6:7]
	v_lshlrev_b32_e32 v100, 11, v77
	v_mov_b32_e32 v101, v67
	v_lshl_add_u64 v[100:101], v[84:85], 0, v[100:101]
	v_bfe_u32 v77, v83, 16, 1
	global_store_dwordx4 v[100:101], v[78:81], off sc1
	v_add3_u32 v77, v83, v77, s22
	v_lshrrev_b32_e32 v77, 16, v77
	v_bfe_u32 v78, v87, 16, 1
	v_add3_u32 v78, v87, v78, s22
	v_and_or_b32 v78, v78, s23, v77
	v_bfe_u32 v77, v89, 16, 1
	v_add3_u32 v77, v89, v77, s22
	v_bfe_u32 v79, v91, 16, 1
	v_lshrrev_b32_e32 v77, 16, v77
	v_add3_u32 v79, v91, v79, s22
	v_and_or_b32 v79, v79, s23, v77
	v_bfe_u32 v77, v93, 16, 1
	v_add3_u32 v77, v93, v77, s22
	v_bfe_u32 v80, v95, 16, 1
	v_lshrrev_b32_e32 v77, 16, v77
	v_add3_u32 v80, v95, v80, s22
	v_and_or_b32 v80, v80, s23, v77
	v_bfe_u32 v77, v97, 16, 1
	v_add3_u32 v77, v97, v77, s22
	v_bfe_u32 v81, v99, 16, 1
	v_lshrrev_b32_e32 v77, 16, v77
	v_add3_u32 v81, v99, v81, s22
	v_and_or_b32 v81, v81, s23, v77
	v_or_b32_e32 v77, s11, v227
	v_lshlrev_b32_e32 v82, 11, v77
	v_mov_b32_e32 v83, v67
	ds_read2_b32 v[86:87], v75 offset0:16 offset1:24
	v_lshl_add_u64 v[82:83], v[84:85], 0, v[82:83]
	global_store_dwordx4 v[82:83], v[78:81], off sc1
	ds_read2_b32 v[82:83], v75 offset0:49 offset1:57
	ds_read2_b32 v[88:89], v75 offset0:82 offset1:90
	ds_read2_b32 v[90:91], v75 offset0:115 offset1:123
	s_waitcnt lgkmcnt(3)
	v_bfe_u32 v77, v86, 16, 1
	v_add3_u32 v77, v86, v77, s22
	s_waitcnt lgkmcnt(2)
	v_bfe_u32 v78, v82, 16, 1
	ds_read2_b32 v[92:93], v75 offset0:148 offset1:156
	v_lshrrev_b32_e32 v77, 16, v77
	v_add3_u32 v78, v82, v78, s22
	ds_read2_b32 v[94:95], v75 offset0:181 offset1:189
	v_and_or_b32 v78, v78, s23, v77
	s_waitcnt lgkmcnt(3)
	v_bfe_u32 v77, v88, 16, 1
	v_add3_u32 v77, v88, v77, s22
	s_waitcnt lgkmcnt(2)
	v_bfe_u32 v79, v90, 16, 1
	ds_read2_b32 v[96:97], v75 offset0:214 offset1:222
	v_lshrrev_b32_e32 v77, 16, v77
	v_add3_u32 v79, v90, v79, s22
	ds_read2_b32 v[98:99], v75 offset0:247 offset1:255
	v_and_or_b32 v79, v79, s23, v77
	s_waitcnt lgkmcnt(3)
	v_bfe_u32 v77, v92, 16, 1
	v_add3_u32 v77, v92, v77, s22
	s_waitcnt lgkmcnt(2)
	v_bfe_u32 v80, v94, 16, 1
	v_lshrrev_b32_e32 v77, 16, v77
	v_add3_u32 v80, v94, v80, s22
	v_and_or_b32 v80, v80, s23, v77
	s_waitcnt lgkmcnt(1)
	v_bfe_u32 v77, v96, 16, 1
	v_add3_u32 v77, v96, v77, s22
	s_waitcnt lgkmcnt(0)
	v_bfe_u32 v81, v98, 16, 1
	v_lshrrev_b32_e32 v77, 16, v77
	v_add3_u32 v81, v98, v81, s22
	v_and_or_b32 v81, v81, s23, v77
	v_or_b32_e32 v77, s11, v228
	v_lshlrev_b32_e32 v100, 11, v77
	v_mov_b32_e32 v101, v67
	v_lshl_add_u64 v[100:101], v[84:85], 0, v[100:101]
	v_bfe_u32 v77, v87, 16, 1
	global_store_dwordx4 v[100:101], v[78:81], off sc1
	v_add3_u32 v77, v87, v77, s22
	v_lshrrev_b32_e32 v77, 16, v77
	v_bfe_u32 v78, v83, 16, 1
	v_add3_u32 v78, v83, v78, s22
	v_and_or_b32 v78, v78, s23, v77
	v_bfe_u32 v77, v89, 16, 1
	v_add3_u32 v77, v89, v77, s22
	v_bfe_u32 v79, v91, 16, 1
	v_lshrrev_b32_e32 v77, 16, v77
	v_add3_u32 v79, v91, v79, s22
	v_and_or_b32 v79, v79, s23, v77
	v_bfe_u32 v77, v93, 16, 1
	v_add3_u32 v77, v93, v77, s22
	v_bfe_u32 v80, v95, 16, 1
	v_lshrrev_b32_e32 v77, 16, v77
	v_add3_u32 v80, v95, v80, s22
	v_and_or_b32 v80, v80, s23, v77
	v_bfe_u32 v77, v97, 16, 1
	v_add3_u32 v77, v97, v77, s22
	v_bfe_u32 v81, v99, 16, 1
	v_lshrrev_b32_e32 v77, 16, v77
	v_add3_u32 v81, v99, v81, s22
	v_and_or_b32 v81, v81, s23, v77
	v_or_b32_e32 v77, s11, v229
	v_lshlrev_b32_e32 v82, 11, v77
	v_mov_b32_e32 v83, v67
	v_lshl_add_u64 v[82:83], v[84:85], 0, v[82:83]
	global_store_dwordx4 v[82:83], v[78:81], off sc1
	s_waitcnt lgkmcnt(0)

.LBB0_1025:
	s_andn2_b64 vcc, exec, s[10:11]
	s_cbranch_vccnz .LBB0_1027
	v_add_u32_e32 v77, v203, v226
	v_add_u32_e32 v78, 0x420, v77
	s_waitcnt vmcnt(7)
	ds_write2_b32 v77, v54, v55 offset1:1
	ds_write2_b32 v77, v56, v57 offset0:2 offset1:3
	s_waitcnt vmcnt(6)
	ds_write2_b32 v78, v50, v51 offset1:1
	v_add_u32_e32 v78, 0x428, v77
	ds_write2_b32 v78, v52, v53 offset1:1
	v_add_u32_e32 v78, 0x840, v77
	s_waitcnt vmcnt(5)
	ds_write2_b32 v78, v42, v43 offset1:1
	v_add_u32_e32 v78, 0x848, v77
	ds_write2_b32 v78, v44, v45 offset1:1
	v_add_u32_e32 v78, 0xc60, v77
	s_waitcnt vmcnt(4)
	ds_write2_b32 v78, v30, v31 offset1:1
	v_add_u32_e32 v78, 0xc68, v77
	ds_write2_b32 v78, v32, v33 offset1:1
	v_add_u32_e32 v78, 0x1080, v77
	s_waitcnt vmcnt(3)
	ds_write2_b32 v78, v34, v35 offset1:1
	v_add_u32_e32 v78, 0x1088, v77
	ds_write2_b32 v78, v36, v37 offset1:1
	v_add_u32_e32 v78, 0x14a0, v77
	s_waitcnt vmcnt(2)
	ds_write2_b32 v78, v22, v23 offset1:1
	v_add_u32_e32 v78, 0x14a8, v77
	ds_write2_b32 v78, v24, v25 offset1:1
	v_add_u32_e32 v78, 0x18c0, v77
	s_waitcnt vmcnt(1)
	ds_write2_b32 v78, v26, v27 offset1:1
	v_add_u32_e32 v78, 0x18c8, v77
	ds_write2_b32 v78, v28, v29 offset1:1
	v_add_u32_e32 v78, 0x1ce0, v77
	v_add_u32_e32 v77, 0x1ce8, v77
	s_waitcnt vmcnt(0)
	ds_write2_b32 v78, v10, v11 offset1:1
	ds_write2_b32 v77, v12, v13 offset1:1
	s_waitcnt lgkmcnt(0)
	ds_read2_b32 v[82:83], v75 offset1:8
	ds_read2_b32 v[86:87], v75 offset0:33 offset1:41
	ds_read2_b32 v[88:89], v75 offset0:66 offset1:74
	ds_read2_b32 v[90:91], v75 offset0:99 offset1:107
	ds_read2_b32 v[92:93], v75 offset0:132 offset1:140
	s_waitcnt lgkmcnt(4)
	v_bfe_u32 v77, v82, 16, 1
	v_add3_u32 v77, v82, v77, s22
	s_waitcnt lgkmcnt(3)
	v_bfe_u32 v78, v86, 16, 1
	v_lshrrev_b32_e32 v77, 16, v77
	v_add3_u32 v78, v86, v78, s22
	ds_read2_b32 v[94:95], v75 offset0:165 offset1:173
	v_and_or_b32 v78, v78, s23, v77
	s_waitcnt lgkmcnt(3)
	v_bfe_u32 v77, v88, 16, 1
	v_add3_u32 v77, v88, v77, s22
	s_waitcnt lgkmcnt(2)
	v_bfe_u32 v79, v90, 16, 1
	ds_read2_b32 v[96:97], v75 offset0:198 offset1:206
	v_lshrrev_b32_e32 v77, 16, v77
	v_add3_u32 v79, v90, v79, s22
	ds_read2_b32 v[98:99], v75 offset0:231 offset1:239
	v_and_or_b32 v79, v79, s23, v77
	s_waitcnt lgkmcnt(3)
	v_bfe_u32 v77, v92, 16, 1
	v_add3_u32 v77, v92, v77, s22
	s_waitcnt lgkmcnt(2)
	v_bfe_u32 v80, v94, 16, 1
	v_lshrrev_b32_e32 v77, 16, v77
	v_add3_u32 v80, v94, v80, s22
	v_and_or_b32 v80, v80, s23, v77
	s_waitcnt lgkmcnt(1)
	v_bfe_u32 v77, v96, 16, 1
	s_add_i32 s6, s20, 0xffff4000
	v_add3_u32 v77, v96, v77, s22
	s_waitcnt lgkmcnt(0)
	v_bfe_u32 v81, v98, 16, 1
	s_and_b32 s10, s21, 0xfc0
	s_and_b32 s11, s6, 0x3e0
	v_lshrrev_b32_e32 v77, 16, v77
	v_add3_u32 v81, v98, v81, s22
	s_lshl_b32 s6, s10, 1
	v_and_or_b32 v81, v81, s23, v77
	v_or_b32_e32 v77, s11, v199
	v_lshl_add_u64 v[84:85], v[70:71], 0, s[6:7]
	v_lshlrev_b32_e32 v100, 11, v77
	v_mov_b32_e32 v101, v67
	v_lshl_add_u64 v[100:101], v[84:85], 0, v[100:101]
	v_bfe_u32 v77, v83, 16, 1
	global_store_dwordx4 v[100:101], v[78:81], off sc1
	v_add3_u32 v77, v83, v77, s22
	v_lshrrev_b32_e32 v77, 16, v77
	v_bfe_u32 v78, v87, 16, 1
	v_add3_u32 v78, v87, v78, s22
	v_and_or_b32 v78, v78, s23, v77
	v_bfe_u32 v77, v89, 16, 1
	v_add3_u32 v77, v89, v77, s22
	v_bfe_u32 v79, v91, 16, 1
	v_lshrrev_b32_e32 v77, 16, v77
	v_add3_u32 v79, v91, v79, s22
	v_and_or_b32 v79, v79, s23, v77
	v_bfe_u32 v77, v93, 16, 1
	v_add3_u32 v77, v93, v77, s22
	v_bfe_u32 v80, v95, 16, 1
	v_lshrrev_b32_e32 v77, 16, v77
	v_add3_u32 v80, v95, v80, s22
	v_and_or_b32 v80, v80, s23, v77
	v_bfe_u32 v77, v97, 16, 1
	v_add3_u32 v77, v97, v77, s22
	v_bfe_u32 v81, v99, 16, 1
	v_lshrrev_b32_e32 v77, 16, v77
	v_add3_u32 v81, v99, v81, s22
	v_and_or_b32 v81, v81, s23, v77
	v_or_b32_e32 v77, s11, v227
	v_lshlrev_b32_e32 v82, 11, v77
	v_mov_b32_e32 v83, v67
	ds_read2_b32 v[86:87], v75 offset0:16 offset1:24
	v_lshl_add_u64 v[82:83], v[84:85], 0, v[82:83]
	global_store_dwordx4 v[82:83], v[78:81], off sc1
	ds_read2_b32 v[82:83], v75 offset0:49 offset1:57
	ds_read2_b32 v[88:89], v75 offset0:82 offset1:90
	ds_read2_b32 v[90:91], v75 offset0:115 offset1:123
	s_waitcnt lgkmcnt(3)
	v_bfe_u32 v77, v86, 16, 1
	v_add3_u32 v77, v86, v77, s22
	s_waitcnt lgkmcnt(2)
	v_bfe_u32 v78, v82, 16, 1
	ds_read2_b32 v[92:93], v75 offset0:148 offset1:156
	v_lshrrev_b32_e32 v77, 16, v77
	v_add3_u32 v78, v82, v78, s22
	ds_read2_b32 v[94:95], v75 offset0:181 offset1:189
	v_and_or_b32 v78, v78, s23, v77
	s_waitcnt lgkmcnt(3)
	v_bfe_u32 v77, v88, 16, 1
	v_add3_u32 v77, v88, v77, s22
	s_waitcnt lgkmcnt(2)
	v_bfe_u32 v79, v90, 16, 1
	ds_read2_b32 v[96:97], v75 offset0:214 offset1:222
	v_lshrrev_b32_e32 v77, 16, v77
	v_add3_u32 v79, v90, v79, s22
	ds_read2_b32 v[98:99], v75 offset0:247 offset1:255
	v_and_or_b32 v79, v79, s23, v77
	s_waitcnt lgkmcnt(3)
	v_bfe_u32 v77, v92, 16, 1
	v_add3_u32 v77, v92, v77, s22
	s_waitcnt lgkmcnt(2)
	v_bfe_u32 v80, v94, 16, 1
	v_lshrrev_b32_e32 v77, 16, v77
	v_add3_u32 v80, v94, v80, s22
	v_and_or_b32 v80, v80, s23, v77
	s_waitcnt lgkmcnt(1)
	v_bfe_u32 v77, v96, 16, 1
	v_add3_u32 v77, v96, v77, s22
	s_waitcnt lgkmcnt(0)
	v_bfe_u32 v81, v98, 16, 1
	v_lshrrev_b32_e32 v77, 16, v77
	v_add3_u32 v81, v98, v81, s22
	v_and_or_b32 v81, v81, s23, v77
	v_or_b32_e32 v77, s11, v228
	v_lshlrev_b32_e32 v100, 11, v77
	v_mov_b32_e32 v101, v67
	v_lshl_add_u64 v[100:101], v[84:85], 0, v[100:101]
	v_bfe_u32 v77, v87, 16, 1
	global_store_dwordx4 v[100:101], v[78:81], off sc1
	v_add3_u32 v77, v87, v77, s22
	v_lshrrev_b32_e32 v77, 16, v77
	v_bfe_u32 v78, v83, 16, 1
	v_add3_u32 v78, v83, v78, s22
	v_and_or_b32 v78, v78, s23, v77
	v_bfe_u32 v77, v89, 16, 1
	v_add3_u32 v77, v89, v77, s22
	v_bfe_u32 v79, v91, 16, 1
	v_lshrrev_b32_e32 v77, 16, v77
	v_add3_u32 v79, v91, v79, s22
	v_and_or_b32 v79, v79, s23, v77
	v_bfe_u32 v77, v93, 16, 1
	v_add3_u32 v77, v93, v77, s22
	v_bfe_u32 v80, v95, 16, 1
	v_lshrrev_b32_e32 v77, 16, v77
	v_add3_u32 v80, v95, v80, s22
	v_and_or_b32 v80, v80, s23, v77
	v_bfe_u32 v77, v97, 16, 1
	v_add3_u32 v77, v97, v77, s22
	v_bfe_u32 v81, v99, 16, 1
	v_lshrrev_b32_e32 v77, 16, v77
	v_add3_u32 v81, v99, v81, s22
	v_and_or_b32 v81, v81, s23, v77
	v_or_b32_e32 v77, s11, v229
	v_lshlrev_b32_e32 v82, 11, v77
	v_mov_b32_e32 v83, v67
	v_lshl_add_u64 v[82:83], v[84:85], 0, v[82:83]
	global_store_dwordx4 v[82:83], v[78:81], off sc1
	s_waitcnt lgkmcnt(0)

.LBB0_1033:
	s_mul_hi_i32 s6, s25, 0x2aaaaaab
	s_lshr_b32 s10, s6, 31
	s_ashr_i32 s6, s6, 4
	s_add_i32 s6, s6, s10
	s_mul_i32 s10, s6, 0xffffffa0
	s_add_i32 s11, s25, s10
	s_lshl_b32 s10, s6, 6
	s_cmp_lt_i32 s11, 16
	s_cselect_b64 vcc, -1, 0
	v_cndmask_b32_e32 v78, 1.0, v76, vcc
	s_waitcnt vmcnt(7)
	v_pk_mul_f32 v[54:55], v[78:79], v[54:55] op_sel_hi:[0,1]
	v_add_u32_e32 v77, v203, v226
	ds_write2_b32 v77, v54, v55 offset1:1
	v_pk_mul_f32 v[54:55], v[78:79], v[56:57] op_sel_hi:[0,1]
	ds_write2_b32 v77, v54, v55 offset0:2 offset1:3
	s_waitcnt vmcnt(6)
	v_pk_mul_f32 v[50:51], v[78:79], v[50:51] op_sel_hi:[0,1]
	v_add_u32_e32 v54, 0x420, v77
	ds_write2_b32 v54, v50, v51 offset1:1
	v_pk_mul_f32 v[50:51], v[78:79], v[52:53] op_sel_hi:[0,1]
	v_add_u32_e32 v52, 0x428, v77
	ds_write2_b32 v52, v50, v51 offset1:1
	s_waitcnt vmcnt(5)
	v_pk_mul_f32 v[42:43], v[78:79], v[42:43] op_sel_hi:[0,1]
	v_add_u32_e32 v50, 0x840, v77
	ds_write2_b32 v50, v42, v43 offset1:1
	v_pk_mul_f32 v[42:43], v[78:79], v[44:45] op_sel_hi:[0,1]
	v_add_u32_e32 v44, 0x848, v77
	ds_write2_b32 v44, v42, v43 offset1:1
	s_waitcnt vmcnt(4)
	v_pk_mul_f32 v[30:31], v[78:79], v[30:31] op_sel_hi:[0,1]
	v_add_u32_e32 v42, 0xc60, v77
	ds_write2_b32 v42, v30, v31 offset1:1
	v_pk_mul_f32 v[30:31], v[78:79], v[32:33] op_sel_hi:[0,1]
	v_add_u32_e32 v32, 0xc68, v77
	ds_write2_b32 v32, v30, v31 offset1:1
	s_waitcnt vmcnt(3)
	v_pk_mul_f32 v[30:31], v[78:79], v[34:35] op_sel_hi:[0,1]
	v_add_u32_e32 v32, 0x1080, v77
	ds_write2_b32 v32, v30, v31 offset1:1
	v_pk_mul_f32 v[30:31], v[78:79], v[36:37] op_sel_hi:[0,1]
	v_add_u32_e32 v32, 0x1088, v77
	ds_write2_b32 v32, v30, v31 offset1:1
	s_waitcnt vmcnt(2)
	v_pk_mul_f32 v[22:23], v[78:79], v[22:23] op_sel_hi:[0,1]
	v_add_u32_e32 v30, 0x14a0, v77
	ds_write2_b32 v30, v22, v23 offset1:1
	v_pk_mul_f32 v[22:23], v[78:79], v[24:25] op_sel_hi:[0,1]
	v_add_u32_e32 v24, 0x14a8, v77
	ds_write2_b32 v24, v22, v23 offset1:1
	s_waitcnt vmcnt(1)
	v_pk_mul_f32 v[22:23], v[26:27], v[78:79] op_sel_hi:[1,0]
	v_add_u32_e32 v24, 0x18c0, v77
	ds_write2_b32 v24, v22, v23 offset1:1
	v_pk_mul_f32 v[22:23], v[28:29], v[78:79] op_sel_hi:[1,0]
	v_add_u32_e32 v24, 0x18c8, v77
	ds_write2_b32 v24, v22, v23 offset1:1
	s_waitcnt vmcnt(0)
	v_pk_mul_f32 v[10:11], v[10:11], v[78:79] op_sel_hi:[1,0]
	v_add_u32_e32 v22, 0x1ce0, v77
	ds_write2_b32 v22, v10, v11 offset1:1
	v_pk_mul_f32 v[10:11], v[12:13], v[78:79] op_sel_hi:[1,0]
	v_add_u32_e32 v12, 0x1ce8, v77
	ds_write2_b32 v12, v10, v11 offset1:1
	s_waitcnt lgkmcnt(0)
	ds_read2_b32 v[22:23], v75 offset1:8
	ds_read2_b32 v[26:27], v75 offset0:33 offset1:41
	ds_read2_b32 v[28:29], v75 offset0:66 offset1:74
	ds_read2_b32 v[30:31], v75 offset0:99 offset1:107
	ds_read2_b32 v[32:33], v75 offset0:132 offset1:140
	s_waitcnt lgkmcnt(4)
	v_bfe_u32 v10, v22, 16, 1
	v_add3_u32 v10, v22, v10, s22
	s_waitcnt lgkmcnt(3)
	v_bfe_u32 v11, v26, 16, 1
	v_lshrrev_b32_e32 v10, 16, v10
	v_add3_u32 v11, v26, v11, s22
	ds_read2_b32 v[34:35], v75 offset0:165 offset1:173
	v_and_or_b32 v10, v11, s23, v10
	s_waitcnt lgkmcnt(3)
	v_bfe_u32 v11, v28, 16, 1
	v_add3_u32 v11, v28, v11, s22
	s_waitcnt lgkmcnt(2)
	v_bfe_u32 v12, v30, 16, 1
	ds_read2_b32 v[36:37], v75 offset0:198 offset1:206
	v_lshrrev_b32_e32 v11, 16, v11
	v_add3_u32 v12, v30, v12, s22
	ds_read2_b32 v[42:43], v75 offset0:231 offset1:239
	v_and_or_b32 v11, v12, s23, v11
	s_waitcnt lgkmcnt(3)
	v_bfe_u32 v12, v32, 16, 1
	v_add3_u32 v12, v32, v12, s22
	s_waitcnt lgkmcnt(2)
	v_bfe_u32 v13, v34, 16, 1
	s_mulk_i32 s6, 0xf400
	v_lshrrev_b32_e32 v12, 16, v12
	v_add3_u32 v13, v34, v13, s22
	s_add_i32 s6, s6, s20
	v_and_or_b32 v12, v13, s23, v12
	s_waitcnt lgkmcnt(1)
	v_bfe_u32 v13, v36, 16, 1
	v_add_u32_e32 v44, s6, v199
	s_ashr_i32 s11, s10, 31
	v_add3_u32 v13, v36, v13, s22
	s_waitcnt lgkmcnt(0)
	v_bfe_u32 v22, v42, 16, 1
	v_ashrrev_i32_e32 v45, 31, v44
	v_lshl_add_u64 v[24:25], s[10:11], 1, v[72:73]
	v_lshrrev_b32_e32 v13, 16, v13
	v_add3_u32 v22, v42, v22, s22
	v_lshlrev_b64 v[50:51], 11, v[44:45]
	v_and_or_b32 v13, v22, s23, v13
	v_lshl_add_u64 v[50:51], v[24:25], 0, v[50:51]
	global_store_dwordx4 v[50:51], v[10:13], off sc1
	v_bfe_u32 v22, v43, 16, 1
	v_add3_u32 v22, v43, v22, s22
	v_bfe_u32 v10, v23, 16, 1
	v_add3_u32 v10, v23, v10, s22
	v_bfe_u32 v11, v27, 16, 1
	v_lshrrev_b32_e32 v10, 16, v10
	v_add3_u32 v11, v27, v11, s22
	v_and_or_b32 v10, v11, s23, v10
	v_bfe_u32 v11, v29, 16, 1
	v_add3_u32 v11, v29, v11, s22
	v_bfe_u32 v12, v31, 16, 1
	v_lshrrev_b32_e32 v11, 16, v11
	v_add3_u32 v12, v31, v12, s22
	v_and_or_b32 v11, v12, s23, v11
	v_bfe_u32 v12, v33, 16, 1
	v_add3_u32 v12, v33, v12, s22
	v_bfe_u32 v13, v35, 16, 1
	v_lshrrev_b32_e32 v12, 16, v12
	v_add3_u32 v13, v35, v13, s22
	v_and_or_b32 v12, v13, s23, v12
	v_bfe_u32 v13, v37, 16, 1
	v_add3_u32 v13, v37, v13, s22
	v_lshrrev_b32_e32 v13, 16, v13
	v_and_or_b32 v13, v22, s23, v13
	v_add_u32_e32 v22, 8, v44
	v_ashrrev_i32_e32 v23, 31, v22
	v_lshlrev_b64 v[22:23], 11, v[22:23]
	ds_read2_b32 v[26:27], v75 offset0:16 offset1:24
	v_lshl_add_u64 v[22:23], v[24:25], 0, v[22:23]
	global_store_dwordx4 v[22:23], v[10:13], off sc1
	ds_read2_b32 v[22:23], v75 offset0:49 offset1:57
	ds_read2_b32 v[28:29], v75 offset0:82 offset1:90
	ds_read2_b32 v[30:31], v75 offset0:115 offset1:123
	s_waitcnt lgkmcnt(3)
	v_bfe_u32 v10, v26, 16, 1
	v_add3_u32 v10, v26, v10, s22
	s_waitcnt lgkmcnt(2)
	v_bfe_u32 v11, v22, 16, 1
	ds_read2_b32 v[32:33], v75 offset0:148 offset1:156
	v_lshrrev_b32_e32 v10, 16, v10
	v_add3_u32 v11, v22, v11, s22
	ds_read2_b32 v[34:35], v75 offset0:181 offset1:189
	v_and_or_b32 v10, v11, s23, v10
	s_waitcnt lgkmcnt(3)
	v_bfe_u32 v11, v28, 16, 1
	v_add3_u32 v11, v28, v11, s22
	s_waitcnt lgkmcnt(2)
	v_bfe_u32 v12, v30, 16, 1
	ds_read2_b32 v[36:37], v75 offset0:214 offset1:222
	v_lshrrev_b32_e32 v11, 16, v11
	v_add3_u32 v12, v30, v12, s22
	ds_read2_b32 v[42:43], v75 offset0:247 offset1:255
	v_and_or_b32 v11, v12, s23, v11
	s_waitcnt lgkmcnt(3)
	v_bfe_u32 v12, v32, 16, 1
	v_add3_u32 v12, v32, v12, s22
	s_waitcnt lgkmcnt(2)
	v_bfe_u32 v13, v34, 16, 1
	v_lshrrev_b32_e32 v12, 16, v12
	v_add3_u32 v13, v34, v13, s22
	v_and_or_b32 v12, v13, s23, v12
	s_waitcnt lgkmcnt(1)
	v_bfe_u32 v13, v36, 16, 1
	v_add_u32_e32 v50, 16, v44
	v_add3_u32 v13, v36, v13, s22
	s_waitcnt lgkmcnt(0)
	v_bfe_u32 v22, v42, 16, 1
	v_ashrrev_i32_e32 v51, 31, v50
	v_lshrrev_b32_e32 v13, 16, v13
	v_add3_u32 v22, v42, v22, s22
	v_lshlrev_b64 v[50:51], 11, v[50:51]
	v_and_or_b32 v13, v22, s23, v13
	v_lshl_add_u64 v[50:51], v[24:25], 0, v[50:51]
	global_store_dwordx4 v[50:51], v[10:13], off sc1
	v_bfe_u32 v22, v43, 16, 1
	v_add3_u32 v22, v43, v22, s22
	v_bfe_u32 v10, v27, 16, 1
	v_add3_u32 v10, v27, v10, s22
	v_bfe_u32 v11, v23, 16, 1
	v_lshrrev_b32_e32 v10, 16, v10
	v_add3_u32 v11, v23, v11, s22
	v_and_or_b32 v10, v11, s23, v10
	v_bfe_u32 v11, v29, 16, 1
	v_add3_u32 v11, v29, v11, s22
	v_bfe_u32 v12, v31, 16, 1
	v_lshrrev_b32_e32 v11, 16, v11
	v_add3_u32 v12, v31, v12, s22
	v_and_or_b32 v11, v12, s23, v11
	v_bfe_u32 v12, v33, 16, 1
	v_add3_u32 v12, v33, v12, s22
	v_bfe_u32 v13, v35, 16, 1
	v_lshrrev_b32_e32 v12, 16, v12
	v_add3_u32 v13, v35, v13, s22
	v_and_or_b32 v12, v13, s23, v12
	v_bfe_u32 v13, v37, 16, 1
	v_add3_u32 v13, v37, v13, s22
	v_lshrrev_b32_e32 v13, 16, v13
	v_and_or_b32 v13, v22, s23, v13
	v_add_u32_e32 v22, 24, v44
	v_ashrrev_i32_e32 v23, 31, v22
	v_lshlrev_b64 v[22:23], 11, v[22:23]
	v_lshl_add_u64 v[22:23], v[24:25], 0, v[22:23]
	global_store_dwordx4 v[22:23], v[10:13], off sc1
	s_waitcnt lgkmcnt(0)
	s_branch .LBB0_1012

.LBB0_1093:
	v_add_u32_e32 v129, 0, v127
	ds_read_b128 v[130:133], v129
	ds_read_b128 v[134:137], v129 offset:16
	ds_read_b128 v[138:141], v129 offset:32
	ds_read_b128 v[142:145], v129 offset:48
	v_add_u32_e32 v146, 0, v126
	s_waitcnt lgkmcnt(3)
	v_fma_f32 v130, v130, v98, v128
	v_fmac_f32_e32 v130, v131, v99
	v_fmac_f32_e32 v130, v132, v100
	v_fmac_f32_e32 v130, v133, v101
	s_waitcnt lgkmcnt(2)
	v_fmac_f32_e32 v130, v134, v102
	v_fmac_f32_e32 v130, v135, v103
	v_fmac_f32_e32 v130, v136, v104
	v_fmac_f32_e32 v130, v137, v105
	s_waitcnt lgkmcnt(1)
	v_fmac_f32_e32 v130, v138, v106
	v_fmac_f32_e32 v130, v139, v107
	v_fmac_f32_e32 v130, v140, v108
	v_fmac_f32_e32 v130, v141, v109
	s_waitcnt lgkmcnt(0)
	v_fmac_f32_e32 v130, v142, v110
	v_fmac_f32_e32 v130, v143, v111
	v_fmac_f32_e32 v130, v144, v112
	v_fmac_f32_e32 v130, v145, v113
	v_min_f32_e32 v131, 0, v130
	v_mul_f32_e64 v130, |v130|, s72
	v_exp_f32_e32 v130, v130
	v_add_u32_e32 v147, 0x10a00, v146
	v_add_u32_e32 v156, 0x10c04, v146
	v_add_u32_e32 v158, 0x10e08, v146
	v_add_f32_e32 v130, 1.0, v130
	v_cmp_gt_f32_e64 s[0:1], s73, v130
	s_add_i32 s9, s9, -4
	v_add_u32_e32 v126, 0x810, v126
	v_cndmask_b32_e64 v132, 0, 32, s[0:1]
	v_ldexp_f32 v130, v130, v132
	v_log_f32_e32 v130, v130
	v_cndmask_b32_e64 v132, 0, v155, s[0:1]
	v_add_u32_e32 v127, 0x100, v127
	v_add_u32_e32 v146, 0x1100c, v146
	v_mul_f32_e32 v133, 0x3f317217, v130
	v_fma_f32 v133, v130, s74, -v133
	v_fmac_f32_e32 v133, 0x3377d1cf, v130
	v_fmac_f32_e32 v133, 0x3f317217, v130
	v_cmp_lt_f32_e64 s[0:1], |v130|, s75
	s_cmp_eq_u32 s9, 0
	s_nop 0
	v_cndmask_b32_e64 v130, v130, v133, s[0:1]
	v_sub_f32_e32 v130, v130, v132
	v_sub_f32_e32 v130, v131, v130
	v_fmac_f32_e32 v114, 0x3d800000, v130
	ds_write_b32 v147, v114
	ds_read_b128 v[130:133], v129 offset:64
	ds_read_b128 v[134:137], v129 offset:80
	ds_read_b128 v[138:141], v129 offset:96
	ds_read_b128 v[142:145], v129 offset:112
	s_waitcnt lgkmcnt(3)
	v_fma_f32 v130, v130, v98, v128
	v_fmac_f32_e32 v130, v131, v99
	v_fmac_f32_e32 v130, v132, v100
	v_fmac_f32_e32 v130, v133, v101
	s_waitcnt lgkmcnt(2)
	v_fmac_f32_e32 v130, v134, v102
	v_fmac_f32_e32 v130, v135, v103
	v_fmac_f32_e32 v130, v136, v104
	v_fmac_f32_e32 v130, v137, v105
	s_waitcnt lgkmcnt(1)
	v_fmac_f32_e32 v130, v138, v106
	v_fmac_f32_e32 v130, v139, v107
	v_fmac_f32_e32 v130, v140, v108
	v_fmac_f32_e32 v130, v141, v109
	s_waitcnt lgkmcnt(0)
	v_fmac_f32_e32 v130, v142, v110
	v_fmac_f32_e32 v130, v143, v111
	v_fmac_f32_e32 v130, v144, v112
	v_fmac_f32_e32 v130, v145, v113
	v_min_f32_e32 v131, 0, v130
	v_mul_f32_e64 v130, |v130|, s72
	v_exp_f32_e32 v130, v130
	s_nop 0
	v_add_f32_e32 v130, 1.0, v130
	v_cmp_gt_f32_e64 s[0:1], s73, v130
	s_nop 1
	v_cndmask_b32_e64 v132, 0, 32, s[0:1]
	v_ldexp_f32 v130, v130, v132
	v_log_f32_e32 v130, v130
	v_cndmask_b32_e64 v132, 0, v155, s[0:1]
	v_mul_f32_e32 v133, 0x3f317217, v130
	v_fma_f32 v133, v130, s74, -v133
	v_fmac_f32_e32 v133, 0x3377d1cf, v130
	v_fmac_f32_e32 v133, 0x3f317217, v130
	v_cmp_lt_f32_e64 s[0:1], |v130|, s75
	s_nop 1
	v_cndmask_b32_e64 v130, v130, v133, s[0:1]
	v_sub_f32_e32 v130, v130, v132
	v_sub_f32_e32 v130, v131, v130
	v_fmac_f32_e32 v114, 0x3d800000, v130
	ds_write_b32 v156, v114
	ds_read_b128 v[130:133], v129 offset:128
	ds_read_b128 v[134:137], v129 offset:144
	ds_read_b128 v[138:141], v129 offset:160
	ds_read_b128 v[142:145], v129 offset:176
	s_waitcnt lgkmcnt(3)
	v_fma_f32 v130, v130, v98, v128
	v_fmac_f32_e32 v130, v131, v99
	v_fmac_f32_e32 v130, v132, v100
	v_fmac_f32_e32 v130, v133, v101
	s_waitcnt lgkmcnt(2)
	v_fmac_f32_e32 v130, v134, v102
	v_fmac_f32_e32 v130, v135, v103
	v_fmac_f32_e32 v130, v136, v104
	v_fmac_f32_e32 v130, v137, v105
	s_waitcnt lgkmcnt(1)
	v_fmac_f32_e32 v130, v138, v106
	v_fmac_f32_e32 v130, v139, v107
	v_fmac_f32_e32 v130, v140, v108
	v_fmac_f32_e32 v130, v141, v109
	s_waitcnt lgkmcnt(0)
	v_fmac_f32_e32 v130, v142, v110
	v_fmac_f32_e32 v130, v143, v111
	v_fmac_f32_e32 v130, v144, v112
	v_fmac_f32_e32 v130, v145, v113
	v_min_f32_e32 v131, 0, v130
	v_mul_f32_e64 v130, |v130|, s72
	v_exp_f32_e32 v130, v130
	s_nop 0
	v_add_f32_e32 v130, 1.0, v130
	v_cmp_gt_f32_e64 s[0:1], s73, v130
	s_nop 1
	v_cndmask_b32_e64 v132, 0, 32, s[0:1]
	v_ldexp_f32 v130, v130, v132
	v_log_f32_e32 v130, v130
	v_cndmask_b32_e64 v132, 0, v155, s[0:1]
	v_mul_f32_e32 v133, 0x3f317217, v130
	v_fma_f32 v133, v130, s74, -v133
	v_fmac_f32_e32 v133, 0x3377d1cf, v130
	v_fmac_f32_e32 v133, 0x3f317217, v130
	v_cmp_lt_f32_e64 s[0:1], |v130|, s75
	s_nop 1
	v_cndmask_b32_e64 v130, v130, v133, s[0:1]
	v_sub_f32_e32 v130, v130, v132
	v_sub_f32_e32 v130, v131, v130
	v_fmac_f32_e32 v114, 0x3d800000, v130
	ds_write_b32 v158, v114
	ds_read_b128 v[130:133], v129 offset:192
	ds_read_b128 v[134:137], v129 offset:208
	ds_read_b128 v[138:141], v129 offset:224
	ds_read_b128 v[142:145], v129 offset:240
	s_waitcnt lgkmcnt(3)
	v_fma_f32 v129, v130, v98, v128
	v_fmac_f32_e32 v129, v131, v99
	v_fmac_f32_e32 v129, v132, v100
	v_fmac_f32_e32 v129, v133, v101
	s_waitcnt lgkmcnt(2)
	v_fmac_f32_e32 v129, v134, v102
	v_fmac_f32_e32 v129, v135, v103
	v_fmac_f32_e32 v129, v136, v104
	v_fmac_f32_e32 v129, v137, v105
	s_waitcnt lgkmcnt(1)
	v_fmac_f32_e32 v129, v138, v106
	v_fmac_f32_e32 v129, v139, v107
	v_fmac_f32_e32 v129, v140, v108
	v_fmac_f32_e32 v129, v141, v109
	s_waitcnt lgkmcnt(0)
	v_fmac_f32_e32 v129, v142, v110
	v_fmac_f32_e32 v129, v143, v111
	v_fmac_f32_e32 v129, v144, v112
	v_fmac_f32_e32 v129, v145, v113
	v_mul_f32_e64 v130, |v129|, s72
	v_exp_f32_e32 v130, v130
	v_min_f32_e32 v129, 0, v129
	v_add_f32_e32 v130, 1.0, v130
	v_cmp_gt_f32_e64 s[0:1], s73, v130
	s_nop 1
	v_cndmask_b32_e64 v131, 0, 32, s[0:1]
	v_ldexp_f32 v130, v130, v131
	v_log_f32_e32 v130, v130
	v_cndmask_b32_e64 v131, 0, v155, s[0:1]
	v_mul_f32_e32 v132, 0x3f317217, v130
	v_fma_f32 v132, v130, s74, -v132
	v_fmac_f32_e32 v132, 0x3377d1cf, v130
	v_fmac_f32_e32 v132, 0x3f317217, v130
	v_cmp_lt_f32_e64 s[0:1], |v130|, s75
	s_nop 1
	v_cndmask_b32_e64 v130, v130, v132, s[0:1]
	v_sub_f32_e32 v130, v130, v131
	v_sub_f32_e32 v129, v129, v130
	v_fmac_f32_e32 v114, 0x3d800000, v129
	ds_write_b32 v146, v114
	s_cbranch_scc0 .LBB0_1093
	s_or_b32 s48, s8, s45
	v_bfe_u32 v158, v124, 5, 1
	s_ashr_i32 s50, s17, 6
	s_ashr_i32 s49, s48, 31
	v_lshl_or_b32 v160, s50, 1, v158
	s_lshl_b64 s[68:69], s[48:49], 4
	v_lshrrev_b32_e32 v98, 1, v124
	v_and_or_b32 v98, v98, 8, s68
	v_mov_b32_e32 v99, s69
	s_ashr_i32 s51, s50, 31
	v_lshlrev_b32_e32 v184, 5, v160
	v_lshl_add_u32 v159, v124, 2, s76
	v_lshl_add_u64 v[98:99], v[98:99], 0, s[50:51]
	v_add_u32_e32 v111, s76, v184
	ds_write_b32 v159, v114
	s_waitcnt lgkmcnt(0)
	s_barrier
	v_lshlrev_b64 v[102:103], 10, v[98:99]
	ds_read_b128 v[104:107], v111
	ds_read_b128 v[98:101], v111 offset:16
	ds_read_b128 v[128:131], v111 offset:512
	ds_read_b128 v[132:135], v111 offset:1024
	ds_read_b128 v[136:139], v111 offset:1536
	v_and_b32_e32 v156, 31, v124
	v_mul_u32_u24_e32 v110, 0x408, v156
	s_add_i32 s18, 0, 0x10a00
	v_cmp_gt_u32_e64 s[0:1], 8, v156
	s_waitcnt lgkmcnt(2)
	v_add_f32_e32 v126, v104, v128
	v_and_b32_e32 v108, 24, v124
	v_cndmask_b32_e64 v109, v104, 0, s[0:1]
	v_add3_u32 v104, s18, v110, v184
	ds_read2_b64 v[142:145], v104 offset1:1
	ds_read2_b64 v[178:181], v104 offset0:2 offset1:3
	v_cmp_lt_u32_e64 s[8:9], 15, v156
	v_cmp_eq_u32_e64 s[10:11], 24, v108
	s_waitcnt lgkmcnt(3)
	v_mov_b32_e32 v108, v132
	v_cndmask_b32_e64 v112, 0, v128, s[8:9]
	v_add_f32_e32 v109, v109, v112
	v_cndmask_b32_e64 v113, 0, v132, s[10:11]
	s_waitcnt lgkmcnt(2)
	v_mov_b32_e32 v112, v136
	v_pk_add_f32 v[108:109], v[108:109], v[112:113]
	s_waitcnt lgkmcnt(1)
	v_mov_b32_e32 v127, v142
	v_pk_add_f32 v[108:109], v[126:127], v[108:109]
	v_cndmask_b32_e64 v127, 0, v133, s[10:11]
	v_sub_f32_e32 v108, v108, v109
	v_mul_f32_e32 v108, 0x3fb8aa3b, v108
	v_mul_f32_e32 v104, 0x3fb8aa3b, v109
	v_mul_f32_e32 v110, 0xbfb8aa3b, v109
	v_exp_f32_e32 v128, v108
	v_cndmask_b32_e64 v108, v105, 0, s[0:1]
	v_cndmask_b32_e64 v109, 0, v129, s[8:9]
	v_add_f32_e32 v109, v108, v109
	v_mov_b32_e32 v108, v133
	v_mov_b32_e32 v126, v137
	v_add_f32_e32 v142, v105, v129
	v_pk_add_f32 v[108:109], v[108:109], v[126:127]
	s_waitcnt vmcnt(7)
	v_lshlrev_b32_e32 v126, 16, v94
	v_pk_add_f32 v[108:109], v[142:143], v[108:109]
	v_and_b32_e32 v127, 0xffff0000, v94
	v_mul_f32_e32 v94, 0xbfb8aa3b, v109
	v_exp_f32_e32 v112, v110
	v_mul_f32_e32 v105, 0x3fb8aa3b, v109
	v_exp_f32_e32 v113, v94
	v_exp_f32_e32 v104, v104
	v_exp_f32_e32 v105, v105
	s_waitcnt vmcnt(6)
	v_lshlrev_b32_e32 v140, 16, v90
	v_and_b32_e32 v141, 0xffff0000, v90
	v_sub_f32_e32 v90, v108, v109
	v_mul_f32_e32 v90, 0x3fb8aa3b, v90
	v_exp_f32_e32 v142, v90
	v_cndmask_b32_e64 v90, v106, 0, s[0:1]
	v_cndmask_b32_e64 v94, 0, v130, s[8:9]
	v_pk_mul_f32 v[182:183], v[112:113], v[140:141]
	v_add_f32_e32 v109, v90, v94
	v_cndmask_b32_e64 v113, 0, v134, s[10:11]
	v_mov_b32_e32 v108, v134
	v_mov_b32_e32 v112, v138
	v_pk_mul_f32 v[104:105], v[104:105], v[126:127]
	v_add_f32_e32 v126, v106, v130
	v_pk_add_f32 v[108:109], v[108:109], v[112:113]
	v_mov_b32_e32 v127, v144
	v_pk_add_f32 v[108:109], v[126:127], v[108:109]
	v_cndmask_b32_e64 v113, 0, v135, s[10:11]
	v_mul_f32_e32 v90, 0x3fb8aa3b, v109
	v_exp_f32_e32 v106, v90
	v_mul_f32_e32 v90, 0xbfb8aa3b, v109
	v_exp_f32_e32 v94, v90
	v_sub_f32_e32 v90, v108, v109
	v_mul_f32_e32 v90, 0x3fb8aa3b, v90
	v_exp_f32_e32 v126, v90
	v_cndmask_b32_e64 v90, v107, 0, s[0:1]
	v_cndmask_b32_e64 v108, 0, v131, s[8:9]
	v_add_f32_e32 v109, v90, v108
	v_mov_b32_e32 v108, v135
	v_mov_b32_e32 v112, v139
	v_add_f32_e32 v144, v107, v131
	v_pk_add_f32 v[108:109], v[108:109], v[112:113]
	ds_read_b128 v[166:169], v111 offset:528
	ds_read_b128 v[170:173], v111 offset:1040
	v_pk_add_f32 v[108:109], v[144:145], v[108:109]
	ds_read_b128 v[174:177], v111 offset:1552
	v_mul_f32_e32 v90, 0x3fb8aa3b, v109
	v_exp_f32_e32 v107, v90
	v_mul_f32_e32 v90, 0xbfb8aa3b, v109
	v_lshlrev_b32_e32 v112, 16, v95
	v_and_b32_e32 v113, 0xffff0000, v95
	v_exp_f32_e32 v95, v90
	v_sub_f32_e32 v90, v108, v109
	v_mul_f32_e32 v90, 0x3fb8aa3b, v90
	v_lshlrev_b32_e32 v134, 16, v91
	v_and_b32_e32 v135, 0xffff0000, v91
	v_exp_f32_e32 v138, v90
	v_cndmask_b32_e64 v90, v98, 0, s[0:1]
	s_waitcnt lgkmcnt(2)
	v_cndmask_b32_e64 v91, 0, v166, s[8:9]
	v_add_f32_e32 v91, v90, v91
	s_waitcnt lgkmcnt(1)
	v_cndmask_b32_e64 v109, 0, v170, s[10:11]
	v_mov_b32_e32 v90, v170
	s_waitcnt lgkmcnt(0)
	v_mov_b32_e32 v108, v174
	v_pk_mul_f32 v[106:107], v[106:107], v[112:113]
	v_add_f32_e32 v112, v98, v166
	v_pk_add_f32 v[90:91], v[90:91], v[108:109]
	v_mov_b32_e32 v113, v178
	v_pk_add_f32 v[90:91], v[112:113], v[90:91]
	v_cndmask_b32_e64 v131, 0, v171, s[10:11]
	v_sub_f32_e32 v90, v90, v91
	v_mul_f32_e32 v90, 0x3fb8aa3b, v90
	v_mul_f32_e32 v98, 0x3fb8aa3b, v91
	v_mul_f32_e32 v108, 0xbfb8aa3b, v91
	v_exp_f32_e32 v112, v90
	v_cndmask_b32_e64 v90, v99, 0, s[0:1]
	v_cndmask_b32_e64 v91, 0, v167, s[8:9]
	v_add_f32_e32 v91, v90, v91
	v_mov_b32_e32 v90, v171
	v_mov_b32_e32 v130, v175
	v_add_f32_e32 v178, v99, v167
	v_pk_add_f32 v[90:91], v[90:91], v[130:131]
	v_exp_f32_e32 v98, v98
	v_pk_add_f32 v[90:91], v[178:179], v[90:91]
	v_lshlrev_b32_e32 v130, 16, v96
	v_mul_f32_e32 v99, 0x3fb8aa3b, v91
	v_exp_f32_e32 v99, v99
	v_sub_f32_e32 v90, v90, v91
	v_mul_f32_e32 v90, 0x3fb8aa3b, v90
	v_and_b32_e32 v131, 0xffff0000, v96
	v_mul_f32_e32 v96, 0xbfb8aa3b, v91
	v_exp_f32_e32 v146, v90
	v_cndmask_b32_e64 v90, v100, 0, s[0:1]
	v_cndmask_b32_e64 v91, 0, v168, s[8:9]
	v_pk_mul_f32 v[98:99], v[98:99], v[130:131]
	v_add_f32_e32 v91, v90, v91
	v_cndmask_b32_e64 v131, 0, v172, s[10:11]
	v_mov_b32_e32 v90, v172
	v_mov_b32_e32 v130, v176
	v_add_f32_e32 v132, v100, v168
	v_pk_add_f32 v[90:91], v[90:91], v[130:131]
	v_mov_b32_e32 v133, v180
	v_pk_add_f32 v[90:91], v[132:133], v[90:91]
	v_lshlrev_b32_e32 v144, 16, v92
	v_sub_f32_e32 v90, v90, v91
	v_and_b32_e32 v145, 0xffff0000, v92
	v_mul_f32_e32 v92, 0x3fb8aa3b, v91
	v_mul_f32_e32 v90, 0x3fb8aa3b, v90
	v_exp_f32_e32 v100, v92
	v_mul_f32_e32 v92, 0xbfb8aa3b, v91
	v_exp_f32_e32 v110, v90
	v_cndmask_b32_e64 v90, v101, 0, s[0:1]
	v_cndmask_b32_e64 v91, 0, v169, s[8:9]
	v_add_f32_e32 v91, v90, v91
	v_cndmask_b32_e64 v131, 0, v173, s[10:11]
	v_mov_b32_e32 v90, v173
	v_mov_b32_e32 v130, v177
	v_add_f32_e32 v180, v101, v169
	v_pk_add_f32 v[90:91], v[90:91], v[130:131]
	v_exp_f32_e32 v109, v96
	v_pk_add_f32 v[90:91], v[180:181], v[90:91]
	v_exp_f32_e32 v96, v92
	v_mul_f32_e32 v92, 0x3fb8aa3b, v91
	v_exp_f32_e32 v101, v92
	v_mul_f32_e32 v92, 0xbfb8aa3b, v91
	v_exp_f32_e32 v108, v108
	v_lshlrev_b32_e32 v130, 16, v97
	v_and_b32_e32 v131, 0xffff0000, v97
	v_exp_f32_e32 v97, v92
	v_lshlrev_b32_e32 v147, 1, v156
	v_and_b32_e32 v165, 32, v124
	v_sub_f32_e32 v90, v90, v91
	v_cvt_pk_bf16_f32 v92, v98, v99
	v_and_or_b32 v98, v147, 30, v165
	v_lshl_add_u32 v164, v160, 4, 0
	v_pk_mul_f32 v[100:101], v[100:101], v[130:131]
	v_lshlrev_b32_e32 v130, 16, v93
	v_and_b32_e32 v131, 0xffff0000, v93
	v_mul_f32_e32 v90, 0x3fb8aa3b, v90
	v_lshl_add_u64 v[132:133], s[56:57], 0, v[102:103]
	v_lshlrev_b32_e32 v114, 4, v98
	v_pk_mul_f32 v[94:95], v[94:95], v[134:135]
	v_pk_mul_f32 v[108:109], v[108:109], v[144:145]
	v_pk_mul_f32 v[96:97], v[96:97], v[130:131]
	v_exp_f32_e32 v136, v90
	v_cvt_pk_bf16_f32 v90, v104, v105
	v_cvt_pk_bf16_f32 v91, v106, v107
	v_cvt_pk_bf16_f32 v93, v100, v101
	v_mad_u32_u24 v100, v156, s83, v164
	v_lshl_add_u64 v[98:99], v[132:133], 0, v[114:115]
	ds_write_b128 v100, v[90:93]
	global_store_dwordx4 v[98:99], v[90:93], off sc1
	v_or_b32_e32 v114, 1, v147
	v_mul_u32_u24_e32 v113, 0x204, v114
	v_cvt_pk_bf16_f32 v90, v182, v183
	v_cvt_pk_bf16_f32 v91, v94, v95
	v_cvt_pk_bf16_f32 v92, v108, v109
	v_cvt_pk_bf16_f32 v93, v96, v97
	ds_write_b128 v100, v[90:93] offset:17408
	ds_read_b128 v[94:97], v111
	ds_read_b128 v[90:93], v111 offset:16
	ds_read_b128 v[98:101], v111 offset:512
	ds_read_b128 v[102:105], v111 offset:1024
	ds_read_b128 v[106:109], v111 offset:1536
	s_waitcnt lgkmcnt(4)
	v_cndmask_b32_e64 v127, v94, 0, s[0:1]
	ds_read_b128 v[166:169], v111 offset:528
	s_waitcnt lgkmcnt(3)
	v_add_f32_e32 v182, v94, v98
	v_add3_u32 v94, s18, v113, v184
	ds_read2_b32 v[184:185], v94 offset1:1
	v_cndmask_b32_e64 v129, 0, v98, s[8:9]
	v_add_f32_e32 v179, v127, v129
	s_waitcnt lgkmcnt(3)
	v_cndmask_b32_e64 v181, 0, v102, s[10:11]
	v_mov_b32_e32 v178, v102
	s_waitcnt lgkmcnt(2)
	v_mov_b32_e32 v180, v106
	v_pk_add_f32 v[178:179], v[178:179], v[180:181]
	s_waitcnt lgkmcnt(0)
	v_mov_b32_e32 v183, v184
	v_pk_add_f32 v[178:179], v[182:183], v[178:179]
	v_cndmask_b32_e64 v106, 0, v99, s[8:9]
	v_sub_f32_e32 v102, v178, v179
	v_mul_f32_e32 v102, 0x3fb8aa3b, v102
	v_exp_f32_e32 v129, v102
	v_cndmask_b32_e64 v102, v95, 0, s[0:1]
	ds_read_b128 v[170:173], v111 offset:1040
	ds_read_b128 v[174:177], v111 offset:1552
	ds_read2_b32 v[180:181], v94 offset0:2 offset1:3
	ds_read2_b32 v[186:187], v94 offset0:4 offset1:5
	ds_read2_b32 v[188:189], v94 offset0:6 offset1:7
	v_mul_f32_e32 v94, 0x3fb8aa3b, v179
	v_mul_f32_e32 v98, 0xbfb8aa3b, v179
	v_add_f32_e32 v179, v102, v106
	v_cndmask_b32_e64 v183, 0, v103, s[10:11]
	v_mov_b32_e32 v178, v103
	v_mov_b32_e32 v182, v107
	v_add_f32_e32 v184, v95, v99
	v_pk_add_f32 v[102:103], v[178:179], v[182:183]
	v_exp_f32_e32 v94, v94
	v_pk_add_f32 v[102:103], v[184:185], v[102:103]
	s_waitcnt vmcnt(6)
	v_lshlrev_b32_e32 v106, 16, v86
	v_mul_f32_e32 v95, 0x3fb8aa3b, v103
	v_exp_f32_e32 v95, v95
	v_and_b32_e32 v107, 0xffff0000, v86
	v_mul_f32_e32 v86, 0xbfb8aa3b, v103
	v_exp_f32_e32 v98, v98
	v_pk_mul_f32 v[94:95], v[94:95], v[106:107]
	s_waitcnt vmcnt(5)
	v_lshlrev_b32_e32 v106, 16, v82
	v_and_b32_e32 v107, 0xffff0000, v82
	v_sub_f32_e32 v82, v102, v103
	v_exp_f32_e32 v99, v86
	v_mul_f32_e32 v82, 0x3fb8aa3b, v82
	v_exp_f32_e32 v143, v82
	v_mov_b32_e32 v178, v140
	v_mov_b32_e32 v179, v106
	v_cndmask_b32_e64 v82, v96, 0, s[0:1]
	v_cndmask_b32_e64 v86, 0, v100, s[8:9]
	v_pk_mul_f32 v[98:99], v[98:99], v[106:107]
	v_pk_mul_f32 v[102:103], v[128:129], v[178:179]
	v_mov_b32_e32 v106, v141
	v_add_f32_e32 v129, v82, v86
	v_cndmask_b32_e64 v141, 0, v104, s[10:11]
	v_mov_b32_e32 v128, v104
	v_mov_b32_e32 v140, v108
	v_pk_mul_f32 v[106:107], v[142:143], v[106:107]
	v_add_f32_e32 v142, v96, v100
	v_pk_add_f32 v[128:129], v[128:129], v[140:141]
	s_waitcnt lgkmcnt(2)
	v_mov_b32_e32 v143, v180
	v_pk_add_f32 v[128:129], v[142:143], v[128:129]
	v_cndmask_b32_e64 v100, 0, v101, s[8:9]
	v_mul_f32_e32 v82, 0x3fb8aa3b, v129
	v_exp_f32_e32 v96, v82
	v_mul_f32_e32 v82, 0xbfb8aa3b, v129
	v_exp_f32_e32 v86, v82
	v_sub_f32_e32 v82, v128, v129
	v_mul_f32_e32 v82, 0x3fb8aa3b, v82
	v_exp_f32_e32 v127, v82
	v_cndmask_b32_e64 v82, v97, 0, s[0:1]
	v_add_f32_e32 v129, v82, v100
	v_cndmask_b32_e64 v141, 0, v105, s[10:11]
	v_mov_b32_e32 v128, v105
	v_mov_b32_e32 v140, v109
	v_add_f32_e32 v180, v97, v101
	v_pk_add_f32 v[100:101], v[128:129], v[140:141]
	v_lshlrev_b32_e32 v104, 16, v87
	v_pk_add_f32 v[100:101], v[180:181], v[100:101]
	v_and_b32_e32 v105, 0xffff0000, v87
	v_mul_f32_e32 v82, 0x3fb8aa3b, v101
	v_exp_f32_e32 v97, v82
	v_mul_f32_e32 v82, 0xbfb8aa3b, v101
	v_sub_f32_e32 v100, v100, v101
	v_exp_f32_e32 v87, v82
	v_mul_f32_e32 v100, 0x3fb8aa3b, v100
	v_exp_f32_e32 v139, v100
	v_lshlrev_b32_e32 v82, 16, v83
	v_and_b32_e32 v83, 0xffff0000, v83
	v_pk_mul_f32 v[96:97], v[96:97], v[104:105]
	v_pk_mul_f32 v[86:87], v[86:87], v[82:83]
	v_mov_b32_e32 v104, v134
	v_mov_b32_e32 v105, v82
	v_mov_b32_e32 v82, v135
	v_pk_mul_f32 v[100:101], v[126:127], v[104:105]
	v_pk_mul_f32 v[104:105], v[138:139], v[82:83]
	v_cndmask_b32_e64 v82, v90, 0, s[0:1]
	v_cndmask_b32_e64 v83, 0, v166, s[8:9]
	v_add_f32_e32 v83, v82, v83
	v_cndmask_b32_e64 v109, 0, v170, s[10:11]
	v_mov_b32_e32 v82, v170
	v_mov_b32_e32 v108, v174
	v_add_f32_e32 v126, v90, v166
	v_pk_add_f32 v[82:83], v[82:83], v[108:109]
	s_waitcnt lgkmcnt(1)
	v_mov_b32_e32 v127, v186
	v_pk_add_f32 v[82:83], v[126:127], v[82:83]
	v_cndmask_b32_e64 v127, 0, v171, s[10:11]
	v_sub_f32_e32 v82, v82, v83
	v_mul_f32_e32 v82, 0x3fb8aa3b, v82
	v_mul_f32_e32 v90, 0x3fb8aa3b, v83
	v_mul_f32_e32 v108, 0xbfb8aa3b, v83
	v_exp_f32_e32 v113, v82
	v_cndmask_b32_e64 v82, v91, 0, s[0:1]
	v_cndmask_b32_e64 v83, 0, v167, s[8:9]
	v_add_f32_e32 v83, v82, v83
	v_mov_b32_e32 v82, v171
	v_mov_b32_e32 v126, v175
	v_add_f32_e32 v186, v91, v167
	v_pk_add_f32 v[82:83], v[82:83], v[126:127]
	v_exp_f32_e32 v90, v90
	v_pk_add_f32 v[82:83], v[186:187], v[82:83]
	v_lshlrev_b32_e32 v126, 16, v88
	v_mul_f32_e32 v91, 0x3fb8aa3b, v83
	v_exp_f32_e32 v91, v91
	v_and_b32_e32 v127, 0xffff0000, v88
	v_sub_f32_e32 v82, v82, v83
	v_mul_f32_e32 v82, 0x3fb8aa3b, v82
	v_pk_mul_f32 v[90:91], v[90:91], v[126:127]
	v_lshlrev_b32_e32 v126, 16, v84
	v_and_b32_e32 v161, 50, v147
	v_mul_f32_e32 v88, 0xbfb8aa3b, v83
	v_mov_b32_e32 v128, v144
	v_exp_f32_e32 v147, v82
	v_mov_b32_e32 v129, v126
	v_cndmask_b32_e64 v82, v92, 0, s[0:1]
	v_cndmask_b32_e64 v83, 0, v168, s[8:9]
	v_pk_mul_f32 v[112:113], v[112:113], v[128:129]
	v_add_f32_e32 v83, v82, v83
	v_cndmask_b32_e64 v129, 0, v172, s[10:11]
	v_mov_b32_e32 v82, v172
	v_mov_b32_e32 v128, v176
	v_add_f32_e32 v134, v92, v168
	v_pk_add_f32 v[82:83], v[82:83], v[128:129]
	s_waitcnt lgkmcnt(0)
	v_mov_b32_e32 v135, v188
	v_pk_add_f32 v[82:83], v[134:135], v[82:83]
	v_and_b32_e32 v127, 0xffff0000, v84
	v_sub_f32_e32 v82, v82, v83
	v_mul_f32_e32 v84, 0x3fb8aa3b, v83
	v_mul_f32_e32 v82, 0x3fb8aa3b, v82
	v_exp_f32_e32 v92, v84
	v_mul_f32_e32 v84, 0xbfb8aa3b, v83
	v_exp_f32_e32 v111, v82
	v_cndmask_b32_e64 v82, v93, 0, s[0:1]
	v_cndmask_b32_e64 v83, 0, v169, s[8:9]
	v_add_f32_e32 v83, v82, v83
	v_cndmask_b32_e64 v129, 0, v173, s[10:11]
	v_mov_b32_e32 v82, v173
	v_mov_b32_e32 v128, v177
	v_add_f32_e32 v188, v93, v169
	v_pk_add_f32 v[82:83], v[82:83], v[128:129]
	v_exp_f32_e32 v109, v88
	v_pk_add_f32 v[82:83], v[188:189], v[82:83]
	v_exp_f32_e32 v88, v84
	v_mul_f32_e32 v84, 0x3fb8aa3b, v83
	v_exp_f32_e32 v93, v84
	v_mul_f32_e32 v84, 0xbfb8aa3b, v83
	v_sub_f32_e32 v82, v82, v83
	v_lshlrev_b32_e32 v128, 16, v89
	v_and_b32_e32 v129, 0xffff0000, v89
	v_exp_f32_e32 v89, v84
	v_mul_f32_e32 v82, 0x3fb8aa3b, v82
	v_exp_f32_e32 v137, v82
	v_exp_f32_e32 v108, v108
	v_lshlrev_b32_e32 v84, 16, v85
	v_and_b32_e32 v85, 0xffff0000, v85
	v_pk_mul_f32 v[92:93], v[92:93], v[128:129]
	v_pk_mul_f32 v[88:89], v[88:89], v[84:85]
	v_mov_b32_e32 v128, v130
	v_mov_b32_e32 v129, v84
	v_mov_b32_e32 v84, v131
	v_pk_mul_f32 v[110:111], v[110:111], v[128:129]
	v_pk_mul_f32 v[128:129], v[136:137], v[84:85]
	v_cvt_pk_bf16_f32 v84, v90, v91
	v_and_or_b32 v90, v114, 31, v165
	v_cvt_pk_bf16_f32 v85, v92, v93
	v_mad_u32_u24 v92, v114, s84, v164
	v_lshlrev_b32_e32 v114, 4, v90
	v_pk_mul_f32 v[108:109], v[108:109], v[126:127]
	v_cvt_pk_bf16_f32 v82, v94, v95
	v_cvt_pk_bf16_f32 v83, v96, v97
	v_lshl_add_u64 v[90:91], v[132:133], 0, v[114:115]
	v_lshlrev_b32_e32 v162, 2, v124
	ds_write_b128 v92, v[82:85]
	global_store_dwordx4 v[90:91], v[82:85], off sc1
	v_and_b32_e32 v163, 4, v124
	v_mov_b32_e32 v126, v145
	v_cvt_pk_bf16_f32 v82, v98, v99
	v_cvt_pk_bf16_f32 v83, v86, v87
	v_cvt_pk_bf16_f32 v84, v108, v109
	v_cvt_pk_bf16_f32 v85, v88, v89
	ds_write_b128 v92, v[82:85] offset:17408
	v_and_b32_e32 v82, 8, v162
	v_or3_b32 v82, v161, v163, v82
	v_lshlrev_b32_e32 v82, 1, v82
	v_mul_lo_u32 v83, v160, s85
	v_add3_u32 v85, 0, v82, v83
	v_cvt_pk_bf16_f32 v84, v102, v103
	v_cvt_pk_bf16_f32 v86, v106, v107
	v_add_u32_e32 v85, 0x8800, v85
	v_pk_mul_f32 v[126:127], v[146:147], v[126:127]
	ds_write2_b32 v85, v84, v86 offset1:36
	v_cvt_pk_bf16_f32 v84, v100, v101
	v_cvt_pk_bf16_f32 v86, v104, v105
	ds_write2_b32 v85, v84, v86 offset0:72 offset1:108
	v_cvt_pk_bf16_f32 v84, v112, v113
	v_cvt_pk_bf16_f32 v86, v126, v127
	ds_write2_b32 v85, v84, v86 offset0:144 offset1:180
	v_cvt_pk_bf16_f32 v84, v110, v111
	v_cvt_pk_bf16_f32 v86, v128, v129
	ds_write2_b32 v85, v84, v86 offset0:216 offset1:252
	s_and_saveexec_b64 s[0:1], vcc
	s_cbranch_execz .LBB0_1096
	ds_read2st64_b32 v[84:85], v159 offset1:2
	ds_read2st64_b32 v[86:87], v159 offset0:4 offset1:6
	s_lshl_b64 s[8:9], s[48:49], 9
	s_add_u32 s8, s79, s8
	s_addc_u32 s9, s80, s9
	s_waitcnt lgkmcnt(1)
	v_mov_b32_e32 v88, v84
	s_waitcnt lgkmcnt(0)
	v_mov_b32_e32 v89, v86
	v_mov_b32_e32 v86, v85
	v_pk_add_f32 v[84:85], v[88:89], v[86:87]
	s_nop 0
	v_add_f32_e32 v84, v84, v85
	v_mul_f32_e32 v84, 0x3fb8aa3b, v84
	v_exp_f32_e32 v86, v84
	v_lshl_add_u64 v[84:85], v[124:125], 2, s[8:9]
	global_store_dword v[84:85], v148, off
	v_add_u32_e32 v84, 0x18b00, v157
	v_mul_f32_e32 v148, v148, v86
	ds_write_b32 v84, v86

.LBB0_1377:
	s_or_b64 exec, exec, s[6:7]
	s_ashr_i32 s0, s24, 2
	s_ashr_i32 s1, s0, 31
	s_lshl_b64 s[0:1], s[0:1], 6
	s_lshl_b32 s6, s23, 5
	s_or_b32 s0, s0, s6
	v_lshlrev_b32_e32 v12, 4, v205
	v_or_b32_e32 v22, s0, v204
	v_mov_b32_e32 v23, s1
	v_readlane_b32 s68, v251, 9
	v_lshlrev_b64 v[26:27], 11, v[22:23]
	v_lshl_or_b32 v28, s44, 1, v12
	v_lshlrev_b32_e32 v10, 5, v205
	v_readlane_b32 s76, v251, 17
	v_readlane_b32 s77, v251, 18
	v_or_b32_e32 v26, v26, v28
	s_nop 3
	global_load_dwordx4 v[2:5], v10, s[76:77] offset:16
	global_load_dwordx4 v[6:9], v10, s[76:77]
	s_waitcnt lgkmcnt(0)
	v_lshl_add_u64 v[10:11], s[60:61], 0, v[26:27]
	global_load_dwordx4 v[18:21], v[10:11], off
	s_mov_b64 s[8:9], s[76:77]
	v_mul_u32_u24_e32 v10, 0x210, v204
	v_add3_u32 v29, s22, v12, v10
	ds_read_b128 v[14:17], v29
	v_lshl_add_u32 v10, v204, 2, s22
	v_add_u32_e32 v30, 0x4000, v10
	ds_read2_b32 v[24:25], v30 offset0:128 offset1:130
	ds_read_b128 v[10:13], v29 offset:1056
	v_readlane_b32 s69, v251, 10
	s_waitcnt lgkmcnt(2)
	v_lshlrev_b32_e32 v32, 16, v14
	v_and_b32_e32 v33, 0xffff0000, v14
	s_waitcnt lgkmcnt(1)
	v_pk_mul_f32 v[32:33], v[24:25], v[32:33] op_sel_hi:[0,1]
	v_lshlrev_b32_e32 v14, 16, v15
	v_and_b32_e32 v15, 0xffff0000, v15
	v_lshlrev_b32_e32 v34, 16, v16
	v_pk_mul_f32 v[14:15], v[24:25], v[14:15] op_sel_hi:[0,1]
	v_readlane_b32 s70, v251, 11
	v_readlane_b32 s71, v251, 12
	v_readlane_b32 s72, v251, 13
	v_readlane_b32 s73, v251, 14
	v_readlane_b32 s74, v251, 15
	v_readlane_b32 s75, v251, 16
	v_readlane_b32 s78, v251, 19
	v_readlane_b32 s79, v251, 20
	v_readlane_b32 s80, v251, 21
	v_readlane_b32 s81, v251, 22
	v_readlane_b32 s82, v251, 23
	v_readlane_b32 s83, v251, 24
	s_waitcnt vmcnt(1)
	v_pk_mul_f32 v[32:33], v[6:7], v[32:33]
	v_pk_mul_f32 v[14:15], v[8:9], v[14:15]
	s_waitcnt vmcnt(0)
	v_lshlrev_b32_e32 v31, 16, v18
	v_and_b32_e32 v35, 0xffff0000, v18
	v_lshlrev_b32_e32 v40, 16, v19
	v_and_b32_e32 v41, 0xffff0000, v19
	v_mul_f32_e32 v18, 0xbfb8aa3b, v31
	v_mul_f32_e32 v19, 0xbfb8aa3b, v35
	v_exp_f32_e32 v18, v18
	v_exp_f32_e32 v19, v19
	v_mul_f32_e32 v36, 0xbfb8aa3b, v40
	v_mul_f32_e32 v37, 0xbfb8aa3b, v41
	v_exp_f32_e32 v36, v36
	v_exp_f32_e32 v37, v37
	v_pk_add_f32 v[18:19], v[18:19], 1.0 op_sel_hi:[1,0]
	v_lshlrev_b32_e32 v42, 16, v20
	v_div_scale_f32 v43, s[0:1], v19, v19, v35
	v_pk_add_f32 v[36:37], v[36:37], 1.0 op_sel_hi:[1,0]
	v_div_scale_f32 v45, s[0:1], v18, v18, v31
	v_rcp_f32_e32 v51, v43
	v_div_scale_f32 v47, s[6:7], v37, v37, v41
	v_rcp_f32_e32 v52, v45
	v_div_scale_f32 v49, s[8:9], v36, v36, v40
	v_rcp_f32_e32 v53, v47
	v_rcp_f32_e32 v54, v49
	v_fma_f32 v55, -v43, v51, 1.0
	v_div_scale_f32 v44, vcc, v35, v19, v35
	v_fma_f32 v56, -v45, v52, 1.0
	v_fmac_f32_e32 v51, v55, v51
	v_div_scale_f32 v46, s[0:1], v31, v18, v31
	v_fma_f32 v57, -v47, v53, 1.0
	v_fmac_f32_e32 v52, v56, v52
	v_mul_f32_e32 v55, v44, v51
	v_and_b32_e32 v20, 0xffff0000, v20
	v_div_scale_f32 v48, s[6:7], v41, v37, v41
	v_fma_f32 v58, -v49, v54, 1.0
	v_fmac_f32_e32 v53, v57, v53
	v_mul_f32_e32 v56, v46, v52
	v_fma_f32 v59, -v43, v55, v44
	v_mul_f32_e32 v38, 0xbfb8aa3b, v42
	v_mul_f32_e32 v39, 0xbfb8aa3b, v20
	v_div_scale_f32 v50, s[8:9], v40, v36, v40
	v_fmac_f32_e32 v54, v58, v54
	v_mul_f32_e32 v57, v48, v53
	v_fma_f32 v60, -v45, v56, v46
	v_fmac_f32_e32 v55, v59, v51
	v_exp_f32_e32 v38, v38
	v_exp_f32_e32 v39, v39
	v_mul_f32_e32 v58, v50, v54
	v_fma_f32 v61, -v47, v57, v48
	v_fmac_f32_e32 v56, v60, v52
	v_fma_f32 v43, -v43, v55, v44
	v_fma_f32 v62, -v49, v58, v50
	v_fmac_f32_e32 v57, v61, v53
	v_fma_f32 v44, -v45, v56, v46
	v_div_fmas_f32 v43, v43, v51, v55
	s_mov_b64 vcc, s[0:1]
	v_fmac_f32_e32 v58, v62, v54
	v_fma_f32 v45, -v47, v57, v48
	v_div_fixup_f32 v19, v43, v19, v35
	v_div_fmas_f32 v35, v44, v52, v56
	s_mov_b64 vcc, s[6:7]
	v_fma_f32 v46, -v49, v58, v50
	v_div_fixup_f32 v18, v35, v18, v31
	v_div_fmas_f32 v31, v45, v53, v57
	s_mov_b64 vcc, s[8:9]
	v_pk_add_f32 v[38:39], v[38:39], 1.0 op_sel_hi:[1,0]
	v_pk_mul_f32 v[18:19], v[32:33], v[18:19]
	v_div_fixup_f32 v33, v31, v37, v41
	v_div_fmas_f32 v31, v46, v54, v58
	v_div_fixup_f32 v32, v31, v36, v40
	v_div_scale_f32 v31, s[0:1], v39, v39, v20
	v_rcp_f32_e32 v36, v31
	v_and_b32_e32 v35, 0xffff0000, v16
	v_pk_mul_f32 v[32:33], v[14:15], v[32:33]
	v_pk_mul_f32 v[14:15], v[24:25], v[34:35] op_sel_hi:[0,1]
	v_fma_f32 v16, -v31, v36, 1.0
	v_fmac_f32_e32 v36, v16, v36
	v_div_scale_f32 v16, vcc, v20, v39, v20
	v_mul_f32_e32 v34, v16, v36
	v_fma_f32 v35, -v31, v34, v16
	v_fmac_f32_e32 v34, v35, v36
	v_fma_f32 v16, -v31, v34, v16
	v_div_scale_f32 v31, s[0:1], v38, v38, v42
	v_rcp_f32_e32 v37, v31
	v_div_fmas_f32 v16, v16, v36, v34
	v_div_fixup_f32 v35, v16, v39, v20
	v_and_b32_e32 v36, 0xffff0000, v21
	v_fma_f32 v16, -v31, v37, 1.0
	v_fmac_f32_e32 v37, v16, v37
	v_div_scale_f32 v16, vcc, v42, v38, v42
	v_mul_f32_e32 v20, v16, v37
	v_fma_f32 v34, -v31, v20, v16
	v_fmac_f32_e32 v20, v34, v37
	v_fma_f32 v16, -v31, v20, v16
	v_lshlrev_b32_e32 v31, 16, v21
	v_div_fmas_f32 v16, v16, v37, v20
	v_mul_f32_e32 v20, 0xbfb8aa3b, v31
	v_mul_f32_e32 v21, 0xbfb8aa3b, v36
	v_exp_f32_e32 v20, v20
	v_exp_f32_e32 v21, v21
	v_div_fixup_f32 v34, v16, v38, v42
	v_pk_mul_f32 v[14:15], v[2:3], v[14:15]
	v_pk_add_f32 v[20:21], v[20:21], 1.0 op_sel_hi:[1,0]
	s_nop 0
	v_div_scale_f32 v16, s[0:1], v21, v21, v36
	v_rcp_f32_e32 v37, v16
	v_pk_mul_f32 v[34:35], v[14:15], v[34:35]
	v_lshlrev_b32_e32 v14, 16, v17
	v_and_b32_e32 v15, 0xffff0000, v17
	v_fma_f32 v17, -v16, v37, 1.0
	v_fmac_f32_e32 v37, v17, v37
	v_div_scale_f32 v17, vcc, v36, v21, v36
	v_pk_mul_f32 v[14:15], v[24:25], v[14:15] op_sel_hi:[0,1]
	v_mul_f32_e32 v24, v17, v37
	v_fma_f32 v38, -v16, v24, v17
	v_fmac_f32_e32 v24, v38, v37
	v_div_scale_f32 v38, s[0:1], v20, v20, v31
	v_rcp_f32_e32 v39, v38
	v_fma_f32 v16, -v16, v24, v17
	v_div_fmas_f32 v16, v16, v37, v24
	v_div_fixup_f32 v17, v16, v21, v36
	v_fma_f32 v16, -v38, v39, 1.0
	v_fmac_f32_e32 v39, v16, v39
	v_div_scale_f32 v16, vcc, v31, v20, v31
	v_mul_f32_e32 v21, v16, v39
	v_fma_f32 v24, -v38, v21, v16
	v_fmac_f32_e32 v21, v24, v39
	v_fma_f32 v16, -v38, v21, v16
	v_div_fmas_f32 v16, v16, v39, v21
	v_pk_mul_f32 v[14:15], v[4:5], v[14:15]
	v_div_fixup_f32 v16, v16, v20, v31
	v_pk_mul_f32 v[20:21], v[14:15], v[16:17]
	v_cvt_pk_bf16_f32 v14, v18, v19
	v_cvt_pk_bf16_f32 v15, v32, v33
	v_cvt_pk_bf16_f32 v16, v34, v35
	v_cvt_pk_bf16_f32 v17, v20, v21
	v_lshl_add_u64 v[18:19], s[36:37], 0, v[26:27]
	global_store_dwordx4 v[18:19], v[14:17], off sc1
	s_waitcnt lgkmcnt(0)
	v_lshlrev_b32_e32 v26, 16, v10
	v_and_b32_e32 v27, 0xffff0000, v10
	v_or_b32_e32 v14, 2, v22
	v_mov_b32_e32 v15, v23
	v_lshlrev_b64 v[18:19], 11, v[14:15]
	v_or_b32_e32 v18, v18, v28
	v_lshl_add_u64 v[14:15], s[60:61], 0, v[18:19]
	global_load_dwordx4 v[14:17], v[14:15], off
	v_mov_b32_e32 v10, v25
	v_pk_mul_f32 v[24:25], v[10:11], v[26:27] op_sel_hi:[0,1]
	v_pk_mul_f32 v[24:25], v[6:7], v[24:25]
	s_waitcnt vmcnt(0)
	v_lshlrev_b32_e32 v31, 16, v14
	v_and_b32_e32 v14, 0xffff0000, v14
	v_mul_f32_e32 v20, 0xbfb8aa3b, v31
	v_mul_f32_e32 v21, 0xbfb8aa3b, v14
	v_exp_f32_e32 v20, v20
	v_exp_f32_e32 v21, v21
	s_nop 0
	v_pk_add_f32 v[20:21], v[20:21], 1.0 op_sel_hi:[1,0]
	s_nop 0
	v_div_scale_f32 v32, s[0:1], v21, v21, v14
	v_rcp_f32_e32 v33, v32
	s_nop 0
	v_fma_f32 v26, -v32, v33, 1.0
	v_fmac_f32_e32 v33, v26, v33
	v_div_scale_f32 v26, vcc, v14, v21, v14
	v_mul_f32_e32 v27, v26, v33
	v_fma_f32 v34, -v32, v27, v26
	v_fmac_f32_e32 v27, v34, v33
	v_fma_f32 v26, -v32, v27, v26
	v_div_scale_f32 v32, s[0:1], v20, v20, v31
	v_rcp_f32_e32 v34, v32
	v_div_fmas_f32 v26, v26, v33, v27
	v_div_fixup_f32 v21, v26, v21, v14
	v_fma_f32 v14, -v32, v34, 1.0
	v_fmac_f32_e32 v34, v14, v34
	v_div_scale_f32 v14, vcc, v31, v20, v31
	v_mul_f32_e32 v26, v14, v34
	v_fma_f32 v27, -v32, v26, v14
	v_fmac_f32_e32 v26, v27, v34
	v_fma_f32 v14, -v32, v26, v14
	v_lshlrev_b32_e32 v32, 16, v15
	v_and_b32_e32 v27, 0xffff0000, v15
	v_div_fmas_f32 v26, v14, v34, v26
	v_mul_f32_e32 v14, 0xbfb8aa3b, v32
	v_mul_f32_e32 v15, 0xbfb8aa3b, v27
	v_exp_f32_e32 v14, v14
	v_exp_f32_e32 v15, v15
	v_div_fixup_f32 v20, v26, v20, v31
	v_pk_mul_f32 v[20:21], v[24:25], v[20:21]
	v_lshlrev_b32_e32 v24, 16, v11
	v_pk_add_f32 v[14:15], v[14:15], 1.0 op_sel_hi:[1,0]
	v_and_b32_e32 v25, 0xffff0000, v11
	v_div_scale_f32 v26, s[0:1], v15, v15, v27
	v_rcp_f32_e32 v31, v26
	v_pk_mul_f32 v[24:25], v[10:11], v[24:25] op_sel_hi:[0,1]
	v_pk_mul_f32 v[24:25], v[8:9], v[24:25]
	v_fma_f32 v11, -v26, v31, 1.0
	v_fmac_f32_e32 v31, v11, v31
	v_div_scale_f32 v11, vcc, v27, v15, v27
	v_mul_f32_e32 v33, v11, v31
	v_fma_f32 v34, -v26, v33, v11
	v_fmac_f32_e32 v33, v34, v31
	v_fma_f32 v11, -v26, v33, v11
	v_div_scale_f32 v26, s[0:1], v14, v14, v32
	v_rcp_f32_e32 v34, v26
	v_div_fmas_f32 v11, v11, v31, v33
	v_div_fixup_f32 v15, v11, v15, v27
	v_fma_f32 v11, -v26, v34, 1.0
	v_fmac_f32_e32 v34, v11, v34
	v_div_scale_f32 v11, vcc, v32, v14, v32
	v_mul_f32_e32 v27, v11, v34
	v_fma_f32 v31, -v26, v27, v11
	v_fmac_f32_e32 v27, v31, v34
	v_fma_f32 v11, -v26, v27, v11
	v_lshlrev_b32_e32 v31, 16, v16
	v_and_b32_e32 v16, 0xffff0000, v16
	v_div_fmas_f32 v11, v11, v34, v27
	v_mul_f32_e32 v26, 0xbfb8aa3b, v31
	v_mul_f32_e32 v27, 0xbfb8aa3b, v16
	v_exp_f32_e32 v26, v26
	v_exp_f32_e32 v27, v27
	v_div_fixup_f32 v14, v11, v14, v32
	v_pk_mul_f32 v[14:15], v[24:25], v[14:15]
	v_lshlrev_b32_e32 v24, 16, v12
	v_pk_add_f32 v[26:27], v[26:27], 1.0 op_sel_hi:[1,0]
	v_and_b32_e32 v25, 0xffff0000, v12
	v_div_scale_f32 v11, s[0:1], v27, v27, v16
	v_rcp_f32_e32 v32, v11
	v_pk_mul_f32 v[24:25], v[10:11], v[24:25] op_sel_hi:[0,1]
	v_pk_mul_f32 v[24:25], v[2:3], v[24:25]
	v_fma_f32 v12, -v11, v32, 1.0
	v_fmac_f32_e32 v32, v12, v32
	v_div_scale_f32 v12, vcc, v16, v27, v16
	v_mul_f32_e32 v33, v12, v32
	v_fma_f32 v34, -v11, v33, v12
	v_fmac_f32_e32 v33, v34, v32
	v_fma_f32 v11, -v11, v33, v12
	v_div_scale_f32 v12, s[0:1], v26, v26, v31
	v_rcp_f32_e32 v34, v12
	v_div_fmas_f32 v11, v11, v32, v33
	v_div_fixup_f32 v27, v11, v27, v16
	v_and_b32_e32 v33, 0xffff0000, v17
	v_fma_f32 v11, -v12, v34, 1.0
	v_fmac_f32_e32 v34, v11, v34
	v_div_scale_f32 v11, vcc, v31, v26, v31
	v_mul_f32_e32 v16, v11, v34
	v_fma_f32 v32, -v12, v16, v11
	v_fmac_f32_e32 v16, v32, v34
	v_lshlrev_b32_e32 v32, 16, v17
	v_fma_f32 v11, -v12, v16, v11
	v_mul_f32_e32 v12, 0xbfb8aa3b, v32
	v_div_fmas_f32 v11, v11, v34, v16
	v_exp_f32_e32 v16, v12
	v_mul_f32_e32 v12, 0xbfb8aa3b, v33
	v_exp_f32_e32 v17, v12
	v_div_fixup_f32 v26, v11, v26, v31
	v_pk_mul_f32 v[24:25], v[24:25], v[26:27]
	v_lshlrev_b32_e32 v12, 16, v13
	v_pk_add_f32 v[16:17], v[16:17], 1.0 op_sel_hi:[1,0]
	v_and_b32_e32 v13, 0xffff0000, v13
	v_div_scale_f32 v26, s[0:1], v17, v17, v33
	v_rcp_f32_e32 v27, v26
	v_pk_mul_f32 v[10:11], v[10:11], v[12:13] op_sel_hi:[0,1]
	v_pk_mul_f32 v[10:11], v[4:5], v[10:11]
	v_fma_f32 v12, -v26, v27, 1.0
	v_fmac_f32_e32 v27, v12, v27
	v_div_scale_f32 v12, vcc, v33, v17, v33
	v_mul_f32_e32 v13, v12, v27
	v_fma_f32 v31, -v26, v13, v12
	v_fmac_f32_e32 v13, v31, v27
	v_fma_f32 v12, -v26, v13, v12
	v_div_scale_f32 v26, s[0:1], v16, v16, v32
	v_rcp_f32_e32 v31, v26
	v_div_fmas_f32 v12, v12, v27, v13
	v_div_fixup_f32 v13, v12, v17, v33
	v_fma_f32 v12, -v26, v31, 1.0
	v_fmac_f32_e32 v31, v12, v31
	v_div_scale_f32 v12, vcc, v32, v16, v32
	v_mul_f32_e32 v17, v12, v31
	v_fma_f32 v27, -v26, v17, v12
	v_fmac_f32_e32 v17, v27, v31
	v_fma_f32 v12, -v26, v17, v12
	v_div_fmas_f32 v12, v12, v31, v17
	v_div_fixup_f32 v12, v12, v16, v32
	v_pk_mul_f32 v[16:17], v[10:11], v[12:13]
	v_cvt_pk_bf16_f32 v10, v20, v21
	v_cvt_pk_bf16_f32 v11, v14, v15
	v_cvt_pk_bf16_f32 v12, v24, v25
	v_cvt_pk_bf16_f32 v13, v16, v17
	v_lshl_add_u64 v[14:15], s[36:37], 0, v[18:19]
	global_store_dwordx4 v[14:15], v[10:13], off sc1
	ds_read_b128 v[14:17], v29 offset:2112
	s_waitcnt lgkmcnt(0)
	v_lshlrev_b32_e32 v34, 16, v14
	v_or_b32_e32 v10, 4, v22
	v_mov_b32_e32 v11, v23
	v_lshlrev_b64 v[26:27], 11, v[10:11]
	v_or_b32_e32 v26, v26, v28
	v_lshl_add_u64 v[10:11], s[60:61], 0, v[26:27]
	global_load_dwordx4 v[18:21], v[10:11], off
	v_and_b32_e32 v35, 0xffff0000, v14
	s_waitcnt vmcnt(0)
	v_lshlrev_b32_e32 v31, 16, v18
	v_and_b32_e32 v18, 0xffff0000, v18
	v_mul_f32_e32 v10, 0xbfb8aa3b, v31
	v_exp_f32_e32 v32, v10
	v_mul_f32_e32 v10, 0xbfb8aa3b, v18
	v_exp_f32_e32 v33, v10
	ds_read2_b32 v[24:25], v30 offset0:132 offset1:134
	ds_read_b128 v[10:13], v29 offset:3168
	v_pk_add_f32 v[32:33], v[32:33], 1.0 op_sel_hi:[1,0]
	s_nop 0
	v_div_scale_f32 v36, s[0:1], v33, v33, v18
	v_rcp_f32_e32 v37, v36
	s_waitcnt lgkmcnt(1)
	v_pk_mul_f32 v[34:35], v[24:25], v[34:35] op_sel_hi:[0,1]
	v_pk_mul_f32 v[34:35], v[6:7], v[34:35]
	v_fma_f32 v14, -v36, v37, 1.0
	v_fmac_f32_e32 v37, v14, v37
	v_div_scale_f32 v14, vcc, v18, v33, v18
	v_mul_f32_e32 v38, v14, v37
	v_fma_f32 v39, -v36, v38, v14
	v_fmac_f32_e32 v38, v39, v37
	v_fma_f32 v14, -v36, v38, v14
	v_div_scale_f32 v36, s[0:1], v32, v32, v31
	v_rcp_f32_e32 v39, v36
	v_div_fmas_f32 v14, v14, v37, v38
	v_div_fixup_f32 v33, v14, v33, v18
	v_fma_f32 v14, -v36, v39, 1.0
	v_fmac_f32_e32 v39, v14, v39
	v_div_scale_f32 v14, vcc, v31, v32, v31
	v_mul_f32_e32 v18, v14, v39
	v_fma_f32 v37, -v36, v18, v14
	v_fmac_f32_e32 v18, v37, v39
	v_fma_f32 v14, -v36, v18, v14
	v_lshlrev_b32_e32 v36, 16, v19
	v_and_b32_e32 v37, 0xffff0000, v19
	v_div_fmas_f32 v14, v14, v39, v18
	v_mul_f32_e32 v18, 0xbfb8aa3b, v36
	v_mul_f32_e32 v19, 0xbfb8aa3b, v37
	v_exp_f32_e32 v18, v18
	v_exp_f32_e32 v19, v19
	v_div_fixup_f32 v32, v14, v32, v31
	v_pk_mul_f32 v[32:33], v[34:35], v[32:33]
	v_lshlrev_b32_e32 v14, 16, v15
	v_pk_add_f32 v[18:19], v[18:19], 1.0 op_sel_hi:[1,0]
	v_and_b32_e32 v15, 0xffff0000, v15
	v_div_scale_f32 v31, s[0:1], v19, v19, v37
	v_rcp_f32_e32 v34, v31
	v_pk_mul_f32 v[14:15], v[24:25], v[14:15] op_sel_hi:[0,1]
	v_pk_mul_f32 v[14:15], v[8:9], v[14:15]
	v_fma_f32 v35, -v31, v34, 1.0
	v_fmac_f32_e32 v34, v35, v34
	v_div_scale_f32 v35, vcc, v37, v19, v37
	v_mul_f32_e32 v38, v35, v34
	v_fma_f32 v39, -v31, v38, v35
	v_fmac_f32_e32 v38, v39, v34
	v_fma_f32 v31, -v31, v38, v35
	v_div_scale_f32 v35, s[0:1], v18, v18, v36
	v_rcp_f32_e32 v39, v35
	v_div_fmas_f32 v31, v31, v34, v38
	v_div_fixup_f32 v19, v31, v19, v37
	v_fma_f32 v31, -v35, v39, 1.0
	v_fmac_f32_e32 v39, v31, v39
	v_div_scale_f32 v31, vcc, v36, v18, v36
	v_mul_f32_e32 v34, v31, v39
	v_fma_f32 v37, -v35, v34, v31
	v_fmac_f32_e32 v34, v37, v39
	v_fma_f32 v31, -v35, v34, v31
	v_lshlrev_b32_e32 v37, 16, v20
	v_and_b32_e32 v20, 0xffff0000, v20
	v_div_fmas_f32 v31, v31, v39, v34
	v_mul_f32_e32 v34, 0xbfb8aa3b, v37
	v_mul_f32_e32 v35, 0xbfb8aa3b, v20
	v_exp_f32_e32 v34, v34
	v_exp_f32_e32 v35, v35
	v_div_fixup_f32 v18, v31, v18, v36
	v_pk_mul_f32 v[18:19], v[14:15], v[18:19]
	v_lshlrev_b32_e32 v14, 16, v16
	v_pk_add_f32 v[34:35], v[34:35], 1.0 op_sel_hi:[1,0]
	v_and_b32_e32 v15, 0xffff0000, v16
	v_div_scale_f32 v31, s[0:1], v35, v35, v20
	v_rcp_f32_e32 v36, v31
	v_pk_mul_f32 v[14:15], v[24:25], v[14:15] op_sel_hi:[0,1]
	v_pk_mul_f32 v[14:15], v[2:3], v[14:15]
	v_fma_f32 v16, -v31, v36, 1.0
	v_fmac_f32_e32 v36, v16, v36
	v_div_scale_f32 v16, vcc, v20, v35, v20
	v_mul_f32_e32 v38, v16, v36
	v_fma_f32 v39, -v31, v38, v16
	v_fmac_f32_e32 v38, v39, v36
	v_fma_f32 v16, -v31, v38, v16
	v_div_scale_f32 v31, s[0:1], v34, v34, v37
	v_rcp_f32_e32 v39, v31
	v_div_fmas_f32 v16, v16, v36, v38
	v_div_fixup_f32 v35, v16, v35, v20
	v_fma_f32 v16, -v31, v39, 1.0
	v_fmac_f32_e32 v39, v16, v39
	v_div_scale_f32 v16, vcc, v37, v34, v37
	v_mul_f32_e32 v20, v16, v39
	v_fma_f32 v36, -v31, v20, v16
	v_fmac_f32_e32 v20, v36, v39
	v_fma_f32 v16, -v31, v20, v16
	v_lshlrev_b32_e32 v31, 16, v21
	v_and_b32_e32 v36, 0xffff0000, v21
	v_div_fmas_f32 v16, v16, v39, v20
	v_mul_f32_e32 v20, 0xbfb8aa3b, v31
	v_mul_f32_e32 v21, 0xbfb8aa3b, v36
	v_exp_f32_e32 v20, v20
	v_exp_f32_e32 v21, v21
	v_div_fixup_f32 v34, v16, v34, v37
	v_pk_mul_f32 v[34:35], v[14:15], v[34:35]
	v_lshlrev_b32_e32 v14, 16, v17
	v_pk_add_f32 v[20:21], v[20:21], 1.0 op_sel_hi:[1,0]
	v_and_b32_e32 v15, 0xffff0000, v17
	v_div_scale_f32 v16, s[0:1], v21, v21, v36
	v_rcp_f32_e32 v37, v16
	v_pk_mul_f32 v[14:15], v[24:25], v[14:15] op_sel_hi:[0,1]
	v_pk_mul_f32 v[14:15], v[4:5], v[14:15]
	v_fma_f32 v17, -v16, v37, 1.0
	v_fmac_f32_e32 v37, v17, v37
	v_div_scale_f32 v17, vcc, v36, v21, v36
	v_mul_f32_e32 v24, v17, v37
	v_fma_f32 v38, -v16, v24, v17
	v_fmac_f32_e32 v24, v38, v37
	v_div_scale_f32 v38, s[0:1], v20, v20, v31
	v_rcp_f32_e32 v39, v38
	v_fma_f32 v16, -v16, v24, v17
	v_div_fmas_f32 v16, v16, v37, v24
	v_div_fixup_f32 v17, v16, v21, v36
	v_fma_f32 v16, -v38, v39, 1.0
	v_fmac_f32_e32 v39, v16, v39
	v_div_scale_f32 v16, vcc, v31, v20, v31
	v_mul_f32_e32 v21, v16, v39
	v_fma_f32 v24, -v38, v21, v16
	v_fmac_f32_e32 v21, v24, v39
	v_fma_f32 v16, -v38, v21, v16
	v_div_fmas_f32 v16, v16, v39, v21
	v_div_fixup_f32 v16, v16, v20, v31
	v_pk_mul_f32 v[20:21], v[14:15], v[16:17]
	v_cvt_pk_bf16_f32 v14, v32, v33
	v_cvt_pk_bf16_f32 v15, v18, v19
	v_cvt_pk_bf16_f32 v16, v34, v35
	v_cvt_pk_bf16_f32 v17, v20, v21
	v_lshl_add_u64 v[18:19], s[36:37], 0, v[26:27]
	global_store_dwordx4 v[18:19], v[14:17], off sc1
	s_waitcnt lgkmcnt(0)
	v_lshlrev_b32_e32 v26, 16, v10
	v_and_b32_e32 v27, 0xffff0000, v10
	v_or_b32_e32 v14, 6, v22
	v_mov_b32_e32 v15, v23
	v_lshlrev_b64 v[18:19], 11, v[14:15]
	v_or_b32_e32 v18, v18, v28
	v_lshl_add_u64 v[14:15], s[60:61], 0, v[18:19]
	global_load_dwordx4 v[14:17], v[14:15], off
	v_mov_b32_e32 v10, v25
	v_pk_mul_f32 v[24:25], v[10:11], v[26:27] op_sel_hi:[0,1]
	v_pk_mul_f32 v[24:25], v[6:7], v[24:25]
	s_waitcnt vmcnt(0)
	v_lshlrev_b32_e32 v31, 16, v14
	v_and_b32_e32 v14, 0xffff0000, v14
	v_mul_f32_e32 v20, 0xbfb8aa3b, v31
	v_mul_f32_e32 v21, 0xbfb8aa3b, v14
	v_exp_f32_e32 v20, v20
	v_exp_f32_e32 v21, v21
	s_nop 0
	v_pk_add_f32 v[20:21], v[20:21], 1.0 op_sel_hi:[1,0]
	s_nop 0
	v_div_scale_f32 v32, s[0:1], v21, v21, v14
	v_rcp_f32_e32 v33, v32
	s_nop 0
	v_fma_f32 v26, -v32, v33, 1.0
	v_fmac_f32_e32 v33, v26, v33
	v_div_scale_f32 v26, vcc, v14, v21, v14
	v_mul_f32_e32 v27, v26, v33
	v_fma_f32 v34, -v32, v27, v26
	v_fmac_f32_e32 v27, v34, v33
	v_fma_f32 v26, -v32, v27, v26
	v_div_scale_f32 v32, s[0:1], v20, v20, v31
	v_rcp_f32_e32 v34, v32
	v_div_fmas_f32 v26, v26, v33, v27
	v_div_fixup_f32 v21, v26, v21, v14
	v_fma_f32 v14, -v32, v34, 1.0
	v_fmac_f32_e32 v34, v14, v34
	v_div_scale_f32 v14, vcc, v31, v20, v31
	v_mul_f32_e32 v26, v14, v34
	v_fma_f32 v27, -v32, v26, v14
	v_fmac_f32_e32 v26, v27, v34
	v_fma_f32 v14, -v32, v26, v14
	v_lshlrev_b32_e32 v32, 16, v15
	v_and_b32_e32 v27, 0xffff0000, v15
	v_div_fmas_f32 v26, v14, v34, v26
	v_mul_f32_e32 v14, 0xbfb8aa3b, v32
	v_mul_f32_e32 v15, 0xbfb8aa3b, v27
	v_exp_f32_e32 v14, v14
	v_exp_f32_e32 v15, v15
	v_div_fixup_f32 v20, v26, v20, v31
	v_pk_mul_f32 v[20:21], v[24:25], v[20:21]
	v_lshlrev_b32_e32 v24, 16, v11
	v_pk_add_f32 v[14:15], v[14:15], 1.0 op_sel_hi:[1,0]
	v_and_b32_e32 v25, 0xffff0000, v11
	v_div_scale_f32 v26, s[0:1], v15, v15, v27
	v_rcp_f32_e32 v31, v26
	v_pk_mul_f32 v[24:25], v[10:11], v[24:25] op_sel_hi:[0,1]
	v_pk_mul_f32 v[24:25], v[8:9], v[24:25]
	v_fma_f32 v11, -v26, v31, 1.0
	v_fmac_f32_e32 v31, v11, v31
	v_div_scale_f32 v11, vcc, v27, v15, v27
	v_mul_f32_e32 v33, v11, v31
	v_fma_f32 v34, -v26, v33, v11
	v_fmac_f32_e32 v33, v34, v31
	v_fma_f32 v11, -v26, v33, v11
	v_div_scale_f32 v26, s[0:1], v14, v14, v32
	v_rcp_f32_e32 v34, v26
	v_div_fmas_f32 v11, v11, v31, v33
	v_div_fixup_f32 v15, v11, v15, v27
	v_fma_f32 v11, -v26, v34, 1.0
	v_fmac_f32_e32 v34, v11, v34
	v_div_scale_f32 v11, vcc, v32, v14, v32
	v_mul_f32_e32 v27, v11, v34
	v_fma_f32 v31, -v26, v27, v11
	v_fmac_f32_e32 v27, v31, v34
	v_fma_f32 v11, -v26, v27, v11
	v_lshlrev_b32_e32 v31, 16, v16
	v_and_b32_e32 v16, 0xffff0000, v16
	v_div_fmas_f32 v11, v11, v34, v27
	v_mul_f32_e32 v26, 0xbfb8aa3b, v31
	v_mul_f32_e32 v27, 0xbfb8aa3b, v16
	v_exp_f32_e32 v26, v26
	v_exp_f32_e32 v27, v27
	v_div_fixup_f32 v14, v11, v14, v32
	v_pk_mul_f32 v[14:15], v[24:25], v[14:15]
	v_lshlrev_b32_e32 v24, 16, v12
	v_pk_add_f32 v[26:27], v[26:27], 1.0 op_sel_hi:[1,0]
	v_and_b32_e32 v25, 0xffff0000, v12
	v_div_scale_f32 v11, s[0:1], v27, v27, v16
	v_rcp_f32_e32 v32, v11
	v_pk_mul_f32 v[24:25], v[10:11], v[24:25] op_sel_hi:[0,1]
	v_pk_mul_f32 v[24:25], v[2:3], v[24:25]
	v_fma_f32 v12, -v11, v32, 1.0
	v_fmac_f32_e32 v32, v12, v32
	v_div_scale_f32 v12, vcc, v16, v27, v16
	v_mul_f32_e32 v33, v12, v32
	v_fma_f32 v34, -v11, v33, v12
	v_fmac_f32_e32 v33, v34, v32
	v_fma_f32 v11, -v11, v33, v12
	v_div_scale_f32 v12, s[0:1], v26, v26, v31
	v_rcp_f32_e32 v34, v12
	v_div_fmas_f32 v11, v11, v32, v33
	v_div_fixup_f32 v27, v11, v27, v16
	v_and_b32_e32 v33, 0xffff0000, v17
	v_fma_f32 v11, -v12, v34, 1.0
	v_fmac_f32_e32 v34, v11, v34
	v_div_scale_f32 v11, vcc, v31, v26, v31
	v_mul_f32_e32 v16, v11, v34
	v_fma_f32 v32, -v12, v16, v11
	v_fmac_f32_e32 v16, v32, v34
	v_lshlrev_b32_e32 v32, 16, v17
	v_fma_f32 v11, -v12, v16, v11
	v_mul_f32_e32 v12, 0xbfb8aa3b, v32
	v_div_fmas_f32 v11, v11, v34, v16
	v_exp_f32_e32 v16, v12
	v_mul_f32_e32 v12, 0xbfb8aa3b, v33
	v_exp_f32_e32 v17, v12
	v_div_fixup_f32 v26, v11, v26, v31
	v_pk_mul_f32 v[24:25], v[24:25], v[26:27]
	v_lshlrev_b32_e32 v12, 16, v13
	v_pk_add_f32 v[16:17], v[16:17], 1.0 op_sel_hi:[1,0]
	v_and_b32_e32 v13, 0xffff0000, v13
	v_div_scale_f32 v26, s[0:1], v17, v17, v33
	v_rcp_f32_e32 v27, v26
	v_pk_mul_f32 v[10:11], v[10:11], v[12:13] op_sel_hi:[0,1]
	v_pk_mul_f32 v[10:11], v[4:5], v[10:11]
	v_fma_f32 v12, -v26, v27, 1.0
	v_fmac_f32_e32 v27, v12, v27
	v_div_scale_f32 v12, vcc, v33, v17, v33
	v_mul_f32_e32 v13, v12, v27
	v_fma_f32 v31, -v26, v13, v12
	v_fmac_f32_e32 v13, v31, v27
	v_fma_f32 v12, -v26, v13, v12
	v_div_scale_f32 v26, s[0:1], v16, v16, v32
	v_rcp_f32_e32 v31, v26
	v_div_fmas_f32 v12, v12, v27, v13
	v_div_fixup_f32 v13, v12, v17, v33
	v_fma_f32 v12, -v26, v31, 1.0
	v_fmac_f32_e32 v31, v12, v31
	v_div_scale_f32 v12, vcc, v32, v16, v32
	v_mul_f32_e32 v17, v12, v31
	v_fma_f32 v27, -v26, v17, v12
	v_fmac_f32_e32 v17, v27, v31
	v_fma_f32 v12, -v26, v17, v12
	v_div_fmas_f32 v12, v12, v31, v17
	v_div_fixup_f32 v12, v12, v16, v32
	v_pk_mul_f32 v[16:17], v[10:11], v[12:13]
	v_cvt_pk_bf16_f32 v10, v20, v21
	v_cvt_pk_bf16_f32 v11, v14, v15
	v_cvt_pk_bf16_f32 v12, v24, v25
	v_cvt_pk_bf16_f32 v13, v16, v17
	v_lshl_add_u64 v[14:15], s[36:37], 0, v[18:19]
	global_store_dwordx4 v[14:15], v[10:13], off sc1
	ds_read_b128 v[14:17], v29 offset:4224
	s_waitcnt lgkmcnt(0)
	v_lshlrev_b32_e32 v34, 16, v14
	v_or_b32_e32 v10, 8, v22
	v_mov_b32_e32 v11, v23
	v_lshlrev_b64 v[26:27], 11, v[10:11]
	v_or_b32_e32 v26, v26, v28
	v_lshl_add_u64 v[10:11], s[60:61], 0, v[26:27]
	global_load_dwordx4 v[18:21], v[10:11], off
	v_and_b32_e32 v35, 0xffff0000, v14
	s_waitcnt vmcnt(0)
	v_lshlrev_b32_e32 v31, 16, v18
	v_and_b32_e32 v18, 0xffff0000, v18
	v_mul_f32_e32 v10, 0xbfb8aa3b, v31
	v_exp_f32_e32 v32, v10
	v_mul_f32_e32 v10, 0xbfb8aa3b, v18
	v_exp_f32_e32 v33, v10
	ds_read2_b32 v[24:25], v30 offset0:136 offset1:138
	ds_read_b128 v[10:13], v29 offset:5280
	v_pk_add_f32 v[32:33], v[32:33], 1.0 op_sel_hi:[1,0]
	s_nop 0
	v_div_scale_f32 v36, s[0:1], v33, v33, v18
	v_rcp_f32_e32 v37, v36
	s_waitcnt lgkmcnt(1)
	v_pk_mul_f32 v[34:35], v[24:25], v[34:35] op_sel_hi:[0,1]
	v_pk_mul_f32 v[34:35], v[6:7], v[34:35]
	v_fma_f32 v14, -v36, v37, 1.0
	v_fmac_f32_e32 v37, v14, v37
	v_div_scale_f32 v14, vcc, v18, v33, v18
	v_mul_f32_e32 v38, v14, v37
	v_fma_f32 v39, -v36, v38, v14
	v_fmac_f32_e32 v38, v39, v37
	v_fma_f32 v14, -v36, v38, v14
	v_div_scale_f32 v36, s[0:1], v32, v32, v31
	v_rcp_f32_e32 v39, v36
	v_div_fmas_f32 v14, v14, v37, v38
	v_div_fixup_f32 v33, v14, v33, v18
	v_fma_f32 v14, -v36, v39, 1.0
	v_fmac_f32_e32 v39, v14, v39
	v_div_scale_f32 v14, vcc, v31, v32, v31
	v_mul_f32_e32 v18, v14, v39
	v_fma_f32 v37, -v36, v18, v14
	v_fmac_f32_e32 v18, v37, v39
	v_fma_f32 v14, -v36, v18, v14
	v_lshlrev_b32_e32 v36, 16, v19
	v_and_b32_e32 v37, 0xffff0000, v19
	v_div_fmas_f32 v14, v14, v39, v18
	v_mul_f32_e32 v18, 0xbfb8aa3b, v36
	v_mul_f32_e32 v19, 0xbfb8aa3b, v37
	v_exp_f32_e32 v18, v18
	v_exp_f32_e32 v19, v19
	v_div_fixup_f32 v32, v14, v32, v31
	v_pk_mul_f32 v[32:33], v[34:35], v[32:33]
	v_lshlrev_b32_e32 v14, 16, v15
	v_pk_add_f32 v[18:19], v[18:19], 1.0 op_sel_hi:[1,0]
	v_and_b32_e32 v15, 0xffff0000, v15
	v_div_scale_f32 v31, s[0:1], v19, v19, v37
	v_rcp_f32_e32 v34, v31
	v_pk_mul_f32 v[14:15], v[24:25], v[14:15] op_sel_hi:[0,1]
	v_pk_mul_f32 v[14:15], v[8:9], v[14:15]
	v_fma_f32 v35, -v31, v34, 1.0
	v_fmac_f32_e32 v34, v35, v34
	v_div_scale_f32 v35, vcc, v37, v19, v37
	v_mul_f32_e32 v38, v35, v34
	v_fma_f32 v39, -v31, v38, v35
	v_fmac_f32_e32 v38, v39, v34
	v_fma_f32 v31, -v31, v38, v35
	v_div_scale_f32 v35, s[0:1], v18, v18, v36
	v_rcp_f32_e32 v39, v35
	v_div_fmas_f32 v31, v31, v34, v38
	v_div_fixup_f32 v19, v31, v19, v37
	v_fma_f32 v31, -v35, v39, 1.0
	v_fmac_f32_e32 v39, v31, v39
	v_div_scale_f32 v31, vcc, v36, v18, v36
	v_mul_f32_e32 v34, v31, v39
	v_fma_f32 v37, -v35, v34, v31
	v_fmac_f32_e32 v34, v37, v39
	v_fma_f32 v31, -v35, v34, v31
	v_lshlrev_b32_e32 v37, 16, v20
	v_and_b32_e32 v20, 0xffff0000, v20
	v_div_fmas_f32 v31, v31, v39, v34
	v_mul_f32_e32 v34, 0xbfb8aa3b, v37
	v_mul_f32_e32 v35, 0xbfb8aa3b, v20
	v_exp_f32_e32 v34, v34
	v_exp_f32_e32 v35, v35
	v_div_fixup_f32 v18, v31, v18, v36
	v_pk_mul_f32 v[18:19], v[14:15], v[18:19]
	v_lshlrev_b32_e32 v14, 16, v16
	v_pk_add_f32 v[34:35], v[34:35], 1.0 op_sel_hi:[1,0]
	v_and_b32_e32 v15, 0xffff0000, v16
	v_div_scale_f32 v31, s[0:1], v35, v35, v20
	v_rcp_f32_e32 v36, v31
	v_pk_mul_f32 v[14:15], v[24:25], v[14:15] op_sel_hi:[0,1]
	v_pk_mul_f32 v[14:15], v[2:3], v[14:15]
	v_fma_f32 v16, -v31, v36, 1.0
	v_fmac_f32_e32 v36, v16, v36
	v_div_scale_f32 v16, vcc, v20, v35, v20
	v_mul_f32_e32 v38, v16, v36
	v_fma_f32 v39, -v31, v38, v16
	v_fmac_f32_e32 v38, v39, v36
	v_fma_f32 v16, -v31, v38, v16
	v_div_scale_f32 v31, s[0:1], v34, v34, v37
	v_rcp_f32_e32 v39, v31
	v_div_fmas_f32 v16, v16, v36, v38
	v_div_fixup_f32 v35, v16, v35, v20
	v_fma_f32 v16, -v31, v39, 1.0
	v_fmac_f32_e32 v39, v16, v39
	v_div_scale_f32 v16, vcc, v37, v34, v37
	v_mul_f32_e32 v20, v16, v39
	v_fma_f32 v36, -v31, v20, v16
	v_fmac_f32_e32 v20, v36, v39
	v_fma_f32 v16, -v31, v20, v16
	v_lshlrev_b32_e32 v31, 16, v21
	v_and_b32_e32 v36, 0xffff0000, v21
	v_div_fmas_f32 v16, v16, v39, v20
	v_mul_f32_e32 v20, 0xbfb8aa3b, v31
	v_mul_f32_e32 v21, 0xbfb8aa3b, v36
	v_exp_f32_e32 v20, v20
	v_exp_f32_e32 v21, v21
	v_div_fixup_f32 v34, v16, v34, v37
	v_pk_mul_f32 v[34:35], v[14:15], v[34:35]
	v_lshlrev_b32_e32 v14, 16, v17
	v_pk_add_f32 v[20:21], v[20:21], 1.0 op_sel_hi:[1,0]
	v_and_b32_e32 v15, 0xffff0000, v17
	v_div_scale_f32 v16, s[0:1], v21, v21, v36
	v_rcp_f32_e32 v37, v16
	v_pk_mul_f32 v[14:15], v[24:25], v[14:15] op_sel_hi:[0,1]
	v_pk_mul_f32 v[14:15], v[4:5], v[14:15]
	v_fma_f32 v17, -v16, v37, 1.0
	v_fmac_f32_e32 v37, v17, v37
	v_div_scale_f32 v17, vcc, v36, v21, v36
	v_mul_f32_e32 v24, v17, v37
	v_fma_f32 v38, -v16, v24, v17
	v_fmac_f32_e32 v24, v38, v37
	v_div_scale_f32 v38, s[0:1], v20, v20, v31
	v_rcp_f32_e32 v39, v38
	v_fma_f32 v16, -v16, v24, v17
	v_div_fmas_f32 v16, v16, v37, v24
	v_div_fixup_f32 v17, v16, v21, v36
	v_fma_f32 v16, -v38, v39, 1.0
	v_fmac_f32_e32 v39, v16, v39
	v_div_scale_f32 v16, vcc, v31, v20, v31
	v_mul_f32_e32 v21, v16, v39
	v_fma_f32 v24, -v38, v21, v16
	v_fmac_f32_e32 v21, v24, v39
	v_fma_f32 v16, -v38, v21, v16
	v_div_fmas_f32 v16, v16, v39, v21
	v_div_fixup_f32 v16, v16, v20, v31
	v_pk_mul_f32 v[20:21], v[14:15], v[16:17]
	v_cvt_pk_bf16_f32 v14, v32, v33
	v_cvt_pk_bf16_f32 v15, v18, v19
	v_cvt_pk_bf16_f32 v16, v34, v35
	v_cvt_pk_bf16_f32 v17, v20, v21
	v_lshl_add_u64 v[18:19], s[36:37], 0, v[26:27]
	global_store_dwordx4 v[18:19], v[14:17], off sc1
	s_waitcnt lgkmcnt(0)
	v_lshlrev_b32_e32 v26, 16, v10
	v_and_b32_e32 v27, 0xffff0000, v10
	v_or_b32_e32 v14, 10, v22
	v_mov_b32_e32 v15, v23
	v_lshlrev_b64 v[18:19], 11, v[14:15]
	v_or_b32_e32 v18, v18, v28
	v_lshl_add_u64 v[14:15], s[60:61], 0, v[18:19]
	global_load_dwordx4 v[14:17], v[14:15], off
	v_mov_b32_e32 v10, v25
	v_pk_mul_f32 v[24:25], v[10:11], v[26:27] op_sel_hi:[0,1]
	v_pk_mul_f32 v[24:25], v[6:7], v[24:25]
	s_waitcnt vmcnt(0)
	v_lshlrev_b32_e32 v31, 16, v14
	v_and_b32_e32 v14, 0xffff0000, v14
	v_mul_f32_e32 v20, 0xbfb8aa3b, v31
	v_mul_f32_e32 v21, 0xbfb8aa3b, v14
	v_exp_f32_e32 v20, v20
	v_exp_f32_e32 v21, v21
	s_nop 0
	v_pk_add_f32 v[20:21], v[20:21], 1.0 op_sel_hi:[1,0]
	s_nop 0
	v_div_scale_f32 v32, s[0:1], v21, v21, v14
	v_rcp_f32_e32 v33, v32
	s_nop 0
	v_fma_f32 v26, -v32, v33, 1.0
	v_fmac_f32_e32 v33, v26, v33
	v_div_scale_f32 v26, vcc, v14, v21, v14
	v_mul_f32_e32 v27, v26, v33
	v_fma_f32 v34, -v32, v27, v26
	v_fmac_f32_e32 v27, v34, v33
	v_fma_f32 v26, -v32, v27, v26
	v_div_scale_f32 v32, s[0:1], v20, v20, v31
	v_rcp_f32_e32 v34, v32
	v_div_fmas_f32 v26, v26, v33, v27
	v_div_fixup_f32 v21, v26, v21, v14
	v_fma_f32 v14, -v32, v34, 1.0
	v_fmac_f32_e32 v34, v14, v34
	v_div_scale_f32 v14, vcc, v31, v20, v31
	v_mul_f32_e32 v26, v14, v34
	v_fma_f32 v27, -v32, v26, v14
	v_fmac_f32_e32 v26, v27, v34
	v_fma_f32 v14, -v32, v26, v14
	v_lshlrev_b32_e32 v32, 16, v15
	v_and_b32_e32 v27, 0xffff0000, v15
	v_div_fmas_f32 v26, v14, v34, v26
	v_mul_f32_e32 v14, 0xbfb8aa3b, v32
	v_mul_f32_e32 v15, 0xbfb8aa3b, v27
	v_exp_f32_e32 v14, v14
	v_exp_f32_e32 v15, v15
	v_div_fixup_f32 v20, v26, v20, v31
	v_pk_mul_f32 v[20:21], v[24:25], v[20:21]
	v_lshlrev_b32_e32 v24, 16, v11
	v_pk_add_f32 v[14:15], v[14:15], 1.0 op_sel_hi:[1,0]
	v_and_b32_e32 v25, 0xffff0000, v11
	v_div_scale_f32 v26, s[0:1], v15, v15, v27
	v_rcp_f32_e32 v31, v26
	v_pk_mul_f32 v[24:25], v[10:11], v[24:25] op_sel_hi:[0,1]
	v_pk_mul_f32 v[24:25], v[8:9], v[24:25]
	v_fma_f32 v11, -v26, v31, 1.0
	v_fmac_f32_e32 v31, v11, v31
	v_div_scale_f32 v11, vcc, v27, v15, v27
	v_mul_f32_e32 v33, v11, v31
	v_fma_f32 v34, -v26, v33, v11
	v_fmac_f32_e32 v33, v34, v31
	v_fma_f32 v11, -v26, v33, v11
	v_div_scale_f32 v26, s[0:1], v14, v14, v32
	v_rcp_f32_e32 v34, v26
	v_div_fmas_f32 v11, v11, v31, v33
	v_div_fixup_f32 v15, v11, v15, v27
	v_fma_f32 v11, -v26, v34, 1.0
	v_fmac_f32_e32 v34, v11, v34
	v_div_scale_f32 v11, vcc, v32, v14, v32
	v_mul_f32_e32 v27, v11, v34
	v_fma_f32 v31, -v26, v27, v11
	v_fmac_f32_e32 v27, v31, v34
	v_fma_f32 v11, -v26, v27, v11
	v_lshlrev_b32_e32 v31, 16, v16
	v_and_b32_e32 v16, 0xffff0000, v16
	v_div_fmas_f32 v11, v11, v34, v27
	v_mul_f32_e32 v26, 0xbfb8aa3b, v31
	v_mul_f32_e32 v27, 0xbfb8aa3b, v16
	v_exp_f32_e32 v26, v26
	v_exp_f32_e32 v27, v27
	v_div_fixup_f32 v14, v11, v14, v32
	v_pk_mul_f32 v[14:15], v[24:25], v[14:15]
	v_lshlrev_b32_e32 v24, 16, v12
	v_pk_add_f32 v[26:27], v[26:27], 1.0 op_sel_hi:[1,0]
	v_and_b32_e32 v25, 0xffff0000, v12
	v_div_scale_f32 v11, s[0:1], v27, v27, v16
	v_rcp_f32_e32 v32, v11
	v_pk_mul_f32 v[24:25], v[10:11], v[24:25] op_sel_hi:[0,1]
	v_pk_mul_f32 v[24:25], v[2:3], v[24:25]
	v_fma_f32 v12, -v11, v32, 1.0
	v_fmac_f32_e32 v32, v12, v32
	v_div_scale_f32 v12, vcc, v16, v27, v16
	v_mul_f32_e32 v33, v12, v32
	v_fma_f32 v34, -v11, v33, v12
	v_fmac_f32_e32 v33, v34, v32
	v_fma_f32 v11, -v11, v33, v12
	v_div_scale_f32 v12, s[0:1], v26, v26, v31
	v_rcp_f32_e32 v34, v12
	v_div_fmas_f32 v11, v11, v32, v33
	v_div_fixup_f32 v27, v11, v27, v16
	v_and_b32_e32 v33, 0xffff0000, v17
	v_fma_f32 v11, -v12, v34, 1.0
	v_fmac_f32_e32 v34, v11, v34
	v_div_scale_f32 v11, vcc, v31, v26, v31
	v_mul_f32_e32 v16, v11, v34
	v_fma_f32 v32, -v12, v16, v11
	v_fmac_f32_e32 v16, v32, v34
	v_lshlrev_b32_e32 v32, 16, v17
	v_fma_f32 v11, -v12, v16, v11
	v_mul_f32_e32 v12, 0xbfb8aa3b, v32
	v_div_fmas_f32 v11, v11, v34, v16
	v_exp_f32_e32 v16, v12
	v_mul_f32_e32 v12, 0xbfb8aa3b, v33
	v_exp_f32_e32 v17, v12
	v_div_fixup_f32 v26, v11, v26, v31
	v_pk_mul_f32 v[24:25], v[24:25], v[26:27]
	v_lshlrev_b32_e32 v12, 16, v13
	v_pk_add_f32 v[16:17], v[16:17], 1.0 op_sel_hi:[1,0]
	v_and_b32_e32 v13, 0xffff0000, v13
	v_div_scale_f32 v26, s[0:1], v17, v17, v33
	v_rcp_f32_e32 v27, v26
	v_pk_mul_f32 v[10:11], v[10:11], v[12:13] op_sel_hi:[0,1]
	v_pk_mul_f32 v[10:11], v[4:5], v[10:11]
	v_fma_f32 v12, -v26, v27, 1.0
	v_fmac_f32_e32 v27, v12, v27
	v_div_scale_f32 v12, vcc, v33, v17, v33
	v_mul_f32_e32 v13, v12, v27
	v_fma_f32 v31, -v26, v13, v12
	v_fmac_f32_e32 v13, v31, v27
	v_fma_f32 v12, -v26, v13, v12
	v_div_scale_f32 v26, s[0:1], v16, v16, v32
	v_rcp_f32_e32 v31, v26
	v_div_fmas_f32 v12, v12, v27, v13
	v_div_fixup_f32 v13, v12, v17, v33
	v_fma_f32 v12, -v26, v31, 1.0
	v_fmac_f32_e32 v31, v12, v31
	v_div_scale_f32 v12, vcc, v32, v16, v32
	v_mul_f32_e32 v17, v12, v31
	v_fma_f32 v27, -v26, v17, v12
	v_fmac_f32_e32 v17, v27, v31
	v_fma_f32 v12, -v26, v17, v12
	v_div_fmas_f32 v12, v12, v31, v17
	v_div_fixup_f32 v12, v12, v16, v32
	v_pk_mul_f32 v[16:17], v[10:11], v[12:13]
	v_cvt_pk_bf16_f32 v10, v20, v21
	v_cvt_pk_bf16_f32 v11, v14, v15
	v_cvt_pk_bf16_f32 v12, v24, v25
	v_cvt_pk_bf16_f32 v13, v16, v17
	v_lshl_add_u64 v[14:15], s[36:37], 0, v[18:19]
	global_store_dwordx4 v[14:15], v[10:13], off sc1
	ds_read_b128 v[14:17], v29 offset:6336
	s_waitcnt lgkmcnt(0)
	v_lshlrev_b32_e32 v34, 16, v14
	v_or_b32_e32 v10, 12, v22
	v_mov_b32_e32 v11, v23
	v_lshlrev_b64 v[26:27], 11, v[10:11]
	v_or_b32_e32 v26, v26, v28
	v_lshl_add_u64 v[10:11], s[60:61], 0, v[26:27]
	global_load_dwordx4 v[18:21], v[10:11], off
	v_and_b32_e32 v35, 0xffff0000, v14
	s_waitcnt vmcnt(0)
	v_lshlrev_b32_e32 v31, 16, v18
	v_and_b32_e32 v18, 0xffff0000, v18
	v_mul_f32_e32 v10, 0xbfb8aa3b, v31
	v_exp_f32_e32 v32, v10
	v_mul_f32_e32 v10, 0xbfb8aa3b, v18
	v_exp_f32_e32 v33, v10
	ds_read2_b32 v[24:25], v30 offset0:140 offset1:142
	ds_read_b128 v[10:13], v29 offset:7392
	v_pk_add_f32 v[32:33], v[32:33], 1.0 op_sel_hi:[1,0]
	s_nop 0
	v_div_scale_f32 v36, s[0:1], v33, v33, v18
	v_rcp_f32_e32 v37, v36
	s_waitcnt lgkmcnt(1)
	v_pk_mul_f32 v[34:35], v[24:25], v[34:35] op_sel_hi:[0,1]
	v_pk_mul_f32 v[34:35], v[6:7], v[34:35]
	v_fma_f32 v14, -v36, v37, 1.0
	v_fmac_f32_e32 v37, v14, v37
	v_div_scale_f32 v14, vcc, v18, v33, v18
	v_mul_f32_e32 v38, v14, v37
	v_fma_f32 v39, -v36, v38, v14
	v_fmac_f32_e32 v38, v39, v37
	v_fma_f32 v14, -v36, v38, v14
	v_div_scale_f32 v36, s[0:1], v32, v32, v31
	v_rcp_f32_e32 v39, v36
	v_div_fmas_f32 v14, v14, v37, v38
	v_div_fixup_f32 v33, v14, v33, v18
	v_fma_f32 v14, -v36, v39, 1.0
	v_fmac_f32_e32 v39, v14, v39
	v_div_scale_f32 v14, vcc, v31, v32, v31
	v_mul_f32_e32 v18, v14, v39
	v_fma_f32 v37, -v36, v18, v14
	v_fmac_f32_e32 v18, v37, v39
	v_fma_f32 v14, -v36, v18, v14
	v_lshlrev_b32_e32 v36, 16, v19
	v_and_b32_e32 v37, 0xffff0000, v19
	v_div_fmas_f32 v14, v14, v39, v18
	v_mul_f32_e32 v18, 0xbfb8aa3b, v36
	v_mul_f32_e32 v19, 0xbfb8aa3b, v37
	v_exp_f32_e32 v18, v18
	v_exp_f32_e32 v19, v19
	v_div_fixup_f32 v32, v14, v32, v31
	v_pk_mul_f32 v[32:33], v[34:35], v[32:33]
	v_lshlrev_b32_e32 v14, 16, v15
	v_pk_add_f32 v[18:19], v[18:19], 1.0 op_sel_hi:[1,0]
	v_and_b32_e32 v15, 0xffff0000, v15
	v_div_scale_f32 v31, s[0:1], v19, v19, v37
	v_rcp_f32_e32 v34, v31
	v_pk_mul_f32 v[14:15], v[24:25], v[14:15] op_sel_hi:[0,1]
	v_pk_mul_f32 v[14:15], v[8:9], v[14:15]
	v_fma_f32 v35, -v31, v34, 1.0
	v_fmac_f32_e32 v34, v35, v34
	v_div_scale_f32 v35, vcc, v37, v19, v37
	v_mul_f32_e32 v38, v35, v34
	v_fma_f32 v39, -v31, v38, v35
	v_fmac_f32_e32 v38, v39, v34
	v_fma_f32 v31, -v31, v38, v35
	v_div_scale_f32 v35, s[0:1], v18, v18, v36
	v_rcp_f32_e32 v39, v35
	v_div_fmas_f32 v31, v31, v34, v38
	v_div_fixup_f32 v19, v31, v19, v37
	v_fma_f32 v31, -v35, v39, 1.0
	v_fmac_f32_e32 v39, v31, v39
	v_div_scale_f32 v31, vcc, v36, v18, v36
	v_mul_f32_e32 v34, v31, v39
	v_fma_f32 v37, -v35, v34, v31
	v_fmac_f32_e32 v34, v37, v39
	v_fma_f32 v31, -v35, v34, v31
	v_lshlrev_b32_e32 v37, 16, v20
	v_and_b32_e32 v20, 0xffff0000, v20
	v_div_fmas_f32 v31, v31, v39, v34
	v_mul_f32_e32 v34, 0xbfb8aa3b, v37
	v_mul_f32_e32 v35, 0xbfb8aa3b, v20
	v_exp_f32_e32 v34, v34
	v_exp_f32_e32 v35, v35
	v_div_fixup_f32 v18, v31, v18, v36
	v_pk_mul_f32 v[18:19], v[14:15], v[18:19]
	v_lshlrev_b32_e32 v14, 16, v16
	v_pk_add_f32 v[34:35], v[34:35], 1.0 op_sel_hi:[1,0]
	v_and_b32_e32 v15, 0xffff0000, v16
	v_div_scale_f32 v31, s[0:1], v35, v35, v20
	v_rcp_f32_e32 v36, v31
	v_pk_mul_f32 v[14:15], v[24:25], v[14:15] op_sel_hi:[0,1]
	v_pk_mul_f32 v[14:15], v[2:3], v[14:15]
	v_fma_f32 v16, -v31, v36, 1.0
	v_fmac_f32_e32 v36, v16, v36
	v_div_scale_f32 v16, vcc, v20, v35, v20
	v_mul_f32_e32 v38, v16, v36
	v_fma_f32 v39, -v31, v38, v16
	v_fmac_f32_e32 v38, v39, v36
	v_fma_f32 v16, -v31, v38, v16
	v_div_scale_f32 v31, s[0:1], v34, v34, v37
	v_rcp_f32_e32 v39, v31
	v_div_fmas_f32 v16, v16, v36, v38
	v_div_fixup_f32 v35, v16, v35, v20
	v_fma_f32 v16, -v31, v39, 1.0
	v_fmac_f32_e32 v39, v16, v39
	v_div_scale_f32 v16, vcc, v37, v34, v37
	v_mul_f32_e32 v20, v16, v39
	v_fma_f32 v36, -v31, v20, v16
	v_fmac_f32_e32 v20, v36, v39
	v_fma_f32 v16, -v31, v20, v16
	v_lshlrev_b32_e32 v31, 16, v21
	v_and_b32_e32 v36, 0xffff0000, v21
	v_div_fmas_f32 v16, v16, v39, v20
	v_mul_f32_e32 v20, 0xbfb8aa3b, v31
	v_mul_f32_e32 v21, 0xbfb8aa3b, v36
	v_exp_f32_e32 v20, v20
	v_exp_f32_e32 v21, v21
	v_div_fixup_f32 v34, v16, v34, v37
	v_pk_mul_f32 v[34:35], v[14:15], v[34:35]
	v_lshlrev_b32_e32 v14, 16, v17
	v_pk_add_f32 v[20:21], v[20:21], 1.0 op_sel_hi:[1,0]
	v_and_b32_e32 v15, 0xffff0000, v17
	v_div_scale_f32 v16, s[0:1], v21, v21, v36
	v_rcp_f32_e32 v37, v16
	v_pk_mul_f32 v[14:15], v[24:25], v[14:15] op_sel_hi:[0,1]
	v_pk_mul_f32 v[14:15], v[4:5], v[14:15]
	v_fma_f32 v17, -v16, v37, 1.0
	v_fmac_f32_e32 v37, v17, v37
	v_div_scale_f32 v17, vcc, v36, v21, v36
	v_mul_f32_e32 v24, v17, v37
	v_fma_f32 v38, -v16, v24, v17
	v_fmac_f32_e32 v24, v38, v37
	v_div_scale_f32 v38, s[0:1], v20, v20, v31
	v_rcp_f32_e32 v39, v38
	v_fma_f32 v16, -v16, v24, v17
	v_div_fmas_f32 v16, v16, v37, v24
	v_div_fixup_f32 v17, v16, v21, v36
	v_fma_f32 v16, -v38, v39, 1.0
	v_fmac_f32_e32 v39, v16, v39
	v_div_scale_f32 v16, vcc, v31, v20, v31
	v_mul_f32_e32 v21, v16, v39
	v_fma_f32 v24, -v38, v21, v16
	v_fmac_f32_e32 v21, v24, v39
	v_fma_f32 v16, -v38, v21, v16
	v_div_fmas_f32 v16, v16, v39, v21
	v_div_fixup_f32 v16, v16, v20, v31
	v_pk_mul_f32 v[20:21], v[14:15], v[16:17]
	v_cvt_pk_bf16_f32 v14, v32, v33
	v_cvt_pk_bf16_f32 v15, v18, v19
	v_cvt_pk_bf16_f32 v16, v34, v35
	v_cvt_pk_bf16_f32 v17, v20, v21
	v_lshl_add_u64 v[18:19], s[36:37], 0, v[26:27]
	global_store_dwordx4 v[18:19], v[14:17], off sc1
	s_waitcnt lgkmcnt(0)
	v_lshlrev_b32_e32 v26, 16, v10
	v_and_b32_e32 v27, 0xffff0000, v10
	v_or_b32_e32 v14, 14, v22
	v_mov_b32_e32 v15, v23
	v_lshlrev_b64 v[18:19], 11, v[14:15]
	v_or_b32_e32 v18, v18, v28
	v_lshl_add_u64 v[14:15], s[60:61], 0, v[18:19]
	global_load_dwordx4 v[14:17], v[14:15], off
	v_mov_b32_e32 v10, v25
	v_pk_mul_f32 v[24:25], v[10:11], v[26:27] op_sel_hi:[0,1]
	v_pk_mul_f32 v[24:25], v[6:7], v[24:25]
	s_waitcnt vmcnt(0)
	v_lshlrev_b32_e32 v31, 16, v14
	v_and_b32_e32 v14, 0xffff0000, v14
	v_mul_f32_e32 v20, 0xbfb8aa3b, v31
	v_mul_f32_e32 v21, 0xbfb8aa3b, v14
	v_exp_f32_e32 v20, v20
	v_exp_f32_e32 v21, v21
	s_nop 0
	v_pk_add_f32 v[20:21], v[20:21], 1.0 op_sel_hi:[1,0]
	s_nop 0
	v_div_scale_f32 v32, s[0:1], v21, v21, v14
	v_rcp_f32_e32 v33, v32
	s_nop 0
	v_fma_f32 v26, -v32, v33, 1.0
	v_fmac_f32_e32 v33, v26, v33
	v_div_scale_f32 v26, vcc, v14, v21, v14
	v_mul_f32_e32 v27, v26, v33
	v_fma_f32 v34, -v32, v27, v26
	v_fmac_f32_e32 v27, v34, v33
	v_fma_f32 v26, -v32, v27, v26
	v_div_scale_f32 v32, s[0:1], v20, v20, v31
	v_rcp_f32_e32 v34, v32
	v_div_fmas_f32 v26, v26, v33, v27
	v_div_fixup_f32 v21, v26, v21, v14
	v_fma_f32 v14, -v32, v34, 1.0
	v_fmac_f32_e32 v34, v14, v34
	v_div_scale_f32 v14, vcc, v31, v20, v31
	v_mul_f32_e32 v26, v14, v34
	v_fma_f32 v27, -v32, v26, v14
	v_fmac_f32_e32 v26, v27, v34
	v_fma_f32 v14, -v32, v26, v14
	v_lshlrev_b32_e32 v32, 16, v15
	v_and_b32_e32 v27, 0xffff0000, v15
	v_div_fmas_f32 v26, v14, v34, v26
	v_mul_f32_e32 v14, 0xbfb8aa3b, v32
	v_mul_f32_e32 v15, 0xbfb8aa3b, v27
	v_exp_f32_e32 v14, v14
	v_exp_f32_e32 v15, v15
	v_div_fixup_f32 v20, v26, v20, v31
	v_pk_mul_f32 v[20:21], v[24:25], v[20:21]
	v_lshlrev_b32_e32 v24, 16, v11
	v_pk_add_f32 v[14:15], v[14:15], 1.0 op_sel_hi:[1,0]
	v_and_b32_e32 v25, 0xffff0000, v11
	v_div_scale_f32 v26, s[0:1], v15, v15, v27
	v_rcp_f32_e32 v31, v26
	v_pk_mul_f32 v[24:25], v[10:11], v[24:25] op_sel_hi:[0,1]
	v_pk_mul_f32 v[24:25], v[8:9], v[24:25]
	v_fma_f32 v11, -v26, v31, 1.0
	v_fmac_f32_e32 v31, v11, v31
	v_div_scale_f32 v11, vcc, v27, v15, v27
	v_mul_f32_e32 v33, v11, v31
	v_fma_f32 v34, -v26, v33, v11
	v_fmac_f32_e32 v33, v34, v31
	v_fma_f32 v11, -v26, v33, v11
	v_div_scale_f32 v26, s[0:1], v14, v14, v32
	v_rcp_f32_e32 v34, v26
	v_div_fmas_f32 v11, v11, v31, v33
	v_div_fixup_f32 v15, v11, v15, v27
	v_fma_f32 v11, -v26, v34, 1.0
	v_fmac_f32_e32 v34, v11, v34
	v_div_scale_f32 v11, vcc, v32, v14, v32
	v_mul_f32_e32 v27, v11, v34
	v_fma_f32 v31, -v26, v27, v11
	v_fmac_f32_e32 v27, v31, v34
	v_fma_f32 v11, -v26, v27, v11
	v_lshlrev_b32_e32 v31, 16, v16
	v_and_b32_e32 v16, 0xffff0000, v16
	v_div_fmas_f32 v11, v11, v34, v27
	v_mul_f32_e32 v26, 0xbfb8aa3b, v31
	v_mul_f32_e32 v27, 0xbfb8aa3b, v16
	v_exp_f32_e32 v26, v26
	v_exp_f32_e32 v27, v27
	v_div_fixup_f32 v14, v11, v14, v32
	v_pk_mul_f32 v[14:15], v[24:25], v[14:15]
	v_lshlrev_b32_e32 v24, 16, v12
	v_pk_add_f32 v[26:27], v[26:27], 1.0 op_sel_hi:[1,0]
	v_and_b32_e32 v25, 0xffff0000, v12
	v_div_scale_f32 v11, s[0:1], v27, v27, v16
	v_rcp_f32_e32 v32, v11
	v_pk_mul_f32 v[24:25], v[10:11], v[24:25] op_sel_hi:[0,1]
	v_pk_mul_f32 v[24:25], v[2:3], v[24:25]
	v_fma_f32 v12, -v11, v32, 1.0
	v_fmac_f32_e32 v32, v12, v32
	v_div_scale_f32 v12, vcc, v16, v27, v16
	v_mul_f32_e32 v33, v12, v32
	v_fma_f32 v34, -v11, v33, v12
	v_fmac_f32_e32 v33, v34, v32
	v_fma_f32 v11, -v11, v33, v12
	v_div_scale_f32 v12, s[0:1], v26, v26, v31
	v_rcp_f32_e32 v34, v12
	v_div_fmas_f32 v11, v11, v32, v33
	v_div_fixup_f32 v27, v11, v27, v16
	v_and_b32_e32 v33, 0xffff0000, v17
	v_fma_f32 v11, -v12, v34, 1.0
	v_fmac_f32_e32 v34, v11, v34
	v_div_scale_f32 v11, vcc, v31, v26, v31
	v_mul_f32_e32 v16, v11, v34
	v_fma_f32 v32, -v12, v16, v11
	v_fmac_f32_e32 v16, v32, v34
	v_lshlrev_b32_e32 v32, 16, v17
	v_fma_f32 v11, -v12, v16, v11
	v_mul_f32_e32 v12, 0xbfb8aa3b, v32
	v_div_fmas_f32 v11, v11, v34, v16
	v_exp_f32_e32 v16, v12
	v_mul_f32_e32 v12, 0xbfb8aa3b, v33
	v_exp_f32_e32 v17, v12
	v_div_fixup_f32 v26, v11, v26, v31
	v_pk_mul_f32 v[24:25], v[24:25], v[26:27]
	v_lshlrev_b32_e32 v12, 16, v13
	v_pk_add_f32 v[16:17], v[16:17], 1.0 op_sel_hi:[1,0]
	v_and_b32_e32 v13, 0xffff0000, v13
	v_div_scale_f32 v26, s[0:1], v17, v17, v33
	v_rcp_f32_e32 v27, v26
	v_pk_mul_f32 v[10:11], v[10:11], v[12:13] op_sel_hi:[0,1]
	v_pk_mul_f32 v[10:11], v[4:5], v[10:11]
	v_fma_f32 v12, -v26, v27, 1.0
	v_fmac_f32_e32 v27, v12, v27
	v_div_scale_f32 v12, vcc, v33, v17, v33
	v_mul_f32_e32 v13, v12, v27
	v_fma_f32 v31, -v26, v13, v12
	v_fmac_f32_e32 v13, v31, v27
	v_fma_f32 v12, -v26, v13, v12
	v_div_scale_f32 v26, s[0:1], v16, v16, v32
	v_rcp_f32_e32 v31, v26
	v_div_fmas_f32 v12, v12, v27, v13
	v_div_fixup_f32 v13, v12, v17, v33
	v_fma_f32 v12, -v26, v31, 1.0
	v_fmac_f32_e32 v31, v12, v31
	v_div_scale_f32 v12, vcc, v32, v16, v32
	v_mul_f32_e32 v17, v12, v31
	v_fma_f32 v27, -v26, v17, v12
	v_fmac_f32_e32 v17, v27, v31
	v_fma_f32 v12, -v26, v17, v12
	v_div_fmas_f32 v12, v12, v31, v17
	v_div_fixup_f32 v12, v12, v16, v32
	v_pk_mul_f32 v[16:17], v[10:11], v[12:13]
	v_cvt_pk_bf16_f32 v10, v20, v21
	v_cvt_pk_bf16_f32 v11, v14, v15
	v_cvt_pk_bf16_f32 v12, v24, v25
	v_cvt_pk_bf16_f32 v13, v16, v17
	v_lshl_add_u64 v[14:15], s[36:37], 0, v[18:19]
	global_store_dwordx4 v[14:15], v[10:13], off sc1
	ds_read_b128 v[14:17], v29 offset:8448
	ds_read2_b32 v[34:35], v30 offset0:144 offset1:146
	v_or_b32_e32 v10, 16, v22
	v_mov_b32_e32 v11, v23
	v_lshlrev_b64 v[24:25], 11, v[10:11]
	v_or_b32_e32 v24, v24, v28
	v_lshl_add_u64 v[10:11], s[60:61], 0, v[24:25]
	global_load_dwordx4 v[18:21], v[10:11], off
	s_waitcnt vmcnt(0)
	v_lshlrev_b32_e32 v31, 16, v18
	v_and_b32_e32 v18, 0xffff0000, v18
	v_mul_f32_e32 v10, 0xbfb8aa3b, v31
	v_exp_f32_e32 v26, v10
	v_mul_f32_e32 v10, 0xbfb8aa3b, v18
	v_exp_f32_e32 v27, v10
	ds_read_b128 v[10:13], v29 offset:9504
	s_waitcnt lgkmcnt(2)
	v_lshlrev_b32_e32 v32, 16, v14
	v_and_b32_e32 v33, 0xffff0000, v14
	v_pk_add_f32 v[26:27], v[26:27], 1.0 op_sel_hi:[1,0]
	s_waitcnt lgkmcnt(1)
	v_pk_mul_f32 v[32:33], v[34:35], v[32:33] op_sel_hi:[0,1]
	v_div_scale_f32 v36, s[0:1], v27, v27, v18
	v_rcp_f32_e32 v37, v36
	v_pk_mul_f32 v[32:33], v[6:7], v[32:33]
	v_fma_f32 v14, -v36, v37, 1.0
	v_fmac_f32_e32 v37, v14, v37
	v_div_scale_f32 v14, vcc, v18, v27, v18
	v_mul_f32_e32 v38, v14, v37
	v_fma_f32 v39, -v36, v38, v14
	v_fmac_f32_e32 v38, v39, v37
	v_fma_f32 v14, -v36, v38, v14
	v_div_scale_f32 v36, s[0:1], v26, v26, v31
	v_rcp_f32_e32 v39, v36
	v_div_fmas_f32 v14, v14, v37, v38
	v_div_fixup_f32 v27, v14, v27, v18
	v_fma_f32 v14, -v36, v39, 1.0
	v_fmac_f32_e32 v39, v14, v39
	v_div_scale_f32 v14, vcc, v31, v26, v31
	v_mul_f32_e32 v18, v14, v39
	v_fma_f32 v37, -v36, v18, v14
	v_fmac_f32_e32 v18, v37, v39
	v_fma_f32 v14, -v36, v18, v14
	v_lshlrev_b32_e32 v36, 16, v19
	v_and_b32_e32 v37, 0xffff0000, v19
	v_div_fmas_f32 v14, v14, v39, v18
	v_mul_f32_e32 v18, 0xbfb8aa3b, v36
	v_mul_f32_e32 v19, 0xbfb8aa3b, v37
	v_exp_f32_e32 v18, v18
	v_exp_f32_e32 v19, v19
	v_div_fixup_f32 v26, v14, v26, v31
	v_pk_mul_f32 v[26:27], v[32:33], v[26:27]
	v_lshlrev_b32_e32 v14, 16, v15
	v_pk_add_f32 v[18:19], v[18:19], 1.0 op_sel_hi:[1,0]
	v_and_b32_e32 v15, 0xffff0000, v15
	v_div_scale_f32 v31, s[0:1], v19, v19, v37
	v_rcp_f32_e32 v32, v31
	v_pk_mul_f32 v[14:15], v[34:35], v[14:15] op_sel_hi:[0,1]
	v_pk_mul_f32 v[14:15], v[8:9], v[14:15]
	v_fma_f32 v33, -v31, v32, 1.0
	v_fmac_f32_e32 v32, v33, v32
	v_div_scale_f32 v33, vcc, v37, v19, v37
	v_mul_f32_e32 v38, v33, v32
	v_fma_f32 v39, -v31, v38, v33
	v_fmac_f32_e32 v38, v39, v32
	v_fma_f32 v31, -v31, v38, v33
	v_div_scale_f32 v33, s[0:1], v18, v18, v36
	v_rcp_f32_e32 v39, v33
	v_div_fmas_f32 v31, v31, v32, v38
	v_div_fixup_f32 v19, v31, v19, v37
	v_fma_f32 v31, -v33, v39, 1.0
	v_fmac_f32_e32 v39, v31, v39
	v_div_scale_f32 v31, vcc, v36, v18, v36
	v_mul_f32_e32 v32, v31, v39
	v_fma_f32 v37, -v33, v32, v31
	v_fmac_f32_e32 v32, v37, v39
	v_fma_f32 v31, -v33, v32, v31
	v_lshlrev_b32_e32 v37, 16, v20
	v_and_b32_e32 v20, 0xffff0000, v20
	v_div_fmas_f32 v31, v31, v39, v32
	v_mul_f32_e32 v32, 0xbfb8aa3b, v37
	v_mul_f32_e32 v33, 0xbfb8aa3b, v20
	v_exp_f32_e32 v32, v32
	v_exp_f32_e32 v33, v33
	v_div_fixup_f32 v18, v31, v18, v36
	v_pk_mul_f32 v[18:19], v[14:15], v[18:19]
	v_lshlrev_b32_e32 v14, 16, v16
	v_pk_add_f32 v[32:33], v[32:33], 1.0 op_sel_hi:[1,0]
	v_and_b32_e32 v15, 0xffff0000, v16
	v_div_scale_f32 v31, s[0:1], v33, v33, v20
	v_rcp_f32_e32 v36, v31
	v_pk_mul_f32 v[14:15], v[34:35], v[14:15] op_sel_hi:[0,1]
	v_pk_mul_f32 v[14:15], v[2:3], v[14:15]
	v_fma_f32 v16, -v31, v36, 1.0
	v_fmac_f32_e32 v36, v16, v36
	v_div_scale_f32 v16, vcc, v20, v33, v20
	v_mul_f32_e32 v38, v16, v36
	v_fma_f32 v39, -v31, v38, v16
	v_fmac_f32_e32 v38, v39, v36
	v_fma_f32 v16, -v31, v38, v16
	v_div_scale_f32 v31, s[0:1], v32, v32, v37
	v_rcp_f32_e32 v39, v31
	v_div_fmas_f32 v16, v16, v36, v38
	v_div_fixup_f32 v33, v16, v33, v20
	v_fma_f32 v16, -v31, v39, 1.0
	v_fmac_f32_e32 v39, v16, v39
	v_div_scale_f32 v16, vcc, v37, v32, v37
	v_mul_f32_e32 v20, v16, v39
	v_fma_f32 v36, -v31, v20, v16
	v_fmac_f32_e32 v20, v36, v39
	v_fma_f32 v16, -v31, v20, v16
	v_lshlrev_b32_e32 v31, 16, v21
	v_and_b32_e32 v36, 0xffff0000, v21
	v_div_fmas_f32 v16, v16, v39, v20
	v_mul_f32_e32 v20, 0xbfb8aa3b, v31
	v_mul_f32_e32 v21, 0xbfb8aa3b, v36
	v_exp_f32_e32 v20, v20
	v_exp_f32_e32 v21, v21
	v_div_fixup_f32 v32, v16, v32, v37
	v_pk_mul_f32 v[32:33], v[14:15], v[32:33]
	v_lshlrev_b32_e32 v14, 16, v17
	v_pk_add_f32 v[20:21], v[20:21], 1.0 op_sel_hi:[1,0]
	v_and_b32_e32 v15, 0xffff0000, v17
	v_div_scale_f32 v16, s[0:1], v21, v21, v36
	v_rcp_f32_e32 v37, v16
	v_pk_mul_f32 v[14:15], v[34:35], v[14:15] op_sel_hi:[0,1]
	v_pk_mul_f32 v[14:15], v[4:5], v[14:15]
	v_fma_f32 v17, -v16, v37, 1.0
	v_fmac_f32_e32 v37, v17, v37
	v_div_scale_f32 v17, vcc, v36, v21, v36
	v_mul_f32_e32 v34, v17, v37
	v_fma_f32 v38, -v16, v34, v17
	v_fmac_f32_e32 v34, v38, v37
	v_div_scale_f32 v38, s[0:1], v20, v20, v31
	v_rcp_f32_e32 v39, v38
	v_fma_f32 v16, -v16, v34, v17
	v_div_fmas_f32 v16, v16, v37, v34
	v_div_fixup_f32 v17, v16, v21, v36
	v_fma_f32 v16, -v38, v39, 1.0
	v_fmac_f32_e32 v39, v16, v39
	v_div_scale_f32 v16, vcc, v31, v20, v31
	v_mul_f32_e32 v21, v16, v39
	v_fma_f32 v34, -v38, v21, v16
	v_fmac_f32_e32 v21, v34, v39
	v_fma_f32 v16, -v38, v21, v16
	v_div_fmas_f32 v16, v16, v39, v21
	v_div_fixup_f32 v16, v16, v20, v31
	v_pk_mul_f32 v[20:21], v[14:15], v[16:17]
	v_cvt_pk_bf16_f32 v14, v26, v27
	v_cvt_pk_bf16_f32 v15, v18, v19
	v_cvt_pk_bf16_f32 v16, v32, v33
	v_cvt_pk_bf16_f32 v17, v20, v21
	v_lshl_add_u64 v[18:19], s[36:37], 0, v[24:25]
	global_store_dwordx4 v[18:19], v[14:17], off sc1
	s_waitcnt lgkmcnt(0)
	v_lshlrev_b32_e32 v24, 16, v10
	v_and_b32_e32 v25, 0xffff0000, v10
	v_or_b32_e32 v14, 18, v22
	v_mov_b32_e32 v15, v23
	v_lshlrev_b64 v[18:19], 11, v[14:15]
	v_or_b32_e32 v18, v18, v28
	v_lshl_add_u64 v[14:15], s[60:61], 0, v[18:19]
	global_load_dwordx4 v[14:17], v[14:15], off
	v_mov_b32_e32 v10, v35
	v_pk_mul_f32 v[24:25], v[10:11], v[24:25] op_sel_hi:[0,1]
	v_pk_mul_f32 v[24:25], v[6:7], v[24:25]
	s_waitcnt vmcnt(0)
	v_lshlrev_b32_e32 v26, 16, v14
	v_and_b32_e32 v14, 0xffff0000, v14
	v_mul_f32_e32 v20, 0xbfb8aa3b, v26
	v_mul_f32_e32 v21, 0xbfb8aa3b, v14
	v_exp_f32_e32 v20, v20
	v_exp_f32_e32 v21, v21
	s_nop 0
	v_pk_add_f32 v[20:21], v[20:21], 1.0 op_sel_hi:[1,0]
	s_nop 0
	v_div_scale_f32 v27, s[0:1], v21, v21, v14
	v_rcp_f32_e32 v31, v27
	s_nop 0
	v_fma_f32 v32, -v27, v31, 1.0
	v_fmac_f32_e32 v31, v32, v31
	v_div_scale_f32 v32, vcc, v14, v21, v14
	v_mul_f32_e32 v33, v32, v31
	v_fma_f32 v34, -v27, v33, v32
	v_fmac_f32_e32 v33, v34, v31
	v_fma_f32 v27, -v27, v33, v32
	v_div_scale_f32 v32, s[0:1], v20, v20, v26
	v_rcp_f32_e32 v34, v32
	v_div_fmas_f32 v27, v27, v31, v33
	v_div_fixup_f32 v21, v27, v21, v14
	v_fma_f32 v14, -v32, v34, 1.0
	v_fmac_f32_e32 v34, v14, v34
	v_div_scale_f32 v14, vcc, v26, v20, v26
	v_mul_f32_e32 v27, v14, v34
	v_fma_f32 v31, -v32, v27, v14
	v_fmac_f32_e32 v27, v31, v34
	v_fma_f32 v14, -v32, v27, v14
	v_lshlrev_b32_e32 v31, 16, v15
	v_and_b32_e32 v32, 0xffff0000, v15
	v_div_fmas_f32 v27, v14, v34, v27
	v_mul_f32_e32 v14, 0xbfb8aa3b, v31
	v_mul_f32_e32 v15, 0xbfb8aa3b, v32
	v_exp_f32_e32 v14, v14
	v_exp_f32_e32 v15, v15
	v_div_fixup_f32 v20, v27, v20, v26
	v_pk_mul_f32 v[20:21], v[24:25], v[20:21]
	v_lshlrev_b32_e32 v24, 16, v11
	v_pk_add_f32 v[14:15], v[14:15], 1.0 op_sel_hi:[1,0]
	v_and_b32_e32 v25, 0xffff0000, v11
	v_div_scale_f32 v26, s[0:1], v15, v15, v32
	v_rcp_f32_e32 v27, v26
	v_pk_mul_f32 v[24:25], v[10:11], v[24:25] op_sel_hi:[0,1]
	v_pk_mul_f32 v[24:25], v[8:9], v[24:25]
	v_fma_f32 v11, -v26, v27, 1.0
	v_fmac_f32_e32 v27, v11, v27
	v_div_scale_f32 v11, vcc, v32, v15, v32
	v_mul_f32_e32 v33, v11, v27
	v_fma_f32 v34, -v26, v33, v11
	v_fmac_f32_e32 v33, v34, v27
	v_fma_f32 v11, -v26, v33, v11
	v_div_scale_f32 v26, s[0:1], v14, v14, v31
	v_rcp_f32_e32 v34, v26
	v_div_fmas_f32 v11, v11, v27, v33
	v_div_fixup_f32 v15, v11, v15, v32
	v_fma_f32 v11, -v26, v34, 1.0
	v_fmac_f32_e32 v34, v11, v34
	v_div_scale_f32 v11, vcc, v31, v14, v31
	v_mul_f32_e32 v27, v11, v34
	v_fma_f32 v32, -v26, v27, v11
	v_fmac_f32_e32 v27, v32, v34
	v_fma_f32 v11, -v26, v27, v11
	v_lshlrev_b32_e32 v32, 16, v16
	v_and_b32_e32 v16, 0xffff0000, v16
	v_div_fmas_f32 v11, v11, v34, v27
	v_mul_f32_e32 v26, 0xbfb8aa3b, v32
	v_mul_f32_e32 v27, 0xbfb8aa3b, v16
	v_exp_f32_e32 v26, v26
	v_exp_f32_e32 v27, v27
	v_div_fixup_f32 v14, v11, v14, v31
	v_pk_mul_f32 v[14:15], v[24:25], v[14:15]
	v_lshlrev_b32_e32 v24, 16, v12
	v_pk_add_f32 v[26:27], v[26:27], 1.0 op_sel_hi:[1,0]
	v_and_b32_e32 v25, 0xffff0000, v12
	v_div_scale_f32 v11, s[0:1], v27, v27, v16
	v_rcp_f32_e32 v31, v11
	v_pk_mul_f32 v[24:25], v[10:11], v[24:25] op_sel_hi:[0,1]
	v_pk_mul_f32 v[24:25], v[2:3], v[24:25]
	v_fma_f32 v12, -v11, v31, 1.0
	v_fmac_f32_e32 v31, v12, v31
	v_div_scale_f32 v12, vcc, v16, v27, v16
	v_mul_f32_e32 v33, v12, v31
	v_fma_f32 v34, -v11, v33, v12
	v_fmac_f32_e32 v33, v34, v31
	v_fma_f32 v11, -v11, v33, v12
	v_div_scale_f32 v12, s[0:1], v26, v26, v32
	v_rcp_f32_e32 v34, v12
	v_div_fmas_f32 v11, v11, v31, v33
	v_div_fixup_f32 v27, v11, v27, v16
	v_and_b32_e32 v33, 0xffff0000, v17
	v_fma_f32 v11, -v12, v34, 1.0
	v_fmac_f32_e32 v34, v11, v34
	v_div_scale_f32 v11, vcc, v32, v26, v32
	v_mul_f32_e32 v16, v11, v34
	v_fma_f32 v31, -v12, v16, v11
	v_fmac_f32_e32 v16, v31, v34
	v_lshlrev_b32_e32 v31, 16, v17
	v_fma_f32 v11, -v12, v16, v11
	v_mul_f32_e32 v12, 0xbfb8aa3b, v31
	v_div_fmas_f32 v11, v11, v34, v16
	v_exp_f32_e32 v16, v12
	v_mul_f32_e32 v12, 0xbfb8aa3b, v33
	v_exp_f32_e32 v17, v12
	v_div_fixup_f32 v26, v11, v26, v32
	v_pk_mul_f32 v[24:25], v[24:25], v[26:27]
	v_lshlrev_b32_e32 v12, 16, v13
	v_pk_add_f32 v[16:17], v[16:17], 1.0 op_sel_hi:[1,0]
	v_and_b32_e32 v13, 0xffff0000, v13
	v_div_scale_f32 v26, s[0:1], v17, v17, v33
	v_rcp_f32_e32 v27, v26
	v_pk_mul_f32 v[10:11], v[10:11], v[12:13] op_sel_hi:[0,1]
	v_pk_mul_f32 v[10:11], v[4:5], v[10:11]
	v_fma_f32 v12, -v26, v27, 1.0
	v_fmac_f32_e32 v27, v12, v27
	v_div_scale_f32 v12, vcc, v33, v17, v33
	v_mul_f32_e32 v13, v12, v27
	v_fma_f32 v32, -v26, v13, v12
	v_fmac_f32_e32 v13, v32, v27
	v_fma_f32 v12, -v26, v13, v12
	v_div_scale_f32 v26, s[0:1], v16, v16, v31
	v_rcp_f32_e32 v32, v26
	v_div_fmas_f32 v12, v12, v27, v13
	v_div_fixup_f32 v13, v12, v17, v33
	v_fma_f32 v12, -v26, v32, 1.0
	v_fmac_f32_e32 v32, v12, v32
	v_div_scale_f32 v12, vcc, v31, v16, v31
	v_mul_f32_e32 v17, v12, v32
	v_fma_f32 v27, -v26, v17, v12
	v_fmac_f32_e32 v17, v27, v32
	v_fma_f32 v12, -v26, v17, v12
	v_div_fmas_f32 v12, v12, v32, v17
	v_div_fixup_f32 v12, v12, v16, v31
	v_pk_mul_f32 v[16:17], v[10:11], v[12:13]
	v_cvt_pk_bf16_f32 v10, v20, v21
	v_cvt_pk_bf16_f32 v11, v14, v15
	v_cvt_pk_bf16_f32 v12, v24, v25
	v_cvt_pk_bf16_f32 v13, v16, v17
	v_lshl_add_u64 v[14:15], s[36:37], 0, v[18:19]
	global_store_dwordx4 v[14:15], v[10:13], off sc1
	ds_read_b128 v[14:17], v29 offset:10560
	s_waitcnt lgkmcnt(0)
	v_lshlrev_b32_e32 v34, 16, v14
	v_or_b32_e32 v10, 20, v22
	v_mov_b32_e32 v11, v23
	v_lshlrev_b64 v[26:27], 11, v[10:11]
	v_or_b32_e32 v26, v26, v28
	v_lshl_add_u64 v[10:11], s[60:61], 0, v[26:27]
	global_load_dwordx4 v[18:21], v[10:11], off
	v_and_b32_e32 v35, 0xffff0000, v14
	s_waitcnt vmcnt(0)
	v_lshlrev_b32_e32 v31, 16, v18
	v_and_b32_e32 v18, 0xffff0000, v18
	v_mul_f32_e32 v10, 0xbfb8aa3b, v31
	v_exp_f32_e32 v32, v10
	v_mul_f32_e32 v10, 0xbfb8aa3b, v18
	v_exp_f32_e32 v33, v10
	ds_read2_b32 v[24:25], v30 offset0:148 offset1:150
	ds_read_b128 v[10:13], v29 offset:11616
	v_pk_add_f32 v[32:33], v[32:33], 1.0 op_sel_hi:[1,0]
	s_nop 0
	v_div_scale_f32 v36, s[0:1], v33, v33, v18
	v_rcp_f32_e32 v37, v36
	s_waitcnt lgkmcnt(1)
	v_pk_mul_f32 v[34:35], v[24:25], v[34:35] op_sel_hi:[0,1]
	v_pk_mul_f32 v[34:35], v[6:7], v[34:35]
	v_fma_f32 v14, -v36, v37, 1.0
	v_fmac_f32_e32 v37, v14, v37
	v_div_scale_f32 v14, vcc, v18, v33, v18
	v_mul_f32_e32 v38, v14, v37
	v_fma_f32 v39, -v36, v38, v14
	v_fmac_f32_e32 v38, v39, v37
	v_fma_f32 v14, -v36, v38, v14
	v_div_scale_f32 v36, s[0:1], v32, v32, v31
	v_rcp_f32_e32 v39, v36
	v_div_fmas_f32 v14, v14, v37, v38
	v_div_fixup_f32 v33, v14, v33, v18
	v_fma_f32 v14, -v36, v39, 1.0
	v_fmac_f32_e32 v39, v14, v39
	v_div_scale_f32 v14, vcc, v31, v32, v31
	v_mul_f32_e32 v18, v14, v39
	v_fma_f32 v37, -v36, v18, v14
	v_fmac_f32_e32 v18, v37, v39
	v_fma_f32 v14, -v36, v18, v14
	v_lshlrev_b32_e32 v36, 16, v19
	v_and_b32_e32 v37, 0xffff0000, v19
	v_div_fmas_f32 v14, v14, v39, v18
	v_mul_f32_e32 v18, 0xbfb8aa3b, v36
	v_mul_f32_e32 v19, 0xbfb8aa3b, v37
	v_exp_f32_e32 v18, v18
	v_exp_f32_e32 v19, v19
	v_div_fixup_f32 v32, v14, v32, v31
	v_pk_mul_f32 v[32:33], v[34:35], v[32:33]
	v_lshlrev_b32_e32 v14, 16, v15
	v_pk_add_f32 v[18:19], v[18:19], 1.0 op_sel_hi:[1,0]
	v_and_b32_e32 v15, 0xffff0000, v15
	v_div_scale_f32 v31, s[0:1], v19, v19, v37
	v_rcp_f32_e32 v34, v31
	v_pk_mul_f32 v[14:15], v[24:25], v[14:15] op_sel_hi:[0,1]
	v_pk_mul_f32 v[14:15], v[8:9], v[14:15]
	v_fma_f32 v35, -v31, v34, 1.0
	v_fmac_f32_e32 v34, v35, v34
	v_div_scale_f32 v35, vcc, v37, v19, v37
	v_mul_f32_e32 v38, v35, v34
	v_fma_f32 v39, -v31, v38, v35
	v_fmac_f32_e32 v38, v39, v34
	v_fma_f32 v31, -v31, v38, v35
	v_div_scale_f32 v35, s[0:1], v18, v18, v36
	v_rcp_f32_e32 v39, v35
	v_div_fmas_f32 v31, v31, v34, v38
	v_div_fixup_f32 v19, v31, v19, v37
	v_fma_f32 v31, -v35, v39, 1.0
	v_fmac_f32_e32 v39, v31, v39
	v_div_scale_f32 v31, vcc, v36, v18, v36
	v_mul_f32_e32 v34, v31, v39
	v_fma_f32 v37, -v35, v34, v31
	v_fmac_f32_e32 v34, v37, v39
	v_fma_f32 v31, -v35, v34, v31
	v_lshlrev_b32_e32 v37, 16, v20
	v_and_b32_e32 v20, 0xffff0000, v20
	v_div_fmas_f32 v31, v31, v39, v34
	v_mul_f32_e32 v34, 0xbfb8aa3b, v37
	v_mul_f32_e32 v35, 0xbfb8aa3b, v20
	v_exp_f32_e32 v34, v34
	v_exp_f32_e32 v35, v35
	v_div_fixup_f32 v18, v31, v18, v36
	v_pk_mul_f32 v[18:19], v[14:15], v[18:19]
	v_lshlrev_b32_e32 v14, 16, v16
	v_pk_add_f32 v[34:35], v[34:35], 1.0 op_sel_hi:[1,0]
	v_and_b32_e32 v15, 0xffff0000, v16
	v_div_scale_f32 v31, s[0:1], v35, v35, v20
	v_rcp_f32_e32 v36, v31
	v_pk_mul_f32 v[14:15], v[24:25], v[14:15] op_sel_hi:[0,1]
	v_pk_mul_f32 v[14:15], v[2:3], v[14:15]
	v_fma_f32 v16, -v31, v36, 1.0
	v_fmac_f32_e32 v36, v16, v36
	v_div_scale_f32 v16, vcc, v20, v35, v20
	v_mul_f32_e32 v38, v16, v36
	v_fma_f32 v39, -v31, v38, v16
	v_fmac_f32_e32 v38, v39, v36
	v_fma_f32 v16, -v31, v38, v16
	v_div_scale_f32 v31, s[0:1], v34, v34, v37
	v_rcp_f32_e32 v39, v31
	v_div_fmas_f32 v16, v16, v36, v38
	v_div_fixup_f32 v35, v16, v35, v20
	v_fma_f32 v16, -v31, v39, 1.0
	v_fmac_f32_e32 v39, v16, v39
	v_div_scale_f32 v16, vcc, v37, v34, v37
	v_mul_f32_e32 v20, v16, v39
	v_fma_f32 v36, -v31, v20, v16
	v_fmac_f32_e32 v20, v36, v39
	v_fma_f32 v16, -v31, v20, v16
	v_lshlrev_b32_e32 v31, 16, v21
	v_and_b32_e32 v36, 0xffff0000, v21
	v_div_fmas_f32 v16, v16, v39, v20
	v_mul_f32_e32 v20, 0xbfb8aa3b, v31
	v_mul_f32_e32 v21, 0xbfb8aa3b, v36
	v_exp_f32_e32 v20, v20
	v_exp_f32_e32 v21, v21
	v_div_fixup_f32 v34, v16, v34, v37
	v_pk_mul_f32 v[34:35], v[14:15], v[34:35]
	v_lshlrev_b32_e32 v14, 16, v17
	v_pk_add_f32 v[20:21], v[20:21], 1.0 op_sel_hi:[1,0]
	v_and_b32_e32 v15, 0xffff0000, v17
	v_div_scale_f32 v16, s[0:1], v21, v21, v36
	v_rcp_f32_e32 v37, v16
	v_pk_mul_f32 v[14:15], v[24:25], v[14:15] op_sel_hi:[0,1]
	v_pk_mul_f32 v[14:15], v[4:5], v[14:15]
	v_fma_f32 v17, -v16, v37, 1.0
	v_fmac_f32_e32 v37, v17, v37
	v_div_scale_f32 v17, vcc, v36, v21, v36
	v_mul_f32_e32 v24, v17, v37
	v_fma_f32 v38, -v16, v24, v17
	v_fmac_f32_e32 v24, v38, v37
	v_div_scale_f32 v38, s[0:1], v20, v20, v31
	v_rcp_f32_e32 v39, v38
	v_fma_f32 v16, -v16, v24, v17
	v_div_fmas_f32 v16, v16, v37, v24
	v_div_fixup_f32 v17, v16, v21, v36
	v_fma_f32 v16, -v38, v39, 1.0
	v_fmac_f32_e32 v39, v16, v39
	v_div_scale_f32 v16, vcc, v31, v20, v31
	v_mul_f32_e32 v21, v16, v39
	v_fma_f32 v24, -v38, v21, v16
	v_fmac_f32_e32 v21, v24, v39
	v_fma_f32 v16, -v38, v21, v16
	v_div_fmas_f32 v16, v16, v39, v21
	v_div_fixup_f32 v16, v16, v20, v31
	v_pk_mul_f32 v[20:21], v[14:15], v[16:17]
	v_cvt_pk_bf16_f32 v14, v32, v33
	v_cvt_pk_bf16_f32 v15, v18, v19
	v_cvt_pk_bf16_f32 v16, v34, v35
	v_cvt_pk_bf16_f32 v17, v20, v21
	v_lshl_add_u64 v[18:19], s[36:37], 0, v[26:27]
	global_store_dwordx4 v[18:19], v[14:17], off sc1
	s_waitcnt lgkmcnt(0)
	v_lshlrev_b32_e32 v26, 16, v10
	v_and_b32_e32 v27, 0xffff0000, v10
	v_or_b32_e32 v14, 22, v22
	v_mov_b32_e32 v15, v23
	v_lshlrev_b64 v[18:19], 11, v[14:15]
	v_or_b32_e32 v18, v18, v28
	v_lshl_add_u64 v[14:15], s[60:61], 0, v[18:19]
	global_load_dwordx4 v[14:17], v[14:15], off
	v_mov_b32_e32 v10, v25
	v_pk_mul_f32 v[24:25], v[10:11], v[26:27] op_sel_hi:[0,1]
	v_pk_mul_f32 v[24:25], v[6:7], v[24:25]
	s_waitcnt vmcnt(0)
	v_lshlrev_b32_e32 v31, 16, v14
	v_and_b32_e32 v14, 0xffff0000, v14
	v_mul_f32_e32 v20, 0xbfb8aa3b, v31
	v_mul_f32_e32 v21, 0xbfb8aa3b, v14
	v_exp_f32_e32 v20, v20
	v_exp_f32_e32 v21, v21
	s_nop 0
	v_pk_add_f32 v[20:21], v[20:21], 1.0 op_sel_hi:[1,0]
	s_nop 0
	v_div_scale_f32 v32, s[0:1], v21, v21, v14
	v_rcp_f32_e32 v33, v32
	s_nop 0
	v_fma_f32 v26, -v32, v33, 1.0
	v_fmac_f32_e32 v33, v26, v33
	v_div_scale_f32 v26, vcc, v14, v21, v14
	v_mul_f32_e32 v27, v26, v33
	v_fma_f32 v34, -v32, v27, v26
	v_fmac_f32_e32 v27, v34, v33
	v_fma_f32 v26, -v32, v27, v26
	v_div_scale_f32 v32, s[0:1], v20, v20, v31
	v_rcp_f32_e32 v34, v32
	v_div_fmas_f32 v26, v26, v33, v27
	v_div_fixup_f32 v21, v26, v21, v14
	v_fma_f32 v14, -v32, v34, 1.0
	v_fmac_f32_e32 v34, v14, v34
	v_div_scale_f32 v14, vcc, v31, v20, v31
	v_mul_f32_e32 v26, v14, v34
	v_fma_f32 v27, -v32, v26, v14
	v_fmac_f32_e32 v26, v27, v34
	v_fma_f32 v14, -v32, v26, v14
	v_lshlrev_b32_e32 v32, 16, v15
	v_and_b32_e32 v27, 0xffff0000, v15
	v_div_fmas_f32 v26, v14, v34, v26
	v_mul_f32_e32 v14, 0xbfb8aa3b, v32
	v_mul_f32_e32 v15, 0xbfb8aa3b, v27
	v_exp_f32_e32 v14, v14
	v_exp_f32_e32 v15, v15
	v_div_fixup_f32 v20, v26, v20, v31
	v_pk_mul_f32 v[20:21], v[24:25], v[20:21]
	v_lshlrev_b32_e32 v24, 16, v11
	v_pk_add_f32 v[14:15], v[14:15], 1.0 op_sel_hi:[1,0]
	v_and_b32_e32 v25, 0xffff0000, v11
	v_div_scale_f32 v26, s[0:1], v15, v15, v27
	v_rcp_f32_e32 v31, v26
	v_pk_mul_f32 v[24:25], v[10:11], v[24:25] op_sel_hi:[0,1]
	v_pk_mul_f32 v[24:25], v[8:9], v[24:25]
	v_fma_f32 v11, -v26, v31, 1.0
	v_fmac_f32_e32 v31, v11, v31
	v_div_scale_f32 v11, vcc, v27, v15, v27
	v_mul_f32_e32 v33, v11, v31
	v_fma_f32 v34, -v26, v33, v11
	v_fmac_f32_e32 v33, v34, v31
	v_fma_f32 v11, -v26, v33, v11
	v_div_scale_f32 v26, s[0:1], v14, v14, v32
	v_rcp_f32_e32 v34, v26
	v_div_fmas_f32 v11, v11, v31, v33
	v_div_fixup_f32 v15, v11, v15, v27
	v_fma_f32 v11, -v26, v34, 1.0
	v_fmac_f32_e32 v34, v11, v34
	v_div_scale_f32 v11, vcc, v32, v14, v32
	v_mul_f32_e32 v27, v11, v34
	v_fma_f32 v31, -v26, v27, v11
	v_fmac_f32_e32 v27, v31, v34
	v_fma_f32 v11, -v26, v27, v11
	v_lshlrev_b32_e32 v31, 16, v16
	v_and_b32_e32 v16, 0xffff0000, v16
	v_div_fmas_f32 v11, v11, v34, v27
	v_mul_f32_e32 v26, 0xbfb8aa3b, v31
	v_mul_f32_e32 v27, 0xbfb8aa3b, v16
	v_exp_f32_e32 v26, v26
	v_exp_f32_e32 v27, v27
	v_div_fixup_f32 v14, v11, v14, v32
	v_pk_mul_f32 v[14:15], v[24:25], v[14:15]
	v_lshlrev_b32_e32 v24, 16, v12
	v_pk_add_f32 v[26:27], v[26:27], 1.0 op_sel_hi:[1,0]
	v_and_b32_e32 v25, 0xffff0000, v12
	v_div_scale_f32 v11, s[0:1], v27, v27, v16
	v_rcp_f32_e32 v32, v11
	v_pk_mul_f32 v[24:25], v[10:11], v[24:25] op_sel_hi:[0,1]
	v_pk_mul_f32 v[24:25], v[2:3], v[24:25]
	v_fma_f32 v12, -v11, v32, 1.0
	v_fmac_f32_e32 v32, v12, v32
	v_div_scale_f32 v12, vcc, v16, v27, v16
	v_mul_f32_e32 v33, v12, v32
	v_fma_f32 v34, -v11, v33, v12
	v_fmac_f32_e32 v33, v34, v32
	v_fma_f32 v11, -v11, v33, v12
	v_div_scale_f32 v12, s[0:1], v26, v26, v31
	v_rcp_f32_e32 v34, v12
	v_div_fmas_f32 v11, v11, v32, v33
	v_div_fixup_f32 v27, v11, v27, v16
	v_and_b32_e32 v33, 0xffff0000, v17
	v_fma_f32 v11, -v12, v34, 1.0
	v_fmac_f32_e32 v34, v11, v34
	v_div_scale_f32 v11, vcc, v31, v26, v31
	v_mul_f32_e32 v16, v11, v34
	v_fma_f32 v32, -v12, v16, v11
	v_fmac_f32_e32 v16, v32, v34
	v_lshlrev_b32_e32 v32, 16, v17
	v_fma_f32 v11, -v12, v16, v11
	v_mul_f32_e32 v12, 0xbfb8aa3b, v32
	v_div_fmas_f32 v11, v11, v34, v16
	v_exp_f32_e32 v16, v12
	v_mul_f32_e32 v12, 0xbfb8aa3b, v33
	v_exp_f32_e32 v17, v12
	v_div_fixup_f32 v26, v11, v26, v31
	v_pk_mul_f32 v[24:25], v[24:25], v[26:27]
	v_lshlrev_b32_e32 v12, 16, v13
	v_pk_add_f32 v[16:17], v[16:17], 1.0 op_sel_hi:[1,0]
	v_and_b32_e32 v13, 0xffff0000, v13
	v_div_scale_f32 v26, s[0:1], v17, v17, v33
	v_rcp_f32_e32 v27, v26
	v_pk_mul_f32 v[10:11], v[10:11], v[12:13] op_sel_hi:[0,1]
	v_pk_mul_f32 v[10:11], v[4:5], v[10:11]
	v_fma_f32 v12, -v26, v27, 1.0
	v_fmac_f32_e32 v27, v12, v27
	v_div_scale_f32 v12, vcc, v33, v17, v33
	v_mul_f32_e32 v13, v12, v27
	v_fma_f32 v31, -v26, v13, v12
	v_fmac_f32_e32 v13, v31, v27
	v_fma_f32 v12, -v26, v13, v12
	v_div_scale_f32 v26, s[0:1], v16, v16, v32
	v_rcp_f32_e32 v31, v26
	v_div_fmas_f32 v12, v12, v27, v13
	v_div_fixup_f32 v13, v12, v17, v33
	v_fma_f32 v12, -v26, v31, 1.0
	v_fmac_f32_e32 v31, v12, v31
	v_div_scale_f32 v12, vcc, v32, v16, v32
	v_mul_f32_e32 v17, v12, v31
	v_fma_f32 v27, -v26, v17, v12
	v_fmac_f32_e32 v17, v27, v31
	v_fma_f32 v12, -v26, v17, v12
	v_div_fmas_f32 v12, v12, v31, v17
	v_div_fixup_f32 v12, v12, v16, v32
	v_pk_mul_f32 v[16:17], v[10:11], v[12:13]
	v_cvt_pk_bf16_f32 v10, v20, v21
	v_cvt_pk_bf16_f32 v11, v14, v15
	v_cvt_pk_bf16_f32 v12, v24, v25
	v_cvt_pk_bf16_f32 v13, v16, v17
	v_lshl_add_u64 v[14:15], s[36:37], 0, v[18:19]
	global_store_dwordx4 v[14:15], v[10:13], off sc1
	ds_read_b128 v[14:17], v29 offset:12672
	s_waitcnt lgkmcnt(0)
	v_lshlrev_b32_e32 v34, 16, v14
	v_or_b32_e32 v10, 24, v22
	v_mov_b32_e32 v11, v23
	v_lshlrev_b64 v[26:27], 11, v[10:11]
	v_or_b32_e32 v26, v26, v28
	v_lshl_add_u64 v[10:11], s[60:61], 0, v[26:27]
	global_load_dwordx4 v[18:21], v[10:11], off
	v_and_b32_e32 v35, 0xffff0000, v14
	s_waitcnt vmcnt(0)
	v_lshlrev_b32_e32 v31, 16, v18
	v_and_b32_e32 v18, 0xffff0000, v18
	v_mul_f32_e32 v10, 0xbfb8aa3b, v31
	v_exp_f32_e32 v32, v10
	v_mul_f32_e32 v10, 0xbfb8aa3b, v18
	v_exp_f32_e32 v33, v10
	ds_read2_b32 v[24:25], v30 offset0:152 offset1:154
	ds_read_b128 v[10:13], v29 offset:13728
	v_pk_add_f32 v[32:33], v[32:33], 1.0 op_sel_hi:[1,0]
	s_nop 0
	v_div_scale_f32 v36, s[0:1], v33, v33, v18
	v_rcp_f32_e32 v37, v36
	s_waitcnt lgkmcnt(1)
	v_pk_mul_f32 v[34:35], v[24:25], v[34:35] op_sel_hi:[0,1]
	v_pk_mul_f32 v[34:35], v[6:7], v[34:35]
	v_fma_f32 v14, -v36, v37, 1.0
	v_fmac_f32_e32 v37, v14, v37
	v_div_scale_f32 v14, vcc, v18, v33, v18
	v_mul_f32_e32 v38, v14, v37
	v_fma_f32 v39, -v36, v38, v14
	v_fmac_f32_e32 v38, v39, v37
	v_fma_f32 v14, -v36, v38, v14
	v_div_scale_f32 v36, s[0:1], v32, v32, v31
	v_rcp_f32_e32 v39, v36
	v_div_fmas_f32 v14, v14, v37, v38
	v_div_fixup_f32 v33, v14, v33, v18
	v_fma_f32 v14, -v36, v39, 1.0
	v_fmac_f32_e32 v39, v14, v39
	v_div_scale_f32 v14, vcc, v31, v32, v31
	v_mul_f32_e32 v18, v14, v39
	v_fma_f32 v37, -v36, v18, v14
	v_fmac_f32_e32 v18, v37, v39
	v_fma_f32 v14, -v36, v18, v14
	v_lshlrev_b32_e32 v36, 16, v19
	v_and_b32_e32 v37, 0xffff0000, v19
	v_div_fmas_f32 v14, v14, v39, v18
	v_mul_f32_e32 v18, 0xbfb8aa3b, v36
	v_mul_f32_e32 v19, 0xbfb8aa3b, v37
	v_exp_f32_e32 v18, v18
	v_exp_f32_e32 v19, v19
	v_div_fixup_f32 v32, v14, v32, v31
	v_pk_mul_f32 v[32:33], v[34:35], v[32:33]
	v_lshlrev_b32_e32 v14, 16, v15
	v_pk_add_f32 v[18:19], v[18:19], 1.0 op_sel_hi:[1,0]
	v_and_b32_e32 v15, 0xffff0000, v15
	v_div_scale_f32 v31, s[0:1], v19, v19, v37
	v_rcp_f32_e32 v34, v31
	v_pk_mul_f32 v[14:15], v[24:25], v[14:15] op_sel_hi:[0,1]
	v_pk_mul_f32 v[14:15], v[8:9], v[14:15]
	v_fma_f32 v35, -v31, v34, 1.0
	v_fmac_f32_e32 v34, v35, v34
	v_div_scale_f32 v35, vcc, v37, v19, v37
	v_mul_f32_e32 v38, v35, v34
	v_fma_f32 v39, -v31, v38, v35
	v_fmac_f32_e32 v38, v39, v34
	v_fma_f32 v31, -v31, v38, v35
	v_div_scale_f32 v35, s[0:1], v18, v18, v36
	v_rcp_f32_e32 v39, v35
	v_div_fmas_f32 v31, v31, v34, v38
	v_div_fixup_f32 v19, v31, v19, v37
	v_fma_f32 v31, -v35, v39, 1.0
	v_fmac_f32_e32 v39, v31, v39
	v_div_scale_f32 v31, vcc, v36, v18, v36
	v_mul_f32_e32 v34, v31, v39
	v_fma_f32 v37, -v35, v34, v31
	v_fmac_f32_e32 v34, v37, v39
	v_fma_f32 v31, -v35, v34, v31
	v_lshlrev_b32_e32 v37, 16, v20
	v_and_b32_e32 v20, 0xffff0000, v20
	v_div_fmas_f32 v31, v31, v39, v34
	v_mul_f32_e32 v34, 0xbfb8aa3b, v37
	v_mul_f32_e32 v35, 0xbfb8aa3b, v20
	v_exp_f32_e32 v34, v34
	v_exp_f32_e32 v35, v35
	v_div_fixup_f32 v18, v31, v18, v36
	v_pk_mul_f32 v[18:19], v[14:15], v[18:19]
	v_lshlrev_b32_e32 v14, 16, v16
	v_pk_add_f32 v[34:35], v[34:35], 1.0 op_sel_hi:[1,0]
	v_and_b32_e32 v15, 0xffff0000, v16
	v_div_scale_f32 v31, s[0:1], v35, v35, v20
	v_rcp_f32_e32 v36, v31
	v_pk_mul_f32 v[14:15], v[24:25], v[14:15] op_sel_hi:[0,1]
	v_pk_mul_f32 v[14:15], v[2:3], v[14:15]
	v_fma_f32 v16, -v31, v36, 1.0
	v_fmac_f32_e32 v36, v16, v36
	v_div_scale_f32 v16, vcc, v20, v35, v20
	v_mul_f32_e32 v38, v16, v36
	v_fma_f32 v39, -v31, v38, v16
	v_fmac_f32_e32 v38, v39, v36
	v_fma_f32 v16, -v31, v38, v16
	v_div_scale_f32 v31, s[0:1], v34, v34, v37
	v_rcp_f32_e32 v39, v31
	v_div_fmas_f32 v16, v16, v36, v38
	v_div_fixup_f32 v35, v16, v35, v20
	v_fma_f32 v16, -v31, v39, 1.0
	v_fmac_f32_e32 v39, v16, v39
	v_div_scale_f32 v16, vcc, v37, v34, v37
	v_mul_f32_e32 v20, v16, v39
	v_fma_f32 v36, -v31, v20, v16
	v_fmac_f32_e32 v20, v36, v39
	v_fma_f32 v16, -v31, v20, v16
	v_lshlrev_b32_e32 v31, 16, v21
	v_and_b32_e32 v36, 0xffff0000, v21
	v_div_fmas_f32 v16, v16, v39, v20
	v_mul_f32_e32 v20, 0xbfb8aa3b, v31
	v_mul_f32_e32 v21, 0xbfb8aa3b, v36
	v_exp_f32_e32 v20, v20
	v_exp_f32_e32 v21, v21
	v_div_fixup_f32 v34, v16, v34, v37
	v_pk_mul_f32 v[34:35], v[14:15], v[34:35]
	v_lshlrev_b32_e32 v14, 16, v17
	v_pk_add_f32 v[20:21], v[20:21], 1.0 op_sel_hi:[1,0]
	v_and_b32_e32 v15, 0xffff0000, v17
	v_div_scale_f32 v16, s[0:1], v21, v21, v36
	v_rcp_f32_e32 v37, v16
	v_pk_mul_f32 v[14:15], v[24:25], v[14:15] op_sel_hi:[0,1]
	v_pk_mul_f32 v[14:15], v[4:5], v[14:15]
	v_fma_f32 v17, -v16, v37, 1.0
	v_fmac_f32_e32 v37, v17, v37
	v_div_scale_f32 v17, vcc, v36, v21, v36
	v_mul_f32_e32 v24, v17, v37
	v_fma_f32 v38, -v16, v24, v17
	v_fmac_f32_e32 v24, v38, v37
	v_div_scale_f32 v38, s[0:1], v20, v20, v31
	v_rcp_f32_e32 v39, v38
	v_fma_f32 v16, -v16, v24, v17
	v_div_fmas_f32 v16, v16, v37, v24
	v_div_fixup_f32 v17, v16, v21, v36
	v_fma_f32 v16, -v38, v39, 1.0
	v_fmac_f32_e32 v39, v16, v39
	v_div_scale_f32 v16, vcc, v31, v20, v31
	v_mul_f32_e32 v21, v16, v39
	v_fma_f32 v24, -v38, v21, v16
	v_fmac_f32_e32 v21, v24, v39
	v_fma_f32 v16, -v38, v21, v16
	v_div_fmas_f32 v16, v16, v39, v21
	v_div_fixup_f32 v16, v16, v20, v31
	v_pk_mul_f32 v[20:21], v[14:15], v[16:17]
	v_cvt_pk_bf16_f32 v14, v32, v33
	v_cvt_pk_bf16_f32 v15, v18, v19
	v_cvt_pk_bf16_f32 v16, v34, v35
	v_cvt_pk_bf16_f32 v17, v20, v21
	v_lshl_add_u64 v[18:19], s[36:37], 0, v[26:27]
	global_store_dwordx4 v[18:19], v[14:17], off sc1
	s_waitcnt lgkmcnt(0)
	v_lshlrev_b32_e32 v26, 16, v10
	v_and_b32_e32 v27, 0xffff0000, v10
	v_or_b32_e32 v14, 26, v22
	v_mov_b32_e32 v15, v23
	v_lshlrev_b64 v[18:19], 11, v[14:15]
	v_or_b32_e32 v18, v18, v28
	v_lshl_add_u64 v[14:15], s[60:61], 0, v[18:19]
	global_load_dwordx4 v[14:17], v[14:15], off
	v_mov_b32_e32 v10, v25
	v_pk_mul_f32 v[24:25], v[10:11], v[26:27] op_sel_hi:[0,1]
	v_pk_mul_f32 v[24:25], v[6:7], v[24:25]
	s_waitcnt vmcnt(0)
	v_lshlrev_b32_e32 v31, 16, v14
	v_and_b32_e32 v14, 0xffff0000, v14
	v_mul_f32_e32 v20, 0xbfb8aa3b, v31
	v_mul_f32_e32 v21, 0xbfb8aa3b, v14
	v_exp_f32_e32 v20, v20
	v_exp_f32_e32 v21, v21
	s_nop 0
	v_pk_add_f32 v[20:21], v[20:21], 1.0 op_sel_hi:[1,0]
	s_nop 0
	v_div_scale_f32 v32, s[0:1], v21, v21, v14
	v_rcp_f32_e32 v33, v32
	s_nop 0
	v_fma_f32 v26, -v32, v33, 1.0
	v_fmac_f32_e32 v33, v26, v33
	v_div_scale_f32 v26, vcc, v14, v21, v14
	v_mul_f32_e32 v27, v26, v33
	v_fma_f32 v34, -v32, v27, v26
	v_fmac_f32_e32 v27, v34, v33
	v_fma_f32 v26, -v32, v27, v26
	v_div_scale_f32 v32, s[0:1], v20, v20, v31
	v_rcp_f32_e32 v34, v32
	v_div_fmas_f32 v26, v26, v33, v27
	v_div_fixup_f32 v21, v26, v21, v14
	v_fma_f32 v14, -v32, v34, 1.0
	v_fmac_f32_e32 v34, v14, v34
	v_div_scale_f32 v14, vcc, v31, v20, v31
	v_mul_f32_e32 v26, v14, v34
	v_fma_f32 v27, -v32, v26, v14
	v_fmac_f32_e32 v26, v27, v34
	v_fma_f32 v14, -v32, v26, v14
	v_lshlrev_b32_e32 v32, 16, v15
	v_and_b32_e32 v27, 0xffff0000, v15
	v_div_fmas_f32 v26, v14, v34, v26
	v_mul_f32_e32 v14, 0xbfb8aa3b, v32
	v_mul_f32_e32 v15, 0xbfb8aa3b, v27
	v_exp_f32_e32 v14, v14
	v_exp_f32_e32 v15, v15
	v_div_fixup_f32 v20, v26, v20, v31
	v_pk_mul_f32 v[20:21], v[24:25], v[20:21]
	v_lshlrev_b32_e32 v24, 16, v11
	v_pk_add_f32 v[14:15], v[14:15], 1.0 op_sel_hi:[1,0]
	v_and_b32_e32 v25, 0xffff0000, v11
	v_div_scale_f32 v26, s[0:1], v15, v15, v27
	v_rcp_f32_e32 v31, v26
	v_pk_mul_f32 v[24:25], v[10:11], v[24:25] op_sel_hi:[0,1]
	v_pk_mul_f32 v[24:25], v[8:9], v[24:25]
	v_fma_f32 v11, -v26, v31, 1.0
	v_fmac_f32_e32 v31, v11, v31
	v_div_scale_f32 v11, vcc, v27, v15, v27
	v_mul_f32_e32 v33, v11, v31
	v_fma_f32 v34, -v26, v33, v11
	v_fmac_f32_e32 v33, v34, v31
	v_fma_f32 v11, -v26, v33, v11
	v_div_scale_f32 v26, s[0:1], v14, v14, v32
	v_rcp_f32_e32 v34, v26
	v_div_fmas_f32 v11, v11, v31, v33
	v_div_fixup_f32 v15, v11, v15, v27
	v_fma_f32 v11, -v26, v34, 1.0
	v_fmac_f32_e32 v34, v11, v34
	v_div_scale_f32 v11, vcc, v32, v14, v32
	v_mul_f32_e32 v27, v11, v34
	v_fma_f32 v31, -v26, v27, v11
	v_fmac_f32_e32 v27, v31, v34
	v_fma_f32 v11, -v26, v27, v11
	v_lshlrev_b32_e32 v31, 16, v16
	v_and_b32_e32 v16, 0xffff0000, v16
	v_div_fmas_f32 v11, v11, v34, v27
	v_mul_f32_e32 v26, 0xbfb8aa3b, v31
	v_mul_f32_e32 v27, 0xbfb8aa3b, v16
	v_exp_f32_e32 v26, v26
	v_exp_f32_e32 v27, v27
	v_div_fixup_f32 v14, v11, v14, v32
	v_pk_mul_f32 v[14:15], v[24:25], v[14:15]
	v_lshlrev_b32_e32 v24, 16, v12
	v_pk_add_f32 v[26:27], v[26:27], 1.0 op_sel_hi:[1,0]
	v_and_b32_e32 v25, 0xffff0000, v12
	v_div_scale_f32 v11, s[0:1], v27, v27, v16
	v_rcp_f32_e32 v32, v11
	v_pk_mul_f32 v[24:25], v[10:11], v[24:25] op_sel_hi:[0,1]
	v_pk_mul_f32 v[24:25], v[2:3], v[24:25]
	v_fma_f32 v12, -v11, v32, 1.0
	v_fmac_f32_e32 v32, v12, v32
	v_div_scale_f32 v12, vcc, v16, v27, v16
	v_mul_f32_e32 v33, v12, v32
	v_fma_f32 v34, -v11, v33, v12
	v_fmac_f32_e32 v33, v34, v32
	v_fma_f32 v11, -v11, v33, v12
	v_div_scale_f32 v12, s[0:1], v26, v26, v31
	v_rcp_f32_e32 v34, v12
	v_div_fmas_f32 v11, v11, v32, v33
	v_div_fixup_f32 v27, v11, v27, v16
	v_and_b32_e32 v33, 0xffff0000, v17
	v_fma_f32 v11, -v12, v34, 1.0
	v_fmac_f32_e32 v34, v11, v34
	v_div_scale_f32 v11, vcc, v31, v26, v31
	v_mul_f32_e32 v16, v11, v34
	v_fma_f32 v32, -v12, v16, v11
	v_fmac_f32_e32 v16, v32, v34
	v_lshlrev_b32_e32 v32, 16, v17
	v_fma_f32 v11, -v12, v16, v11
	v_mul_f32_e32 v12, 0xbfb8aa3b, v32
	v_div_fmas_f32 v11, v11, v34, v16
	v_exp_f32_e32 v16, v12
	v_mul_f32_e32 v12, 0xbfb8aa3b, v33
	v_exp_f32_e32 v17, v12
	v_div_fixup_f32 v26, v11, v26, v31
	v_pk_mul_f32 v[24:25], v[24:25], v[26:27]
	v_lshlrev_b32_e32 v12, 16, v13
	v_pk_add_f32 v[16:17], v[16:17], 1.0 op_sel_hi:[1,0]
	v_and_b32_e32 v13, 0xffff0000, v13
	v_div_scale_f32 v26, s[0:1], v17, v17, v33
	v_rcp_f32_e32 v27, v26
	v_pk_mul_f32 v[10:11], v[10:11], v[12:13] op_sel_hi:[0,1]
	v_pk_mul_f32 v[10:11], v[4:5], v[10:11]
	v_fma_f32 v12, -v26, v27, 1.0
	v_fmac_f32_e32 v27, v12, v27
	v_div_scale_f32 v12, vcc, v33, v17, v33
	v_mul_f32_e32 v13, v12, v27
	v_fma_f32 v31, -v26, v13, v12
	v_fmac_f32_e32 v13, v31, v27
	v_fma_f32 v12, -v26, v13, v12
	v_div_scale_f32 v26, s[0:1], v16, v16, v32
	v_rcp_f32_e32 v31, v26
	v_div_fmas_f32 v12, v12, v27, v13
	v_div_fixup_f32 v13, v12, v17, v33
	v_fma_f32 v12, -v26, v31, 1.0
	v_fmac_f32_e32 v31, v12, v31
	v_div_scale_f32 v12, vcc, v32, v16, v32
	v_mul_f32_e32 v17, v12, v31
	v_fma_f32 v27, -v26, v17, v12
	v_fmac_f32_e32 v17, v27, v31
	v_fma_f32 v12, -v26, v17, v12
	v_div_fmas_f32 v12, v12, v31, v17
	v_div_fixup_f32 v12, v12, v16, v32
	v_pk_mul_f32 v[16:17], v[10:11], v[12:13]
	v_cvt_pk_bf16_f32 v10, v20, v21
	v_cvt_pk_bf16_f32 v11, v14, v15
	v_cvt_pk_bf16_f32 v12, v24, v25
	v_cvt_pk_bf16_f32 v13, v16, v17
	v_lshl_add_u64 v[14:15], s[36:37], 0, v[18:19]
	global_store_dwordx4 v[14:15], v[10:13], off sc1
	ds_read_b128 v[14:17], v29 offset:14784
	s_waitcnt lgkmcnt(0)
	v_and_b32_e32 v31, 0xffff0000, v14
	v_or_b32_e32 v10, 28, v22
	v_mov_b32_e32 v11, v23
	v_lshlrev_b64 v[26:27], 11, v[10:11]
	v_or_b32_e32 v26, v26, v28
	v_lshl_add_u64 v[10:11], s[60:61], 0, v[26:27]
	global_load_dwordx4 v[18:21], v[10:11], off
	v_or_b32_e32 v22, 30, v22
	s_waitcnt vmcnt(0)
	v_lshlrev_b32_e32 v34, 16, v18
	v_and_b32_e32 v18, 0xffff0000, v18
	v_mul_f32_e32 v10, 0xbfb8aa3b, v34
	v_exp_f32_e32 v32, v10
	v_mul_f32_e32 v10, 0xbfb8aa3b, v18
	v_exp_f32_e32 v33, v10
	ds_read2_b32 v[24:25], v30 offset0:156 offset1:158
	ds_read_b128 v[10:13], v29 offset:15840
	v_lshlrev_b32_e32 v30, 16, v14
	v_pk_add_f32 v[32:33], v[32:33], 1.0 op_sel_hi:[1,0]
	s_nop 0
	v_div_scale_f32 v29, s[0:1], v33, v33, v18
	v_rcp_f32_e32 v35, v29
	s_waitcnt lgkmcnt(1)
	v_pk_mul_f32 v[30:31], v[24:25], v[30:31] op_sel_hi:[0,1]
	v_pk_mul_f32 v[30:31], v[6:7], v[30:31]
	v_fma_f32 v14, -v29, v35, 1.0
	v_fmac_f32_e32 v35, v14, v35
	v_div_scale_f32 v14, vcc, v18, v33, v18
	v_mul_f32_e32 v36, v14, v35
	v_fma_f32 v37, -v29, v36, v14
	v_fmac_f32_e32 v36, v37, v35
	v_fma_f32 v14, -v29, v36, v14
	v_div_scale_f32 v29, s[0:1], v32, v32, v34
	v_rcp_f32_e32 v37, v29
	v_div_fmas_f32 v14, v14, v35, v36
	v_div_fixup_f32 v33, v14, v33, v18
	v_fma_f32 v14, -v29, v37, 1.0
	v_fmac_f32_e32 v37, v14, v37
	v_div_scale_f32 v14, vcc, v34, v32, v34
	v_mul_f32_e32 v18, v14, v37
	v_fma_f32 v35, -v29, v18, v14
	v_fmac_f32_e32 v18, v35, v37
	v_fma_f32 v14, -v29, v18, v14
	v_lshlrev_b32_e32 v29, 16, v19
	v_and_b32_e32 v35, 0xffff0000, v19
	v_div_fmas_f32 v14, v14, v37, v18
	v_mul_f32_e32 v18, 0xbfb8aa3b, v29
	v_mul_f32_e32 v19, 0xbfb8aa3b, v35
	v_exp_f32_e32 v18, v18
	v_exp_f32_e32 v19, v19
	v_div_fixup_f32 v32, v14, v32, v34
	v_pk_mul_f32 v[30:31], v[30:31], v[32:33]
	v_lshlrev_b32_e32 v14, 16, v15
	v_pk_add_f32 v[18:19], v[18:19], 1.0 op_sel_hi:[1,0]
	v_and_b32_e32 v15, 0xffff0000, v15
	v_div_scale_f32 v32, s[0:1], v19, v19, v35
	v_rcp_f32_e32 v33, v32
	v_pk_mul_f32 v[14:15], v[24:25], v[14:15] op_sel_hi:[0,1]
	v_pk_mul_f32 v[14:15], v[8:9], v[14:15]
	v_fma_f32 v34, -v32, v33, 1.0
	v_fmac_f32_e32 v33, v34, v33
	v_div_scale_f32 v34, vcc, v35, v19, v35
	v_mul_f32_e32 v36, v34, v33
	v_fma_f32 v37, -v32, v36, v34
	v_fmac_f32_e32 v36, v37, v33
	v_fma_f32 v32, -v32, v36, v34
	v_div_scale_f32 v34, s[0:1], v18, v18, v29
	v_rcp_f32_e32 v37, v34
	v_div_fmas_f32 v32, v32, v33, v36
	v_div_fixup_f32 v19, v32, v19, v35
	v_fma_f32 v32, -v34, v37, 1.0
	v_fmac_f32_e32 v37, v32, v37
	v_div_scale_f32 v32, vcc, v29, v18, v29
	v_mul_f32_e32 v33, v32, v37
	v_fma_f32 v35, -v34, v33, v32
	v_fmac_f32_e32 v33, v35, v37
	v_fma_f32 v32, -v34, v33, v32
	v_lshlrev_b32_e32 v35, 16, v20
	v_and_b32_e32 v20, 0xffff0000, v20
	v_div_fmas_f32 v34, v32, v37, v33
	v_mul_f32_e32 v32, 0xbfb8aa3b, v35
	v_mul_f32_e32 v33, 0xbfb8aa3b, v20
	v_exp_f32_e32 v32, v32
	v_exp_f32_e32 v33, v33
	v_div_fixup_f32 v18, v34, v18, v29
	v_pk_mul_f32 v[18:19], v[14:15], v[18:19]
	v_lshlrev_b32_e32 v14, 16, v16
	v_pk_add_f32 v[32:33], v[32:33], 1.0 op_sel_hi:[1,0]
	v_and_b32_e32 v15, 0xffff0000, v16
	v_div_scale_f32 v29, s[0:1], v33, v33, v20
	v_rcp_f32_e32 v34, v29
	v_pk_mul_f32 v[14:15], v[24:25], v[14:15] op_sel_hi:[0,1]
	v_pk_mul_f32 v[14:15], v[2:3], v[14:15]
	v_fma_f32 v16, -v29, v34, 1.0
	v_fmac_f32_e32 v34, v16, v34
	v_div_scale_f32 v16, vcc, v20, v33, v20
	v_mul_f32_e32 v36, v16, v34
	v_fma_f32 v37, -v29, v36, v16
	v_fmac_f32_e32 v36, v37, v34
	v_fma_f32 v16, -v29, v36, v16
	v_div_scale_f32 v29, s[0:1], v32, v32, v35
	v_rcp_f32_e32 v37, v29
	v_div_fmas_f32 v16, v16, v34, v36
	v_div_fixup_f32 v33, v16, v33, v20
	v_fma_f32 v16, -v29, v37, 1.0
	v_fmac_f32_e32 v37, v16, v37
	v_div_scale_f32 v16, vcc, v35, v32, v35
	v_mul_f32_e32 v20, v16, v37
	v_fma_f32 v34, -v29, v20, v16
	v_fmac_f32_e32 v20, v34, v37
	v_fma_f32 v16, -v29, v20, v16
	v_lshlrev_b32_e32 v29, 16, v21
	v_and_b32_e32 v34, 0xffff0000, v21
	v_div_fmas_f32 v16, v16, v37, v20
	v_mul_f32_e32 v20, 0xbfb8aa3b, v29
	v_mul_f32_e32 v21, 0xbfb8aa3b, v34
	v_exp_f32_e32 v20, v20
	v_exp_f32_e32 v21, v21
	v_div_fixup_f32 v32, v16, v32, v35
	v_pk_mul_f32 v[32:33], v[14:15], v[32:33]
	v_lshlrev_b32_e32 v14, 16, v17
	v_pk_add_f32 v[20:21], v[20:21], 1.0 op_sel_hi:[1,0]
	v_and_b32_e32 v15, 0xffff0000, v17
	v_div_scale_f32 v16, s[0:1], v21, v21, v34
	v_rcp_f32_e32 v35, v16
	v_pk_mul_f32 v[14:15], v[24:25], v[14:15] op_sel_hi:[0,1]
	v_pk_mul_f32 v[14:15], v[4:5], v[14:15]
	v_fma_f32 v17, -v16, v35, 1.0
	v_fmac_f32_e32 v35, v17, v35
	v_div_scale_f32 v17, vcc, v34, v21, v34
	v_mul_f32_e32 v24, v17, v35
	v_fma_f32 v36, -v16, v24, v17
	v_fmac_f32_e32 v24, v36, v35
	v_div_scale_f32 v36, s[0:1], v20, v20, v29
	v_rcp_f32_e32 v37, v36
	v_fma_f32 v16, -v16, v24, v17
	v_div_fmas_f32 v16, v16, v35, v24
	v_div_fixup_f32 v17, v16, v21, v34
	v_fma_f32 v16, -v36, v37, 1.0
	v_fmac_f32_e32 v37, v16, v37
	v_div_scale_f32 v16, vcc, v29, v20, v29
	v_mul_f32_e32 v21, v16, v37
	v_fma_f32 v24, -v36, v21, v16
	v_fmac_f32_e32 v21, v24, v37
	v_fma_f32 v16, -v36, v21, v16
	v_div_fmas_f32 v16, v16, v37, v21
	v_div_fixup_f32 v16, v16, v20, v29
	v_pk_mul_f32 v[20:21], v[14:15], v[16:17]
	v_cvt_pk_bf16_f32 v14, v30, v31
	v_cvt_pk_bf16_f32 v15, v18, v19
	v_cvt_pk_bf16_f32 v16, v32, v33
	v_cvt_pk_bf16_f32 v17, v20, v21
	v_lshl_add_u64 v[18:19], s[36:37], 0, v[26:27]
	global_store_dwordx4 v[18:19], v[14:17], off sc1
	v_lshlrev_b64 v[18:19], 11, v[22:23]
	v_or_b32_e32 v18, v18, v28
	v_lshl_add_u64 v[14:15], s[60:61], 0, v[18:19]
	global_load_dwordx4 v[14:17], v[14:15], off
	s_waitcnt lgkmcnt(0)
	v_lshlrev_b32_e32 v22, 16, v10
	v_and_b32_e32 v23, 0xffff0000, v10
	v_mov_b32_e32 v10, v25
	v_pk_mul_f32 v[22:23], v[10:11], v[22:23] op_sel_hi:[0,1]
	v_pk_mul_f32 v[6:7], v[6:7], v[22:23]
	s_waitcnt vmcnt(0)
	v_lshlrev_b32_e32 v24, 16, v14
	v_and_b32_e32 v14, 0xffff0000, v14
	v_mul_f32_e32 v20, 0xbfb8aa3b, v24
	v_mul_f32_e32 v21, 0xbfb8aa3b, v14
	v_exp_f32_e32 v20, v20
	v_exp_f32_e32 v21, v21
	s_nop 0
	v_pk_add_f32 v[20:21], v[20:21], 1.0 op_sel_hi:[1,0]
	s_nop 0
	v_div_scale_f32 v26, s[0:1], v21, v21, v14
	v_rcp_f32_e32 v27, v26
	s_nop 0
	v_fma_f32 v22, -v26, v27, 1.0
	v_fmac_f32_e32 v27, v22, v27
	v_div_scale_f32 v22, vcc, v14, v21, v14
	v_mul_f32_e32 v23, v22, v27
	v_fma_f32 v25, -v26, v23, v22
	v_fmac_f32_e32 v23, v25, v27
	v_div_scale_f32 v25, s[0:1], v20, v20, v24
	v_fma_f32 v22, -v26, v23, v22
	v_rcp_f32_e32 v26, v25
	v_div_fmas_f32 v22, v22, v27, v23
	v_div_fixup_f32 v21, v22, v21, v14
	v_fma_f32 v14, -v25, v26, 1.0
	v_fmac_f32_e32 v26, v14, v26
	v_div_scale_f32 v14, vcc, v24, v20, v24
	v_mul_f32_e32 v22, v14, v26
	v_fma_f32 v23, -v25, v22, v14
	v_fmac_f32_e32 v22, v23, v26
	v_fma_f32 v14, -v25, v22, v14
	v_lshlrev_b32_e32 v23, 16, v15
	v_and_b32_e32 v25, 0xffff0000, v15
	v_div_fmas_f32 v22, v14, v26, v22
	v_mul_f32_e32 v14, 0xbfb8aa3b, v23
	v_mul_f32_e32 v15, 0xbfb8aa3b, v25
	v_exp_f32_e32 v14, v14
	v_exp_f32_e32 v15, v15
	v_div_fixup_f32 v20, v22, v20, v24
	v_pk_mul_f32 v[6:7], v[6:7], v[20:21]
	v_lshlrev_b32_e32 v20, 16, v11
	v_pk_add_f32 v[14:15], v[14:15], 1.0 op_sel_hi:[1,0]
	v_and_b32_e32 v21, 0xffff0000, v11
	v_div_scale_f32 v22, s[0:1], v15, v15, v25
	v_rcp_f32_e32 v24, v22
	v_pk_mul_f32 v[20:21], v[10:11], v[20:21] op_sel_hi:[0,1]
	v_pk_mul_f32 v[8:9], v[8:9], v[20:21]
	v_fma_f32 v11, -v22, v24, 1.0
	v_fmac_f32_e32 v24, v11, v24
	v_div_scale_f32 v11, vcc, v25, v15, v25
	v_mul_f32_e32 v20, v11, v24
	v_fma_f32 v21, -v22, v20, v11
	v_fmac_f32_e32 v20, v21, v24
	v_div_scale_f32 v21, s[0:1], v14, v14, v23
	v_fma_f32 v11, -v22, v20, v11
	v_rcp_f32_e32 v22, v21
	v_div_fmas_f32 v11, v11, v24, v20
	v_div_fixup_f32 v15, v11, v15, v25
	v_fma_f32 v11, -v21, v22, 1.0
	v_fmac_f32_e32 v22, v11, v22
	v_div_scale_f32 v11, vcc, v23, v14, v23
	v_mul_f32_e32 v20, v11, v22
	v_fma_f32 v24, -v21, v20, v11
	v_fmac_f32_e32 v20, v24, v22
	v_fma_f32 v11, -v21, v20, v11
	v_div_fmas_f32 v11, v11, v22, v20
	v_lshlrev_b32_e32 v22, 16, v16
	v_and_b32_e32 v16, 0xffff0000, v16
	v_mul_f32_e32 v20, 0xbfb8aa3b, v22
	v_mul_f32_e32 v21, 0xbfb8aa3b, v16
	v_exp_f32_e32 v20, v20
	v_exp_f32_e32 v21, v21
	v_div_fixup_f32 v14, v11, v14, v23
	v_pk_mul_f32 v[8:9], v[8:9], v[14:15]
	v_lshlrev_b32_e32 v14, 16, v12
	v_pk_add_f32 v[20:21], v[20:21], 1.0 op_sel_hi:[1,0]
	v_and_b32_e32 v15, 0xffff0000, v12
	v_div_scale_f32 v11, s[0:1], v21, v21, v16
	v_rcp_f32_e32 v23, v11
	v_pk_mul_f32 v[14:15], v[10:11], v[14:15] op_sel_hi:[0,1]
	v_pk_mul_f32 v[2:3], v[2:3], v[14:15]
	v_fma_f32 v12, -v11, v23, 1.0
	v_fmac_f32_e32 v23, v12, v23
	v_div_scale_f32 v12, vcc, v16, v21, v16
	v_mul_f32_e32 v14, v12, v23
	v_fma_f32 v15, -v11, v14, v12
	v_fmac_f32_e32 v14, v15, v23
	v_fma_f32 v11, -v11, v14, v12
	v_div_scale_f32 v12, s[0:1], v20, v20, v22
	v_rcp_f32_e32 v24, v12
	v_div_fmas_f32 v11, v11, v23, v14
	v_div_fixup_f32 v15, v11, v21, v16
	v_and_b32_e32 v21, 0xffff0000, v17
	v_fma_f32 v11, -v12, v24, 1.0
	v_fmac_f32_e32 v24, v11, v24
	v_div_scale_f32 v11, vcc, v22, v20, v22
	v_mul_f32_e32 v14, v11, v24
	v_fma_f32 v16, -v12, v14, v11
	v_fmac_f32_e32 v14, v16, v24
	v_fma_f32 v11, -v12, v14, v11
	v_lshlrev_b32_e32 v12, 16, v17
	v_div_fmas_f32 v11, v11, v24, v14
	v_mul_f32_e32 v14, 0xbfb8aa3b, v12
	v_exp_f32_e32 v16, v14
	v_mul_f32_e32 v14, 0xbfb8aa3b, v21
	v_exp_f32_e32 v17, v14
	v_div_fixup_f32 v14, v11, v20, v22
	v_pk_mul_f32 v[14:15], v[2:3], v[14:15]
	v_lshlrev_b32_e32 v2, 16, v13
	v_pk_add_f32 v[16:17], v[16:17], 1.0 op_sel_hi:[1,0]
	v_and_b32_e32 v3, 0xffff0000, v13
	v_div_scale_f32 v11, s[0:1], v17, v17, v21
	v_rcp_f32_e32 v20, v11
	v_pk_mul_f32 v[2:3], v[10:11], v[2:3] op_sel_hi:[0,1]
	v_pk_mul_f32 v[2:3], v[4:5], v[2:3]
	v_fma_f32 v4, -v11, v20, 1.0
	v_fmac_f32_e32 v20, v4, v20
	v_div_scale_f32 v4, vcc, v21, v17, v21
	v_mul_f32_e32 v5, v4, v20
	v_fma_f32 v10, -v11, v5, v4
	v_fmac_f32_e32 v5, v10, v20
	v_div_scale_f32 v10, s[0:1], v16, v16, v12
	v_fma_f32 v4, -v11, v5, v4
	v_rcp_f32_e32 v11, v10
	v_div_fmas_f32 v4, v4, v20, v5
	v_div_fixup_f32 v5, v4, v17, v21
	v_fma_f32 v4, -v10, v11, 1.0
	v_fmac_f32_e32 v11, v4, v11
	v_div_scale_f32 v4, vcc, v12, v16, v12
	v_mul_f32_e32 v13, v4, v11
	v_fma_f32 v17, -v10, v13, v4
	v_fmac_f32_e32 v13, v17, v11
	v_fma_f32 v4, -v10, v13, v4
	v_div_fmas_f32 v4, v4, v11, v13
	v_div_fixup_f32 v4, v4, v16, v12
	v_pk_mul_f32 v[10:11], v[2:3], v[4:5]
	v_cvt_pk_bf16_f32 v2, v6, v7
	v_cvt_pk_bf16_f32 v3, v8, v9
	v_cvt_pk_bf16_f32 v4, v14, v15
	v_cvt_pk_bf16_f32 v5, v10, v11
	v_lshl_add_u64 v[6:7], s[36:37], 0, v[18:19]
	global_store_dwordx4 v[6:7], v[2:5], off sc1
	s_waitcnt vmcnt(0)
	s_barrier
	s_and_saveexec_b64 s[0:1], s[14:15]
	s_cbranch_execz .LBB0_1429
	s_add_i32 s6, 0, 0x22160
	v_mov_b32_e32 v2, s6
	s_waitcnt vmcnt(0) expcnt(0) lgkmcnt(0)
	ds_read_b32 v4, v2
	s_add_i32 s6, 0, 0x22164
	v_mov_b32_e32 v2, s6
	ds_read_b32 v2, v2
	s_waitcnt lgkmcnt(1)
	v_cmp_ne_u32_e32 vcc, 0, v4
	s_cbranch_vccnz .LBB0_1393
	v_readlane_b32 s8, v251, 53
	v_readlane_b32 s9, v251, 54
	s_load_dwordx2 s[6:7], s[8:9], 0x4
	s_mov_b32 s33, 1
	v_mov_b32_e32 v18, 0
	s_waitcnt lgkmcnt(0)
	s_mul_i32 s6, s6, s7
	s_lshl_b32 s60, s6, 8
	s_add_u32 s6, s34, 0x4200
	s_addc_u32 s7, s35, 0
	s_add_u32 s8, s34, 0x4400
	s_addc_u32 s9, s35, 0
	s_add_u32 s10, s34, 0x4500
	s_addc_u32 s11, s35, 0
	s_add_u32 s12, s34, 0x4600
	s_addc_u32 s13, s35, 0
	s_add_u32 s16, s34, 0x4700
	s_addc_u32 s17, s35, 0
	s_add_u32 s18, s34, 0x4800
	s_addc_u32 s19, s35, 0
	s_add_u32 s20, s34, 0x4900
	s_addc_u32 s21, s35, 0
	s_add_u32 s22, s34, 0x4a00
	s_addc_u32 s23, s35, 0
	s_add_u32 s24, s34, 0x4b00
	s_addc_u32 s25, s35, 0
	s_add_u32 s26, s34, 0x4c00
	s_addc_u32 s27, s35, 0
	s_add_u32 s28, s34, 0x4d00
	s_addc_u32 s29, s35, 0
	s_add_u32 s30, s34, 0x4e00
	s_addc_u32 s31, s35, 0
	s_add_u32 s38, s34, 0x4f00
	s_addc_u32 s39, s35, 0
	s_add_u32 s40, s34, 0x5000
	s_addc_u32 s41, s35, 0
	s_add_u32 s42, s34, 0x5100
	s_addc_u32 s43, s35, 0
	s_add_u32 s44, s34, 0x5200
	s_addc_u32 s45, s35, 0
	s_add_u32 s46, s34, 0x5300
	s_addc_u32 s47, s35, 0
	s_branch .LBB0_1381

.LBB0_1596:
	v_mul_f32_e32 v146, 0xbfb8aa3b, v126
	v_exp_f32_e32 v155, v146
	v_mul_f32_e32 v146, 0xbfb8aa3b, v127
	v_exp_f32_e32 v158, v146
	v_lshl_or_b32 v156, s47, 7, v150
	v_add_f32_e32 v155, 1.0, v155
	v_rcp_f32_e32 v155, v155
	v_add_f32_e32 v158, 1.0, v158
	v_rcp_f32_e32 v160, v158
	v_lshl_add_u32 v154, s24, 8, v148
	v_mul_f32_e32 v126, v126, v155
	v_mul_f32_e32 v118, v126, v118
	v_mul_f32_e32 v126, v127, v160
	v_mul_f32_e32 v127, 0xbfb8aa3b, v128
	v_exp_f32_e32 v127, v127
	v_mul_f32_e32 v155, 0xbfb8aa3b, v129
	v_exp_f32_e32 v155, v155
	v_mul_f32_e32 v119, v126, v119
	v_add_f32_e32 v126, 1.0, v127
	v_rcp_f32_e32 v126, v126
	v_add_f32_e32 v127, 1.0, v155
	v_mul_f32_e32 v155, 0xbfb8aa3b, v122
	v_rcp_f32_e32 v127, v127
	v_exp_f32_e32 v155, v155
	v_mul_f32_e32 v126, v128, v126
	v_mul_f32_e32 v126, v126, v120
	v_mul_f32_e32 v120, v129, v127
	v_add_f32_e32 v127, 1.0, v155
	v_rcp_f32_e32 v127, v127
	v_mul_f32_e32 v128, 0xbfb8aa3b, v123
	v_mul_f32_e32 v129, v120, v121
	v_exp_f32_e32 v128, v128
	v_mul_f32_e32 v120, v122, v127
	v_mul_f32_e32 v122, v120, v114
	v_mul_f32_e32 v120, 0xbfb8aa3b, v124
	v_exp_f32_e32 v120, v120
	v_mul_f32_e32 v121, 0xbfb8aa3b, v125
	v_exp_f32_e32 v121, v121
	v_add_f32_e32 v114, 1.0, v128
	v_rcp_f32_e32 v114, v114
	v_add_f32_e32 v120, 1.0, v120
	v_rcp_f32_e32 v120, v120
	v_add_f32_e32 v121, 1.0, v121
	v_rcp_f32_e32 v121, v121
	v_mul_f32_e32 v114, v123, v114
	v_mul_f32_e32 v123, v114, v115
	v_mul_f32_e32 v114, v124, v120
	v_ashrrev_i32_e32 v157, 31, v156
	v_mov_b64_e32 v[146:147], s[36:37]
	v_mul_f32_e32 v124, v114, v116
	v_mul_f32_e32 v114, v125, v121
	v_mad_i64_i32 v[158:159], s[26:27], v154, s46, v[146:147]
	v_mul_f32_e32 v125, v114, v117
	v_lshlrev_b64 v[114:115], 1, v[156:157]
	v_lshl_add_u64 v[120:121], v[158:159], 0, v[114:115]
	v_cvt_pk_bf16_f32 v116, v118, v119
	v_cvt_pk_bf16_f32 v117, v126, v129
	v_cvt_pk_bf16_f32 v118, v122, v123
	v_cvt_pk_bf16_f32 v119, v124, v125
	global_store_dwordx4 v[120:121], v[116:119], off sc1
	s_andn2_b64 vcc, exec, s[0:1]
	s_mov_b64 s[0:1], -1
	v_mul_f32_e32 v116, 0xbfb8aa3b, v110
	v_exp_f32_e32 v116, v116
	v_mul_f32_e32 v117, 0xbfb8aa3b, v111
	v_exp_f32_e32 v117, v117
	v_or_b32_e32 v118, 16, v154
	v_add_f32_e32 v116, 1.0, v116
	v_rcp_f32_e32 v119, v116
	v_add_f32_e32 v116, 1.0, v117
	v_rcp_f32_e32 v120, v116
	v_mad_i64_i32 v[116:117], s[26:27], v118, s46, v[146:147]
	v_mul_f32_e32 v110, v110, v119
	v_mul_f32_e32 v110, v110, v102
	v_mul_f32_e32 v102, v111, v120
	v_mul_f32_e32 v111, 0xbfb8aa3b, v112
	v_exp_f32_e32 v111, v111
	v_mul_f32_e32 v118, 0xbfb8aa3b, v113
	v_exp_f32_e32 v118, v118
	v_mul_f32_e32 v119, v102, v103
	v_add_f32_e32 v102, 1.0, v111
	v_rcp_f32_e32 v102, v102
	v_add_f32_e32 v103, 1.0, v118
	v_mul_f32_e32 v111, 0xbfb8aa3b, v106
	v_rcp_f32_e32 v103, v103
	v_exp_f32_e32 v111, v111
	v_mul_f32_e32 v102, v112, v102
	v_mul_f32_e32 v104, v102, v104
	v_mul_f32_e32 v102, v113, v103
	v_add_f32_e32 v103, 1.0, v111
	v_rcp_f32_e32 v103, v103
	v_mul_f32_e32 v111, 0xbfb8aa3b, v107
	v_mul_f32_e32 v105, v102, v105
	v_exp_f32_e32 v111, v111
	v_mul_f32_e32 v102, v106, v103
	v_mul_f32_e32 v106, v102, v98
	v_mul_f32_e32 v102, 0xbfb8aa3b, v108
	v_exp_f32_e32 v102, v102
	v_mul_f32_e32 v103, 0xbfb8aa3b, v109
	v_exp_f32_e32 v103, v103
	v_add_f32_e32 v98, 1.0, v111
	v_rcp_f32_e32 v98, v98
	v_add_f32_e32 v102, 1.0, v102
	v_rcp_f32_e32 v102, v102
	v_add_f32_e32 v103, 1.0, v103
	v_rcp_f32_e32 v103, v103
	v_mul_f32_e32 v98, v107, v98
	v_mul_f32_e32 v107, v98, v99
	v_mul_f32_e32 v98, v108, v102
	v_mul_f32_e32 v108, v98, v100
	v_mul_f32_e32 v98, v109, v103
	v_mul_f32_e32 v101, v98, v101
	v_lshl_add_u64 v[102:103], v[116:117], 0, v[114:115]
	v_cvt_pk_bf16_f32 v98, v110, v119
	v_cvt_pk_bf16_f32 v99, v104, v105
	v_cvt_pk_bf16_f32 v100, v106, v107
	v_cvt_pk_bf16_f32 v101, v108, v101
	global_store_dwordx4 v[102:103], v[98:101], off sc1
	s_nop 1
	v_mul_f32_e32 v98, 0xbfb8aa3b, v94
	v_exp_f32_e32 v98, v98
	v_mul_f32_e32 v99, 0xbfb8aa3b, v95
	v_exp_f32_e32 v99, v99
	v_or_b32_e32 v100, 32, v154
	v_add_f32_e32 v98, 1.0, v98
	v_rcp_f32_e32 v101, v98
	v_add_f32_e32 v98, 1.0, v99
	v_rcp_f32_e32 v102, v98
	v_mad_i64_i32 v[98:99], s[26:27], v100, s46, v[146:147]
	v_mul_f32_e32 v94, v94, v101
	v_mul_f32_e32 v94, v94, v86
	v_mul_f32_e32 v86, v95, v102
	v_mul_f32_e32 v95, 0xbfb8aa3b, v96
	v_exp_f32_e32 v95, v95
	v_mul_f32_e32 v100, 0xbfb8aa3b, v97
	v_exp_f32_e32 v100, v100
	v_mul_f32_e32 v101, v86, v87
	v_add_f32_e32 v86, 1.0, v95
	v_rcp_f32_e32 v86, v86
	v_add_f32_e32 v87, 1.0, v100
	v_mul_f32_e32 v95, 0xbfb8aa3b, v90
	v_rcp_f32_e32 v87, v87
	v_exp_f32_e32 v95, v95
	v_mul_f32_e32 v86, v96, v86
	v_mul_f32_e32 v88, v86, v88
	v_mul_f32_e32 v86, v97, v87
	v_add_f32_e32 v87, 1.0, v95
	v_rcp_f32_e32 v87, v87
	v_mul_f32_e32 v95, 0xbfb8aa3b, v91
	v_mul_f32_e32 v89, v86, v89
	v_exp_f32_e32 v95, v95
	v_mul_f32_e32 v86, v90, v87
	v_mul_f32_e32 v90, v86, v82
	v_mul_f32_e32 v86, 0xbfb8aa3b, v92
	v_exp_f32_e32 v86, v86
	v_mul_f32_e32 v87, 0xbfb8aa3b, v93
	v_exp_f32_e32 v87, v87
	v_add_f32_e32 v82, 1.0, v95
	v_rcp_f32_e32 v82, v82
	v_add_f32_e32 v86, 1.0, v86
	v_rcp_f32_e32 v86, v86
	v_add_f32_e32 v87, 1.0, v87
	v_rcp_f32_e32 v87, v87
	v_mul_f32_e32 v82, v91, v82
	v_mul_f32_e32 v91, v82, v83
	v_mul_f32_e32 v82, v92, v86
	v_mul_f32_e32 v92, v82, v84
	v_mul_f32_e32 v82, v93, v87
	v_mul_f32_e32 v85, v82, v85
	v_lshl_add_u64 v[86:87], v[98:99], 0, v[114:115]
	v_cvt_pk_bf16_f32 v82, v94, v101
	v_cvt_pk_bf16_f32 v83, v88, v89
	v_cvt_pk_bf16_f32 v84, v90, v91
	v_cvt_pk_bf16_f32 v85, v92, v85
	global_store_dwordx4 v[86:87], v[82:85], off sc1
	s_nop 1
	v_mul_f32_e32 v82, 0xbfb8aa3b, v78
	v_exp_f32_e32 v82, v82
	v_mul_f32_e32 v83, 0xbfb8aa3b, v79
	v_exp_f32_e32 v83, v83
	v_or_b32_e32 v84, 48, v154
	v_add_f32_e32 v82, 1.0, v82
	v_rcp_f32_e32 v85, v82
	v_add_f32_e32 v82, 1.0, v83
	v_rcp_f32_e32 v86, v82
	v_mad_i64_i32 v[82:83], s[26:27], v84, s46, v[146:147]
	v_mul_f32_e32 v78, v78, v85
	v_mul_f32_e32 v78, v78, v70
	v_mul_f32_e32 v70, v79, v86
	v_mul_f32_e32 v79, 0xbfb8aa3b, v80
	v_exp_f32_e32 v79, v79
	v_mul_f32_e32 v84, 0xbfb8aa3b, v81
	v_exp_f32_e32 v84, v84
	v_mul_f32_e32 v85, v70, v71
	v_add_f32_e32 v70, 1.0, v79
	v_rcp_f32_e32 v70, v70
	v_add_f32_e32 v71, 1.0, v84
	v_mul_f32_e32 v79, 0xbfb8aa3b, v74
	v_rcp_f32_e32 v71, v71
	v_exp_f32_e32 v79, v79
	v_mul_f32_e32 v70, v80, v70
	v_mul_f32_e32 v72, v70, v72
	v_mul_f32_e32 v70, v81, v71
	v_add_f32_e32 v71, 1.0, v79
	v_rcp_f32_e32 v71, v71
	v_mul_f32_e32 v79, 0xbfb8aa3b, v75
	v_mul_f32_e32 v73, v70, v73
	v_exp_f32_e32 v79, v79
	v_mul_f32_e32 v70, v74, v71
	v_mul_f32_e32 v74, v70, v66
	v_mul_f32_e32 v70, 0xbfb8aa3b, v76
	v_exp_f32_e32 v70, v70
	v_mul_f32_e32 v71, 0xbfb8aa3b, v77
	v_exp_f32_e32 v71, v71
	v_add_f32_e32 v66, 1.0, v79
	v_rcp_f32_e32 v66, v66
	v_add_f32_e32 v70, 1.0, v70
	v_rcp_f32_e32 v70, v70
	v_add_f32_e32 v71, 1.0, v71
	v_rcp_f32_e32 v71, v71
	v_mul_f32_e32 v66, v75, v66
	v_mul_f32_e32 v75, v66, v67
	v_mul_f32_e32 v66, v76, v70
	v_mul_f32_e32 v76, v66, v68
	v_mul_f32_e32 v66, v77, v71
	v_mul_f32_e32 v69, v66, v69
	v_lshl_add_u64 v[70:71], v[82:83], 0, v[114:115]
	v_cvt_pk_bf16_f32 v66, v78, v85
	v_cvt_pk_bf16_f32 v67, v72, v73
	v_cvt_pk_bf16_f32 v68, v74, v75
	v_cvt_pk_bf16_f32 v69, v76, v69
	global_store_dwordx4 v[70:71], v[66:69], off sc1
	s_nop 1
	v_mul_f32_e32 v66, 0xbfb8aa3b, v62
	v_exp_f32_e32 v66, v66
	v_mul_f32_e32 v67, 0xbfb8aa3b, v63
	v_exp_f32_e32 v67, v67
	v_add_u32_e32 v68, 0x80, v154
	v_add_f32_e32 v66, 1.0, v66
	v_rcp_f32_e32 v69, v66
	v_add_f32_e32 v66, 1.0, v67
	v_rcp_f32_e32 v70, v66
	v_mad_i64_i32 v[66:67], s[26:27], v68, s46, v[146:147]
	v_mul_f32_e32 v62, v62, v69
	v_mul_f32_e32 v62, v62, v54
	v_mul_f32_e32 v54, v63, v70
	v_mul_f32_e32 v63, 0xbfb8aa3b, v64
	v_exp_f32_e32 v63, v63
	v_mul_f32_e32 v68, 0xbfb8aa3b, v65
	v_exp_f32_e32 v68, v68
	v_mul_f32_e32 v69, v54, v55
	v_add_f32_e32 v54, 1.0, v63
	v_rcp_f32_e32 v54, v54
	v_add_f32_e32 v55, 1.0, v68
	v_mul_f32_e32 v63, 0xbfb8aa3b, v58
	v_rcp_f32_e32 v55, v55
	v_exp_f32_e32 v63, v63
	v_mul_f32_e32 v54, v64, v54
	v_mul_f32_e32 v56, v54, v56
	v_mul_f32_e32 v54, v65, v55
	v_add_f32_e32 v55, 1.0, v63
	v_rcp_f32_e32 v55, v55
	v_mul_f32_e32 v63, 0xbfb8aa3b, v59
	v_mul_f32_e32 v57, v54, v57
	v_exp_f32_e32 v63, v63
	v_mul_f32_e32 v54, v58, v55
	v_mul_f32_e32 v58, v54, v50
	v_mul_f32_e32 v54, 0xbfb8aa3b, v60
	v_exp_f32_e32 v54, v54
	v_mul_f32_e32 v55, 0xbfb8aa3b, v61
	v_exp_f32_e32 v55, v55
	v_add_f32_e32 v50, 1.0, v63
	v_rcp_f32_e32 v50, v50
	v_add_f32_e32 v54, 1.0, v54
	v_rcp_f32_e32 v54, v54
	v_add_f32_e32 v55, 1.0, v55
	v_rcp_f32_e32 v55, v55
	v_mul_f32_e32 v50, v59, v50
	v_mul_f32_e32 v59, v50, v51
	v_mul_f32_e32 v50, v60, v54
	v_mul_f32_e32 v60, v50, v52
	v_mul_f32_e32 v50, v61, v55
	v_mul_f32_e32 v53, v50, v53
	v_lshl_add_u64 v[54:55], v[66:67], 0, v[114:115]
	v_cvt_pk_bf16_f32 v50, v62, v69
	v_cvt_pk_bf16_f32 v51, v56, v57
	v_cvt_pk_bf16_f32 v52, v58, v59
	v_cvt_pk_bf16_f32 v53, v60, v53
	global_store_dwordx4 v[54:55], v[50:53], off sc1
	s_nop 1
	v_mul_f32_e32 v50, 0xbfb8aa3b, v46
	v_exp_f32_e32 v50, v50
	v_mul_f32_e32 v51, 0xbfb8aa3b, v47
	v_exp_f32_e32 v51, v51
	v_add_u32_e32 v52, 0x90, v154
	v_add_f32_e32 v50, 1.0, v50
	v_rcp_f32_e32 v53, v50
	v_add_f32_e32 v50, 1.0, v51
	v_rcp_f32_e32 v54, v50
	v_mad_i64_i32 v[50:51], s[26:27], v52, s46, v[146:147]
	v_mul_f32_e32 v46, v46, v53
	v_mul_f32_e32 v46, v46, v38
	v_mul_f32_e32 v38, v47, v54
	v_mul_f32_e32 v47, 0xbfb8aa3b, v48
	v_exp_f32_e32 v47, v47
	v_mul_f32_e32 v52, 0xbfb8aa3b, v49
	v_exp_f32_e32 v52, v52
	v_mul_f32_e32 v53, v38, v39
	v_add_f32_e32 v38, 1.0, v47
	v_rcp_f32_e32 v38, v38
	v_add_f32_e32 v39, 1.0, v52
	v_mul_f32_e32 v47, 0xbfb8aa3b, v42
	v_rcp_f32_e32 v39, v39
	v_exp_f32_e32 v47, v47
	v_mul_f32_e32 v38, v48, v38
	v_mul_f32_e32 v40, v38, v40
	v_mul_f32_e32 v38, v49, v39
	v_add_f32_e32 v39, 1.0, v47
	v_rcp_f32_e32 v39, v39
	v_mul_f32_e32 v47, 0xbfb8aa3b, v43
	v_mul_f32_e32 v41, v38, v41
	v_exp_f32_e32 v47, v47
	v_mul_f32_e32 v38, v42, v39
	v_mul_f32_e32 v42, v38, v34
	v_mul_f32_e32 v38, 0xbfb8aa3b, v44
	v_exp_f32_e32 v38, v38
	v_mul_f32_e32 v39, 0xbfb8aa3b, v45
	v_exp_f32_e32 v39, v39
	v_add_f32_e32 v34, 1.0, v47
	v_rcp_f32_e32 v34, v34
	v_add_f32_e32 v38, 1.0, v38
	v_rcp_f32_e32 v38, v38
	v_add_f32_e32 v39, 1.0, v39
	v_rcp_f32_e32 v39, v39
	v_mul_f32_e32 v34, v43, v34
	v_mul_f32_e32 v43, v34, v35
	v_mul_f32_e32 v34, v44, v38
	v_mul_f32_e32 v44, v34, v36
	v_mul_f32_e32 v34, v45, v39
	v_mul_f32_e32 v37, v34, v37
	v_lshl_add_u64 v[38:39], v[50:51], 0, v[114:115]
	v_cvt_pk_bf16_f32 v34, v46, v53
	v_cvt_pk_bf16_f32 v35, v40, v41
	v_cvt_pk_bf16_f32 v36, v42, v43
	v_cvt_pk_bf16_f32 v37, v44, v37
	global_store_dwordx4 v[38:39], v[34:37], off sc1
	s_nop 1
	v_mul_f32_e32 v34, 0xbfb8aa3b, v30
	v_exp_f32_e32 v34, v34
	v_mul_f32_e32 v35, 0xbfb8aa3b, v31
	v_exp_f32_e32 v35, v35
	v_add_u32_e32 v36, 0xa0, v154
	v_add_f32_e32 v34, 1.0, v34
	v_rcp_f32_e32 v37, v34
	v_add_f32_e32 v34, 1.0, v35
	v_rcp_f32_e32 v38, v34
	v_mad_i64_i32 v[34:35], s[26:27], v36, s46, v[146:147]
	v_mul_f32_e32 v30, v30, v37
	v_mul_f32_e32 v30, v30, v22
	v_mul_f32_e32 v22, v31, v38
	v_mul_f32_e32 v31, 0xbfb8aa3b, v32
	v_exp_f32_e32 v31, v31
	v_mul_f32_e32 v36, 0xbfb8aa3b, v33
	v_exp_f32_e32 v36, v36
	v_mul_f32_e32 v37, v22, v23
	v_add_f32_e32 v22, 1.0, v31
	v_rcp_f32_e32 v22, v22
	v_add_f32_e32 v23, 1.0, v36
	v_mul_f32_e32 v31, 0xbfb8aa3b, v26
	v_rcp_f32_e32 v23, v23
	v_exp_f32_e32 v31, v31
	v_mul_f32_e32 v22, v32, v22
	v_mul_f32_e32 v24, v22, v24
	v_mul_f32_e32 v22, v33, v23
	v_add_f32_e32 v23, 1.0, v31
	v_rcp_f32_e32 v23, v23
	v_mul_f32_e32 v31, 0xbfb8aa3b, v27
	v_mul_f32_e32 v25, v22, v25
	v_exp_f32_e32 v31, v31
	v_mul_f32_e32 v22, v26, v23
	v_mul_f32_e32 v26, v22, v18
	v_mul_f32_e32 v22, 0xbfb8aa3b, v28
	v_exp_f32_e32 v22, v22
	v_mul_f32_e32 v23, 0xbfb8aa3b, v29
	v_exp_f32_e32 v23, v23
	v_add_f32_e32 v18, 1.0, v31
	v_rcp_f32_e32 v18, v18
	v_add_f32_e32 v22, 1.0, v22
	v_rcp_f32_e32 v22, v22
	v_add_f32_e32 v23, 1.0, v23
	v_rcp_f32_e32 v23, v23
	v_mul_f32_e32 v18, v27, v18
	v_mul_f32_e32 v27, v18, v19
	v_mul_f32_e32 v18, v28, v22
	v_mul_f32_e32 v28, v18, v20
	v_mul_f32_e32 v18, v29, v23
	v_mul_f32_e32 v21, v18, v21
	v_lshl_add_u64 v[22:23], v[34:35], 0, v[114:115]
	v_cvt_pk_bf16_f32 v18, v30, v37
	v_cvt_pk_bf16_f32 v19, v24, v25
	v_cvt_pk_bf16_f32 v20, v26, v27
	v_cvt_pk_bf16_f32 v21, v28, v21
	global_store_dwordx4 v[22:23], v[18:21], off sc1
	s_nop 1
	v_mul_f32_e32 v18, 0xbfb8aa3b, v14
	v_exp_f32_e32 v18, v18
	v_mul_f32_e32 v19, 0xbfb8aa3b, v15
	v_exp_f32_e32 v19, v19
	v_add_u32_e32 v20, 0xb0, v154
	v_add_f32_e32 v18, 1.0, v18
	v_rcp_f32_e32 v21, v18
	v_add_f32_e32 v18, 1.0, v19
	v_rcp_f32_e32 v22, v18
	v_mad_i64_i32 v[18:19], s[26:27], v20, s46, v[146:147]
	v_mul_f32_e32 v14, v14, v21
	v_mul_f32_e32 v14, v14, v6
	v_mul_f32_e32 v6, v15, v22
	v_mul_f32_e32 v15, 0xbfb8aa3b, v16
	v_exp_f32_e32 v15, v15
	v_mul_f32_e32 v20, 0xbfb8aa3b, v17
	v_exp_f32_e32 v20, v20
	v_mul_f32_e32 v21, v6, v7
	v_add_f32_e32 v6, 1.0, v15
	v_rcp_f32_e32 v6, v6
	v_add_f32_e32 v7, 1.0, v20
	v_mul_f32_e32 v15, 0xbfb8aa3b, v10
	v_rcp_f32_e32 v7, v7
	v_exp_f32_e32 v15, v15
	v_mul_f32_e32 v6, v16, v6
	v_mul_f32_e32 v8, v6, v8
	v_mul_f32_e32 v6, v17, v7
	v_add_f32_e32 v7, 1.0, v15
	v_rcp_f32_e32 v7, v7
	v_mul_f32_e32 v15, 0xbfb8aa3b, v11
	v_mul_f32_e32 v9, v6, v9
	v_exp_f32_e32 v15, v15
	v_mul_f32_e32 v6, v10, v7
	v_mul_f32_e32 v10, v6, v2
	v_mul_f32_e32 v6, 0xbfb8aa3b, v12
	v_exp_f32_e32 v6, v6
	v_mul_f32_e32 v7, 0xbfb8aa3b, v13
	v_exp_f32_e32 v7, v7
	v_add_f32_e32 v2, 1.0, v15
	v_rcp_f32_e32 v2, v2
	v_add_f32_e32 v6, 1.0, v6
	v_rcp_f32_e32 v6, v6
	v_add_f32_e32 v7, 1.0, v7
	v_rcp_f32_e32 v7, v7
	v_mul_f32_e32 v2, v11, v2
	v_mul_f32_e32 v11, v2, v3
	v_mul_f32_e32 v2, v12, v6
	v_mul_f32_e32 v12, v2, v4
	v_mul_f32_e32 v2, v13, v7
	v_mul_f32_e32 v5, v2, v5
	v_lshl_add_u64 v[6:7], v[18:19], 0, v[114:115]
	v_cvt_pk_bf16_f32 v2, v14, v21
	v_cvt_pk_bf16_f32 v3, v8, v9
	v_cvt_pk_bf16_f32 v4, v10, v11
	v_cvt_pk_bf16_f32 v5, v12, v5
	global_store_dwordx4 v[6:7], v[2:5], off sc1
	s_cbranch_vccnz .LBB0_1589
	s_andn2_b64 vcc, exec, s[8:9]
	s_cbranch_vccnz .LBB0_1588
	s_barrier
	s_branch .LBB0_1588

.LBB0_1678:
	s_lshl_b32 s16, s24, 8
	v_add_u32_e32 v249, s16, v149
	v_lshlrev_b32_e32 v249, 11, v249
	s_lshl_b32 s17, s8, 8
	s_lshl_b32 s18, s25, 5
	s_or_b32 s17, s17, s18
	v_lshrrev_b32_e32 v230, 2, v0
	v_and_or_b32 v230, v230, 12, s17
	v_lshl_add_u32 v248, v230, 1, v249
	s_lshl_b32 s19, s24, 5
	s_and_b32 s19, s19, 0xfffffc00
	s_lshl_b32 s19, s19, 2
	s_add_i32 s19, s19, 0x112000
	v_lshl_add_u32 v250, v230, 2, s19
	global_load_dwordx4 v[232:235], v250, s[34:35]
	global_load_dwordx4 v[236:239], v250, s[34:35] offset:64
	global_load_dwordx4 v[240:243], v250, s[34:35] offset:512
	global_load_dwordx4 v[244:247], v250, s[34:35] offset:576
	global_load_dwordx2 v[164:165], v248, s[56:57]
	global_load_dwordx2 v[166:167], v248, s[56:57] offset:32
	global_load_dwordx2 v[168:169], v248, s[56:57] offset:256
	global_load_dwordx2 v[170:171], v248, s[56:57] offset:288
	v_add_u32_e32 v249, 0x8000, v248
	global_load_dwordx2 v[172:173], v249, s[56:57]
	global_load_dwordx2 v[174:175], v249, s[56:57] offset:32
	global_load_dwordx2 v[176:177], v249, s[56:57] offset:256
	global_load_dwordx2 v[178:179], v249, s[56:57] offset:288
	v_add_u32_e32 v249, 0x10000, v248
	global_load_dwordx2 v[180:181], v249, s[56:57]
	global_load_dwordx2 v[182:183], v249, s[56:57] offset:32
	global_load_dwordx2 v[184:185], v249, s[56:57] offset:256
	global_load_dwordx2 v[186:187], v249, s[56:57] offset:288
	v_add_u32_e32 v249, 0x18000, v248
	global_load_dwordx2 v[188:189], v249, s[56:57]
	global_load_dwordx2 v[190:191], v249, s[56:57] offset:32
	global_load_dwordx2 v[192:193], v249, s[56:57] offset:256
	global_load_dwordx2 v[194:195], v249, s[56:57] offset:288
	v_add_u32_e32 v249, 0x40000, v248
	global_load_dwordx2 v[196:197], v249, s[56:57]
	global_load_dwordx2 v[198:199], v249, s[56:57] offset:32
	global_load_dwordx2 v[200:201], v249, s[56:57] offset:256
	global_load_dwordx2 v[204:205], v249, s[56:57] offset:288
	v_add_u32_e32 v249, 0x48000, v248
	global_load_dwordx2 v[206:207], v249, s[56:57]
	global_load_dwordx2 v[208:209], v249, s[56:57] offset:32
	global_load_dwordx2 v[210:211], v249, s[56:57] offset:256
	global_load_dwordx2 v[212:213], v249, s[56:57] offset:288
	v_add_u32_e32 v249, 0x50000, v248
	global_load_dwordx2 v[214:215], v249, s[56:57]
	global_load_dwordx2 v[216:217], v249, s[56:57] offset:32
	global_load_dwordx2 v[218:219], v249, s[56:57] offset:256
	global_load_dwordx2 v[220:221], v249, s[56:57] offset:288
	v_add_u32_e32 v249, 0x58000, v248
	global_load_dwordx2 v[222:223], v249, s[56:57]
	global_load_dwordx2 v[224:225], v249, s[56:57] offset:32
	global_load_dwordx2 v[226:227], v249, s[56:57] offset:256
	global_load_dwordx2 v[228:229], v249, s[56:57] offset:288
	v_mov_b32_e32 v130, v127
	v_mov_b32_e32 v131, v128
	v_mov_b32_e32 v132, v126
	v_mov_b32_e32 v133, v129
	v_pk_add_f32 v[130:131], v[130:131], v[132:133]
	v_mov_b32_e32 v132, v123
	v_mov_b32_e32 v133, v124
	v_mov_b32_e32 v134, v122
	v_mov_b32_e32 v135, v125
	v_pk_add_f32 v[132:133], v[132:133], v[134:135]
	v_add_f32_e32 v130, v130, v131
	v_pk_add_f32 v[132:133], v[132:133], v[132:133] op_sel_hi:[0,1]
	v_add_f32_e32 v131, 0, v130
	v_add_f32_e32 v135, v118, v119
	v_add_f32_e32 v137, v120, v121
	v_mov_b32_e32 v134, v110
	v_mov_b32_e32 v136, v111
	v_mov_b32_e32 v132, v112
	v_mov_b32_e32 v130, v113
	v_pk_add_f32 v[134:135], v[134:135], v[136:137]
	v_pk_add_f32 v[130:131], v[132:133], v[130:131]
	v_mov_b32_e32 v133, v126
	v_pk_add_f32 v[130:131], v[134:135], v[130:131]
	v_mov_b32_e32 v134, v127
	v_add_f32_e32 v130, v130, v131
	ds_bpermute_b32 v131, v1, v130
	v_mov_b32_e32 v135, v123
	s_lshl_b32 s0, s25, 3
	s_add_i32 s2, s0, 0
	s_barrier
	s_waitcnt lgkmcnt(0)
	v_add_f32_e32 v130, v130, v131
	ds_bpermute_b32 v131, v202, v130
	s_waitcnt lgkmcnt(0)
	v_add_f32_e32 v131, v130, v131
	v_fmamk_f32 v132, v131, 0xbc800000, v129
	v_fmac_f32_e32 v134, 0xbc800000, v131
	v_fmamk_f32 v130, v131, 0xbc800000, v128
	v_fmac_f32_e32 v133, 0xbc800000, v131
	v_mul_f32_e32 v134, v134, v134
	v_mul_f32_e32 v132, v132, v132
	v_fmac_f32_e32 v134, v133, v133
	v_fmac_f32_e32 v132, v130, v130
	v_add_f32_e32 v130, v134, v132
	v_fmamk_f32 v133, v131, 0xbc800000, v125
	v_mov_b32_e32 v134, v122
	v_fmac_f32_e32 v135, 0xbc800000, v131
	v_fmamk_f32 v132, v131, 0xbc800000, v124
	v_fmac_f32_e32 v134, 0xbc800000, v131
	v_mul_f32_e32 v135, v135, v135
	v_mul_f32_e32 v133, v133, v133
	v_fmac_f32_e32 v135, v134, v134
	v_fmac_f32_e32 v133, v132, v132
	v_add_f32_e32 v132, v135, v133
	v_mov_b32_e32 v135, v119
	v_fmamk_f32 v133, v131, 0xbc800000, v121
	v_mov_b32_e32 v134, v118
	v_fmac_f32_e32 v135, 0xbc800000, v131
	v_add_f32_e32 v130, v130, v132
	v_fmamk_f32 v132, v131, 0xbc800000, v120
	v_fmac_f32_e32 v134, 0xbc800000, v131
	v_mul_f32_e32 v135, v135, v135
	v_mul_f32_e32 v133, v133, v133
	v_fmac_f32_e32 v135, v134, v134
	v_fmac_f32_e32 v133, v132, v132
	v_add_f32_e32 v132, v135, v133
	v_mov_b32_e32 v135, v111
	v_fmamk_f32 v133, v131, 0xbc800000, v113
	v_mov_b32_e32 v134, v110
	v_fmac_f32_e32 v135, 0xbc800000, v131
	v_add_f32_e32 v130, v132, v130
	v_fmamk_f32 v132, v131, 0xbc800000, v112
	v_fmac_f32_e32 v134, 0xbc800000, v131
	v_mul_f32_e32 v135, v135, v135
	v_mul_f32_e32 v133, v133, v133
	v_fmac_f32_e32 v135, v134, v134
	v_fmac_f32_e32 v133, v132, v132
	v_add_f32_e32 v132, v135, v133
	v_add_f32_e32 v132, v132, v130
	ds_bpermute_b32 v133, v1, v132
	v_and_b32_e32 v130, 63, v0
	v_cmp_gt_u32_e32 vcc, 16, v130
	s_waitcnt lgkmcnt(0)
	v_add_f32_e32 v132, v132, v133
	ds_bpermute_b32 v133, v202, v132
	s_and_saveexec_b64 s[0:1], vcc
	s_cbranch_execz .LBB0_1680
	s_lshl_b32 s3, s27, 11
	s_add_i32 s3, s2, s3
	v_mul_f32_e32 v134, 0x3c800000, v131
	s_waitcnt lgkmcnt(0)
	v_add_f32_e32 v135, v132, v133
	v_lshl_add_u32 v131, v146, 5, s3
	ds_write_b64 v131, v[134:135]

.LBB0_1718:
	s_or_b64 exec, exec, s[2:3]
	s_lshl_b32 s0, s24, 5
	s_and_b32 s0, s0, 0xfffffc00
	s_ashr_i32 s1, s0, 31
	s_lshl_b32 s2, s25, 5
	s_lshl_b64 s[0:1], s[0:1], 2
	s_add_u32 s0, s34, s0
	s_addc_u32 s1, s35, s1
	s_lshl_b32 s3, s8, 8
	v_lshrrev_b32_e32 v0, 2, v0
	s_or_b32 s2, s3, s2
	v_add_u32_e32 v146, s4, v149
	v_and_or_b32 v0, v0, 12, s2
	v_ashrrev_i32_e32 v147, 31, v146
	v_ashrrev_i32_e32 v1, 31, v0
	v_lshlrev_b64 v[134:135], 10, v[146:147]
	v_lshl_add_u64 v[134:135], v[134:135], 0, v[0:1]
	v_lshlrev_b64 v[154:155], 1, v[134:135]
	v_lshl_add_u64 v[130:131], v[0:1], 2, s[0:1]
	s_waitcnt lgkmcnt(0)
	s_barrier
	s_mov_b32 s0, 0x112000
	v_lshl_add_u64 v[136:137], s[56:57], 0, v[154:155]
	v_add_co_u32_e32 v136, vcc, s0, v130
	v_lshl_add_u32 v133, v149, 3, 0
	s_nop 0
	v_addc_co_u32_e32 v137, vcc, 0, v131, vcc
	v_add_u32_e32 v149, 0x2000, v133
	ds_read2_b64 v[142:145], v149 offset1:16
	s_waitcnt vmcnt(0) lgkmcnt(0)
	v_or_b32_e32 v148, v132, v148
	s_mov_b64 s[0:1], 0x112000
	v_mov_b32_e32 v147, 0x7fc00000
	v_cmp_ne_u32_e32 vcc, 0, v148
	v_pk_mul_f32 v[152:153], v[126:127], v[142:143] op_sel:[0,1]
	v_pk_mul_f32 v[156:157], v[128:129], v[142:143] op_sel:[0,1]
	v_lshl_add_u64 v[126:127], v[130:131], 0, s[0:1]
	v_lshl_add_u64 v[158:159], v[134:135], 2, s[94:95]
	v_or_b32_e32 v160, 32, v154
	v_mov_b32_e32 v161, v155
	s_nop 0
	v_lshl_add_u64 v[160:161], s[56:57], 0, v[160:161]
	v_pk_mul_f32 v[124:125], v[124:125], v[142:143] op_sel:[0,1]
	v_pk_mul_f32 v[122:123], v[122:123], v[142:143] op_sel:[0,1]
	v_pk_mul_f32 v[120:121], v[120:121], v[142:143] op_sel:[0,1]
	v_pk_mul_f32 v[118:119], v[118:119], v[142:143] op_sel:[0,1]
	v_pk_mul_f32 v[112:113], v[112:113], v[142:143] op_sel:[0,1]
	v_pk_mul_f32 v[110:111], v[110:111], v[142:143] op_sel:[0,1]
	v_pk_mul_f32 v[114:115], v[114:115], v[144:145] op_sel:[0,1]
	v_pk_mul_f32 v[108:109], v[108:109], v[144:145] op_sel:[0,1]
	v_pk_mul_f32 v[106:107], v[106:107], v[144:145] op_sel:[0,1]
	v_pk_mul_f32 v[104:105], v[104:105], v[144:145] op_sel:[0,1]
	v_pk_mul_f32 v[102:103], v[102:103], v[144:145] op_sel:[0,1]
	v_pk_mul_f32 v[100:101], v[100:101], v[144:145] op_sel:[0,1]
	v_pk_mul_f32 v[98:99], v[98:99], v[144:145] op_sel:[0,1]
	v_lshlrev_b32_e32 v162, 16, v164
	v_and_b32_e32 v163, 0xffff0000, v164
	v_lshlrev_b32_e32 v150, 16, v165
	v_and_b32_e32 v151, 0xffff0000, v165
	v_pk_fma_f32 v[156:157], v[234:235], v[156:157], v[150:151]
	v_pk_fma_f32 v[150:151], v[232:233], v[152:153], v[162:163]
	v_cndmask_b32_e32 v153, v157, v147, vcc
	v_cndmask_b32_e32 v151, v151, v147, vcc
	v_cndmask_b32_e32 v150, v150, v147, vcc
	v_cndmask_b32_e32 v152, v156, v147, vcc
	global_store_dwordx4 v[158:159], v[150:153], off sc1
	v_lshlrev_b32_e32 v156, 16, v166
	v_and_b32_e32 v157, 0xffff0000, v166
	v_lshlrev_b32_e32 v150, 16, v167
	v_and_b32_e32 v151, 0xffff0000, v167
	v_pk_fma_f32 v[122:123], v[236:237], v[122:123], v[156:157]
	v_pk_fma_f32 v[124:125], v[238:239], v[124:125], v[150:151]
	v_or_b32_e32 v152, 0x100, v154
	v_mov_b32_e32 v153, v155
	v_cndmask_b32_e32 v125, v125, v147, vcc
	v_cndmask_b32_e32 v124, v124, v147, vcc
	v_cndmask_b32_e32 v123, v123, v147, vcc
	v_cndmask_b32_e32 v122, v122, v147, vcc
	v_lshl_add_u64 v[152:153], s[56:57], 0, v[152:153]
	global_store_dwordx4 v[158:159], v[122:125], off offset:64 sc1
	s_nop 1
	v_or_b32_e32 v154, 0x120, v154
	v_lshl_add_u64 v[124:125], s[56:57], 0, v[154:155]
	v_lshlrev_b32_e32 v150, 16, v168
	v_and_b32_e32 v151, 0xffff0000, v168
	v_lshlrev_b32_e32 v122, 16, v169
	v_and_b32_e32 v123, 0xffff0000, v169
	v_pk_fma_f32 v[118:119], v[240:241], v[118:119], v[150:151]
	v_pk_fma_f32 v[120:121], v[242:243], v[120:121], v[122:123]
	v_cndmask_b32_e32 v119, v119, v147, vcc
	v_cndmask_b32_e32 v121, v121, v147, vcc
	v_cndmask_b32_e32 v120, v120, v147, vcc
	v_cndmask_b32_e32 v118, v118, v147, vcc
	global_store_dwordx4 v[158:159], v[118:121], off offset:512 sc1
	s_nop 1
	v_lshlrev_b32_e32 v142, 16, v170
	v_add_u32_e32 v120, 16, v146
	v_ashrrev_i32_e32 v121, 31, v120
	v_lshlrev_b64 v[120:121], 10, v[120:121]
	v_and_b32_e32 v143, 0xffff0000, v170
	v_lshlrev_b32_e32 v118, 16, v171
	v_and_b32_e32 v119, 0xffff0000, v171
	v_lshl_add_u64 v[120:121], v[120:121], 0, v[0:1]
	v_pk_fma_f32 v[110:111], v[244:245], v[110:111], v[142:143]
	v_pk_fma_f32 v[112:113], v[246:247], v[112:113], v[118:119]
	v_lshlrev_b64 v[122:123], 1, v[120:121]
	v_cndmask_b32_e32 v113, v113, v147, vcc
	v_cndmask_b32_e32 v112, v112, v147, vcc
	v_cndmask_b32_e32 v111, v111, v147, vcc
	v_cndmask_b32_e32 v110, v110, v147, vcc
	v_lshl_add_u64 v[124:125], s[56:57], 0, v[122:123]
	global_store_dwordx4 v[158:159], v[110:113], off offset:576 sc1
	s_nop 1
	v_or_b32_e32 v118, 32, v122
	v_pk_mul_f32 v[112:113], v[116:117], v[144:145] op_sel:[0,1]
	v_lshl_add_u64 v[116:117], v[120:121], 2, s[94:95]
	v_mov_b32_e32 v119, v123
	v_lshl_add_u64 v[118:119], s[56:57], 0, v[118:119]
	v_lshlrev_b32_e32 v120, 16, v172
	v_and_b32_e32 v121, 0xffff0000, v172
	v_lshlrev_b32_e32 v110, 16, v173
	v_and_b32_e32 v111, 0xffff0000, v173
	v_pk_fma_f32 v[114:115], v[232:233], v[114:115], v[120:121]
	v_pk_fma_f32 v[110:111], v[234:235], v[112:113], v[110:111]
	s_nop 0
	v_cndmask_b32_e32 v113, v111, v147, vcc
	v_cndmask_b32_e32 v112, v110, v147, vcc
	v_cndmask_b32_e32 v111, v115, v147, vcc
	v_cndmask_b32_e32 v110, v114, v147, vcc
	global_store_dwordx4 v[116:117], v[110:113], off sc1
	v_lshlrev_b32_e32 v114, 16, v174
	v_and_b32_e32 v115, 0xffff0000, v174
	v_lshlrev_b32_e32 v110, 16, v175
	v_and_b32_e32 v111, 0xffff0000, v175
	v_pk_fma_f32 v[106:107], v[236:237], v[106:107], v[114:115]
	v_pk_fma_f32 v[108:109], v[238:239], v[108:109], v[110:111]
	v_or_b32_e32 v112, 0x100, v122
	v_mov_b32_e32 v113, v123
	v_cndmask_b32_e32 v109, v109, v147, vcc
	v_cndmask_b32_e32 v108, v108, v147, vcc
	v_cndmask_b32_e32 v107, v107, v147, vcc
	v_cndmask_b32_e32 v106, v106, v147, vcc
	v_lshl_add_u64 v[112:113], s[56:57], 0, v[112:113]
	global_store_dwordx4 v[116:117], v[106:109], off offset:64 sc1
	s_nop 1
	v_or_b32_e32 v122, 0x120, v122
	v_lshl_add_u64 v[108:109], s[56:57], 0, v[122:123]
	v_lshlrev_b32_e32 v110, 16, v176
	v_and_b32_e32 v111, 0xffff0000, v176
	v_lshlrev_b32_e32 v106, 16, v177
	v_and_b32_e32 v107, 0xffff0000, v177
	v_pk_fma_f32 v[102:103], v[240:241], v[102:103], v[110:111]
	v_pk_fma_f32 v[104:105], v[242:243], v[104:105], v[106:107]
	v_cndmask_b32_e32 v103, v103, v147, vcc
	v_cndmask_b32_e32 v105, v105, v147, vcc
	v_cndmask_b32_e32 v104, v104, v147, vcc
	v_cndmask_b32_e32 v102, v102, v147, vcc
	global_store_dwordx4 v[116:117], v[102:105], off offset:512 sc1
	s_nop 1
	v_lshlrev_b32_e32 v110, 16, v178
	v_add_u32_e32 v104, 32, v146
	v_ashrrev_i32_e32 v105, 31, v104
	v_and_b32_e32 v111, 0xffff0000, v178
	v_lshlrev_b32_e32 v102, 16, v179
	v_and_b32_e32 v103, 0xffff0000, v179
	v_lshlrev_b64 v[104:105], 10, v[104:105]
	v_pk_fma_f32 v[98:99], v[244:245], v[98:99], v[110:111]
	v_pk_fma_f32 v[100:101], v[246:247], v[100:101], v[102:103]
	v_lshl_add_u64 v[104:105], v[104:105], 0, v[0:1]
	v_cndmask_b32_e32 v101, v101, v147, vcc
	v_cndmask_b32_e32 v100, v100, v147, vcc
	v_cndmask_b32_e32 v99, v99, v147, vcc
	v_cndmask_b32_e32 v98, v98, v147, vcc
	v_lshlrev_b64 v[106:107], 1, v[104:105]
	global_store_dwordx4 v[116:117], v[98:101], off offset:576 sc1
	v_lshl_add_u64 v[108:109], s[56:57], 0, v[106:107]
	ds_read2_b64 v[98:101], v149 offset0:32 offset1:48
	v_lshl_add_u64 v[104:105], v[104:105], 2, s[94:95]
	v_or_b32_e32 v108, 32, v106
	v_mov_b32_e32 v109, v107
	v_lshl_add_u64 v[108:109], s[56:57], 0, v[108:109]
	s_waitcnt lgkmcnt(0)
	v_pk_mul_f32 v[96:97], v[96:97], v[98:99] op_sel:[0,1]
	v_pk_mul_f32 v[94:95], v[94:95], v[98:99] op_sel:[0,1]
	v_pk_mul_f32 v[92:93], v[92:93], v[98:99] op_sel:[0,1]
	v_pk_mul_f32 v[90:91], v[90:91], v[98:99] op_sel:[0,1]
	v_pk_mul_f32 v[88:89], v[88:89], v[98:99] op_sel:[0,1]
	v_pk_mul_f32 v[86:87], v[86:87], v[98:99] op_sel:[0,1]
	v_pk_mul_f32 v[84:85], v[84:85], v[98:99] op_sel:[0,1]
	v_pk_mul_f32 v[82:83], v[82:83], v[98:99] op_sel:[0,1]
	v_pk_mul_f32 v[80:81], v[80:81], v[100:101] op_sel:[0,1]
	v_pk_mul_f32 v[78:79], v[78:79], v[100:101] op_sel:[0,1]
	v_pk_mul_f32 v[76:77], v[76:77], v[100:101] op_sel:[0,1]
	v_pk_mul_f32 v[74:75], v[74:75], v[100:101] op_sel:[0,1]
	v_pk_mul_f32 v[72:73], v[72:73], v[100:101] op_sel:[0,1]
	v_pk_mul_f32 v[70:71], v[70:71], v[100:101] op_sel:[0,1]
	v_pk_mul_f32 v[68:69], v[68:69], v[100:101] op_sel:[0,1]
	v_pk_mul_f32 v[66:67], v[66:67], v[100:101] op_sel:[0,1]
	v_lshlrev_b32_e32 v110, 16, v180
	v_and_b32_e32 v111, 0xffff0000, v180
	v_lshlrev_b32_e32 v102, 16, v181
	v_and_b32_e32 v103, 0xffff0000, v181
	v_pk_fma_f32 v[94:95], v[232:233], v[94:95], v[110:111]
	v_pk_fma_f32 v[96:97], v[234:235], v[96:97], v[102:103]
	v_cndmask_b32_e32 v95, v95, v147, vcc
	v_cndmask_b32_e32 v97, v97, v147, vcc
	v_cndmask_b32_e32 v96, v96, v147, vcc
	v_cndmask_b32_e32 v94, v94, v147, vcc
	global_store_dwordx4 v[104:105], v[94:97], off sc1
	v_lshlrev_b32_e32 v102, 16, v182
	v_and_b32_e32 v103, 0xffff0000, v182
	v_lshlrev_b32_e32 v94, 16, v183
	v_and_b32_e32 v95, 0xffff0000, v183
	v_pk_fma_f32 v[90:91], v[236:237], v[90:91], v[102:103]
	v_pk_fma_f32 v[92:93], v[238:239], v[92:93], v[94:95]
	v_or_b32_e32 v96, 0x100, v106
	v_mov_b32_e32 v97, v107
	v_cndmask_b32_e32 v93, v93, v147, vcc
	v_cndmask_b32_e32 v92, v92, v147, vcc
	v_cndmask_b32_e32 v91, v91, v147, vcc
	v_cndmask_b32_e32 v90, v90, v147, vcc
	v_lshl_add_u64 v[96:97], s[56:57], 0, v[96:97]
	global_store_dwordx4 v[104:105], v[90:93], off offset:64 sc1
	s_nop 1
	v_or_b32_e32 v106, 0x120, v106
	v_lshl_add_u64 v[92:93], s[56:57], 0, v[106:107]
	v_lshlrev_b32_e32 v94, 16, v184
	v_and_b32_e32 v95, 0xffff0000, v184
	v_lshlrev_b32_e32 v90, 16, v185
	v_and_b32_e32 v91, 0xffff0000, v185
	v_pk_fma_f32 v[86:87], v[240:241], v[86:87], v[94:95]
	v_pk_fma_f32 v[88:89], v[242:243], v[88:89], v[90:91]
	v_cndmask_b32_e32 v87, v87, v147, vcc
	v_cndmask_b32_e32 v89, v89, v147, vcc
	v_cndmask_b32_e32 v88, v88, v147, vcc
	v_cndmask_b32_e32 v86, v86, v147, vcc
	global_store_dwordx4 v[104:105], v[86:89], off offset:512 sc1
	s_nop 1
	v_lshlrev_b32_e32 v94, 16, v186
	v_add_u32_e32 v88, 48, v146
	v_ashrrev_i32_e32 v89, 31, v88
	v_lshlrev_b64 v[88:89], 10, v[88:89]
	v_and_b32_e32 v95, 0xffff0000, v186
	v_lshlrev_b32_e32 v86, 16, v187
	v_and_b32_e32 v87, 0xffff0000, v187
	v_lshl_add_u64 v[88:89], v[88:89], 0, v[0:1]
	v_pk_fma_f32 v[82:83], v[244:245], v[82:83], v[94:95]
	v_pk_fma_f32 v[84:85], v[246:247], v[84:85], v[86:87]
	v_lshlrev_b64 v[90:91], 1, v[88:89]
	v_cndmask_b32_e32 v85, v85, v147, vcc
	v_cndmask_b32_e32 v84, v84, v147, vcc
	v_cndmask_b32_e32 v83, v83, v147, vcc
	v_cndmask_b32_e32 v82, v82, v147, vcc
	v_lshl_add_u64 v[92:93], s[56:57], 0, v[90:91]
	global_store_dwordx4 v[104:105], v[82:85], off offset:576 sc1
	s_nop 1
	v_or_b32_e32 v86, 32, v90
	v_lshl_add_u64 v[84:85], v[88:89], 2, s[94:95]
	v_mov_b32_e32 v87, v91
	v_lshl_add_u64 v[86:87], s[56:57], 0, v[86:87]
	v_lshlrev_b32_e32 v88, 16, v188
	v_and_b32_e32 v89, 0xffff0000, v188
	v_lshlrev_b32_e32 v82, 16, v189
	v_and_b32_e32 v83, 0xffff0000, v189
	v_pk_fma_f32 v[78:79], v[232:233], v[78:79], v[88:89]
	v_pk_fma_f32 v[80:81], v[234:235], v[80:81], v[82:83]
	v_cndmask_b32_e32 v79, v79, v147, vcc
	v_cndmask_b32_e32 v81, v81, v147, vcc
	v_cndmask_b32_e32 v80, v80, v147, vcc
	v_cndmask_b32_e32 v78, v78, v147, vcc
	global_store_dwordx4 v[84:85], v[78:81], off sc1
	v_lshlrev_b32_e32 v82, 16, v190
	v_and_b32_e32 v83, 0xffff0000, v190
	v_lshlrev_b32_e32 v78, 16, v191
	v_and_b32_e32 v79, 0xffff0000, v191
	v_pk_fma_f32 v[74:75], v[236:237], v[74:75], v[82:83]
	v_pk_fma_f32 v[76:77], v[238:239], v[76:77], v[78:79]
	v_or_b32_e32 v80, 0x100, v90
	v_mov_b32_e32 v81, v91
	v_cndmask_b32_e32 v77, v77, v147, vcc
	v_cndmask_b32_e32 v76, v76, v147, vcc
	v_cndmask_b32_e32 v75, v75, v147, vcc
	v_cndmask_b32_e32 v74, v74, v147, vcc
	v_lshl_add_u64 v[80:81], s[56:57], 0, v[80:81]
	global_store_dwordx4 v[84:85], v[74:77], off offset:64 sc1
	s_nop 1
	v_or_b32_e32 v90, 0x120, v90
	v_lshl_add_u64 v[76:77], s[56:57], 0, v[90:91]
	v_lshlrev_b32_e32 v78, 16, v192
	v_and_b32_e32 v79, 0xffff0000, v192
	v_lshlrev_b32_e32 v74, 16, v193
	v_and_b32_e32 v75, 0xffff0000, v193
	v_pk_fma_f32 v[70:71], v[240:241], v[70:71], v[78:79]
	v_pk_fma_f32 v[72:73], v[242:243], v[72:73], v[74:75]
	v_cndmask_b32_e32 v71, v71, v147, vcc
	v_cndmask_b32_e32 v73, v73, v147, vcc
	v_cndmask_b32_e32 v72, v72, v147, vcc
	v_cndmask_b32_e32 v70, v70, v147, vcc
	global_store_dwordx4 v[84:85], v[70:73], off offset:512 sc1
	s_nop 1
	v_lshlrev_b32_e32 v78, 16, v194
	v_add_u32_e32 v72, 0x80, v146
	v_ashrrev_i32_e32 v73, 31, v72
	v_and_b32_e32 v79, 0xffff0000, v194
	v_lshlrev_b32_e32 v70, 16, v195
	v_and_b32_e32 v71, 0xffff0000, v195
	v_lshlrev_b64 v[72:73], 10, v[72:73]
	v_pk_fma_f32 v[66:67], v[244:245], v[66:67], v[78:79]
	v_pk_fma_f32 v[68:69], v[246:247], v[68:69], v[70:71]
	v_lshl_add_u64 v[72:73], v[72:73], 0, v[0:1]
	v_cndmask_b32_e32 v69, v69, v147, vcc
	v_cndmask_b32_e32 v68, v68, v147, vcc
	v_cndmask_b32_e32 v67, v67, v147, vcc
	v_cndmask_b32_e32 v66, v66, v147, vcc
	v_lshlrev_b64 v[74:75], 1, v[72:73]
	global_store_dwordx4 v[84:85], v[66:69], off offset:576 sc1
	v_lshl_add_u64 v[76:77], s[56:57], 0, v[74:75]
	ds_read2_b64 v[66:69], v149 offset0:128 offset1:144
	v_lshl_add_u64 v[72:73], v[72:73], 2, s[94:95]
	v_or_b32_e32 v76, 32, v74
	v_mov_b32_e32 v77, v75
	v_lshl_add_u64 v[76:77], s[56:57], 0, v[76:77]
	s_waitcnt lgkmcnt(0)
	v_pk_mul_f32 v[64:65], v[64:65], v[66:67] op_sel:[0,1]
	v_pk_mul_f32 v[62:63], v[62:63], v[66:67] op_sel:[0,1]
	v_pk_mul_f32 v[60:61], v[60:61], v[66:67] op_sel:[0,1]
	v_pk_mul_f32 v[58:59], v[58:59], v[66:67] op_sel:[0,1]
	v_pk_mul_f32 v[56:57], v[56:57], v[66:67] op_sel:[0,1]
	v_pk_mul_f32 v[54:55], v[54:55], v[66:67] op_sel:[0,1]
	v_pk_mul_f32 v[52:53], v[52:53], v[66:67] op_sel:[0,1]
	v_pk_mul_f32 v[50:51], v[50:51], v[66:67] op_sel:[0,1]
	v_pk_mul_f32 v[48:49], v[48:49], v[68:69] op_sel:[0,1]
	v_pk_mul_f32 v[46:47], v[46:47], v[68:69] op_sel:[0,1]
	v_pk_mul_f32 v[44:45], v[44:45], v[68:69] op_sel:[0,1]
	v_pk_mul_f32 v[42:43], v[42:43], v[68:69] op_sel:[0,1]
	v_pk_mul_f32 v[40:41], v[40:41], v[68:69] op_sel:[0,1]
	v_pk_mul_f32 v[38:39], v[38:39], v[68:69] op_sel:[0,1]
	v_pk_mul_f32 v[36:37], v[36:37], v[68:69] op_sel:[0,1]
	v_pk_mul_f32 v[34:35], v[34:35], v[68:69] op_sel:[0,1]
	v_lshlrev_b32_e32 v78, 16, v196
	v_and_b32_e32 v79, 0xffff0000, v196
	v_lshlrev_b32_e32 v70, 16, v197
	v_and_b32_e32 v71, 0xffff0000, v197
	v_pk_fma_f32 v[62:63], v[232:233], v[62:63], v[78:79]
	v_pk_fma_f32 v[64:65], v[234:235], v[64:65], v[70:71]
	v_cndmask_b32_e32 v63, v63, v147, vcc
	v_cndmask_b32_e32 v65, v65, v147, vcc
	v_cndmask_b32_e32 v64, v64, v147, vcc
	v_cndmask_b32_e32 v62, v62, v147, vcc
	global_store_dwordx4 v[72:73], v[62:65], off sc1
	v_lshlrev_b32_e32 v70, 16, v198
	v_and_b32_e32 v71, 0xffff0000, v198
	v_lshlrev_b32_e32 v62, 16, v199
	v_and_b32_e32 v63, 0xffff0000, v199
	v_pk_fma_f32 v[58:59], v[236:237], v[58:59], v[70:71]
	v_pk_fma_f32 v[60:61], v[238:239], v[60:61], v[62:63]
	v_or_b32_e32 v64, 0x100, v74
	v_mov_b32_e32 v65, v75
	v_cndmask_b32_e32 v61, v61, v147, vcc
	v_cndmask_b32_e32 v60, v60, v147, vcc
	v_cndmask_b32_e32 v59, v59, v147, vcc
	v_cndmask_b32_e32 v58, v58, v147, vcc
	v_lshl_add_u64 v[64:65], s[56:57], 0, v[64:65]
	global_store_dwordx4 v[72:73], v[58:61], off offset:64 sc1
	s_nop 1
	v_or_b32_e32 v74, 0x120, v74
	v_lshl_add_u64 v[60:61], s[56:57], 0, v[74:75]
	v_lshlrev_b32_e32 v62, 16, v200
	v_and_b32_e32 v63, 0xffff0000, v200
	v_lshlrev_b32_e32 v58, 16, v201
	v_and_b32_e32 v59, 0xffff0000, v201
	v_pk_fma_f32 v[54:55], v[240:241], v[54:55], v[62:63]
	v_pk_fma_f32 v[56:57], v[242:243], v[56:57], v[58:59]
	v_cndmask_b32_e32 v55, v55, v147, vcc
	v_cndmask_b32_e32 v57, v57, v147, vcc
	v_cndmask_b32_e32 v56, v56, v147, vcc
	v_cndmask_b32_e32 v54, v54, v147, vcc
	global_store_dwordx4 v[72:73], v[54:57], off offset:512 sc1
	s_nop 1
	v_lshlrev_b32_e32 v62, 16, v204
	v_add_u32_e32 v56, 0x90, v146
	v_ashrrev_i32_e32 v57, 31, v56
	v_lshlrev_b64 v[56:57], 10, v[56:57]
	v_and_b32_e32 v63, 0xffff0000, v204
	v_lshlrev_b32_e32 v54, 16, v205
	v_and_b32_e32 v55, 0xffff0000, v205
	v_lshl_add_u64 v[56:57], v[56:57], 0, v[0:1]
	v_pk_fma_f32 v[50:51], v[244:245], v[50:51], v[62:63]
	v_pk_fma_f32 v[52:53], v[246:247], v[52:53], v[54:55]
	v_lshlrev_b64 v[58:59], 1, v[56:57]
	v_cndmask_b32_e32 v53, v53, v147, vcc
	v_cndmask_b32_e32 v52, v52, v147, vcc
	v_cndmask_b32_e32 v51, v51, v147, vcc
	v_cndmask_b32_e32 v50, v50, v147, vcc
	v_lshl_add_u64 v[60:61], s[56:57], 0, v[58:59]
	global_store_dwordx4 v[72:73], v[50:53], off offset:576 sc1
	s_nop 1
	v_or_b32_e32 v54, 32, v58
	v_lshl_add_u64 v[52:53], v[56:57], 2, s[94:95]
	v_mov_b32_e32 v55, v59
	v_lshl_add_u64 v[54:55], s[56:57], 0, v[54:55]
	v_lshlrev_b32_e32 v56, 16, v206
	v_and_b32_e32 v57, 0xffff0000, v206
	v_lshlrev_b32_e32 v50, 16, v207
	v_and_b32_e32 v51, 0xffff0000, v207
	v_pk_fma_f32 v[46:47], v[232:233], v[46:47], v[56:57]
	v_pk_fma_f32 v[48:49], v[234:235], v[48:49], v[50:51]
	v_cndmask_b32_e32 v47, v47, v147, vcc
	v_cndmask_b32_e32 v49, v49, v147, vcc
	v_cndmask_b32_e32 v48, v48, v147, vcc
	v_cndmask_b32_e32 v46, v46, v147, vcc
	global_store_dwordx4 v[52:53], v[46:49], off sc1
	v_lshlrev_b32_e32 v50, 16, v208
	v_and_b32_e32 v51, 0xffff0000, v208
	v_lshlrev_b32_e32 v46, 16, v209
	v_and_b32_e32 v47, 0xffff0000, v209
	v_pk_fma_f32 v[42:43], v[236:237], v[42:43], v[50:51]
	v_pk_fma_f32 v[44:45], v[238:239], v[44:45], v[46:47]
	v_or_b32_e32 v48, 0x100, v58
	v_mov_b32_e32 v49, v59
	v_cndmask_b32_e32 v45, v45, v147, vcc
	v_cndmask_b32_e32 v44, v44, v147, vcc
	v_cndmask_b32_e32 v43, v43, v147, vcc
	v_cndmask_b32_e32 v42, v42, v147, vcc
	v_lshl_add_u64 v[48:49], s[56:57], 0, v[48:49]
	global_store_dwordx4 v[52:53], v[42:45], off offset:64 sc1
	s_nop 1
	v_or_b32_e32 v58, 0x120, v58
	v_lshl_add_u64 v[44:45], s[56:57], 0, v[58:59]
	v_lshlrev_b32_e32 v46, 16, v210
	v_and_b32_e32 v47, 0xffff0000, v210
	v_lshlrev_b32_e32 v42, 16, v211
	v_and_b32_e32 v43, 0xffff0000, v211
	v_pk_fma_f32 v[38:39], v[240:241], v[38:39], v[46:47]
	v_pk_fma_f32 v[40:41], v[242:243], v[40:41], v[42:43]
	v_cndmask_b32_e32 v39, v39, v147, vcc
	v_cndmask_b32_e32 v41, v41, v147, vcc
	v_cndmask_b32_e32 v40, v40, v147, vcc
	v_cndmask_b32_e32 v38, v38, v147, vcc
	global_store_dwordx4 v[52:53], v[38:41], off offset:512 sc1
	s_nop 1
	v_lshlrev_b32_e32 v46, 16, v212
	v_add_u32_e32 v40, 0xa0, v146
	v_ashrrev_i32_e32 v41, 31, v40
	v_and_b32_e32 v47, 0xffff0000, v212
	v_lshlrev_b32_e32 v38, 16, v213
	v_and_b32_e32 v39, 0xffff0000, v213
	v_lshlrev_b64 v[40:41], 10, v[40:41]
	v_pk_fma_f32 v[34:35], v[244:245], v[34:35], v[46:47]
	v_pk_fma_f32 v[36:37], v[246:247], v[36:37], v[38:39]
	v_lshl_add_u64 v[40:41], v[40:41], 0, v[0:1]
	v_cndmask_b32_e32 v37, v37, v147, vcc
	v_cndmask_b32_e32 v36, v36, v147, vcc
	v_cndmask_b32_e32 v35, v35, v147, vcc
	v_cndmask_b32_e32 v34, v34, v147, vcc
	v_lshlrev_b64 v[42:43], 1, v[40:41]
	global_store_dwordx4 v[52:53], v[34:37], off offset:576 sc1
	v_lshl_add_u64 v[44:45], s[56:57], 0, v[42:43]
	ds_read2_b64 v[34:37], v149 offset0:160 offset1:176
	v_lshl_add_u64 v[40:41], v[40:41], 2, s[94:95]
	v_or_b32_e32 v44, 32, v42
	v_mov_b32_e32 v45, v43
	v_lshl_add_u64 v[44:45], s[56:57], 0, v[44:45]
	s_waitcnt lgkmcnt(0)
	v_pk_mul_f32 v[32:33], v[32:33], v[34:35] op_sel:[0,1]
	v_pk_mul_f32 v[30:31], v[30:31], v[34:35] op_sel:[0,1]
	v_pk_mul_f32 v[28:29], v[28:29], v[34:35] op_sel:[0,1]
	v_pk_mul_f32 v[26:27], v[26:27], v[34:35] op_sel:[0,1]
	v_pk_mul_f32 v[24:25], v[24:25], v[34:35] op_sel:[0,1]
	v_pk_mul_f32 v[22:23], v[22:23], v[34:35] op_sel:[0,1]
	v_pk_mul_f32 v[20:21], v[20:21], v[34:35] op_sel:[0,1]
	v_pk_mul_f32 v[18:19], v[18:19], v[34:35] op_sel:[0,1]
	v_pk_mul_f32 v[16:17], v[16:17], v[36:37] op_sel:[0,1]
	v_pk_mul_f32 v[14:15], v[14:15], v[36:37] op_sel:[0,1]
	v_pk_mul_f32 v[12:13], v[12:13], v[36:37] op_sel:[0,1]
	v_pk_mul_f32 v[10:11], v[10:11], v[36:37] op_sel:[0,1]
	v_pk_mul_f32 v[8:9], v[8:9], v[36:37] op_sel:[0,1]
	v_pk_mul_f32 v[6:7], v[6:7], v[36:37] op_sel:[0,1]
	v_pk_mul_f32 v[4:5], v[4:5], v[36:37] op_sel:[0,1]
	v_pk_mul_f32 v[2:3], v[2:3], v[36:37] op_sel:[0,1]
	v_lshlrev_b32_e32 v46, 16, v214
	v_and_b32_e32 v47, 0xffff0000, v214
	v_lshlrev_b32_e32 v38, 16, v215
	v_and_b32_e32 v39, 0xffff0000, v215
	v_pk_fma_f32 v[30:31], v[232:233], v[30:31], v[46:47]
	v_pk_fma_f32 v[32:33], v[234:235], v[32:33], v[38:39]
	v_cndmask_b32_e32 v31, v31, v147, vcc
	v_cndmask_b32_e32 v33, v33, v147, vcc
	v_cndmask_b32_e32 v32, v32, v147, vcc
	v_cndmask_b32_e32 v30, v30, v147, vcc
	global_store_dwordx4 v[40:41], v[30:33], off sc1
	v_lshlrev_b32_e32 v38, 16, v216
	v_and_b32_e32 v39, 0xffff0000, v216
	v_lshlrev_b32_e32 v30, 16, v217
	v_and_b32_e32 v31, 0xffff0000, v217
	v_pk_fma_f32 v[26:27], v[236:237], v[26:27], v[38:39]
	v_pk_fma_f32 v[28:29], v[238:239], v[28:29], v[30:31]
	v_or_b32_e32 v32, 0x100, v42
	v_mov_b32_e32 v33, v43
	v_cndmask_b32_e32 v29, v29, v147, vcc
	v_cndmask_b32_e32 v28, v28, v147, vcc
	v_cndmask_b32_e32 v27, v27, v147, vcc
	v_cndmask_b32_e32 v26, v26, v147, vcc
	v_lshl_add_u64 v[32:33], s[56:57], 0, v[32:33]
	global_store_dwordx4 v[40:41], v[26:29], off offset:64 sc1
	s_nop 1
	v_or_b32_e32 v42, 0x120, v42
	v_lshl_add_u64 v[28:29], s[56:57], 0, v[42:43]
	v_lshlrev_b32_e32 v30, 16, v218
	v_and_b32_e32 v31, 0xffff0000, v218
	v_lshlrev_b32_e32 v26, 16, v219
	v_and_b32_e32 v27, 0xffff0000, v219
	v_pk_fma_f32 v[22:23], v[240:241], v[22:23], v[30:31]
	v_pk_fma_f32 v[24:25], v[242:243], v[24:25], v[26:27]
	v_cndmask_b32_e32 v23, v23, v147, vcc
	v_cndmask_b32_e32 v25, v25, v147, vcc
	v_cndmask_b32_e32 v24, v24, v147, vcc
	v_cndmask_b32_e32 v22, v22, v147, vcc
	global_store_dwordx4 v[40:41], v[22:25], off offset:512 sc1
	s_nop 1
	v_lshlrev_b32_e32 v28, 16, v220
	v_add_u32_e32 v24, 0xb0, v146
	v_ashrrev_i32_e32 v25, 31, v24
	v_lshlrev_b64 v[24:25], 10, v[24:25]
	v_and_b32_e32 v29, 0xffff0000, v220
	v_lshlrev_b32_e32 v22, 16, v221
	v_and_b32_e32 v23, 0xffff0000, v221
	v_lshl_add_u64 v[0:1], v[24:25], 0, v[0:1]
	v_pk_fma_f32 v[18:19], v[244:245], v[18:19], v[28:29]
	v_pk_fma_f32 v[20:21], v[246:247], v[20:21], v[22:23]
	v_lshlrev_b64 v[24:25], 1, v[0:1]
	v_cndmask_b32_e32 v21, v21, v147, vcc
	v_cndmask_b32_e32 v20, v20, v147, vcc
	v_cndmask_b32_e32 v19, v19, v147, vcc
	v_cndmask_b32_e32 v18, v18, v147, vcc
	v_lshl_add_u64 v[26:27], s[56:57], 0, v[24:25]
	global_store_dwordx4 v[40:41], v[18:21], off offset:576 sc1
	v_lshlrev_b32_e32 v22, 16, v222
	v_and_b32_e32 v23, 0xffff0000, v222
	v_lshlrev_b32_e32 v18, 16, v223
	v_and_b32_e32 v19, 0xffff0000, v223
	v_pk_fma_f32 v[14:15], v[232:233], v[14:15], v[22:23]
	v_pk_fma_f32 v[16:17], v[234:235], v[16:17], v[18:19]
	v_lshl_add_u64 v[20:21], v[0:1], 2, s[94:95]
	v_or_b32_e32 v0, 32, v24
	v_mov_b32_e32 v1, v25
	v_cndmask_b32_e32 v17, v17, v147, vcc
	v_cndmask_b32_e32 v16, v16, v147, vcc
	v_cndmask_b32_e32 v15, v15, v147, vcc
	v_cndmask_b32_e32 v14, v14, v147, vcc
	v_lshl_add_u64 v[0:1], s[56:57], 0, v[0:1]
	global_store_dwordx4 v[20:21], v[14:17], off sc1
	s_nop 1
	s_nop 0
	v_or_b32_e32 v14, 0x100, v24
	v_mov_b32_e32 v15, v25
	v_lshl_add_u64 v[14:15], s[56:57], 0, v[14:15]
	v_or_b32_e32 v24, 0x120, v24
	v_lshlrev_b32_e32 v16, 16, v224
	v_and_b32_e32 v17, 0xffff0000, v224
	v_lshlrev_b32_e32 v0, 16, v225
	v_and_b32_e32 v1, 0xffff0000, v225
	v_pk_fma_f32 v[10:11], v[236:237], v[10:11], v[16:17]
	v_pk_fma_f32 v[0:1], v[238:239], v[12:13], v[0:1]
	v_cndmask_b32_e32 v11, v11, v147, vcc
	v_cndmask_b32_e32 v13, v1, v147, vcc
	v_cndmask_b32_e32 v12, v0, v147, vcc
	v_cndmask_b32_e32 v10, v10, v147, vcc
	global_store_dwordx4 v[20:21], v[10:13], off offset:64 sc1
	s_nop 1
	s_nop 0
	v_lshl_add_u64 v[10:11], s[56:57], 0, v[24:25]
	v_lshlrev_b32_e32 v12, 16, v226
	v_and_b32_e32 v13, 0xffff0000, v226
	v_lshlrev_b32_e32 v0, 16, v227
	v_and_b32_e32 v1, 0xffff0000, v227
	v_pk_fma_f32 v[6:7], v[240:241], v[6:7], v[12:13]
	v_pk_fma_f32 v[0:1], v[242:243], v[8:9], v[0:1]
	v_cndmask_b32_e32 v7, v7, v147, vcc
	v_cndmask_b32_e32 v9, v1, v147, vcc
	v_cndmask_b32_e32 v8, v0, v147, vcc
	v_cndmask_b32_e32 v6, v6, v147, vcc
	global_store_dwordx4 v[20:21], v[6:9], off offset:512 sc1
	s_nop 1
	v_lshlrev_b32_e32 v6, 16, v228
	v_and_b32_e32 v7, 0xffff0000, v228
	v_lshlrev_b32_e32 v0, 16, v229
	v_and_b32_e32 v1, 0xffff0000, v229
	v_pk_fma_f32 v[6:7], v[244:245], v[2:3], v[6:7]
	v_pk_fma_f32 v[0:1], v[246:247], v[4:5], v[0:1]
	s_nop 0
	v_cndmask_b32_e32 v3, v1, v147, vcc
	v_cndmask_b32_e32 v2, v0, v147, vcc
	v_cndmask_b32_e32 v1, v7, v147, vcc
	v_cndmask_b32_e32 v0, v6, v147, vcc
	global_store_dwordx4 v[20:21], v[0:3], off offset:576 sc1
